# MFMA-block satisfied waits and mid-block setprio pair removed; in-proj/qkv epilogue vmcnt ladder (guards only preloads completed by K-loop waits) replaced by s_nop; LDS-DMA m0 save/restore removed
# speedup vs baseline: 1.0420x; 1.0420x over previous
; __device__ __forceinline__ int otid() { int t = threadIdx.x; asm volatile("" : "+v"(t)); return t; }
; template <class Epi, class Sched, bool ALIGN_EPI>
; __device__ __forceinline__ void gemm_phase(LAS unsigned char* lds, const Gemm g, const Sched& S, const Epi& E) {
;     const int tid = otid(), wid = __builtin_amdgcn_readfirstlane(tid >> 6), lane = tid & 63, wr = wid >> 2, wc = wid & 3, fr = lane & 15, fq = lane >> 4;
;     const int K = g.K, nt = K / BK;
;     unsigned voffA[2], voffB[2];
; #pragma unroll
;     for (int i = 0; i < 2; ++i) { int R, C; stage_rc(tid * 16 + i * 8192, R, C); const int Rb = (R & ~31) + perm32(R & 31);
;         voffA[i] = (unsigned)(R * g.lda + C) * 2u; voffB[i] = (unsigned)(Rb * g.ldb + C) * 2u; }
;     const size_t kstep = (size_t)(BK * 2);
;     const size_t hstepA = (size_t)HALF * g.lda * 2, hstepB = (size_t)HALF * g.ldb * 2;
;     const size_t tstepA = 2 * hstepA, tstepB = 2 * hstepB;
;     const unsigned ldsw = (unsigned)wid * 1024u;
;     const int aoff = lds_byte(wr * 64 + fr, fq * 8), boff = lds_byte(wc * 32 + fr, fq * 8);
;     ...
;     const unsigned ldsb0 = (unsigned)(uintptr_t)lds + ldsw;
;     ...
;     Unit cur, nxt; int ui = 0;
;     if (!S.next(0, cur)) return;
;     f32x4 acc[2][2][4][2];
; #pragma unroll
;     for (int a = 0; a < 2; ++a)
; #pragma unroll
;         for (int b = 0; b < 2; ++b)
; #pragma unroll
;             for (int m = 0; m < 4; ++m)
; #pragma unroll
;                 for (int n = 0; n < 2; ++n) acc[a][b][m][n] = (f32x4){0.f, 0.f, 0.f, 0.f};
;     bf16x8 At[4][2], B0[2][2], B1[2][2];
;     float pre[Epi::NPRE > 0 ? Epi::NPRE : 1];
;     if constexpr (Epi::NPRE > 0) E.preload(cur, wr, fr, pre);
;     const char* cA = (const char*)g.A + (size_t)cur.pm * tstepA + (size_t)cur.pn * g.a_koff * 2; const char* cB = (const char*)g.Bt + (size_t)cur.pn * tstepB;
;     PG8_STAGE(PG8_SB(0, 0), cB, voffB); PG8_STAGE(PG8_SB(0, 1), cB + hstepB, voffB); PG8_STAGE(PG8_SA(0, 0), cA, voffA); PG8_STAGE(PG8_SA(0, 1), cA + hstepA, voffA);
;     __device__ __forceinline__ void preload(const pg8::Unit& u, int wr, int fr, float* rsv) const {
; #pragma unroll
;         for (int k = 0; k < 8; ++k) rsv[k] = ssq[u.pm * 256 + (k >> 2) * 128 + wr * 64 + (k & 3) * 16 + fr]; }
.LBB0_99:
	s_or_b64 exec, exec, s[4:5]
	s_cmpk_lg_i32 s76, 0x100
	s_cselect_b64 s[20:21], -1, 0
	s_cmpk_gt_i32 s86, 0x1ff
	s_cselect_b64 s[18:19], -1, 0
	s_lshl_b32 s2, s86, 2
	s_and_b32 s4, s2, 24
	s_bfe_u32 s5, s86, 0x30003
	s_or_b32 s26, s4, s5
	s_and_b32 s2, s2, 4
	s_ashr_i32 s4, s86, 6
	s_ashr_i32 s24, s86, 5
	s_and_b32 s25, s86, 31
	s_add_i32 s27, s2, s4
	s_cmpk_eq_i32 s76, 0x100
	s_cselect_b64 s[22:23], -1, 0
	v_writelane_b32 v242, s22, 10
	s_mov_b64 s[10:11], s[0:1]
	s_mov_b64 s[12:13], s[0:1]
	v_writelane_b32 v242, s23, 11
	s_and_b64 s[22:23], s[22:23], exec
	s_mov_b64 s[14:15], s[0:1]
	s_mov_b64 s[6:7], s[0:1]
	s_mov_b64 s[16:17], s[0:1]
	s_mov_b64 s[4:5], s[0:1]
	s_mov_b64 s[8:9], s[0:1]
	s_mov_b64 s[28:29], s[0:1]
	s_mov_b64 s[30:31], s[0:1]
	s_mov_b64 s[34:35], s[0:1]
	s_waitcnt lgkmcnt(0)
	v_mov_b32_e32 v2, v0
	s_cselect_b32 s22, s27, s24
	s_cselect_b32 s60, s26, s25
	s_and_b64 s[18:19], s[20:21], s[18:19]
	s_barrier
	v_writelane_b32 v242, s27, 12
	v_readfirstlane_b32 s2, v2
	s_and_b64 vcc, exec, s[18:19]
	v_writelane_b32 v242, s26, 13
	s_cbranch_vccnz .LBB0_376
	v_bfe_i32 v4, v2, 27, 1
	v_lshlrev_b32_e32 v6, 4, v2
	v_lshrrev_b32_e32 v4, 22, v4
	v_add_u32_e32 v4, v6, v4
	v_and_b32_e32 v4, 0xfffffc00, v4
	v_sub_u32_e32 v4, v6, v4
	s_load_dwordx2 s[10:11], s[10:11], 0xb0
	s_nop 0
	s_load_dwordx2 s[12:13], s[12:13], 0xb0
	s_nop 0
	s_load_dwordx2 s[18:19], s[14:15], 0xb0
	s_nop 0
	s_load_dwordx2 s[14:15], s[6:7], 0xb0
	s_nop 0
	s_load_dwordx2 s[16:17], s[16:17], 0xa8
	v_ashrrev_i32_e32 v3, 31, v2
	v_lshrrev_b32_e32 v5, 4, v4
	s_waitcnt lgkmcnt(0)
	s_add_u32 s53, s10, 0x1d800000
	v_lshrrev_b32_e32 v3, 26, v3
	v_bitop3_b32 v5, v5, v4, 32 bitop3:0x6c
	v_ashrrev_i32_e32 v4, 31, v4
	s_addc_u32 s54, s11, 0
	v_add_u32_e32 v3, v2, v3
	v_lshrrev_b32_e32 v4, 26, v4
	s_add_u32 s55, s12, 0x100000
	v_ashrrev_i32_e32 v3, 6, v3
	v_add_u32_e32 v4, v5, v4
	s_addc_u32 s57, s13, 0
	v_lshlrev_b32_e32 v7, 3, v3
	v_ashrrev_i32_e32 v8, 6, v4
	v_lshlrev_b32_e32 v3, 5, v3
	s_add_u32 s10, s18, 0x10000
	v_and_b32_e32 v9, 32, v3
	v_mul_i32_i24_e32 v3, 64, v8
	s_addc_u32 s11, s19, 0
	s_ashr_i32 s25, s2, 8
	v_sub_u32_e32 v3, v5, v3
	v_mov_b32_e32 v10, 1
	s_load_dwordx2 s[18:19], s[4:5], 0xb0
	s_load_dwordx2 s[26:27], s[8:9], 0xb0
	s_nop 0
	s_load_dwordx2 s[28:29], s[28:29], 0xb0
	s_nop 0
	s_load_dwordx2 s[30:31], s[30:31], 0xa8
	s_nop 0
	s_load_dwordx2 s[8:9], s[34:35], 0xa8
	v_ashrrev_i16_sdwa v3, v10, sext(v3) dst_sel:DWORD dst_unused:UNUSED_PAD src0_sel:DWORD src1_sel:BYTE_0
	s_lshl_b32 s36, s25, 6
	s_lshl_b32 s4, s60, 8
	v_bfe_i32 v11, v3, 0, 16
	v_and_b32_e32 v3, 15, v2
	s_add_i32 s4, s4, s36
	v_or_b32_e32 v4, s4, v3
	v_ashrrev_i32_e32 v5, 31, v4
	v_lshl_add_u64 v[4:5], v[4:5], 2, s[10:11]
	global_load_dword v134, v[4:5], off
	global_load_dword v170, v[4:5], off offset:64
	global_load_dword v169, v[4:5], off offset:128
	global_load_dword v168, v[4:5], off offset:192
	global_load_dword v167, v[4:5], off offset:512
	global_load_dword v165, v[4:5], off offset:576
	global_load_dword v164, v[4:5], off offset:640
	global_load_dword v163, v[4:5], off offset:704
	v_and_b32_e32 v7, -16, v7
	v_add_u32_e32 v7, v8, v7
	v_lshlrev_b32_e32 v4, 1, v7
	v_lshrrev_b32_e32 v5, 2, v7
	v_and_b32_e32 v8, 3, v8
	s_mov_b32 s4, 0xfffe0
	v_and_b32_e32 v4, 24, v4
	v_and_b32_e32 v5, 4, v5
	v_and_or_b32 v8, v7, s4, v8
	v_or3_b32 v4, v8, v5, v4
	v_add_lshl_u32 v5, v9, v11, 1
	v_lshl_add_u32 v152, v4, 12, v5
	v_add_u32_e32 v4, 0x2000, v6
	v_lshl_add_u32 v151, v7, 12, v5
	v_ashrrev_i32_e32 v5, 31, v4
	v_lshrrev_b32_e32 v5, 22, v5
	v_add_u32_e32 v5, v4, v5
	v_ashrrev_i32_e32 v5, 10, v5
	v_mul_i32_i24_e32 v6, 0x400, v5
	v_sub_u32_e32 v4, v4, v6
	v_lshrrev_b32_e32 v6, 4, v4
	v_bitop3_b32 v4, v6, v4, 32 bitop3:0x6c
	v_ashrrev_i32_e32 v7, 31, v4
	v_lshrrev_b32_e32 v7, 26, v7
	v_lshlrev_b32_e32 v6, 3, v5
	v_add_u32_e32 v7, v4, v7
	v_and_b32_e32 v6, -16, v6
	v_ashrrev_i32_e32 v8, 6, v7
	v_add_u32_e32 v6, v8, v6
	v_and_b32_e32 v7, 0xc0, v7
	v_and_b32_e32 v8, 3, v8
	s_ashr_i32 s37, s2, 6
	v_sub_u32_e32 v4, v4, v7
	v_and_or_b32 v8, v6, s4, v8
	s_lshl_b32 s4, s37, 10
	s_ashr_i32 s23, s22, 31
	v_lshlrev_b32_e32 v5, 5, v5
	v_ashrrev_i16_sdwa v4, v10, sext(v4) dst_sel:DWORD dst_unused:UNUSED_PAD src0_sel:DWORD src1_sel:BYTE_0
	v_lshlrev_b32_e32 v7, 1, v6
	v_lshrrev_b32_e32 v9, 2, v6
	s_add_i32 s61, s4, 0
	s_lshl_b32 s12, s60, 20
	s_lshl_b64 s[4:5], s[22:23], 20
	v_and_b32_e32 v5, 32, v5
	v_bfe_i32 v4, v4, 0, 16
	v_and_b32_e32 v7, 24, v7
	v_and_b32_e32 v9, 4, v9
	s_add_u32 s6, s55, s4
	v_or3_b32 v7, v8, v9, v7
	v_add_lshl_u32 v4, v5, v4, 1
	s_addc_u32 s7, s57, s5
	s_add_i32 s23, s61, 0x10000
	s_mov_b32 m0, s23
	s_nop 0
	global_load_lds_dwordx4 v152, s[6:7]
	v_lshl_add_u32 v154, v7, 12, v4
	s_add_i32 s62, s61, 0x12000
	s_mov_b32 m0, s62
	s_nop 0
	global_load_lds_dwordx4 v154, s[6:7]
	s_add_u32 s4, s6, 0x80000
	s_addc_u32 s5, s7, 0
	s_add_i32 s63, s61, 0x14000
	s_mov_b32 m0, s63
	s_nop 0
	global_load_lds_dwordx4 v152, s[4:5]
	s_add_i32 s64, s61, 0x16000
	s_mov_b32 m0, s64
	s_nop 0
	global_load_lds_dwordx4 v154, s[4:5]
	s_add_u32 s4, s53, s12
	s_addc_u32 s5, s54, 0
	s_mov_b32 m0, s61
	s_nop 0
	global_load_lds_dwordx4 v151, s[4:5]
	s_add_i32 s65, s61, 0x2000
	v_lshl_add_u32 v153, v6, 12, v4
	s_mov_b32 m0, s65
	s_nop 0
	global_load_lds_dwordx4 v153, s[4:5]
	s_add_u32 s34, s4, 0x80000
	s_addc_u32 s35, s5, 0
	s_add_i32 s66, s61, 0x4000
	s_mov_b32 m0, s66
	s_nop 0
	global_load_lds_dwordx4 v151, s[34:35]
	s_add_i32 s67, s61, 0x6000
	s_mov_b32 m0, s67
	s_nop 0
	global_load_lds_dwordx4 v153, s[34:35]
	s_cmp_eq_u32 s25, 1
	s_mov_b32 s24, 0
	s_cselect_b64 s[12:13], -1, 0
	s_cmp_lg_u32 s25, 1
	s_cbranch_scc1 .LBB0_102
	s_barrier
; #define PG8_STAGE(bufoff, gbase, voff) do { _Pragma("unroll") for (int _i = 0; _i < 2; ++_i) { unsigned keep_; \
;         asm volatile("s_mov_b32 %0, m0\n\ts_mov_b32 m0, %3\n\ts_nop 0\n\tglobal_load_lds_dwordx4 %1, %2\n\ts_mov_b32 m0, %0" \
;             : "=&s"(keep_) : "v"((voff)[_i]), "s"((const void*)(gbase)), "s"(ldsb0 + (unsigned)(bufoff) + (unsigned)(_i * 8192)) : "memory"); } } while (0)
; #define PG8_WAIT_V(n) asm volatile("s_waitcnt vmcnt(" #n ")" ::: "memory")
; #define PG8_BAR __builtin_amdgcn_s_barrier()
; template <class Epi, class Sched, bool ALIGN_EPI>
; __device__ __forceinline__ void gemm_phase(LAS unsigned char* lds, const Gemm g, const Sched& S, const Epi& E) {
;     ...
;     const int aoff = lds_byte(wr * 64 + fr, fq * 8), boff = lds_byte(wc * 32 + fr, fq * 8);
;     ...
;     const unsigned ldsb0 = (unsigned)(uintptr_t)lds + ldsw;
;     ...
;     Unit cur, nxt; int ui = 0;
;     if (!S.next(0, cur)) return;
;     f32x4 acc[2][2][4][2];
; #pragma unroll
;     for (int a = 0; a < 2; ++a)
; #pragma unroll
;         for (int b = 0; b < 2; ++b)
; #pragma unroll
;             for (int m = 0; m < 4; ++m)
; #pragma unroll
;                 for (int n = 0; n < 2; ++n) acc[a][b][m][n] = (f32x4){0.f, 0.f, 0.f, 0.f};
;     bf16x8 At[4][2], B0[2][2], B1[2][2];
;     float pre[Epi::NPRE > 0 ? Epi::NPRE : 1];
;     if constexpr (Epi::NPRE > 0) E.preload(cur, wr, fr, pre);
;     const char* cA = (const char*)g.A + (size_t)cur.pm * tstepA + (size_t)cur.pn * g.a_koff * 2; const char* cB = (const char*)g.Bt + (size_t)cur.pn * tstepB;
;     PG8_STAGE(PG8_SB(0, 0), cB, voffB); PG8_STAGE(PG8_SB(0, 1), cB + hstepB, voffB); PG8_STAGE(PG8_SA(0, 0), cA, voffA); PG8_STAGE(PG8_SA(0, 1), cA + hstepA, voffA);
;     if (wr == 1) PG8_BAR;
;     PG8_WAIT_V(2); PG8_BAR;
;     PG8_STAGE(PG8_SB(1, 0), cB + kstep, voffB); PG8_STAGE(PG8_SA(1, 0), cA + kstep, voffA); PG8_STAGE(PG8_SB(1, 1), cB + hstepB + kstep, voffB);
;     PG8_WAIT_V(6); PG8_BAR;
.LBB0_102:
	v_readlane_b32 s34, v242, 12
	s_add_i32 s68, s34, 8
	s_add_u32 s14, s14, 0xe000000
	s_addc_u32 s15, s15, 0
	s_add_u32 s16, s16, 0x4100000
	s_addc_u32 s17, s17, 0
	s_waitcnt lgkmcnt(0)
	s_add_u32 s18, s18, 0x10100000
	s_addc_u32 s19, s19, 0
	s_add_u32 s26, s26, 0x12200000
	s_addc_u32 s27, s27, 0
	s_add_u32 s28, s28, 0x14300000
	s_addc_u32 s29, s29, 0
	s_add_u32 s30, s30, 0x410f000
	v_lshrrev_b32_e32 v2, 1, v2
	s_addc_u32 s31, s31, 0
	v_or_b32_e32 v155, s36, v3
	v_and_b32_e32 v2, 24, v2
	s_add_u32 s34, s8, 0x610f000
	v_lshlrev_b32_e32 v4, 6, v155
	v_lshlrev_b32_e32 v5, 1, v2
	s_movk_i32 s8, 0x3c0
	v_lshlrev_b32_e32 v6, 2, v155
	s_addc_u32 s35, s9, 0
	v_and_or_b32 v4, v4, s8, v5
	s_lshl_b32 s8, s25, 13
	v_and_b32_e32 v6, 32, v6
	v_bitop3_b32 v4, v4, s8, v6 bitop3:0xde
	s_lshl_b32 s8, s37, 5
	s_and_b32 s25, s8, 0x60
	v_lshl_or_b32 v5, v3, 6, v5
	v_lshlrev_b32_e32 v3, 2, v3
	s_lshl_b32 s8, s25, 7
	v_and_b32_e32 v3, 32, v3
	v_bitop3_b32 v3, v5, s8, v3 bitop3:0xde
	s_add_u32 s8, s6, 0x80
	s_waitcnt vmcnt(2)
	s_barrier
	s_addc_u32 s9, s7, 0
	s_add_i32 s69, s61, 0x18000
	s_mov_b32 m0, s69
	s_nop 0
	global_load_lds_dwordx4 v152, s[8:9]
	s_add_i32 s70, s61, 0x1a000
	s_mov_b32 m0, s70
	s_nop 0
	global_load_lds_dwordx4 v154, s[8:9]
	s_add_u32 s8, s4, 0x80
	s_addc_u32 s9, s5, 0
	s_add_i32 s71, s61, 0x8000
	s_mov_b32 m0, s71
	s_nop 0
	global_load_lds_dwordx4 v151, s[8:9]
	s_add_i32 s72, s61, 0xa000
	s_mov_b32 m0, s72
	s_nop 0
	global_load_lds_dwordx4 v153, s[8:9]
	s_add_u32 s8, s6, 0x80080
	s_addc_u32 s9, s7, 0
	s_add_i32 s73, s61, 0x1c000
	s_mov_b32 m0, s73
	s_nop 0
	global_load_lds_dwordx4 v152, s[8:9]
	s_add_i32 s74, s61, 0x1e000
	s_mov_b32 m0, s74
	s_nop 0
	global_load_lds_dwordx4 v154, s[8:9]
	s_waitcnt vmcnt(6)
	s_add_i32 s75, s61, 0xc000
	s_cmpk_lt_u32 s2, 0x100
	v_or_b32_e32 v156, s25, v2
	v_add_u32_e32 v2, 0, v3
	s_cselect_b64 s[36:37], -1, 0
	s_add_i32 s77, s61, 0xe000
	v_add_u32_e32 v157, 0x10000, v2
	v_add_u32_e32 v158, 0x14000, v2
	v_add_u32_e32 v159, 0, v4
	v_add_u32_e32 v160, 0x18000, v2
	v_add_u32_e32 v161, 0x1c000, v2
	v_mov_b32_e32 v162, 0x358637bd
	s_movk_i32 s78, 0x1ff0
	v_mov_b32_e32 v135, 0
	s_mov_b32 s2, s22
	s_mov_b32 s25, s60
	s_barrier
	s_branch .LBB0_105

; #define PG8_STAGE(bufoff, gbase, voff) do { _Pragma("unroll") for (int _i = 0; _i < 2; ++_i) { unsigned keep_; \
;         asm volatile("s_mov_b32 %0, m0\n\ts_mov_b32 m0, %3\n\ts_nop 0\n\tglobal_load_lds_dwordx4 %1, %2\n\ts_mov_b32 m0, %0" \
;             : "=&s"(keep_) : "v"((voff)[_i]), "s"((const void*)(gbase)), "s"(ldsb0 + (unsigned)(bufoff) + (unsigned)(_i * 8192)) : "memory"); } } while (0)
; #define PG8_LDA(dst, b, h) do { _Pragma("unroll") for (int m = 0; m < 4; ++m) _Pragma("unroll") for (int k = 0; k < 2; ++k) dst[m][k] = *(const LAS bf16x8*)(lds + PG8_SA(b, h) + aoff + m * 2048 + k * 1024); } while (0)
; #define PG8_LDB(dst, b, h) do { _Pragma("unroll") for (int n = 0; n < 2; ++n) _Pragma("unroll") for (int k = 0; k < 2; ++k) dst[n][k] = *(const LAS bf16x8*)(lds + PG8_SB(b, h) + boff + n * 2048 + k * 1024); } while (0)
; #define PG8_MMA(ai, bj, At, Bt) do { __builtin_amdgcn_s_setprio(1); _Pragma("unroll") for (int m = 0; m < 4; ++m) _Pragma("unroll") for (int n = 0; n < 2; ++n) _Pragma("unroll") for (int k = 0; k < 2; ++k) \
;         acc[ai][bj][m][n] = __builtin_amdgcn_mfma_f32_16x16x32_bf16(Bt[n][k], At[m][k], acc[ai][bj][m][n], 0, 0, 0); __builtin_amdgcn_s_setprio(0); } while (0)
; #define PG8_WAIT_V(n) asm volatile("s_waitcnt vmcnt(" #n ")" ::: "memory")
; #define PG8_BAR __builtin_amdgcn_s_barrier()
; template <class Epi, class Sched, bool ALIGN_EPI>
; __device__ __forceinline__ void gemm_phase(LAS unsigned char* lds, const Gemm g, const Sched& S, const Epi& E) {
;     ...
;         for (int t = 0; t < nt; t += 2) {
;             const bool last = (t == nt - 2);
;             const char* a1 = cA + (size_t)(t + 1) * kstep;
;             const char* a2 = last ? nA : cA + (size_t)(t + 2) * kstep; const char* b2 = last ? nB : cB + (size_t)(t + 2) * kstep;
;             const char* a3 = a2 + kstep; const char* b3 = b2 + kstep;
;             PG8_LDB(B0, 0, 0); PG8_LDB(B1, 0, 1); PG8_SCHED; PG8_LDA(At, 0, 0); PG8_STAGE(PG8_SA(1, 1), a1 + hstepA, voffA);
;             PG8_WAIT_V(8); PG8_WAIT_L(0); PG8_BAR; PG8_MMA(0, 0, At, B0); PG8_MMA(0, 1, At, B1); PG8_BAR; PG8_SCHED;
;             PG8_LDA(At, 0, 1); PG8_STAGE(PG8_SB(0, 0), b2, voffB); PG8_STAGE(PG8_SB(0, 1), b2 + hstepB, voffB); PG8_STAGE(PG8_SA(0, 0), a2, voffA);
;             PG8_WAIT_V(8); PG8_WAIT_L(0); PG8_BAR; PG8_MMA(1, 0, At, B0); PG8_MMA(1, 1, At, B1); PG8_BAR; PG8_SCHED;
.LBB0_113:
	ds_read_b128 v[136:139], v157
	ds_read_b128 v[140:143], v157 offset:1024
	ds_read_b128 v[144:147], v157 offset:2048
	ds_read_b128 v[172:175], v157 offset:3072
	ds_read_b128 v[180:183], v158
	ds_read_b128 v[184:187], v158 offset:1024
	ds_read_b128 v[188:191], v158 offset:2048
	ds_read_b128 v[192:195], v158 offset:3072
	s_add_u32 s6, s4, 0x100
	s_addc_u32 s7, s5, 0
	s_cmp_eq_u32 s81, 28
	s_cselect_b32 s50, s39, s6
	s_cselect_b32 s51, s24, s7
	s_cselect_b32 s48, s58, s59
	s_cselect_b32 s49, s41, s80
	s_add_u32 s8, s50, 0x80
	s_addc_u32 s9, s51, 0
	ds_read_b128 v[196:199], v159
	ds_read_b128 v[206:209], v159 offset:1024
	ds_read_b128 v[210:213], v159 offset:2048
	ds_read_b128 v[214:217], v159 offset:3072
	ds_read_b128 v[218:221], v159 offset:4096
	ds_read_b128 v[222:225], v159 offset:5120
	ds_read_b128 v[226:229], v159 offset:6144
	ds_read_b128 v[230:233], v159 offset:7168
	s_add_u32 s4, s4, 0x80080
	s_addc_u32 s5, s5, 0
	s_mov_b32 m0, s75
	s_nop 0
	global_load_lds_dwordx4 v151, s[4:5]
	s_nop 0
	s_mov_b32 m0, s77
	s_nop 0
	global_load_lds_dwordx4 v153, s[4:5]
	s_waitcnt vmcnt(8)
	s_waitcnt lgkmcnt(0)
	s_barrier
	s_setprio 1
	v_mfma_f32_16x16x32_bf16 v[126:129], v[136:139], v[196:199], v[126:129]
	v_mfma_f32_16x16x32_bf16 v[122:125], v[144:147], v[196:199], v[122:125]
	v_mfma_f32_16x16x32_bf16 v[110:113], v[136:139], v[210:213], v[110:113]
	v_mfma_f32_16x16x32_bf16 v[106:109], v[144:147], v[210:213], v[106:109]
	v_mfma_f32_16x16x32_bf16 v[94:97], v[136:139], v[218:221], v[94:97]
	v_mfma_f32_16x16x32_bf16 v[90:93], v[144:147], v[218:221], v[90:93]
	v_mfma_f32_16x16x32_bf16 v[78:81], v[136:139], v[226:229], v[78:81]
	v_mfma_f32_16x16x32_bf16 v[74:77], v[144:147], v[226:229], v[74:77]
	v_mfma_f32_16x16x32_bf16 v[126:129], v[140:143], v[206:209], v[126:129]
	v_mfma_f32_16x16x32_bf16 v[122:125], v[172:175], v[206:209], v[122:125]
	v_mfma_f32_16x16x32_bf16 v[110:113], v[140:143], v[214:217], v[110:113]
	v_mfma_f32_16x16x32_bf16 v[106:109], v[172:175], v[214:217], v[106:109]
	v_mfma_f32_16x16x32_bf16 v[94:97], v[140:143], v[222:225], v[94:97]
	v_mfma_f32_16x16x32_bf16 v[90:93], v[172:175], v[222:225], v[90:93]
	v_mfma_f32_16x16x32_bf16 v[78:81], v[140:143], v[230:233], v[78:81]
	v_mfma_f32_16x16x32_bf16 v[74:77], v[172:175], v[230:233], v[74:77]
	v_mfma_f32_16x16x32_bf16 v[118:121], v[180:183], v[196:199], v[118:121]
	v_mfma_f32_16x16x32_bf16 v[114:117], v[188:191], v[196:199], v[114:117]
	v_mfma_f32_16x16x32_bf16 v[102:105], v[180:183], v[210:213], v[102:105]
	v_mfma_f32_16x16x32_bf16 v[98:101], v[188:191], v[210:213], v[98:101]
	v_mfma_f32_16x16x32_bf16 v[86:89], v[180:183], v[218:221], v[86:89]
	v_mfma_f32_16x16x32_bf16 v[82:85], v[188:191], v[218:221], v[82:85]
	v_mfma_f32_16x16x32_bf16 v[70:73], v[180:183], v[226:229], v[70:73]
	v_mfma_f32_16x16x32_bf16 v[66:69], v[188:191], v[226:229], v[66:69]
	v_mfma_f32_16x16x32_bf16 v[118:121], v[184:187], v[206:209], v[118:121]
	v_mfma_f32_16x16x32_bf16 v[114:117], v[192:195], v[206:209], v[114:117]
	v_mfma_f32_16x16x32_bf16 v[102:105], v[184:187], v[214:217], v[102:105]
	v_mfma_f32_16x16x32_bf16 v[98:101], v[192:195], v[214:217], v[98:101]
	v_mfma_f32_16x16x32_bf16 v[86:89], v[184:187], v[222:225], v[86:89]
	v_mfma_f32_16x16x32_bf16 v[82:85], v[192:195], v[222:225], v[82:85]
	v_mfma_f32_16x16x32_bf16 v[70:73], v[184:187], v[230:233], v[70:73]
	v_mfma_f32_16x16x32_bf16 v[66:69], v[192:195], v[230:233], v[66:69]
	s_setprio 0
	s_barrier
	ds_read_b128 v[196:199], v159 offset:16384
	ds_read_b128 v[206:209], v159 offset:17408
	ds_read_b128 v[210:213], v159 offset:18432
	ds_read_b128 v[214:217], v159 offset:19456
	ds_read_b128 v[218:221], v159 offset:20480
	ds_read_b128 v[222:225], v159 offset:21504
	ds_read_b128 v[226:229], v159 offset:22528
	ds_read_b128 v[230:233], v159 offset:23552
	s_mov_b32 m0, s23
	s_nop 0
	global_load_lds_dwordx4 v152, s[48:49]
	s_nop 0
	s_mov_b32 m0, s62
	s_nop 0
	global_load_lds_dwordx4 v154, s[48:49]
	s_add_u32 s4, s48, 0x80000
	s_addc_u32 s5, s49, 0
	s_mov_b32 m0, s63
	s_nop 0
	global_load_lds_dwordx4 v152, s[4:5]
	s_nop 0
	s_mov_b32 m0, s64
	s_nop 0
	global_load_lds_dwordx4 v154, s[4:5]
	s_mov_b32 m0, s61
	s_nop 0
	global_load_lds_dwordx4 v151, s[50:51]
	s_nop 0
	s_mov_b32 m0, s65
	s_nop 0
	global_load_lds_dwordx4 v153, s[50:51]
	s_waitcnt vmcnt(8)
	s_waitcnt lgkmcnt(0)
	s_barrier
	s_setprio 1
	v_mfma_f32_16x16x32_bf16 v[62:65], v[136:139], v[196:199], v[62:65]
	v_mfma_f32_16x16x32_bf16 v[58:61], v[144:147], v[196:199], v[58:61]
	v_mfma_f32_16x16x32_bf16 v[46:49], v[136:139], v[210:213], v[46:49]
	v_mfma_f32_16x16x32_bf16 v[42:45], v[144:147], v[210:213], v[42:45]
	v_mfma_f32_16x16x32_bf16 v[30:33], v[136:139], v[218:221], v[30:33]
	v_mfma_f32_16x16x32_bf16 v[26:29], v[144:147], v[218:221], v[26:29]
	v_mfma_f32_16x16x32_bf16 v[14:17], v[136:139], v[226:229], v[14:17]
	v_mfma_f32_16x16x32_bf16 v[10:13], v[144:147], v[226:229], v[10:13]
	v_mfma_f32_16x16x32_bf16 v[62:65], v[140:143], v[206:209], v[62:65]
	v_mfma_f32_16x16x32_bf16 v[58:61], v[172:175], v[206:209], v[58:61]
	v_mfma_f32_16x16x32_bf16 v[46:49], v[140:143], v[214:217], v[46:49]
	v_mfma_f32_16x16x32_bf16 v[42:45], v[172:175], v[214:217], v[42:45]
	v_mfma_f32_16x16x32_bf16 v[30:33], v[140:143], v[222:225], v[30:33]
	v_mfma_f32_16x16x32_bf16 v[26:29], v[172:175], v[222:225], v[26:29]
	v_mfma_f32_16x16x32_bf16 v[14:17], v[140:143], v[230:233], v[14:17]
	v_mfma_f32_16x16x32_bf16 v[10:13], v[172:175], v[230:233], v[10:13]
	v_mfma_f32_16x16x32_bf16 v[54:57], v[180:183], v[196:199], v[54:57]
	v_mfma_f32_16x16x32_bf16 v[50:53], v[188:191], v[196:199], v[50:53]
	v_mfma_f32_16x16x32_bf16 v[38:41], v[180:183], v[210:213], v[38:41]
	v_mfma_f32_16x16x32_bf16 v[34:37], v[188:191], v[210:213], v[34:37]
	v_mfma_f32_16x16x32_bf16 v[22:25], v[180:183], v[218:221], v[22:25]
	v_mfma_f32_16x16x32_bf16 v[18:21], v[188:191], v[218:221], v[18:21]
	v_mfma_f32_16x16x32_bf16 v[6:9], v[180:183], v[226:229], v[6:9]
	v_mfma_f32_16x16x32_bf16 v[2:5], v[188:191], v[226:229], v[2:5]
	v_mfma_f32_16x16x32_bf16 v[54:57], v[184:187], v[206:209], v[54:57]
	v_mfma_f32_16x16x32_bf16 v[50:53], v[192:195], v[206:209], v[50:53]
	v_mfma_f32_16x16x32_bf16 v[38:41], v[184:187], v[214:217], v[38:41]
	v_mfma_f32_16x16x32_bf16 v[34:37], v[192:195], v[214:217], v[34:37]
	v_mfma_f32_16x16x32_bf16 v[22:25], v[184:187], v[222:225], v[22:25]
	v_mfma_f32_16x16x32_bf16 v[18:21], v[192:195], v[222:225], v[18:21]
	v_mfma_f32_16x16x32_bf16 v[6:9], v[184:187], v[230:233], v[6:9]
	v_mfma_f32_16x16x32_bf16 v[2:5], v[192:195], v[230:233], v[2:5]
	s_setprio 0
	s_barrier
; #define PG8_STAGE(bufoff, gbase, voff) do { _Pragma("unroll") for (int _i = 0; _i < 2; ++_i) { unsigned keep_; \
;         asm volatile("s_mov_b32 %0, m0\n\ts_mov_b32 m0, %3\n\ts_nop 0\n\tglobal_load_lds_dwordx4 %1, %2\n\ts_mov_b32 m0, %0" \
;             : "=&s"(keep_) : "v"((voff)[_i]), "s"((const void*)(gbase)), "s"(ldsb0 + (unsigned)(bufoff) + (unsigned)(_i * 8192)) : "memory"); } } while (0)
; #define PG8_LDA(dst, b, h) do { _Pragma("unroll") for (int m = 0; m < 4; ++m) _Pragma("unroll") for (int k = 0; k < 2; ++k) dst[m][k] = *(const LAS bf16x8*)(lds + PG8_SA(b, h) + aoff + m * 2048 + k * 1024); } while (0)
; #define PG8_LDB(dst, b, h) do { _Pragma("unroll") for (int n = 0; n < 2; ++n) _Pragma("unroll") for (int k = 0; k < 2; ++k) dst[n][k] = *(const LAS bf16x8*)(lds + PG8_SB(b, h) + boff + n * 2048 + k * 1024); } while (0)
; #define PG8_MMA(ai, bj, At, Bt) do { __builtin_amdgcn_s_setprio(1); _Pragma("unroll") for (int m = 0; m < 4; ++m) _Pragma("unroll") for (int n = 0; n < 2; ++n) _Pragma("unroll") for (int k = 0; k < 2; ++k) \
;         acc[ai][bj][m][n] = __builtin_amdgcn_mfma_f32_16x16x32_bf16(Bt[n][k], At[m][k], acc[ai][bj][m][n], 0, 0, 0); __builtin_amdgcn_s_setprio(0); } while (0)
; #define PG8_WAIT_V(n) asm volatile("s_waitcnt vmcnt(" #n ")" ::: "memory")
; #define PG8_WAIT_L(n) asm volatile("s_waitcnt lgkmcnt(" #n ")" ::: "memory")
; #define PG8_BAR __builtin_amdgcn_s_barrier()
; #define PG8_SCHED __builtin_amdgcn_sched_barrier(0)
; template <class Epi, class Sched, bool ALIGN_EPI>
; __device__ __forceinline__ void gemm_phase(LAS unsigned char* lds, const Gemm g, const Sched& S, const Epi& E) {
;     ...
;             PG8_LDB(B0, 1, 0); PG8_LDB(B1, 1, 1); PG8_SCHED; PG8_LDA(At, 1, 0); PG8_STAGE(PG8_SA(0, 1), a2 + hstepA, voffA);
;             PG8_WAIT_V(8); PG8_WAIT_L(0); PG8_BAR; PG8_MMA(0, 0, At, B0); PG8_MMA(0, 1, At, B1); PG8_BAR; PG8_SCHED;
;             PG8_LDA(At, 1, 1); PG8_STAGE(PG8_SB(1, 0), b3, voffB); PG8_STAGE(PG8_SB(1, 1), b3 + hstepB, voffB); PG8_STAGE(PG8_SA(1, 0), a3, voffA);
;             PG8_WAIT_V(8); PG8_WAIT_L(0); PG8_BAR; PG8_MMA(1, 0, At, B0); PG8_MMA(1, 1, At, B1); PG8_BAR; PG8_SCHED;
;         }
	ds_read_b128 v[136:139], v160
	ds_read_b128 v[140:143], v160 offset:1024
	ds_read_b128 v[144:147], v160 offset:2048
	ds_read_b128 v[172:175], v160 offset:3072
	ds_read_b128 v[180:183], v161
	ds_read_b128 v[184:187], v161 offset:1024
	ds_read_b128 v[188:191], v161 offset:2048
	ds_read_b128 v[192:195], v161 offset:3072
	ds_read_b128 v[196:199], v159 offset:32768
	ds_read_b128 v[206:209], v159 offset:33792
	ds_read_b128 v[210:213], v159 offset:34816
	ds_read_b128 v[214:217], v159 offset:35840
	ds_read_b128 v[218:221], v159 offset:36864
	ds_read_b128 v[222:225], v159 offset:37888
	ds_read_b128 v[226:229], v159 offset:38912
	ds_read_b128 v[230:233], v159 offset:39936
	s_add_u32 s4, s50, 0x80000
	s_addc_u32 s5, s51, 0
	s_mov_b32 m0, s66
	s_nop 0
	global_load_lds_dwordx4 v151, s[4:5]
	s_nop 0
	s_mov_b32 m0, s67
	s_nop 0
	global_load_lds_dwordx4 v153, s[4:5]
	s_waitcnt vmcnt(8)
	s_waitcnt lgkmcnt(0)
	s_barrier
	s_setprio 1
	v_mfma_f32_16x16x32_bf16 v[126:129], v[136:139], v[196:199], v[126:129]
	v_mfma_f32_16x16x32_bf16 v[122:125], v[144:147], v[196:199], v[122:125]
	v_mfma_f32_16x16x32_bf16 v[110:113], v[136:139], v[210:213], v[110:113]
	v_mfma_f32_16x16x32_bf16 v[106:109], v[144:147], v[210:213], v[106:109]
	v_mfma_f32_16x16x32_bf16 v[94:97], v[136:139], v[218:221], v[94:97]
	v_mfma_f32_16x16x32_bf16 v[90:93], v[144:147], v[218:221], v[90:93]
	v_mfma_f32_16x16x32_bf16 v[78:81], v[136:139], v[226:229], v[78:81]
	v_mfma_f32_16x16x32_bf16 v[74:77], v[144:147], v[226:229], v[74:77]
	v_mfma_f32_16x16x32_bf16 v[126:129], v[140:143], v[206:209], v[126:129]
	v_mfma_f32_16x16x32_bf16 v[122:125], v[172:175], v[206:209], v[122:125]
	v_mfma_f32_16x16x32_bf16 v[110:113], v[140:143], v[214:217], v[110:113]
	v_mfma_f32_16x16x32_bf16 v[106:109], v[172:175], v[214:217], v[106:109]
	v_mfma_f32_16x16x32_bf16 v[94:97], v[140:143], v[222:225], v[94:97]
	v_mfma_f32_16x16x32_bf16 v[90:93], v[172:175], v[222:225], v[90:93]
	v_mfma_f32_16x16x32_bf16 v[78:81], v[140:143], v[230:233], v[78:81]
	v_mfma_f32_16x16x32_bf16 v[74:77], v[172:175], v[230:233], v[74:77]
	v_mfma_f32_16x16x32_bf16 v[118:121], v[180:183], v[196:199], v[118:121]
	v_mfma_f32_16x16x32_bf16 v[114:117], v[188:191], v[196:199], v[114:117]
	v_mfma_f32_16x16x32_bf16 v[102:105], v[180:183], v[210:213], v[102:105]
	v_mfma_f32_16x16x32_bf16 v[98:101], v[188:191], v[210:213], v[98:101]
	v_mfma_f32_16x16x32_bf16 v[86:89], v[180:183], v[218:221], v[86:89]
	v_mfma_f32_16x16x32_bf16 v[82:85], v[188:191], v[218:221], v[82:85]
	v_mfma_f32_16x16x32_bf16 v[70:73], v[180:183], v[226:229], v[70:73]
	v_mfma_f32_16x16x32_bf16 v[66:69], v[188:191], v[226:229], v[66:69]
	v_mfma_f32_16x16x32_bf16 v[118:121], v[184:187], v[206:209], v[118:121]
	v_mfma_f32_16x16x32_bf16 v[114:117], v[192:195], v[206:209], v[114:117]
	v_mfma_f32_16x16x32_bf16 v[102:105], v[184:187], v[214:217], v[102:105]
	v_mfma_f32_16x16x32_bf16 v[98:101], v[192:195], v[214:217], v[98:101]
	v_mfma_f32_16x16x32_bf16 v[86:89], v[184:187], v[222:225], v[86:89]
	v_mfma_f32_16x16x32_bf16 v[82:85], v[192:195], v[222:225], v[82:85]
	v_mfma_f32_16x16x32_bf16 v[70:73], v[184:187], v[230:233], v[70:73]
	v_mfma_f32_16x16x32_bf16 v[66:69], v[192:195], v[230:233], v[66:69]
	s_setprio 0
	s_barrier
	ds_read_b128 v[196:199], v159 offset:49152
	ds_read_b128 v[206:209], v159 offset:50176
	ds_read_b128 v[210:213], v159 offset:51200
	ds_read_b128 v[214:217], v159 offset:52224
	ds_read_b128 v[218:221], v159 offset:53248
	ds_read_b128 v[222:225], v159 offset:54272
	ds_read_b128 v[226:229], v159 offset:55296
	ds_read_b128 v[230:233], v159 offset:56320
	s_add_u32 s4, s48, 0x80
	s_addc_u32 s5, s49, 0
	s_mov_b32 m0, s69
	s_nop 0
	global_load_lds_dwordx4 v152, s[4:5]
	s_nop 0
	s_mov_b32 m0, s70
	s_nop 0
	global_load_lds_dwordx4 v154, s[4:5]
	s_add_u32 s4, s48, 0x80080
	s_addc_u32 s5, s49, 0
	s_mov_b32 m0, s73
	s_nop 0
	global_load_lds_dwordx4 v152, s[4:5]
	s_nop 0
	s_mov_b32 m0, s74
	s_nop 0
	global_load_lds_dwordx4 v154, s[4:5]
	s_mov_b32 m0, s71
	s_nop 0
	global_load_lds_dwordx4 v151, s[8:9]
	s_nop 0
	s_mov_b32 m0, s72
	s_nop 0
	global_load_lds_dwordx4 v153, s[8:9]
	s_waitcnt vmcnt(8)
	s_waitcnt lgkmcnt(0)
	s_barrier
	s_setprio 1
	v_mfma_f32_16x16x32_bf16 v[62:65], v[136:139], v[196:199], v[62:65]
	v_mfma_f32_16x16x32_bf16 v[58:61], v[144:147], v[196:199], v[58:61]
	v_mfma_f32_16x16x32_bf16 v[46:49], v[136:139], v[210:213], v[46:49]
	v_mfma_f32_16x16x32_bf16 v[42:45], v[144:147], v[210:213], v[42:45]
	v_mfma_f32_16x16x32_bf16 v[30:33], v[136:139], v[218:221], v[30:33]
	v_mfma_f32_16x16x32_bf16 v[26:29], v[144:147], v[218:221], v[26:29]
	v_mfma_f32_16x16x32_bf16 v[14:17], v[136:139], v[226:229], v[14:17]
	v_mfma_f32_16x16x32_bf16 v[10:13], v[144:147], v[226:229], v[10:13]
	v_mfma_f32_16x16x32_bf16 v[62:65], v[140:143], v[206:209], v[62:65]
	v_mfma_f32_16x16x32_bf16 v[58:61], v[172:175], v[206:209], v[58:61]
	v_mfma_f32_16x16x32_bf16 v[46:49], v[140:143], v[214:217], v[46:49]
	v_mfma_f32_16x16x32_bf16 v[42:45], v[172:175], v[214:217], v[42:45]
	v_mfma_f32_16x16x32_bf16 v[30:33], v[140:143], v[222:225], v[30:33]
	v_mfma_f32_16x16x32_bf16 v[26:29], v[172:175], v[222:225], v[26:29]
	v_mfma_f32_16x16x32_bf16 v[14:17], v[140:143], v[230:233], v[14:17]
	v_mfma_f32_16x16x32_bf16 v[10:13], v[172:175], v[230:233], v[10:13]
	v_mfma_f32_16x16x32_bf16 v[54:57], v[180:183], v[196:199], v[54:57]
	v_mfma_f32_16x16x32_bf16 v[50:53], v[188:191], v[196:199], v[50:53]
	v_mfma_f32_16x16x32_bf16 v[38:41], v[180:183], v[210:213], v[38:41]
	v_mfma_f32_16x16x32_bf16 v[34:37], v[188:191], v[210:213], v[34:37]
	v_mfma_f32_16x16x32_bf16 v[22:25], v[180:183], v[218:221], v[22:25]
	v_mfma_f32_16x16x32_bf16 v[18:21], v[188:191], v[218:221], v[18:21]
	v_mfma_f32_16x16x32_bf16 v[6:9], v[180:183], v[226:229], v[6:9]
	v_mfma_f32_16x16x32_bf16 v[2:5], v[188:191], v[226:229], v[2:5]
	v_mfma_f32_16x16x32_bf16 v[54:57], v[184:187], v[206:209], v[54:57]
	v_mfma_f32_16x16x32_bf16 v[50:53], v[192:195], v[206:209], v[50:53]
	v_mfma_f32_16x16x32_bf16 v[38:41], v[184:187], v[214:217], v[38:41]
	v_mfma_f32_16x16x32_bf16 v[34:37], v[192:195], v[214:217], v[34:37]
	v_mfma_f32_16x16x32_bf16 v[22:25], v[184:187], v[222:225], v[22:25]
	v_mfma_f32_16x16x32_bf16 v[18:21], v[192:195], v[222:225], v[18:21]
	v_mfma_f32_16x16x32_bf16 v[6:9], v[184:187], v[230:233], v[6:9]
	v_mfma_f32_16x16x32_bf16 v[2:5], v[192:195], v[230:233], v[2:5]
	s_setprio 0
	s_barrier
	s_add_i32 s81, s81, 2
	s_add_u32 s59, s59, 0x100
	s_addc_u32 s80, s80, 0
	s_cmp_gt_u32 s81, 29
	s_mov_b64 s[4:5], s[6:7]
	s_cbranch_scc0 .LBB0_113
	s_and_b64 vcc, exec, s[36:37]
	s_cbranch_vccz .LBB0_116
	s_barrier
; __device__ __forceinline__ float rs_val(float ssqv) { return __builtin_amdgcn_rsqf(ssqv * (1.f / DM) + EPS); }
; __device__ __forceinline__ void st_bf16x8(bf16* p, f32x4 a, f32x4 b) { *(bf16x8*)p = pack8(a, b); }
;     __device__ __forceinline__ void operator()(const Acc& acc, const pg8::Unit& u, int wr, int wc, int fr, int fq, const float* rsv) const {
;         const int sec = u.pn >> 2, cin = (u.pn & 3) * 256 + wc * 32 + fq * 8;
; #pragma unroll
;         for (int ai = 0; ai < 2; ++ai)
; #pragma unroll
;             for (int m = 0; m < 4; ++m) { const int row = u.pm * 256 + ai * 128 + wr * 64 + m * 16 + fr; const float rs = rs_val(rsv[ai * 4 + m]);
; #pragma unroll
;                 for (int bj = 0; bj < 2; ++bj) { const f32x4 v0 = acc[ai][bj][m][0] * rs, v1 = acc[ai][bj][m][1] * rs; const int c = cin + bj * 128;
;                     if (sec == 0) { st_bf16x8(UB + (size_t)row * PW + c, v0, v1);
;                         if (row >= SEQ - 15) { float* p = poolp + (size_t)(row - (SEQ - 15)) * PW + c; *(f32x4*)p = v0; *(f32x4*)(p + 4) = v1; } }
;                     else if (sec == 1) st_bf16x8(QB + (size_t)row * DM + c, v0, v1);
;                     else if (sec == 2) { float* p = fk + (size_t)row * FW + c; *(f32x4*)p = v0; *(f32x4*)(p + 4) = v1; st_bf16x8(KB + (size_t)row * DM + c, v0, v1); }
;                     else { float* p = fv + (size_t)row * FW + c; *(f32x4*)p = v0; *(f32x4*)(p + 4) = v1; st_bf16x8(VB + (size_t)row * DM + c, v0, v1); } } }
.LBB0_116:
	s_nop 0
	v_fmamk_f32 v134, v134, 0x3a000000, v162
	s_lshl_b32 s4, s2, 8
	v_rsq_f32_e32 v144, v134
	s_ashr_i32 s24, s2, 2
	s_and_b32 s4, s4, 0x300
	v_lshl_add_u32 v138, s25, 8, v155
	s_cmp_gt_u32 s2, 3
	v_or_b32_e32 v166, s4, v156
	s_cselect_b64 s[4:5], -1, 0
	v_ashrrev_i32_e32 v139, 31, v138
	v_lshlrev_b64 v[140:141], 12, v[138:139]
	v_cmp_lt_i32_e64 s[8:9], s78, v138
	v_pk_mul_f32 v[128:129], v[144:145], v[128:129] op_sel_hi:[0,1]
	v_pk_mul_f32 v[126:127], v[144:145], v[126:127] op_sel_hi:[0,1]
	v_pk_mul_f32 v[124:125], v[144:145], v[124:125] op_sel_hi:[0,1]
	v_pk_mul_f32 v[122:123], v[144:145], v[122:123] op_sel_hi:[0,1]
	s_mov_b64 s[6:7], -1
	s_and_b64 vcc, exec, s[4:5]
	s_cbranch_vccz .LBB0_128
	s_mov_b64 s[50:51], -1
	s_mov_b64 s[6:7], 0
	s_cmp_lt_i32 s24, 2
	s_mov_b64 s[48:49], 0
	s_cbranch_scc1 .LBB0_123
	s_cmp_eq_u32 s24, 2
	s_mov_b64 s[48:49], -1
	s_cbranch_scc0 .LBB0_120
	v_lshl_add_u64 v[136:137], s[30:31], 0, v[140:141]
	v_lshlrev_b32_e32 v134, 2, v166
	v_lshl_add_u64 v[136:137], v[136:137], 0, v[134:135]
	global_store_dwordx4 v[136:137], v[126:129], off
	global_store_dwordx4 v[136:137], v[122:125], off offset:16
	v_lshl_add_u64 v[136:137], s[26:27], 0, v[140:141]
	v_lshlrev_b32_e32 v134, 1, v166
	v_lshl_add_u64 v[136:137], v[136:137], 0, v[134:135]
	v_cvt_pk_bf16_f32 v172, v126, v127
	v_cvt_pk_bf16_f32 v173, v128, v129
	v_cvt_pk_bf16_f32 v174, v122, v123
	v_cvt_pk_bf16_f32 v175, v124, v125
	global_store_dwordx4 v[136:137], v[172:175], off
	s_mov_b64 s[48:49], 0

; __device__ __forceinline__ float rs_val(float ssqv) { return __builtin_amdgcn_rsqf(ssqv * (1.f / DM) + EPS); }
; __device__ __forceinline__ void st_bf16x8(bf16* p, f32x4 a, f32x4 b) { *(bf16x8*)p = pack8(a, b); }
;     __device__ __forceinline__ void operator()(const Acc& acc, const pg8::Unit& u, int wr, int wc, int fr, int fq, const float* rsv) const {
;         const int sec = u.pn >> 2, cin = (u.pn & 3) * 256 + wc * 32 + fq * 8;
; #pragma unroll
;         for (int ai = 0; ai < 2; ++ai)
; #pragma unroll
;             for (int m = 0; m < 4; ++m) { const int row = u.pm * 256 + ai * 128 + wr * 64 + m * 16 + fr; const float rs = rs_val(rsv[ai * 4 + m]);
; #pragma unroll
;                 for (int bj = 0; bj < 2; ++bj) { const f32x4 v0 = acc[ai][bj][m][0] * rs, v1 = acc[ai][bj][m][1] * rs; const int c = cin + bj * 128;
;                     if (sec == 0) { st_bf16x8(UB + (size_t)row * PW + c, v0, v1);
;                         if (row >= SEQ - 15) { float* p = poolp + (size_t)(row - (SEQ - 15)) * PW + c; *(f32x4*)p = v0; *(f32x4*)(p + 4) = v1; } }
;                     else if (sec == 1) st_bf16x8(QB + (size_t)row * DM + c, v0, v1);
;                     else if (sec == 2) { float* p = fk + (size_t)row * FW + c; *(f32x4*)p = v0; *(f32x4*)(p + 4) = v1; st_bf16x8(KB + (size_t)row * DM + c, v0, v1); }
;                     else { float* p = fv + (size_t)row * FW + c; *(f32x4*)p = v0; *(f32x4*)(p + 4) = v1; st_bf16x8(VB + (size_t)row * DM + c, v0, v1); } } }
.LBB0_148:
	s_nop 0
	v_fmamk_f32 v114, v170, 0x3a000000, v162
	v_rsq_f32_e32 v118, v114
	v_or_b32_e32 v116, 16, v138
	v_ashrrev_i32_e32 v117, 31, v116
	v_lshlrev_b64 v[114:115], 12, v[116:117]
	v_cmp_lt_i32_e64 s[8:9], s78, v116
	v_pk_mul_f32 v[112:113], v[118:119], v[112:113] op_sel_hi:[0,1]
	v_pk_mul_f32 v[110:111], v[118:119], v[110:111] op_sel_hi:[0,1]
	v_pk_mul_f32 v[108:109], v[118:119], v[108:109] op_sel_hi:[0,1]
	v_pk_mul_f32 v[106:107], v[118:119], v[106:107] op_sel_hi:[0,1]
	s_and_b64 vcc, exec, s[6:7]
	s_mov_b64 s[4:5], -1
	s_cbranch_vccnz .LBB0_160
	s_mov_b64 s[50:51], -1
	s_mov_b64 s[4:5], 0
	s_cmp_lt_i32 s24, 2
	s_mov_b64 s[48:49], 0
	s_cbranch_scc1 .LBB0_155
	s_cmp_eq_u32 s24, 2
	s_mov_b64 s[48:49], -1
	s_cbranch_scc0 .LBB0_152
	v_lshl_add_u64 v[120:121], s[30:31], 0, v[114:115]
	v_lshlrev_b32_e32 v134, 2, v166
	v_lshl_add_u64 v[120:121], v[120:121], 0, v[134:135]
	global_store_dwordx4 v[120:121], v[110:113], off
	global_store_dwordx4 v[120:121], v[106:109], off offset:16
	v_lshl_add_u64 v[120:121], s[26:27], 0, v[114:115]
	v_mov_b32_e32 v137, v135
	v_lshl_add_u64 v[124:125], v[120:121], 0, v[136:137]
	v_cvt_pk_bf16_f32 v120, v110, v111
	v_cvt_pk_bf16_f32 v121, v112, v113
	v_cvt_pk_bf16_f32 v122, v106, v107
	v_cvt_pk_bf16_f32 v123, v108, v109
	global_store_dwordx4 v[124:125], v[120:123], off
	s_mov_b64 s[48:49], 0

; __device__ __forceinline__ float rs_val(float ssqv) { return __builtin_amdgcn_rsqf(ssqv * (1.f / DM) + EPS); }
; __device__ __forceinline__ void st_bf16x8(bf16* p, f32x4 a, f32x4 b) { *(bf16x8*)p = pack8(a, b); }
;     __device__ __forceinline__ void operator()(const Acc& acc, const pg8::Unit& u, int wr, int wc, int fr, int fq, const float* rsv) const {
;         const int sec = u.pn >> 2, cin = (u.pn & 3) * 256 + wc * 32 + fq * 8;
; #pragma unroll
;         for (int ai = 0; ai < 2; ++ai)
; #pragma unroll
;             for (int m = 0; m < 4; ++m) { const int row = u.pm * 256 + ai * 128 + wr * 64 + m * 16 + fr; const float rs = rs_val(rsv[ai * 4 + m]);
; #pragma unroll
;                 for (int bj = 0; bj < 2; ++bj) { const f32x4 v0 = acc[ai][bj][m][0] * rs, v1 = acc[ai][bj][m][1] * rs; const int c = cin + bj * 128;
;                     if (sec == 0) { st_bf16x8(UB + (size_t)row * PW + c, v0, v1);
;                         if (row >= SEQ - 15) { float* p = poolp + (size_t)(row - (SEQ - 15)) * PW + c; *(f32x4*)p = v0; *(f32x4*)(p + 4) = v1; } }
;                     else if (sec == 1) st_bf16x8(QB + (size_t)row * DM + c, v0, v1);
;                     else if (sec == 2) { float* p = fk + (size_t)row * FW + c; *(f32x4*)p = v0; *(f32x4*)(p + 4) = v1; st_bf16x8(KB + (size_t)row * DM + c, v0, v1); }
;                     else { float* p = fv + (size_t)row * FW + c; *(f32x4*)p = v0; *(f32x4*)(p + 4) = v1; st_bf16x8(VB + (size_t)row * DM + c, v0, v1); } } }
.LBB0_180:
	s_nop 0
	v_fmamk_f32 v98, v169, 0x3a000000, v162
	v_rsq_f32_e32 v102, v98
	v_or_b32_e32 v100, 32, v138
	v_ashrrev_i32_e32 v101, 31, v100
	v_lshlrev_b64 v[98:99], 12, v[100:101]
	v_cmp_lt_i32_e64 s[8:9], s78, v100
	v_pk_mul_f32 v[96:97], v[102:103], v[96:97] op_sel_hi:[0,1]
	v_pk_mul_f32 v[94:95], v[102:103], v[94:95] op_sel_hi:[0,1]
	v_pk_mul_f32 v[92:93], v[102:103], v[92:93] op_sel_hi:[0,1]
	v_pk_mul_f32 v[90:91], v[102:103], v[90:91] op_sel_hi:[0,1]
	s_and_b64 vcc, exec, s[6:7]
	s_mov_b64 s[4:5], -1
	s_cbranch_vccnz .LBB0_192
	s_mov_b64 s[50:51], -1
	s_mov_b64 s[4:5], 0
	s_cmp_lt_i32 s24, 2
	s_mov_b64 s[48:49], 0
	s_cbranch_scc1 .LBB0_187
	s_cmp_eq_u32 s24, 2
	s_mov_b64 s[48:49], -1
	s_cbranch_scc0 .LBB0_184
	v_lshl_add_u64 v[104:105], s[30:31], 0, v[98:99]
	v_lshlrev_b32_e32 v134, 2, v166
	v_lshl_add_u64 v[104:105], v[104:105], 0, v[134:135]
	global_store_dwordx4 v[104:105], v[94:97], off
	global_store_dwordx4 v[104:105], v[90:93], off offset:16
	v_lshl_add_u64 v[104:105], s[26:27], 0, v[98:99]
	v_mov_b32_e32 v137, v135
	v_lshl_add_u64 v[108:109], v[104:105], 0, v[136:137]
	v_cvt_pk_bf16_f32 v104, v94, v95
	v_cvt_pk_bf16_f32 v105, v96, v97
	v_cvt_pk_bf16_f32 v106, v90, v91
	v_cvt_pk_bf16_f32 v107, v92, v93
	global_store_dwordx4 v[108:109], v[104:107], off
	s_mov_b64 s[48:49], 0

; __device__ __forceinline__ float rs_val(float ssqv) { return __builtin_amdgcn_rsqf(ssqv * (1.f / DM) + EPS); }
; __device__ __forceinline__ void st_bf16x8(bf16* p, f32x4 a, f32x4 b) { *(bf16x8*)p = pack8(a, b); }
;     __device__ __forceinline__ void operator()(const Acc& acc, const pg8::Unit& u, int wr, int wc, int fr, int fq, const float* rsv) const {
;         const int sec = u.pn >> 2, cin = (u.pn & 3) * 256 + wc * 32 + fq * 8;
; #pragma unroll
;         for (int ai = 0; ai < 2; ++ai)
; #pragma unroll
;             for (int m = 0; m < 4; ++m) { const int row = u.pm * 256 + ai * 128 + wr * 64 + m * 16 + fr; const float rs = rs_val(rsv[ai * 4 + m]);
; #pragma unroll
;                 for (int bj = 0; bj < 2; ++bj) { const f32x4 v0 = acc[ai][bj][m][0] * rs, v1 = acc[ai][bj][m][1] * rs; const int c = cin + bj * 128;
;                     if (sec == 0) { st_bf16x8(UB + (size_t)row * PW + c, v0, v1);
;                         if (row >= SEQ - 15) { float* p = poolp + (size_t)(row - (SEQ - 15)) * PW + c; *(f32x4*)p = v0; *(f32x4*)(p + 4) = v1; } }
;                     else if (sec == 1) st_bf16x8(QB + (size_t)row * DM + c, v0, v1);
;                     else if (sec == 2) { float* p = fk + (size_t)row * FW + c; *(f32x4*)p = v0; *(f32x4*)(p + 4) = v1; st_bf16x8(KB + (size_t)row * DM + c, v0, v1); }
;                     else { float* p = fv + (size_t)row * FW + c; *(f32x4*)p = v0; *(f32x4*)(p + 4) = v1; st_bf16x8(VB + (size_t)row * DM + c, v0, v1); } } }
.LBB0_212:
	s_nop 0
	v_fmamk_f32 v82, v168, 0x3a000000, v162
	v_rsq_f32_e32 v86, v82
	v_or_b32_e32 v84, 48, v138
	v_ashrrev_i32_e32 v85, 31, v84
	v_lshlrev_b64 v[82:83], 12, v[84:85]
	v_cmp_lt_i32_e64 s[8:9], s78, v84
	v_pk_mul_f32 v[80:81], v[86:87], v[80:81] op_sel_hi:[0,1]
	v_pk_mul_f32 v[78:79], v[86:87], v[78:79] op_sel_hi:[0,1]
	v_pk_mul_f32 v[76:77], v[86:87], v[76:77] op_sel_hi:[0,1]
	v_pk_mul_f32 v[74:75], v[86:87], v[74:75] op_sel_hi:[0,1]
	s_and_b64 vcc, exec, s[6:7]
	s_mov_b64 s[4:5], -1
	s_cbranch_vccnz .LBB0_224
	s_mov_b64 s[50:51], -1
	s_mov_b64 s[4:5], 0
	s_cmp_lt_i32 s24, 2
	s_mov_b64 s[48:49], 0
	s_cbranch_scc1 .LBB0_219
	s_cmp_eq_u32 s24, 2
	s_mov_b64 s[48:49], -1
	s_cbranch_scc0 .LBB0_216
	v_lshl_add_u64 v[88:89], s[30:31], 0, v[82:83]
	v_lshlrev_b32_e32 v134, 2, v166
	v_lshl_add_u64 v[88:89], v[88:89], 0, v[134:135]
	global_store_dwordx4 v[88:89], v[78:81], off
	global_store_dwordx4 v[88:89], v[74:77], off offset:16
	v_lshl_add_u64 v[88:89], s[26:27], 0, v[82:83]
	v_mov_b32_e32 v137, v135
	v_lshl_add_u64 v[92:93], v[88:89], 0, v[136:137]
	v_cvt_pk_bf16_f32 v88, v78, v79
	v_cvt_pk_bf16_f32 v89, v80, v81
	v_cvt_pk_bf16_f32 v90, v74, v75
	v_cvt_pk_bf16_f32 v91, v76, v77
	global_store_dwordx4 v[92:93], v[88:91], off
	s_mov_b64 s[48:49], 0

; __device__ __forceinline__ float rs_val(float ssqv) { return __builtin_amdgcn_rsqf(ssqv * (1.f / DM) + EPS); }
; __device__ __forceinline__ void st_bf16x8(bf16* p, f32x4 a, f32x4 b) { *(bf16x8*)p = pack8(a, b); }
;     __device__ __forceinline__ void operator()(const Acc& acc, const pg8::Unit& u, int wr, int wc, int fr, int fq, const float* rsv) const {
;         const int sec = u.pn >> 2, cin = (u.pn & 3) * 256 + wc * 32 + fq * 8;
; #pragma unroll
;         for (int ai = 0; ai < 2; ++ai)
; #pragma unroll
;             for (int m = 0; m < 4; ++m) { const int row = u.pm * 256 + ai * 128 + wr * 64 + m * 16 + fr; const float rs = rs_val(rsv[ai * 4 + m]);
; #pragma unroll
;                 for (int bj = 0; bj < 2; ++bj) { const f32x4 v0 = acc[ai][bj][m][0] * rs, v1 = acc[ai][bj][m][1] * rs; const int c = cin + bj * 128;
;                     if (sec == 0) { st_bf16x8(UB + (size_t)row * PW + c, v0, v1);
;                         if (row >= SEQ - 15) { float* p = poolp + (size_t)(row - (SEQ - 15)) * PW + c; *(f32x4*)p = v0; *(f32x4*)(p + 4) = v1; } }
;                     else if (sec == 1) st_bf16x8(QB + (size_t)row * DM + c, v0, v1);
;                     else if (sec == 2) { float* p = fk + (size_t)row * FW + c; *(f32x4*)p = v0; *(f32x4*)(p + 4) = v1; st_bf16x8(KB + (size_t)row * DM + c, v0, v1); }
;                     else { float* p = fv + (size_t)row * FW + c; *(f32x4*)p = v0; *(f32x4*)(p + 4) = v1; st_bf16x8(VB + (size_t)row * DM + c, v0, v1); } } }
.LBB0_244:
	s_nop 0
	v_fmamk_f32 v66, v167, 0x3a000000, v162
	v_rsq_f32_e32 v70, v66
	v_add_u32_e32 v68, 0x80, v138
	v_ashrrev_i32_e32 v69, 31, v68
	v_lshlrev_b64 v[66:67], 12, v[68:69]
	v_cmp_lt_i32_e64 s[8:9], s78, v68
	v_pk_mul_f32 v[64:65], v[70:71], v[64:65] op_sel_hi:[0,1]
	v_pk_mul_f32 v[62:63], v[70:71], v[62:63] op_sel_hi:[0,1]
	v_pk_mul_f32 v[60:61], v[70:71], v[60:61] op_sel_hi:[0,1]
	v_pk_mul_f32 v[58:59], v[70:71], v[58:59] op_sel_hi:[0,1]
	s_and_b64 vcc, exec, s[6:7]
	s_mov_b64 s[4:5], -1
	s_cbranch_vccnz .LBB0_256
	s_mov_b64 s[50:51], -1
	s_mov_b64 s[4:5], 0
	s_cmp_lt_i32 s24, 2
	s_mov_b64 s[48:49], 0
	s_cbranch_scc1 .LBB0_251
	s_cmp_eq_u32 s24, 2
	s_mov_b64 s[48:49], -1
	s_cbranch_scc0 .LBB0_248
	v_lshl_add_u64 v[72:73], s[30:31], 0, v[66:67]
	v_lshlrev_b32_e32 v134, 2, v166
	v_lshl_add_u64 v[72:73], v[72:73], 0, v[134:135]
	global_store_dwordx4 v[72:73], v[62:65], off
	global_store_dwordx4 v[72:73], v[58:61], off offset:16
	v_lshl_add_u64 v[72:73], s[26:27], 0, v[66:67]
	v_mov_b32_e32 v137, v135
	v_lshl_add_u64 v[76:77], v[72:73], 0, v[136:137]
	v_cvt_pk_bf16_f32 v72, v62, v63
	v_cvt_pk_bf16_f32 v73, v64, v65
	v_cvt_pk_bf16_f32 v74, v58, v59
	v_cvt_pk_bf16_f32 v75, v60, v61
	global_store_dwordx4 v[76:77], v[72:75], off
	s_mov_b64 s[48:49], 0

; __device__ __forceinline__ float rs_val(float ssqv) { return __builtin_amdgcn_rsqf(ssqv * (1.f / DM) + EPS); }
; __device__ __forceinline__ void st_bf16x8(bf16* p, f32x4 a, f32x4 b) { *(bf16x8*)p = pack8(a, b); }
;     __device__ __forceinline__ void operator()(const Acc& acc, const pg8::Unit& u, int wr, int wc, int fr, int fq, const float* rsv) const {
;         const int sec = u.pn >> 2, cin = (u.pn & 3) * 256 + wc * 32 + fq * 8;
; #pragma unroll
;         for (int ai = 0; ai < 2; ++ai)
; #pragma unroll
;             for (int m = 0; m < 4; ++m) { const int row = u.pm * 256 + ai * 128 + wr * 64 + m * 16 + fr; const float rs = rs_val(rsv[ai * 4 + m]);
; #pragma unroll
;                 for (int bj = 0; bj < 2; ++bj) { const f32x4 v0 = acc[ai][bj][m][0] * rs, v1 = acc[ai][bj][m][1] * rs; const int c = cin + bj * 128;
;                     if (sec == 0) { st_bf16x8(UB + (size_t)row * PW + c, v0, v1);
;                         if (row >= SEQ - 15) { float* p = poolp + (size_t)(row - (SEQ - 15)) * PW + c; *(f32x4*)p = v0; *(f32x4*)(p + 4) = v1; } }
;                     else if (sec == 1) st_bf16x8(QB + (size_t)row * DM + c, v0, v1);
;                     else if (sec == 2) { float* p = fk + (size_t)row * FW + c; *(f32x4*)p = v0; *(f32x4*)(p + 4) = v1; st_bf16x8(KB + (size_t)row * DM + c, v0, v1); }
;                     else { float* p = fv + (size_t)row * FW + c; *(f32x4*)p = v0; *(f32x4*)(p + 4) = v1; st_bf16x8(VB + (size_t)row * DM + c, v0, v1); } } }
.LBB0_276:
	s_nop 0
	v_fmamk_f32 v50, v165, 0x3a000000, v162
	v_rsq_f32_e32 v54, v50
	v_add_u32_e32 v52, 0x90, v138
	v_ashrrev_i32_e32 v53, 31, v52
	v_lshlrev_b64 v[50:51], 12, v[52:53]
	v_cmp_lt_i32_e64 s[8:9], s78, v52
	v_pk_mul_f32 v[48:49], v[54:55], v[48:49] op_sel_hi:[0,1]
	v_pk_mul_f32 v[46:47], v[54:55], v[46:47] op_sel_hi:[0,1]
	v_pk_mul_f32 v[44:45], v[54:55], v[44:45] op_sel_hi:[0,1]
	v_pk_mul_f32 v[42:43], v[54:55], v[42:43] op_sel_hi:[0,1]
	s_and_b64 vcc, exec, s[6:7]
	s_mov_b64 s[4:5], -1
	s_cbranch_vccnz .LBB0_288
	s_mov_b64 s[50:51], -1
	s_mov_b64 s[4:5], 0
	s_cmp_lt_i32 s24, 2
	s_mov_b64 s[48:49], 0
	s_cbranch_scc1 .LBB0_283
	s_cmp_eq_u32 s24, 2
	s_mov_b64 s[48:49], -1
	s_cbranch_scc0 .LBB0_280
	v_lshl_add_u64 v[56:57], s[30:31], 0, v[50:51]
	v_lshlrev_b32_e32 v134, 2, v166
	v_lshl_add_u64 v[56:57], v[56:57], 0, v[134:135]
	global_store_dwordx4 v[56:57], v[46:49], off
	global_store_dwordx4 v[56:57], v[42:45], off offset:16
	v_lshl_add_u64 v[56:57], s[26:27], 0, v[50:51]
	v_mov_b32_e32 v137, v135
	v_lshl_add_u64 v[60:61], v[56:57], 0, v[136:137]
	v_cvt_pk_bf16_f32 v56, v46, v47
	v_cvt_pk_bf16_f32 v57, v48, v49
	v_cvt_pk_bf16_f32 v58, v42, v43
	v_cvt_pk_bf16_f32 v59, v44, v45
	global_store_dwordx4 v[60:61], v[56:59], off
	s_mov_b64 s[48:49], 0

; __device__ __forceinline__ float rs_val(float ssqv) { return __builtin_amdgcn_rsqf(ssqv * (1.f / DM) + EPS); }
; __device__ __forceinline__ void st_bf16x8(bf16* p, f32x4 a, f32x4 b) { *(bf16x8*)p = pack8(a, b); }
;     __device__ __forceinline__ void operator()(const Acc& acc, const pg8::Unit& u, int wr, int wc, int fr, int fq, const float* rsv) const {
;         const int sec = u.pn >> 2, cin = (u.pn & 3) * 256 + wc * 32 + fq * 8;
; #pragma unroll
;         for (int ai = 0; ai < 2; ++ai)
; #pragma unroll
;             for (int m = 0; m < 4; ++m) { const int row = u.pm * 256 + ai * 128 + wr * 64 + m * 16 + fr; const float rs = rs_val(rsv[ai * 4 + m]);
; #pragma unroll
;                 for (int bj = 0; bj < 2; ++bj) { const f32x4 v0 = acc[ai][bj][m][0] * rs, v1 = acc[ai][bj][m][1] * rs; const int c = cin + bj * 128;
;                     if (sec == 0) { st_bf16x8(UB + (size_t)row * PW + c, v0, v1);
;                         if (row >= SEQ - 15) { float* p = poolp + (size_t)(row - (SEQ - 15)) * PW + c; *(f32x4*)p = v0; *(f32x4*)(p + 4) = v1; } }
;                     else if (sec == 1) st_bf16x8(QB + (size_t)row * DM + c, v0, v1);
;                     else if (sec == 2) { float* p = fk + (size_t)row * FW + c; *(f32x4*)p = v0; *(f32x4*)(p + 4) = v1; st_bf16x8(KB + (size_t)row * DM + c, v0, v1); }
;                     else { float* p = fv + (size_t)row * FW + c; *(f32x4*)p = v0; *(f32x4*)(p + 4) = v1; st_bf16x8(VB + (size_t)row * DM + c, v0, v1); } } }
.LBB0_308:
	s_nop 0
	v_fmamk_f32 v34, v164, 0x3a000000, v162
	v_rsq_f32_e32 v38, v34
	v_add_u32_e32 v36, 0xa0, v138
	v_ashrrev_i32_e32 v37, 31, v36
	v_lshlrev_b64 v[34:35], 12, v[36:37]
	v_cmp_lt_i32_e64 s[8:9], s78, v36
	v_pk_mul_f32 v[32:33], v[38:39], v[32:33] op_sel_hi:[0,1]
	v_pk_mul_f32 v[30:31], v[38:39], v[30:31] op_sel_hi:[0,1]
	v_pk_mul_f32 v[28:29], v[38:39], v[28:29] op_sel_hi:[0,1]
	v_pk_mul_f32 v[26:27], v[38:39], v[26:27] op_sel_hi:[0,1]
	s_and_b64 vcc, exec, s[6:7]
	s_mov_b64 s[4:5], -1
	s_cbranch_vccnz .LBB0_320
	s_mov_b64 s[50:51], -1
	s_mov_b64 s[4:5], 0
	s_cmp_lt_i32 s24, 2
	s_mov_b64 s[48:49], 0
	s_cbranch_scc1 .LBB0_315
	s_cmp_eq_u32 s24, 2
	s_mov_b64 s[48:49], -1
	s_cbranch_scc0 .LBB0_312
	v_lshl_add_u64 v[40:41], s[30:31], 0, v[34:35]
	v_lshlrev_b32_e32 v134, 2, v166
	v_lshl_add_u64 v[40:41], v[40:41], 0, v[134:135]
	global_store_dwordx4 v[40:41], v[30:33], off
	global_store_dwordx4 v[40:41], v[26:29], off offset:16
	v_lshl_add_u64 v[40:41], s[26:27], 0, v[34:35]
	v_mov_b32_e32 v137, v135
	v_lshl_add_u64 v[44:45], v[40:41], 0, v[136:137]
	v_cvt_pk_bf16_f32 v40, v30, v31
	v_cvt_pk_bf16_f32 v41, v32, v33
	v_cvt_pk_bf16_f32 v42, v26, v27
	v_cvt_pk_bf16_f32 v43, v28, v29
	global_store_dwordx4 v[44:45], v[40:43], off
	s_mov_b64 s[48:49], 0

; __device__ __forceinline__ float rs_val(float ssqv) { return __builtin_amdgcn_rsqf(ssqv * (1.f / DM) + EPS); }
; __device__ __forceinline__ void st_bf16x8(bf16* p, f32x4 a, f32x4 b) { *(bf16x8*)p = pack8(a, b); }
;     __device__ __forceinline__ void operator()(const Acc& acc, const pg8::Unit& u, int wr, int wc, int fr, int fq, const float* rsv) const {
;         const int sec = u.pn >> 2, cin = (u.pn & 3) * 256 + wc * 32 + fq * 8;
; #pragma unroll
;         for (int ai = 0; ai < 2; ++ai)
; #pragma unroll
;             for (int m = 0; m < 4; ++m) { const int row = u.pm * 256 + ai * 128 + wr * 64 + m * 16 + fr; const float rs = rs_val(rsv[ai * 4 + m]);
; #pragma unroll
;                 for (int bj = 0; bj < 2; ++bj) { const f32x4 v0 = acc[ai][bj][m][0] * rs, v1 = acc[ai][bj][m][1] * rs; const int c = cin + bj * 128;
;                     if (sec == 0) { st_bf16x8(UB + (size_t)row * PW + c, v0, v1);
;                         if (row >= SEQ - 15) { float* p = poolp + (size_t)(row - (SEQ - 15)) * PW + c; *(f32x4*)p = v0; *(f32x4*)(p + 4) = v1; } }
;                     else if (sec == 1) st_bf16x8(QB + (size_t)row * DM + c, v0, v1);
;                     else if (sec == 2) { float* p = fk + (size_t)row * FW + c; *(f32x4*)p = v0; *(f32x4*)(p + 4) = v1; st_bf16x8(KB + (size_t)row * DM + c, v0, v1); }
;                     else { float* p = fv + (size_t)row * FW + c; *(f32x4*)p = v0; *(f32x4*)(p + 4) = v1; st_bf16x8(VB + (size_t)row * DM + c, v0, v1); } } }
.LBB0_340:
	s_nop 0
	v_fmamk_f32 v18, v163, 0x3a000000, v162
	v_rsq_f32_e32 v22, v18
	v_add_u32_e32 v20, 0xb0, v138
	v_ashrrev_i32_e32 v21, 31, v20
	v_lshlrev_b64 v[18:19], 12, v[20:21]
	v_cmp_lt_i32_e64 s[8:9], s78, v20
	v_pk_mul_f32 v[16:17], v[22:23], v[16:17] op_sel_hi:[0,1]
	v_pk_mul_f32 v[14:15], v[22:23], v[14:15] op_sel_hi:[0,1]
	v_pk_mul_f32 v[12:13], v[22:23], v[12:13] op_sel_hi:[0,1]
	v_pk_mul_f32 v[10:11], v[22:23], v[10:11] op_sel_hi:[0,1]
	s_and_b64 vcc, exec, s[6:7]
	s_mov_b64 s[4:5], -1
	s_cbranch_vccnz .LBB0_352
	s_mov_b64 s[50:51], -1
	s_mov_b64 s[4:5], 0
	s_cmp_lt_i32 s24, 2
	s_mov_b64 s[48:49], 0
	s_cbranch_scc1 .LBB0_347
	s_cmp_eq_u32 s24, 2
	s_mov_b64 s[48:49], -1
	s_cbranch_scc0 .LBB0_344
	v_lshl_add_u64 v[24:25], s[30:31], 0, v[18:19]
	v_lshlrev_b32_e32 v134, 2, v166
	v_lshl_add_u64 v[24:25], v[24:25], 0, v[134:135]
	global_store_dwordx4 v[24:25], v[14:17], off
	global_store_dwordx4 v[24:25], v[10:13], off offset:16
	v_lshl_add_u64 v[24:25], s[26:27], 0, v[18:19]
	v_mov_b32_e32 v137, v135
	v_lshl_add_u64 v[28:29], v[24:25], 0, v[136:137]
	v_cvt_pk_bf16_f32 v24, v14, v15
	v_cvt_pk_bf16_f32 v25, v16, v17
	v_cvt_pk_bf16_f32 v26, v10, v11
	v_cvt_pk_bf16_f32 v27, v12, v13
	global_store_dwordx4 v[28:29], v[24:27], off
	s_mov_b64 s[48:49], 0

;     __device__ bool next(int i, Unit& u) const {
;         const long L = (long)i * G + c; if (L >= nwg) return false;
;         int wgid = (int)L; { const int q = nwg / NXCD, r = nwg % NXCD, xcd = wgid % NXCD, off = wgid / NXCD; wgid = (xcd < r ? xcd * (q + 1) : r * (q + 1) + (xcd - r) * q) + off; }
;         const int nig = WGM * nN, gid = wgid / nig, fm = gid * WGM, gsz = (nM - fm) < WGM ? (nM - fm) : WGM;
;         u.pm = fm + ((wgid % nig) % gsz); u.pn = (wgid % nig) / gsz; return true;
; template <class Epi, class Sched, bool ALIGN_EPI>
; __device__ __forceinline__ void gemm_phase(LAS unsigned char* lds, const Gemm g, const Sched& S, const Epi& E) {
;     ...
;     for (int i = 0; i < 2; ++i) { int R, C; stage_rc(tid * 16 + i * 8192, R, C); const int Rb = (R & ~31) + perm32(R & 31);
;         voffA[i] = (unsigned)(R * g.lda + C) * 2u; voffB[i] = (unsigned)(Rb * g.ldb + C) * 2u; }
;     const size_t kstep = (size_t)(BK * 2);
;     const size_t hstepA = (size_t)HALF * g.lda * 2, hstepB = (size_t)HALF * g.ldb * 2;
;     const size_t tstepA = 2 * hstepA, tstepB = 2 * hstepB;
;     const unsigned ldsw = (unsigned)wid * 1024u;
;     const int aoff = lds_byte(wr * 64 + fr, fq * 8), boff = lds_byte(wc * 32 + fr, fq * 8);
;     ...
;     const unsigned ldsb0 = (unsigned)(uintptr_t)lds + ldsw;
;     ...
;     Unit cur, nxt; int ui = 0;
;     if (!S.next(0, cur)) return;
;     f32x4 acc[2][2][4][2];
; #pragma unroll
;     for (int a = 0; a < 2; ++a)
; #pragma unroll
;         for (int b = 0; b < 2; ++b)
; #pragma unroll
;             for (int m = 0; m < 4; ++m)
; #pragma unroll
;                 for (int n = 0; n < 2; ++n) acc[a][b][m][n] = (f32x4){0.f, 0.f, 0.f, 0.f};
;     bf16x8 At[4][2], B0[2][2], B1[2][2];
;     float pre[Epi::NPRE > 0 ? Epi::NPRE : 1];
;     if constexpr (Epi::NPRE > 0) E.preload(cur, wr, fr, pre);
;     const char* cA = (const char*)g.A + (size_t)cur.pm * tstepA + (size_t)cur.pn * g.a_koff * 2; const char* cB = (const char*)g.Bt + (size_t)cur.pn * tstepB;
;     PG8_STAGE(PG8_SB(0, 0), cB, voffB); PG8_STAGE(PG8_SB(0, 1), cB + hstepB, voffB); PG8_STAGE(PG8_SA(0, 0), cA, voffA); PG8_STAGE(PG8_SA(0, 1), cA + hstepA, voffA);
;     if (wr == 1) PG8_BAR;
;     PG8_WAIT_V(2); PG8_BAR;
;     PG8_STAGE(PG8_SB(1, 0), cB + kstep, voffB); PG8_STAGE(PG8_SA(1, 0), cA + kstep, voffA); PG8_STAGE(PG8_SB(1, 1), cB + hstepB + kstep, voffB);
;     PG8_WAIT_V(6); PG8_BAR;
.LBB0_792:
	s_or_b64 exec, exec, s[4:5]
	s_mov_b64 s[8:9], s[0:1]
	s_mov_b64 s[10:11], s[0:1]
	s_mov_b64 s[12:13], s[0:1]
	s_mov_b64 s[14:15], s[0:1]
	s_waitcnt lgkmcnt(0)
	v_mov_b32_e32 v2, v0
	s_barrier
	s_ashr_i32 s77, s76, 31
	s_ashr_i32 s87, s86, 31
	s_and_b64 vcc, exec, s[18:19]
	v_readfirstlane_b32 s3, v2
	s_cbranch_vccz .LBB0_812
	v_bfe_i32 v5, v2, 27, 1
	v_lshlrev_b32_e32 v3, 4, v2
	v_lshrrev_b32_e32 v5, 22, v5
	v_add_u32_e32 v5, v3, v5
	v_and_b32_e32 v5, 0xfffffc00, v5
	v_sub_u32_e32 v5, v3, v5
	v_ashrrev_i32_e32 v4, 31, v2
	v_lshrrev_b32_e32 v6, 4, v5
	v_lshrrev_b32_e32 v4, 26, v4
	v_bitop3_b32 v6, v6, v5, 32 bitop3:0x6c
	v_ashrrev_i32_e32 v5, 31, v5
	v_add_u32_e32 v4, v2, v4
	v_lshrrev_b32_e32 v5, 26, v5
	v_ashrrev_i32_e32 v4, 6, v4
	v_add_u32_e32 v5, v6, v5
	v_lshlrev_b32_e32 v7, 3, v4
	v_ashrrev_i32_e32 v5, 6, v5
	v_and_b32_e32 v7, -16, v7
	v_mul_i32_i24_e32 v8, 64, v5
	v_add_u32_e32 v7, v5, v7
	v_sub_u32_e32 v6, v6, v8
	v_mov_b32_e32 v8, 1
	v_lshlrev_b32_e32 v4, 5, v4
	v_ashrrev_i16_sdwa v6, v8, sext(v6) dst_sel:DWORD dst_unused:UNUSED_PAD src0_sel:DWORD src1_sel:BYTE_0
	v_lshlrev_b32_e32 v9, 1, v7
	v_lshrrev_b32_e32 v10, 2, v7
	v_and_b32_e32 v5, 3, v5
	s_mov_b32 s2, 0x7fffe0
	v_and_b32_e32 v4, 32, v4
	v_bfe_i32 v6, v6, 0, 16
	v_and_b32_e32 v9, 24, v9
	v_and_b32_e32 v10, 4, v10
	v_and_or_b32 v5, v7, s2, v5
	v_or3_b32 v5, v5, v10, v9
	v_add_lshl_u32 v4, v4, v6, 1
	v_add_u32_e32 v3, 0x2000, v3
	v_lshl_add_u32 v144, v7, 11, v4
	v_lshl_add_u32 v145, v5, 9, v4
	v_ashrrev_i32_e32 v4, 31, v3
	v_lshrrev_b32_e32 v4, 22, v4
	v_add_u32_e32 v4, v3, v4
	v_ashrrev_i32_e32 v4, 10, v4
	v_mul_i32_i24_e32 v5, 0x400, v4
	v_sub_u32_e32 v3, v3, v5
	v_lshrrev_b32_e32 v5, 4, v3
	s_load_dwordx2 s[16:17], s[8:9], 0xb0
	s_load_dwordx2 s[18:19], s[10:11], 0xb0
	s_load_dwordx2 s[4:5], s[12:13], 0x60
	s_load_dwordx2 s[6:7], s[14:15], 0xb0
	v_bitop3_b32 v3, v5, v3, 32 bitop3:0x6c
	v_ashrrev_i32_e32 v6, 31, v3
	s_waitcnt lgkmcnt(0)
	s_add_u32 s23, s16, 0x16400000
	v_lshrrev_b32_e32 v6, 26, v6
	s_addc_u32 s24, s17, 0
	v_lshlrev_b32_e32 v5, 3, v4
	v_add_u32_e32 v6, v3, v6
	s_add_u32 s25, s18, 0x1200000
	v_and_b32_e32 v5, -16, v5
	v_ashrrev_i32_e32 v7, 6, v6
	s_addc_u32 s54, s19, 0
	v_add_u32_e32 v5, v7, v5
	v_and_b32_e32 v7, 3, v7
	s_ashr_i32 s13, s3, 6
	v_and_or_b32 v7, v5, s2, v7
	s_lshl_b32 s2, s13, 10
	s_add_i32 s56, s2, 0
	s_lshr_b32 s2, s87, 29
	s_add_i32 s2, s86, s2
	s_and_b32 s8, s2, -8
	s_sub_i32 s8, s86, s8
	s_ashr_i32 s12, s3, 8
	s_lshl_b32 s10, s8, 4
	s_ashr_i32 s2, s2, 3
	s_mul_i32 s9, s8, 17
	s_cmp_lt_i32 s8, 0
	s_cselect_b32 s8, s9, s10
	s_add_i32 s2, s8, s2
	s_ashr_i32 s8, s2, 31
	s_lshr_b32 s8, s8, 27
	s_add_i32 s8, s2, s8
	s_ashr_i32 s9, s8, 5
	s_andn2_b32 s8, s8, 31
	s_sub_i32 s2, s2, s8
	s_bfe_i32 s8, s2, 0x80000
	s_bfe_u32 s8, s8, 0x3000c
	s_add_i32 s8, s2, s8
	s_bfe_i32 s10, s8, 0x80000
	s_and_b32 s8, s8, 0xf8
	s_sub_i32 s2, s2, s8
	s_lshl_b32 s9, s9, 3
	s_sext_i32_i16 s10, s10
	s_sext_i32_i8 s2, s2
	v_and_b32_e32 v6, 0xc0, v6
	s_lshr_b32 s10, s10, 3
	s_add_i32 s28, s9, s2
	v_sub_u32_e32 v3, v3, v6
	s_ashr_i32 s29, s28, 31
	s_bfe_i64 s[14:15], s[10:11], 0x100000
	v_lshlrev_b32_e32 v4, 5, v4
	v_ashrrev_i16_sdwa v3, v8, sext(v3) dst_sel:DWORD dst_unused:UNUSED_PAD src0_sel:DWORD src1_sel:BYTE_0
	v_lshlrev_b32_e32 v6, 1, v5
	v_lshrrev_b32_e32 v8, 2, v5
	s_lshl_b64 s[8:9], s[28:29], 19
	s_lshl_b64 s[16:17], s[14:15], 9
	s_lshl_b64 s[14:15], s[14:15], 17
	v_and_b32_e32 v4, 32, v4
	v_bfe_i32 v3, v3, 0, 16
	v_and_b32_e32 v6, 24, v6
	v_and_b32_e32 v8, 4, v8
	s_add_u32 s30, s25, s14
	v_or3_b32 v6, v7, v8, v6
	v_add_lshl_u32 v3, v4, v3, 1
	s_addc_u32 s31, s54, s15
	s_add_i32 s29, s56, 0x10000
	s_mov_b32 m0, s29
	s_nop 0
	global_load_lds_dwordx4 v145, s[30:31]
	v_lshl_add_u32 v147, v6, 9, v3
	s_add_i32 s57, s56, 0x12000
	s_mov_b32 m0, s57
	s_nop 0
	global_load_lds_dwordx4 v147, s[30:31]
	s_add_u32 s2, s23, s8
	s_addc_u32 s11, s24, s9
	s_add_u32 s8, s30, 0x10000
	s_addc_u32 s9, s31, 0
	s_add_i32 s58, s56, 0x14000
	s_mov_b32 m0, s58
	s_nop 0
	global_load_lds_dwordx4 v145, s[8:9]
	s_add_i32 s59, s56, 0x16000
	s_mov_b32 m0, s59
	s_nop 0
	global_load_lds_dwordx4 v147, s[8:9]
	s_add_u32 s34, s2, s16
	s_addc_u32 s35, s11, s17
	s_mov_b32 m0, s56
	s_nop 0
	global_load_lds_dwordx4 v144, s[34:35]
	s_add_i32 s61, s56, 0x2000
	v_lshl_add_u32 v146, v5, 11, v3
	s_mov_b32 m0, s61
	s_nop 0
	global_load_lds_dwordx4 v146, s[34:35]
	s_add_u32 s14, s34, 0x40000
	s_addc_u32 s15, s35, 0
	s_add_i32 s62, s56, 0x4000
	s_mov_b32 m0, s62
	s_nop 0
	global_load_lds_dwordx4 v144, s[14:15]
	s_add_i32 s63, s56, 0x6000
	s_mov_b32 m0, s63
	s_nop 0
	global_load_lds_dwordx4 v146, s[14:15]
	s_cmp_eq_u32 s12, 1
	s_mov_b32 s55, 0
	s_cselect_b64 s[8:9], -1, 0
	s_cmp_lg_u32 s12, 1
	s_cbranch_scc1 .LBB0_795
	s_barrier
.LBB0_795:
	v_lshrrev_b32_e32 v4, 1, v2
	v_and_b32_e32 v4, 24, v4
	s_sext_i32_i8 s2, s10
	s_add_u32 s10, s6, 0x17500000
	v_and_b32_e32 v3, 15, v2
	v_lshlrev_b32_e32 v5, 1, v4
	v_lshlrev_b32_e32 v2, 2, v2
	s_addc_u32 s11, s7, 0
	v_lshl_or_b32 v149, s12, 6, v3
	v_lshl_or_b32 v3, v3, 6, v5
	s_lshl_b32 s6, s12, 13
	v_and_b32_e32 v2, 32, v2
	v_bitop3_b32 v5, v3, s6, v2 bitop3:0xde
	s_lshl_b32 s6, s13, 5
	s_and_b32 s14, s6, 0x60
	s_lshl_b32 s6, s14, 7
	v_bitop3_b32 v2, v3, s6, v2 bitop3:0xde
	s_add_u32 s6, s30, 0x80
	s_waitcnt vmcnt(2)
	s_barrier
	s_addc_u32 s7, s31, 0
	s_add_i32 s64, s56, 0x18000
	s_mov_b32 m0, s64
	s_nop 0
	global_load_lds_dwordx4 v145, s[6:7]
	s_add_i32 s65, s56, 0x1a000
	s_mov_b32 m0, s65
	s_nop 0
	global_load_lds_dwordx4 v147, s[6:7]
	s_add_u32 s6, s34, 0x80
	s_addc_u32 s7, s35, 0
	s_add_i32 s66, s56, 0x8000
	s_mov_b32 m0, s66
	s_nop 0
	global_load_lds_dwordx4 v144, s[6:7]
	s_add_i32 s67, s56, 0xa000
	s_mov_b32 m0, s67
	s_nop 0
	global_load_lds_dwordx4 v146, s[6:7]
	s_add_u32 s6, s30, 0x10080
	s_addc_u32 s7, s31, 0
	s_add_i32 s68, s56, 0x1c000
	s_mov_b32 m0, s68
	s_nop 0
	global_load_lds_dwordx4 v145, s[6:7]
	s_add_i32 s69, s56, 0x1e000
	s_mov_b32 m0, s69
	s_nop 0
	global_load_lds_dwordx4 v147, s[6:7]
	s_waitcnt vmcnt(6)
	s_add_i32 s70, s56, 0xc000
	s_cmpk_lt_u32 s3, 0x100
	v_add_u32_e32 v2, 0, v2
	s_cselect_b64 s[12:13], -1, 0
	s_add_i32 s71, s56, 0xe000
	v_or_b32_e32 v150, s14, v4
	v_mov_b64_e32 v[138:139], 0x80
	v_mov_b64_e32 v[140:141], 0x7f
	v_add_u32_e32 v151, 0x10000, v2
	v_add_u32_e32 v152, 0x14000, v2
	v_add_u32_e32 v153, 0, v5
	v_add_u32_e32 v154, 0x18000, v2
	v_add_u32_e32 v155, 0x1c000, v2
	s_barrier
	s_branch .LBB0_798

; #define PG8_STAGE(bufoff, gbase, voff) do { _Pragma("unroll") for (int _i = 0; _i < 2; ++_i) { unsigned keep_; \
;         asm volatile("s_mov_b32 %0, m0\n\ts_mov_b32 m0, %3\n\ts_nop 0\n\tglobal_load_lds_dwordx4 %1, %2\n\ts_mov_b32 m0, %0" \
;             : "=&s"(keep_) : "v"((voff)[_i]), "s"((const void*)(gbase)), "s"(ldsb0 + (unsigned)(bufoff) + (unsigned)(_i * 8192)) : "memory"); } } while (0)
; #define PG8_LDA(dst, b, h) do { _Pragma("unroll") for (int m = 0; m < 4; ++m) _Pragma("unroll") for (int k = 0; k < 2; ++k) dst[m][k] = *(const LAS bf16x8*)(lds + PG8_SA(b, h) + aoff + m * 2048 + k * 1024); } while (0)
; #define PG8_LDB(dst, b, h) do { _Pragma("unroll") for (int n = 0; n < 2; ++n) _Pragma("unroll") for (int k = 0; k < 2; ++k) dst[n][k] = *(const LAS bf16x8*)(lds + PG8_SB(b, h) + boff + n * 2048 + k * 1024); } while (0)
; #define PG8_MMA(ai, bj, At, Bt) do { __builtin_amdgcn_s_setprio(1); _Pragma("unroll") for (int m = 0; m < 4; ++m) _Pragma("unroll") for (int n = 0; n < 2; ++n) _Pragma("unroll") for (int k = 0; k < 2; ++k) \
;         acc[ai][bj][m][n] = __builtin_amdgcn_mfma_f32_16x16x32_bf16(Bt[n][k], At[m][k], acc[ai][bj][m][n], 0, 0, 0); __builtin_amdgcn_s_setprio(0); } while (0)
; #define PG8_WAIT_V(n) asm volatile("s_waitcnt vmcnt(" #n ")" ::: "memory")
; #define PG8_BAR __builtin_amdgcn_s_barrier()
; template <class Epi, class Sched, bool ALIGN_EPI>
; __device__ __forceinline__ void gemm_phase(LAS unsigned char* lds, const Gemm g, const Sched& S, const Epi& E) {
;     ...
;         for (int t = 0; t < nt; t += 2) {
;             const bool last = (t == nt - 2);
;             const char* a1 = cA + (size_t)(t + 1) * kstep;
;             const char* a2 = last ? nA : cA + (size_t)(t + 2) * kstep; const char* b2 = last ? nB : cB + (size_t)(t + 2) * kstep;
;             const char* a3 = a2 + kstep; const char* b3 = b2 + kstep;
;             PG8_LDB(B0, 0, 0); PG8_LDB(B1, 0, 1); PG8_SCHED; PG8_LDA(At, 0, 0); PG8_STAGE(PG8_SA(1, 1), a1 + hstepA, voffA);
;             PG8_WAIT_V(8); PG8_WAIT_L(0); PG8_BAR; PG8_MMA(0, 0, At, B0); PG8_MMA(0, 1, At, B1); PG8_BAR; PG8_SCHED;
;             PG8_LDA(At, 0, 1); PG8_STAGE(PG8_SB(0, 0), b2, voffB); PG8_STAGE(PG8_SB(0, 1), b2 + hstepB, voffB); PG8_STAGE(PG8_SA(0, 0), a2, voffA);
;             PG8_WAIT_V(8); PG8_WAIT_L(0); PG8_BAR; PG8_MMA(1, 0, At, B0); PG8_MMA(1, 1, At, B1); PG8_BAR; PG8_SCHED;
.LBB0_805:
	s_add_u32 s48, s34, s40
	s_addc_u32 s49, s35, s41
	s_add_u32 s44, s48, 0x100
	s_addc_u32 s45, s49, 0
	s_and_b64 s[42:43], s[38:39], exec
	s_cselect_b32 s45, s3, s45
	s_cselect_b32 s44, s17, s44
	s_add_u32 s40, s30, s40
	s_addc_u32 s41, s31, s41
	s_add_u32 s42, s40, 0x100
	s_addc_u32 s43, s41, 0
	s_add_u32 s40, s44, 0x80
	s_addc_u32 s41, s45, 0
	ds_read_b128 v[130:133], v151
	s_waitcnt vmcnt(7)
	ds_read_b128 v[134:137], v151 offset:1024
	ds_read_b128 v[156:159], v151 offset:2048
	s_waitcnt vmcnt(0)
	ds_read_b128 v[160:163], v151 offset:3072
	ds_read_b128 v[164:167], v152
	ds_read_b128 v[168:171], v152 offset:1024
	ds_read_b128 v[172:175], v152 offset:2048
	ds_read_b128 v[180:183], v152 offset:3072
	s_and_b64 s[38:39], s[38:39], exec
	s_cselect_b32 s47, s15, s43
	s_cselect_b32 s46, s72, s42
	s_add_u32 s52, s48, 0x40080
	s_addc_u32 s53, s49, 0
	s_add_u32 s48, s46, 0x10000
	s_addc_u32 s49, s47, 0
	s_add_u32 s42, s44, 0x40000
	s_addc_u32 s43, s45, 0
	s_add_u32 s38, s46, 0x80
	s_addc_u32 s39, s47, 0
	s_add_u32 s50, s46, 0x10080
	s_addc_u32 s51, s47, 0
	ds_read_b128 v[184:187], v153
	ds_read_b128 v[188:191], v153 offset:1024
	ds_read_b128 v[192:195], v153 offset:2048
	ds_read_b128 v[196:199], v153 offset:3072
	ds_read_b128 v[200:203], v153 offset:4096
	ds_read_b128 v[204:207], v153 offset:5120
	ds_read_b128 v[208:211], v153 offset:6144
	ds_read_b128 v[212:215], v153 offset:7168
	s_mov_b32 m0, s70
	s_nop 0
	global_load_lds_dwordx4 v144, s[52:53]
	s_nop 0
	s_mov_b32 m0, s71
	s_nop 0
	global_load_lds_dwordx4 v146, s[52:53]
	s_waitcnt vmcnt(8)
	s_waitcnt lgkmcnt(0)
	s_barrier
	s_setprio 1
	v_mfma_f32_16x16x32_bf16 v[126:129], v[130:133], v[184:187], v[126:129]
	v_mfma_f32_16x16x32_bf16 v[122:125], v[156:159], v[184:187], v[122:125]
	v_mfma_f32_16x16x32_bf16 v[118:121], v[130:133], v[192:195], v[118:121]
	v_mfma_f32_16x16x32_bf16 v[114:117], v[156:159], v[192:195], v[114:117]
	v_mfma_f32_16x16x32_bf16 v[110:113], v[130:133], v[200:203], v[110:113]
	v_mfma_f32_16x16x32_bf16 v[106:109], v[156:159], v[200:203], v[106:109]
	v_mfma_f32_16x16x32_bf16 v[102:105], v[130:133], v[208:211], v[102:105]
	v_mfma_f32_16x16x32_bf16 v[98:101], v[156:159], v[208:211], v[98:101]
	v_mfma_f32_16x16x32_bf16 v[126:129], v[134:137], v[188:191], v[126:129]
	v_mfma_f32_16x16x32_bf16 v[122:125], v[160:163], v[188:191], v[122:125]
	v_mfma_f32_16x16x32_bf16 v[118:121], v[134:137], v[196:199], v[118:121]
	v_mfma_f32_16x16x32_bf16 v[114:117], v[160:163], v[196:199], v[114:117]
	v_mfma_f32_16x16x32_bf16 v[110:113], v[134:137], v[204:207], v[110:113]
	v_mfma_f32_16x16x32_bf16 v[106:109], v[160:163], v[204:207], v[106:109]
	v_mfma_f32_16x16x32_bf16 v[102:105], v[134:137], v[212:215], v[102:105]
	v_mfma_f32_16x16x32_bf16 v[98:101], v[160:163], v[212:215], v[98:101]
	v_mfma_f32_16x16x32_bf16 v[70:73], v[164:167], v[184:187], v[70:73]
	v_mfma_f32_16x16x32_bf16 v[66:69], v[172:175], v[184:187], v[66:69]
	v_mfma_f32_16x16x32_bf16 v[58:61], v[164:167], v[192:195], v[58:61]
	v_mfma_f32_16x16x32_bf16 v[50:53], v[172:175], v[192:195], v[50:53]
	v_mfma_f32_16x16x32_bf16 v[46:49], v[164:167], v[200:203], v[46:49]
	v_mfma_f32_16x16x32_bf16 v[42:45], v[172:175], v[200:203], v[42:45]
	v_mfma_f32_16x16x32_bf16 v[38:41], v[164:167], v[208:211], v[38:41]
	v_mfma_f32_16x16x32_bf16 v[34:37], v[172:175], v[208:211], v[34:37]
	v_mfma_f32_16x16x32_bf16 v[70:73], v[168:171], v[188:191], v[70:73]
	v_mfma_f32_16x16x32_bf16 v[66:69], v[180:183], v[188:191], v[66:69]
	v_mfma_f32_16x16x32_bf16 v[58:61], v[168:171], v[196:199], v[58:61]
	v_mfma_f32_16x16x32_bf16 v[50:53], v[180:183], v[196:199], v[50:53]
	v_mfma_f32_16x16x32_bf16 v[46:49], v[168:171], v[204:207], v[46:49]
	v_mfma_f32_16x16x32_bf16 v[42:45], v[180:183], v[204:207], v[42:45]
	v_mfma_f32_16x16x32_bf16 v[38:41], v[168:171], v[212:215], v[38:41]
	v_mfma_f32_16x16x32_bf16 v[34:37], v[180:183], v[212:215], v[34:37]
	s_setprio 0
	s_barrier
	ds_read_b128 v[184:187], v153 offset:16384
	ds_read_b128 v[188:191], v153 offset:17408
	ds_read_b128 v[192:195], v153 offset:18432
	ds_read_b128 v[196:199], v153 offset:19456
	ds_read_b128 v[200:203], v153 offset:20480
	ds_read_b128 v[204:207], v153 offset:21504
	ds_read_b128 v[208:211], v153 offset:22528
	ds_read_b128 v[212:215], v153 offset:23552
	s_mov_b32 m0, s29
	s_nop 0
	global_load_lds_dwordx4 v145, s[46:47]
	s_nop 0
	s_mov_b32 m0, s57
	s_nop 0
	global_load_lds_dwordx4 v147, s[46:47]
	s_mov_b32 m0, s58
	s_nop 0
	global_load_lds_dwordx4 v145, s[48:49]
	s_nop 0
	s_mov_b32 m0, s59
	s_nop 0
	global_load_lds_dwordx4 v147, s[48:49]
	s_nop 0
	s_mov_b32 m0, s56
	s_nop 0
	global_load_lds_dwordx4 v144, s[44:45]
	s_nop 0
	s_mov_b32 m0, s61
	s_nop 0
	global_load_lds_dwordx4 v146, s[44:45]
	s_waitcnt vmcnt(8)
	s_waitcnt lgkmcnt(0)
	s_barrier
; #define PG8_STAGE(bufoff, gbase, voff) do { _Pragma("unroll") for (int _i = 0; _i < 2; ++_i) { unsigned keep_; \
;         asm volatile("s_mov_b32 %0, m0\n\ts_mov_b32 m0, %3\n\ts_nop 0\n\tglobal_load_lds_dwordx4 %1, %2\n\ts_mov_b32 m0, %0" \
;             : "=&s"(keep_) : "v"((voff)[_i]), "s"((const void*)(gbase)), "s"(ldsb0 + (unsigned)(bufoff) + (unsigned)(_i * 8192)) : "memory"); } } while (0)
; #define PG8_LDA(dst, b, h) do { _Pragma("unroll") for (int m = 0; m < 4; ++m) _Pragma("unroll") for (int k = 0; k < 2; ++k) dst[m][k] = *(const LAS bf16x8*)(lds + PG8_SA(b, h) + aoff + m * 2048 + k * 1024); } while (0)
; #define PG8_LDB(dst, b, h) do { _Pragma("unroll") for (int n = 0; n < 2; ++n) _Pragma("unroll") for (int k = 0; k < 2; ++k) dst[n][k] = *(const LAS bf16x8*)(lds + PG8_SB(b, h) + boff + n * 2048 + k * 1024); } while (0)
; #define PG8_MMA(ai, bj, At, Bt) do { __builtin_amdgcn_s_setprio(1); _Pragma("unroll") for (int m = 0; m < 4; ++m) _Pragma("unroll") for (int n = 0; n < 2; ++n) _Pragma("unroll") for (int k = 0; k < 2; ++k) \
;         acc[ai][bj][m][n] = __builtin_amdgcn_mfma_f32_16x16x32_bf16(Bt[n][k], At[m][k], acc[ai][bj][m][n], 0, 0, 0); __builtin_amdgcn_s_setprio(0); } while (0)
; #define PG8_WAIT_V(n) asm volatile("s_waitcnt vmcnt(" #n ")" ::: "memory")
; #define PG8_WAIT_L(n) asm volatile("s_waitcnt lgkmcnt(" #n ")" ::: "memory")
; #define PG8_BAR __builtin_amdgcn_s_barrier()
; #define PG8_SCHED __builtin_amdgcn_sched_barrier(0)
; template <class Epi, class Sched, bool ALIGN_EPI>
; __device__ __forceinline__ void gemm_phase(LAS unsigned char* lds, const Gemm g, const Sched& S, const Epi& E) {
;     ...
;             PG8_WAIT_V(8); PG8_WAIT_L(0); PG8_BAR; PG8_MMA(0, 0, At, B0); PG8_MMA(0, 1, At, B1); PG8_BAR; PG8_SCHED;
;             PG8_LDA(At, 0, 1); PG8_STAGE(PG8_SB(0, 0), b2, voffB); PG8_STAGE(PG8_SB(0, 1), b2 + hstepB, voffB); PG8_STAGE(PG8_SA(0, 0), a2, voffA);
;             PG8_WAIT_V(8); PG8_WAIT_L(0); PG8_BAR; PG8_MMA(1, 0, At, B0); PG8_MMA(1, 1, At, B1); PG8_BAR; PG8_SCHED;
;             PG8_LDB(B0, 1, 0); PG8_LDB(B1, 1, 1); PG8_SCHED; PG8_LDA(At, 1, 0); PG8_STAGE(PG8_SA(0, 1), a2 + hstepA, voffA);
;             PG8_WAIT_V(8); PG8_WAIT_L(0); PG8_BAR; PG8_MMA(0, 0, At, B0); PG8_MMA(0, 1, At, B1); PG8_BAR; PG8_SCHED;
	s_setprio 1
	v_mfma_f32_16x16x32_bf16 v[94:97], v[130:133], v[184:187], v[94:97]
	v_mfma_f32_16x16x32_bf16 v[90:93], v[156:159], v[184:187], v[90:93]
	v_mfma_f32_16x16x32_bf16 v[86:89], v[130:133], v[192:195], v[86:89]
	v_mfma_f32_16x16x32_bf16 v[82:85], v[156:159], v[192:195], v[82:85]
	v_mfma_f32_16x16x32_bf16 v[78:81], v[130:133], v[200:203], v[78:81]
	v_mfma_f32_16x16x32_bf16 v[74:77], v[156:159], v[200:203], v[74:77]
	v_mfma_f32_16x16x32_bf16 v[62:65], v[130:133], v[208:211], v[62:65]
	v_mfma_f32_16x16x32_bf16 v[54:57], v[156:159], v[208:211], v[54:57]
	v_mfma_f32_16x16x32_bf16 v[94:97], v[134:137], v[188:191], v[94:97]
	v_mfma_f32_16x16x32_bf16 v[90:93], v[160:163], v[188:191], v[90:93]
	v_mfma_f32_16x16x32_bf16 v[86:89], v[134:137], v[196:199], v[86:89]
	v_mfma_f32_16x16x32_bf16 v[82:85], v[160:163], v[196:199], v[82:85]
	v_mfma_f32_16x16x32_bf16 v[78:81], v[134:137], v[204:207], v[78:81]
	v_mfma_f32_16x16x32_bf16 v[74:77], v[160:163], v[204:207], v[74:77]
	v_mfma_f32_16x16x32_bf16 v[62:65], v[134:137], v[212:215], v[62:65]
	v_mfma_f32_16x16x32_bf16 v[54:57], v[160:163], v[212:215], v[54:57]
	v_mfma_f32_16x16x32_bf16 v[30:33], v[164:167], v[184:187], v[30:33]
	v_mfma_f32_16x16x32_bf16 v[26:29], v[172:175], v[184:187], v[26:29]
	v_mfma_f32_16x16x32_bf16 v[22:25], v[164:167], v[192:195], v[22:25]
	v_mfma_f32_16x16x32_bf16 v[18:21], v[172:175], v[192:195], v[18:21]
	v_mfma_f32_16x16x32_bf16 v[14:17], v[164:167], v[200:203], v[14:17]
	v_mfma_f32_16x16x32_bf16 v[10:13], v[172:175], v[200:203], v[10:13]
	v_mfma_f32_16x16x32_bf16 v[6:9], v[164:167], v[208:211], v[6:9]
	v_mfma_f32_16x16x32_bf16 v[2:5], v[172:175], v[208:211], v[2:5]
	v_mfma_f32_16x16x32_bf16 v[30:33], v[168:171], v[188:191], v[30:33]
	v_mfma_f32_16x16x32_bf16 v[26:29], v[180:183], v[188:191], v[26:29]
	v_mfma_f32_16x16x32_bf16 v[22:25], v[168:171], v[196:199], v[22:25]
	v_mfma_f32_16x16x32_bf16 v[18:21], v[180:183], v[196:199], v[18:21]
	v_mfma_f32_16x16x32_bf16 v[14:17], v[168:171], v[204:207], v[14:17]
	v_mfma_f32_16x16x32_bf16 v[10:13], v[180:183], v[204:207], v[10:13]
	v_mfma_f32_16x16x32_bf16 v[6:9], v[168:171], v[212:215], v[6:9]
	v_mfma_f32_16x16x32_bf16 v[2:5], v[180:183], v[212:215], v[2:5]
	s_setprio 0
	s_barrier
	ds_read_b128 v[130:133], v154
	ds_read_b128 v[134:137], v154 offset:1024
	ds_read_b128 v[156:159], v154 offset:2048
	ds_read_b128 v[160:163], v154 offset:3072
	ds_read_b128 v[164:167], v155
	ds_read_b128 v[168:171], v155 offset:1024
	ds_read_b128 v[172:175], v155 offset:2048
	ds_read_b128 v[180:183], v155 offset:3072
	ds_read_b128 v[184:187], v153 offset:32768
	ds_read_b128 v[188:191], v153 offset:33792
	ds_read_b128 v[192:195], v153 offset:34816
	ds_read_b128 v[196:199], v153 offset:35840
	ds_read_b128 v[200:203], v153 offset:36864
	ds_read_b128 v[204:207], v153 offset:37888
	ds_read_b128 v[208:211], v153 offset:38912
	ds_read_b128 v[212:215], v153 offset:39936
	s_mov_b32 m0, s62
	s_nop 0
	global_load_lds_dwordx4 v144, s[42:43]
	s_nop 0
	s_mov_b32 m0, s63
	s_nop 0
	global_load_lds_dwordx4 v146, s[42:43]
	s_waitcnt vmcnt(8)
	s_waitcnt lgkmcnt(0)
	s_barrier
	s_setprio 1
	v_mfma_f32_16x16x32_bf16 v[126:129], v[130:133], v[184:187], v[126:129]
	v_mfma_f32_16x16x32_bf16 v[122:125], v[156:159], v[184:187], v[122:125]
	v_mfma_f32_16x16x32_bf16 v[118:121], v[130:133], v[192:195], v[118:121]
	v_mfma_f32_16x16x32_bf16 v[114:117], v[156:159], v[192:195], v[114:117]
	v_mfma_f32_16x16x32_bf16 v[110:113], v[130:133], v[200:203], v[110:113]
	v_mfma_f32_16x16x32_bf16 v[106:109], v[156:159], v[200:203], v[106:109]
	v_mfma_f32_16x16x32_bf16 v[102:105], v[130:133], v[208:211], v[102:105]
	v_mfma_f32_16x16x32_bf16 v[98:101], v[156:159], v[208:211], v[98:101]
	v_mfma_f32_16x16x32_bf16 v[126:129], v[134:137], v[188:191], v[126:129]
	v_mfma_f32_16x16x32_bf16 v[122:125], v[160:163], v[188:191], v[122:125]
	v_mfma_f32_16x16x32_bf16 v[118:121], v[134:137], v[196:199], v[118:121]
	v_mfma_f32_16x16x32_bf16 v[114:117], v[160:163], v[196:199], v[114:117]
	v_mfma_f32_16x16x32_bf16 v[110:113], v[134:137], v[204:207], v[110:113]
	v_mfma_f32_16x16x32_bf16 v[106:109], v[160:163], v[204:207], v[106:109]
	v_mfma_f32_16x16x32_bf16 v[102:105], v[134:137], v[212:215], v[102:105]
	v_mfma_f32_16x16x32_bf16 v[98:101], v[160:163], v[212:215], v[98:101]
	v_mfma_f32_16x16x32_bf16 v[70:73], v[164:167], v[184:187], v[70:73]
	v_mfma_f32_16x16x32_bf16 v[66:69], v[172:175], v[184:187], v[66:69]
	v_mfma_f32_16x16x32_bf16 v[58:61], v[164:167], v[192:195], v[58:61]
	v_mfma_f32_16x16x32_bf16 v[50:53], v[172:175], v[192:195], v[50:53]
	v_mfma_f32_16x16x32_bf16 v[46:49], v[164:167], v[200:203], v[46:49]
	v_mfma_f32_16x16x32_bf16 v[42:45], v[172:175], v[200:203], v[42:45]
	v_mfma_f32_16x16x32_bf16 v[38:41], v[164:167], v[208:211], v[38:41]
	v_mfma_f32_16x16x32_bf16 v[34:37], v[172:175], v[208:211], v[34:37]
	v_mfma_f32_16x16x32_bf16 v[70:73], v[168:171], v[188:191], v[70:73]
	v_mfma_f32_16x16x32_bf16 v[66:69], v[180:183], v[188:191], v[66:69]
	v_mfma_f32_16x16x32_bf16 v[58:61], v[168:171], v[196:199], v[58:61]
	v_mfma_f32_16x16x32_bf16 v[50:53], v[180:183], v[196:199], v[50:53]
	v_mfma_f32_16x16x32_bf16 v[46:49], v[168:171], v[204:207], v[46:49]
	v_mfma_f32_16x16x32_bf16 v[42:45], v[180:183], v[204:207], v[42:45]
	v_mfma_f32_16x16x32_bf16 v[38:41], v[168:171], v[212:215], v[38:41]
	v_mfma_f32_16x16x32_bf16 v[34:37], v[180:183], v[212:215], v[34:37]
	s_setprio 0
	s_barrier
; #define PG8_STAGE(bufoff, gbase, voff) do { _Pragma("unroll") for (int _i = 0; _i < 2; ++_i) { unsigned keep_; \
;         asm volatile("s_mov_b32 %0, m0\n\ts_mov_b32 m0, %3\n\ts_nop 0\n\tglobal_load_lds_dwordx4 %1, %2\n\ts_mov_b32 m0, %0" \
;             : "=&s"(keep_) : "v"((voff)[_i]), "s"((const void*)(gbase)), "s"(ldsb0 + (unsigned)(bufoff) + (unsigned)(_i * 8192)) : "memory"); } } while (0)
; #define PG8_LDA(dst, b, h) do { _Pragma("unroll") for (int m = 0; m < 4; ++m) _Pragma("unroll") for (int k = 0; k < 2; ++k) dst[m][k] = *(const LAS bf16x8*)(lds + PG8_SA(b, h) + aoff + m * 2048 + k * 1024); } while (0)
; #define PG8_MMA(ai, bj, At, Bt) do { __builtin_amdgcn_s_setprio(1); _Pragma("unroll") for (int m = 0; m < 4; ++m) _Pragma("unroll") for (int n = 0; n < 2; ++n) _Pragma("unroll") for (int k = 0; k < 2; ++k) \
;         acc[ai][bj][m][n] = __builtin_amdgcn_mfma_f32_16x16x32_bf16(Bt[n][k], At[m][k], acc[ai][bj][m][n], 0, 0, 0); __builtin_amdgcn_s_setprio(0); } while (0)
; #define PG8_WAIT_V(n) asm volatile("s_waitcnt vmcnt(" #n ")" ::: "memory")
; #define PG8_WAIT_L(n) asm volatile("s_waitcnt lgkmcnt(" #n ")" ::: "memory")
; #define PG8_BAR __builtin_amdgcn_s_barrier()
; #define PG8_SCHED __builtin_amdgcn_sched_barrier(0)
; template <class Epi, class Sched, bool ALIGN_EPI>
; __device__ __forceinline__ void gemm_phase(LAS unsigned char* lds, const Gemm g, const Sched& S, const Epi& E) {
;     ...
;             PG8_LDA(At, 1, 1); PG8_STAGE(PG8_SB(1, 0), b3, voffB); PG8_STAGE(PG8_SB(1, 1), b3 + hstepB, voffB); PG8_STAGE(PG8_SA(1, 0), a3, voffA);
;             PG8_WAIT_V(8); PG8_WAIT_L(0); PG8_BAR; PG8_MMA(1, 0, At, B0); PG8_MMA(1, 1, At, B1); PG8_BAR; PG8_SCHED;
;         }
	ds_read_b128 v[184:187], v153 offset:49152
	ds_read_b128 v[188:191], v153 offset:50176
	ds_read_b128 v[192:195], v153 offset:51200
	ds_read_b128 v[196:199], v153 offset:52224
	ds_read_b128 v[200:203], v153 offset:53248
	ds_read_b128 v[204:207], v153 offset:54272
	ds_read_b128 v[208:211], v153 offset:55296
	ds_read_b128 v[212:215], v153 offset:56320
	s_mov_b32 m0, s64
	s_nop 0
	global_load_lds_dwordx4 v145, s[38:39]
	s_nop 0
	s_mov_b32 m0, s65
	s_nop 0
	global_load_lds_dwordx4 v147, s[38:39]
	s_mov_b32 m0, s68
	s_nop 0
	global_load_lds_dwordx4 v145, s[50:51]
	s_nop 0
	s_mov_b32 m0, s69
	s_nop 0
	global_load_lds_dwordx4 v147, s[50:51]
	s_nop 0
	s_mov_b32 m0, s66
	s_nop 0
	global_load_lds_dwordx4 v144, s[40:41]
	s_nop 0
	s_mov_b32 m0, s67
	s_nop 0
	global_load_lds_dwordx4 v146, s[40:41]
	s_waitcnt vmcnt(8)
	s_waitcnt lgkmcnt(0)
	s_barrier
	s_setprio 1
	v_mfma_f32_16x16x32_bf16 v[94:97], v[130:133], v[184:187], v[94:97]
	v_mfma_f32_16x16x32_bf16 v[90:93], v[156:159], v[184:187], v[90:93]
	v_mfma_f32_16x16x32_bf16 v[86:89], v[130:133], v[192:195], v[86:89]
	v_mfma_f32_16x16x32_bf16 v[82:85], v[156:159], v[192:195], v[82:85]
	v_mfma_f32_16x16x32_bf16 v[78:81], v[130:133], v[200:203], v[78:81]
	v_mfma_f32_16x16x32_bf16 v[74:77], v[156:159], v[200:203], v[74:77]
	v_mfma_f32_16x16x32_bf16 v[62:65], v[130:133], v[208:211], v[62:65]
	v_mfma_f32_16x16x32_bf16 v[54:57], v[156:159], v[208:211], v[54:57]
	v_mfma_f32_16x16x32_bf16 v[94:97], v[134:137], v[188:191], v[94:97]
	v_mfma_f32_16x16x32_bf16 v[90:93], v[160:163], v[188:191], v[90:93]
	v_mfma_f32_16x16x32_bf16 v[86:89], v[134:137], v[196:199], v[86:89]
	v_mfma_f32_16x16x32_bf16 v[82:85], v[160:163], v[196:199], v[82:85]
	v_mfma_f32_16x16x32_bf16 v[78:81], v[134:137], v[204:207], v[78:81]
	v_mfma_f32_16x16x32_bf16 v[74:77], v[160:163], v[204:207], v[74:77]
	v_mfma_f32_16x16x32_bf16 v[62:65], v[134:137], v[212:215], v[62:65]
	v_mfma_f32_16x16x32_bf16 v[54:57], v[160:163], v[212:215], v[54:57]
	v_mfma_f32_16x16x32_bf16 v[30:33], v[164:167], v[184:187], v[30:33]
	v_mfma_f32_16x16x32_bf16 v[26:29], v[172:175], v[184:187], v[26:29]
	v_mfma_f32_16x16x32_bf16 v[22:25], v[164:167], v[192:195], v[22:25]
	v_mfma_f32_16x16x32_bf16 v[18:21], v[172:175], v[192:195], v[18:21]
	v_mfma_f32_16x16x32_bf16 v[14:17], v[164:167], v[200:203], v[14:17]
	v_mfma_f32_16x16x32_bf16 v[10:13], v[172:175], v[200:203], v[10:13]
	v_mfma_f32_16x16x32_bf16 v[6:9], v[164:167], v[208:211], v[6:9]
	v_mfma_f32_16x16x32_bf16 v[2:5], v[172:175], v[208:211], v[2:5]
	v_mfma_f32_16x16x32_bf16 v[30:33], v[168:171], v[188:191], v[30:33]
	v_mfma_f32_16x16x32_bf16 v[26:29], v[180:183], v[188:191], v[26:29]
	v_mfma_f32_16x16x32_bf16 v[22:25], v[168:171], v[196:199], v[22:25]
	v_mfma_f32_16x16x32_bf16 v[18:21], v[180:183], v[196:199], v[18:21]
	v_mfma_f32_16x16x32_bf16 v[14:17], v[168:171], v[204:207], v[14:17]
	v_mfma_f32_16x16x32_bf16 v[10:13], v[180:183], v[204:207], v[10:13]
	v_mfma_f32_16x16x32_bf16 v[6:9], v[168:171], v[212:215], v[6:9]
	v_mfma_f32_16x16x32_bf16 v[2:5], v[180:183], v[212:215], v[2:5]
	s_setprio 0
	s_barrier
	s_andn2_b64 vcc, exec, s[36:37]
	s_mov_b64 s[38:39], -1
	s_mov_b64 s[36:37], 0
	s_mov_b64 s[40:41], 0x100
	s_cbranch_vccz .LBB0_805
	s_and_b64 vcc, exec, s[12:13]
	s_cbranch_vccz .LBB0_808
	s_barrier

;     __device__ bool next(int i, Unit& u) const {
;         const long L = (long)i * G + c; if (L >= nwg) return false;
;         int wgid = (int)L; { const int q = nwg / NXCD, r = nwg % NXCD, xcd = wgid % NXCD, off = wgid / NXCD; wgid = (xcd < r ? xcd * (q + 1) : r * (q + 1) + (xcd - r) * q) + off; }
;         const int nig = WGM * nN, gid = wgid / nig, fm = gid * WGM, gsz = (nM - fm) < WGM ? (nM - fm) : WGM;
;         u.pm = fm + ((wgid % nig) % gsz); u.pn = (wgid % nig) / gsz; return true;
; template <class Epi, class Sched, bool ALIGN_EPI>
; __device__ __forceinline__ void gemm_phase(LAS unsigned char* lds, const Gemm g, const Sched& S, const Epi& E) {
;     ...
;     for (int i = 0; i < 2; ++i) { int R, C; stage_rc(tid * 16 + i * 8192, R, C); const int Rb = (R & ~31) + perm32(R & 31);
;         voffA[i] = (unsigned)(R * g.lda + C) * 2u; voffB[i] = (unsigned)(Rb * g.ldb + C) * 2u; }
;     const size_t kstep = (size_t)(BK * 2);
;     const size_t hstepA = (size_t)HALF * g.lda * 2, hstepB = (size_t)HALF * g.ldb * 2;
;     const size_t tstepA = 2 * hstepA, tstepB = 2 * hstepB;
;     const unsigned ldsw = (unsigned)wid * 1024u;
;     const int aoff = lds_byte(wr * 64 + fr, fq * 8), boff = lds_byte(wc * 32 + fr, fq * 8);
;     ...
;     const unsigned ldsb0 = (unsigned)(uintptr_t)lds + ldsw;
;     ...
;     Unit cur, nxt; int ui = 0;
;     if (!S.next(0, cur)) return;
;     f32x4 acc[2][2][4][2];
; #pragma unroll
;     for (int a = 0; a < 2; ++a)
; #pragma unroll
;         for (int b = 0; b < 2; ++b)
; #pragma unroll
;             for (int m = 0; m < 4; ++m)
; #pragma unroll
;                 for (int n = 0; n < 2; ++n) acc[a][b][m][n] = (f32x4){0.f, 0.f, 0.f, 0.f};
;     bf16x8 At[4][2], B0[2][2], B1[2][2];
;     float pre[Epi::NPRE > 0 ? Epi::NPRE : 1];
;     if constexpr (Epi::NPRE > 0) E.preload(cur, wr, fr, pre);
;     const char* cA = (const char*)g.A + (size_t)cur.pm * tstepA + (size_t)cur.pn * g.a_koff * 2; const char* cB = (const char*)g.Bt + (size_t)cur.pn * tstepB;
;     PG8_STAGE(PG8_SB(0, 0), cB, voffB); PG8_STAGE(PG8_SB(0, 1), cB + hstepB, voffB); PG8_STAGE(PG8_SA(0, 0), cA, voffA); PG8_STAGE(PG8_SA(0, 1), cA + hstepA, voffA);
;     if (wr == 1) PG8_BAR;
;     PG8_WAIT_V(2); PG8_BAR;
;     PG8_STAGE(PG8_SB(1, 0), cB + kstep, voffB); PG8_STAGE(PG8_SA(1, 0), cA + kstep, voffA); PG8_STAGE(PG8_SB(1, 1), cB + hstepB + kstep, voffB);
;     PG8_WAIT_V(6); PG8_BAR;
.LBB0_1125:
	v_bfe_i32 v5, v2, 27, 1
	v_lshlrev_b32_e32 v3, 4, v2
	v_lshrrev_b32_e32 v5, 22, v5
	v_add_u32_e32 v5, v3, v5
	v_and_b32_e32 v5, 0xfffffc00, v5
	v_sub_u32_e32 v5, v3, v5
	v_ashrrev_i32_e32 v4, 31, v2
	v_lshrrev_b32_e32 v6, 4, v5
	v_lshrrev_b32_e32 v4, 26, v4
	v_bitop3_b32 v6, v6, v5, 32 bitop3:0x6c
	v_ashrrev_i32_e32 v5, 31, v5
	v_add_u32_e32 v4, v2, v4
	v_lshrrev_b32_e32 v5, 26, v5
	v_ashrrev_i32_e32 v4, 6, v4
	v_add_u32_e32 v5, v6, v5
	v_lshlrev_b32_e32 v7, 3, v4
	v_ashrrev_i32_e32 v5, 6, v5
	v_and_b32_e32 v7, -16, v7
	v_mul_i32_i24_e32 v8, 64, v5
	v_add_u32_e32 v7, v5, v7
	v_sub_u32_e32 v6, v6, v8
	v_mov_b32_e32 v8, 1
	v_lshlrev_b32_e32 v4, 5, v4
	v_ashrrev_i16_sdwa v6, v8, sext(v6) dst_sel:DWORD dst_unused:UNUSED_PAD src0_sel:DWORD src1_sel:BYTE_0
	v_lshlrev_b32_e32 v9, 1, v7
	v_lshrrev_b32_e32 v10, 2, v7
	v_and_b32_e32 v5, 3, v5
	s_mov_b32 s5, 0xfffe0
	v_and_b32_e32 v4, 32, v4
	v_bfe_i32 v6, v6, 0, 16
	v_and_b32_e32 v9, 24, v9
	v_and_b32_e32 v10, 4, v10
	v_and_or_b32 v5, v7, s5, v5
	v_or3_b32 v5, v5, v10, v9
	v_add_lshl_u32 v4, v4, v6, 1
	v_add_u32_e32 v3, 0x2000, v3
	v_lshl_add_u32 v179, v7, 12, v4
	v_lshl_add_u32 v200, v5, 12, v4
	v_ashrrev_i32_e32 v4, 31, v3
	v_lshrrev_b32_e32 v4, 22, v4
	v_add_u32_e32 v4, v3, v4
	v_ashrrev_i32_e32 v4, 10, v4
	v_mul_i32_i24_e32 v5, 0x400, v4
	v_sub_u32_e32 v3, v3, v5
	s_ashr_i32 s4, s6, 3
	v_lshrrev_b32_e32 v5, 4, v3
	s_waitcnt lgkmcnt(0)
	s_add_u32 s23, s14, 0x17500000
	v_bitop3_b32 v3, v5, v3, 32 bitop3:0x6c
	s_addc_u32 s24, s15, 0
	v_ashrrev_i32_e32 v6, 31, v3
	s_add_u32 s25, s8, 0x1300000
	v_lshrrev_b32_e32 v6, 26, v6
	s_addc_u32 s42, s9, 0
	v_lshlrev_b32_e32 v5, 3, v4
	v_add_u32_e32 v6, v3, v6
	s_add_i32 s2, s2, s4
	v_and_b32_e32 v5, -16, v5
	v_ashrrev_i32_e32 v7, 6, v6
	s_ashr_i32 s4, s2, 31
	v_add_u32_e32 v5, v7, v5
	v_and_b32_e32 v7, 3, v7
	s_ashr_i32 s7, s3, 6
	s_lshr_b32 s4, s4, 26
	v_and_or_b32 v7, v5, s5, v7
	s_lshl_b32 s5, s7, 10
	s_add_i32 s4, s2, s4
	s_add_i32 s44, s5, 0
	s_ashr_i32 s5, s4, 6
	s_andn2_b32 s4, s4, 63
	s_sub_i32 s2, s2, s4
	s_bfe_i32 s4, s2, 0x80000
	s_bfe_u32 s4, s4, 0x3000c
	s_add_i32 s4, s2, s4
	s_bfe_i32 s8, s4, 0x80000
	s_and_b32 s4, s4, 0xf8
	s_sub_i32 s2, s2, s4
	s_lshl_b32 s5, s5, 3
	s_sext_i32_i16 s8, s8
	s_sext_i32_i8 s2, s2
	v_and_b32_e32 v6, 0xc0, v6
	s_lshr_b32 s14, s8, 3
	s_add_i32 s4, s5, s2
	v_sub_u32_e32 v3, v3, v6
	s_ashr_i32 s5, s4, 31
	s_bfe_i64 s[16:17], s[14:15], 0x100000
	s_ashr_i32 s6, s3, 8
	v_lshlrev_b32_e32 v4, 5, v4
	v_ashrrev_i16_sdwa v3, v8, sext(v3) dst_sel:DWORD dst_unused:UNUSED_PAD src0_sel:DWORD src1_sel:BYTE_0
	v_lshlrev_b32_e32 v6, 1, v5
	v_lshrrev_b32_e32 v8, 2, v5
	s_lshl_b64 s[8:9], s[4:5], 20
	s_lshl_b64 s[16:17], s[16:17], 20
	v_and_b32_e32 v4, 32, v4
	v_bfe_i32 v3, v3, 0, 16
	v_and_b32_e32 v6, 24, v6
	v_and_b32_e32 v8, 4, v8
	s_add_u32 s34, s25, s16
	v_or3_b32 v6, v7, v8, v6
	v_add_lshl_u32 v3, v4, v3, 1
	s_addc_u32 s35, s42, s17
	s_add_i32 s45, s44, 0x10000
	s_mov_b32 m0, s45
	s_nop 0
	global_load_lds_dwordx4 v200, s[34:35]
	s_add_i32 s46, s44, 0x12000
	v_lshl_add_u32 v203, v6, 12, v3
	s_mov_b32 m0, s46
	s_nop 0
	global_load_lds_dwordx4 v203, s[34:35]
	s_add_u32 s16, s34, 0x80000
	s_addc_u32 s17, s35, 0
	s_add_i32 s47, s44, 0x14000
	s_mov_b32 m0, s47
	s_nop 0
	global_load_lds_dwordx4 v200, s[16:17]
	s_add_i32 s48, s44, 0x16000
	s_mov_b32 m0, s48
	s_nop 0
	global_load_lds_dwordx4 v203, s[16:17]
	s_add_u32 s36, s23, s8
	s_addc_u32 s37, s24, s9
	s_mov_b32 m0, s44
	s_nop 0
	global_load_lds_dwordx4 v179, s[36:37]
	s_add_i32 s49, s44, 0x2000
	v_lshl_add_u32 v201, v5, 12, v3
	s_mov_b32 m0, s49
	s_nop 0
	global_load_lds_dwordx4 v201, s[36:37]
	s_add_u32 s18, s36, 0x80000
	s_addc_u32 s19, s37, 0
	s_add_i32 s50, s44, 0x4000
	s_mov_b32 m0, s50
	s_nop 0
	global_load_lds_dwordx4 v179, s[18:19]
	s_add_i32 s51, s44, 0x6000
	s_mov_b32 m0, s51
	s_nop 0
	global_load_lds_dwordx4 v201, s[18:19]
	s_cmp_eq_u32 s6, 1
	s_mov_b32 s43, 0
	s_cselect_b64 s[8:9], -1, 0
	s_cmp_lg_u32 s6, 1
	s_cbranch_scc1 .LBB0_1127
	s_barrier
.LBB0_1127:
	s_sext_i32_i8 s2, s14
	s_add_u32 s14, s10, 0x1d800000
	v_bfe_u32 v5, v2, 4, 2
	v_and_b32_e32 v3, 15, v2
	s_addc_u32 s15, s11, 0
	s_lshl_b32 s18, s6, 6
	v_lshlrev_b32_e32 v2, 4, v5
	v_lshlrev_b32_e32 v4, 2, v3
	v_or_b32_e32 v204, s18, v3
	v_lshl_or_b32 v6, v3, 6, v2
	s_lshl_b32 s5, s6, 13
	v_and_b32_e32 v3, 32, v4
	v_bitop3_b32 v7, v6, s5, v3 bitop3:0xde
	s_lshl_b32 s5, s7, 5
	s_and_b32 s5, s5, 0x60
	s_lshl_b32 s6, s5, 7
	v_bitop3_b32 v6, v6, s6, v3 bitop3:0xde
	s_add_u32 s6, s34, 0x80
	s_waitcnt vmcnt(2)
	s_barrier
	s_addc_u32 s7, s35, 0
	s_add_i32 s52, s44, 0x18000
	s_mov_b32 m0, s52
	s_nop 0
	global_load_lds_dwordx4 v200, s[6:7]
	s_add_i32 s53, s44, 0x1a000
	s_mov_b32 m0, s53
	s_nop 0
	global_load_lds_dwordx4 v203, s[6:7]
	s_add_u32 s6, s36, 0x80
	s_addc_u32 s7, s37, 0
	s_add_i32 s54, s44, 0x8000
	s_mov_b32 m0, s54
	s_nop 0
	global_load_lds_dwordx4 v179, s[6:7]
	s_add_i32 s55, s44, 0xa000
	s_mov_b32 m0, s55
	s_nop 0
	global_load_lds_dwordx4 v201, s[6:7]
	s_add_u32 s6, s16, 0x80
	s_addc_u32 s7, s17, 0
	s_add_i32 s56, s44, 0x1c000
	s_add_i32 s57, s44, 0x1e000
	s_add_i32 s58, s44, 0xc000
	s_cmpk_lt_u32 s3, 0x100
	s_mov_b32 m0, s56
	s_nop 0
	global_load_lds_dwordx4 v200, s[6:7]
	s_cselect_b64 s[16:17], -1, 0
	s_lshl_b32 s3, s5, 1
	s_mov_b32 m0, s57
	s_nop 0
	global_load_lds_dwordx4 v203, s[6:7]
	s_add_u32 s6, s14, s3
	s_addc_u32 s7, s15, 0
	v_mov_b32_e32 v3, 0
	s_ashr_i32 s19, s18, 31
	v_lshl_add_u64 v[180:181], s[6:7], 0, v[2:3]
	s_add_i32 s59, s44, 0xe000
	s_lshl_b64 s[6:7], s[18:19], 2
	s_add_u32 s6, s12, s6
	v_lshl_or_b32 v205, v5, 3, s5
	v_cmp_eq_u32_e64 s[10:11], 0, v5
	s_addc_u32 s7, s13, s7
	v_mov_b32_e32 v5, v3
	s_waitcnt vmcnt(6)
	v_lshl_add_u64 v[2:3], s[6:7], 0, v[4:5]
	s_mov_b64 s[6:7], 0x18400
	v_lshl_add_u64 v[182:183], v[2:3], 0, s[6:7]
	v_add_u32_e32 v2, 0, v6
	v_mov_b64_e32 v[184:185], 0x100
	v_mov_b64_e32 v[186:187], 0xff
	v_add_u32_e32 v206, 0x10000, v2
	v_add_u32_e32 v207, 0x14000, v2
	v_add_u32_e32 v208, 0, v7
	v_add_u32_e32 v209, 0x18000, v2
	v_add_u32_e32 v210, 0x1c000, v2
	s_barrier
	s_branch .LBB0_1130

; #define PG8_STAGE(bufoff, gbase, voff) do { _Pragma("unroll") for (int _i = 0; _i < 2; ++_i) { unsigned keep_; \
;         asm volatile("s_mov_b32 %0, m0\n\ts_mov_b32 m0, %3\n\ts_nop 0\n\tglobal_load_lds_dwordx4 %1, %2\n\ts_mov_b32 m0, %0" \
;             : "=&s"(keep_) : "v"((voff)[_i]), "s"((const void*)(gbase)), "s"(ldsb0 + (unsigned)(bufoff) + (unsigned)(_i * 8192)) : "memory"); } } while (0)
; #define PG8_LDA(dst, b, h) do { _Pragma("unroll") for (int m = 0; m < 4; ++m) _Pragma("unroll") for (int k = 0; k < 2; ++k) dst[m][k] = *(const LAS bf16x8*)(lds + PG8_SA(b, h) + aoff + m * 2048 + k * 1024); } while (0)
; #define PG8_LDB(dst, b, h) do { _Pragma("unroll") for (int n = 0; n < 2; ++n) _Pragma("unroll") for (int k = 0; k < 2; ++k) dst[n][k] = *(const LAS bf16x8*)(lds + PG8_SB(b, h) + boff + n * 2048 + k * 1024); } while (0)
; #define PG8_MMA(ai, bj, At, Bt) do { __builtin_amdgcn_s_setprio(1); _Pragma("unroll") for (int m = 0; m < 4; ++m) _Pragma("unroll") for (int n = 0; n < 2; ++n) _Pragma("unroll") for (int k = 0; k < 2; ++k) \
;         acc[ai][bj][m][n] = __builtin_amdgcn_mfma_f32_16x16x32_bf16(Bt[n][k], At[m][k], acc[ai][bj][m][n], 0, 0, 0); __builtin_amdgcn_s_setprio(0); } while (0)
; #define PG8_WAIT_V(n) asm volatile("s_waitcnt vmcnt(" #n ")" ::: "memory")
; #define PG8_BAR __builtin_amdgcn_s_barrier()
; template <class Epi, class Sched, bool ALIGN_EPI>
; __device__ __forceinline__ void gemm_phase(LAS unsigned char* lds, const Gemm g, const Sched& S, const Epi& E) {
;     ...
;         for (int t = 0; t < nt; t += 2) {
;             const bool last = (t == nt - 2);
;             const char* a1 = cA + (size_t)(t + 1) * kstep;
;             const char* a2 = last ? nA : cA + (size_t)(t + 2) * kstep; const char* b2 = last ? nB : cB + (size_t)(t + 2) * kstep;
;             const char* a3 = a2 + kstep; const char* b3 = b2 + kstep;
;             PG8_LDB(B0, 0, 0); PG8_LDB(B1, 0, 1); PG8_SCHED; PG8_LDA(At, 0, 0); PG8_STAGE(PG8_SA(1, 1), a1 + hstepA, voffA);
;             PG8_WAIT_V(8); PG8_WAIT_L(0); PG8_BAR; PG8_MMA(0, 0, At, B0); PG8_MMA(0, 1, At, B1); PG8_BAR; PG8_SCHED;
;             PG8_LDA(At, 0, 1); PG8_STAGE(PG8_SB(0, 0), b2, voffB); PG8_STAGE(PG8_SB(0, 1), b2 + hstepB, voffB); PG8_STAGE(PG8_SA(0, 0), a2, voffA);
;             PG8_WAIT_V(8); PG8_WAIT_L(0); PG8_BAR; PG8_MMA(1, 0, At, B0); PG8_MMA(1, 1, At, B1); PG8_BAR; PG8_SCHED;
.LBB0_1137:
	ds_read_b128 v[110:113], v206
	ds_read_b128 v[126:129], v206 offset:1024
	ds_read_b128 v[130:133], v206 offset:2048
	ds_read_b128 v[142:145], v206 offset:3072
	ds_read_b128 v[146:149], v207
	ds_read_b128 v[150:153], v207 offset:1024
	ds_read_b128 v[154:157], v207 offset:2048
	ds_read_b128 v[158:161], v207 offset:3072
	s_cmp_eq_u32 s63, 28
	s_cselect_b32 s40, s5, s19
	s_cselect_b32 s41, s3, s27
	s_cselect_b32 s38, s7, s61
	s_cselect_b32 s39, s6, s62
	s_add_u32 s36, s40, 0x80
	s_addc_u32 s37, s41, 0
	ds_read_b128 v[162:165], v208
	ds_read_b128 v[166:169], v208 offset:1024
	ds_read_b128 v[170:173], v208 offset:2048
	ds_read_b128 v[174:177], v208 offset:3072
	ds_read_b128 v[188:191], v208 offset:4096
	ds_read_b128 v[192:195], v208 offset:5120
	ds_read_b128 v[196:199], v208 offset:6144
	ds_read_b128 v[212:215], v208 offset:7168
	s_mov_b32 m0, s58
	s_nop 0
	global_load_lds_dwordx4 v179, s[34:35]
	s_nop 0
	s_mov_b32 m0, s59
	s_nop 0
	global_load_lds_dwordx4 v201, s[34:35]
	s_waitcnt vmcnt(8)
	s_waitcnt lgkmcnt(0)
	s_barrier
	s_setprio 1
	v_mfma_f32_16x16x32_bf16 v[138:141], v[110:113], v[162:165], v[138:141]
	v_mfma_f32_16x16x32_bf16 v[134:137], v[130:133], v[162:165], v[134:137]
	v_mfma_f32_16x16x32_bf16 v[114:117], v[110:113], v[170:173], v[114:117]
	v_mfma_f32_16x16x32_bf16 v[106:109], v[130:133], v[170:173], v[106:109]
	v_mfma_f32_16x16x32_bf16 v[94:97], v[110:113], v[188:191], v[94:97]
	v_mfma_f32_16x16x32_bf16 v[90:93], v[130:133], v[188:191], v[90:93]
	v_mfma_f32_16x16x32_bf16 v[78:81], v[110:113], v[196:199], v[78:81]
	v_mfma_f32_16x16x32_bf16 v[74:77], v[130:133], v[196:199], v[74:77]
	v_mfma_f32_16x16x32_bf16 v[138:141], v[126:129], v[166:169], v[138:141]
	v_mfma_f32_16x16x32_bf16 v[134:137], v[142:145], v[166:169], v[134:137]
	v_mfma_f32_16x16x32_bf16 v[114:117], v[126:129], v[174:177], v[114:117]
	v_mfma_f32_16x16x32_bf16 v[106:109], v[142:145], v[174:177], v[106:109]
	v_mfma_f32_16x16x32_bf16 v[94:97], v[126:129], v[192:195], v[94:97]
	v_mfma_f32_16x16x32_bf16 v[90:93], v[142:145], v[192:195], v[90:93]
	v_mfma_f32_16x16x32_bf16 v[78:81], v[126:129], v[212:215], v[78:81]
	v_mfma_f32_16x16x32_bf16 v[74:77], v[142:145], v[212:215], v[74:77]
	v_mfma_f32_16x16x32_bf16 v[122:125], v[146:149], v[162:165], v[122:125]
	v_mfma_f32_16x16x32_bf16 v[118:121], v[154:157], v[162:165], v[118:121]
	v_mfma_f32_16x16x32_bf16 v[102:105], v[146:149], v[170:173], v[102:105]
	v_mfma_f32_16x16x32_bf16 v[98:101], v[154:157], v[170:173], v[98:101]
	v_mfma_f32_16x16x32_bf16 v[86:89], v[146:149], v[188:191], v[86:89]
	v_mfma_f32_16x16x32_bf16 v[82:85], v[154:157], v[188:191], v[82:85]
	v_mfma_f32_16x16x32_bf16 v[70:73], v[146:149], v[196:199], v[70:73]
	v_mfma_f32_16x16x32_bf16 v[66:69], v[154:157], v[196:199], v[66:69]
	v_mfma_f32_16x16x32_bf16 v[122:125], v[150:153], v[166:169], v[122:125]
	v_mfma_f32_16x16x32_bf16 v[118:121], v[158:161], v[166:169], v[118:121]
	v_mfma_f32_16x16x32_bf16 v[102:105], v[150:153], v[174:177], v[102:105]
	v_mfma_f32_16x16x32_bf16 v[98:101], v[158:161], v[174:177], v[98:101]
	v_mfma_f32_16x16x32_bf16 v[86:89], v[150:153], v[192:195], v[86:89]
	v_mfma_f32_16x16x32_bf16 v[82:85], v[158:161], v[192:195], v[82:85]
	v_mfma_f32_16x16x32_bf16 v[70:73], v[150:153], v[212:215], v[70:73]
	v_mfma_f32_16x16x32_bf16 v[66:69], v[158:161], v[212:215], v[66:69]
	s_setprio 0
	s_barrier
	ds_read_b128 v[162:165], v208 offset:16384
	ds_read_b128 v[166:169], v208 offset:17408
	ds_read_b128 v[170:173], v208 offset:18432
	ds_read_b128 v[174:177], v208 offset:19456
	ds_read_b128 v[188:191], v208 offset:20480
	ds_read_b128 v[192:195], v208 offset:21504
	ds_read_b128 v[196:199], v208 offset:22528
	ds_read_b128 v[212:215], v208 offset:23552
	s_mov_b32 m0, s45
	s_nop 0
	global_load_lds_dwordx4 v200, s[38:39]
	s_nop 0
	s_mov_b32 m0, s46
	s_nop 0
	global_load_lds_dwordx4 v203, s[38:39]
	s_add_u32 s64, s38, 0x80000
	s_addc_u32 s65, s39, 0
	s_mov_b32 m0, s47
	s_nop 0
	global_load_lds_dwordx4 v200, s[64:65]
	s_nop 0
	s_mov_b32 m0, s48
	s_nop 0
	global_load_lds_dwordx4 v203, s[64:65]
	s_mov_b32 m0, s44
	s_nop 0
	global_load_lds_dwordx4 v179, s[40:41]
	s_nop 0
	s_mov_b32 m0, s49
	s_nop 0
	global_load_lds_dwordx4 v201, s[40:41]
	s_waitcnt vmcnt(8)
	s_waitcnt lgkmcnt(0)
	s_barrier
	s_setprio 1
	v_mfma_f32_16x16x32_bf16 v[62:65], v[110:113], v[162:165], v[62:65]
	v_mfma_f32_16x16x32_bf16 v[58:61], v[130:133], v[162:165], v[58:61]
	v_mfma_f32_16x16x32_bf16 v[46:49], v[110:113], v[170:173], v[46:49]
	v_mfma_f32_16x16x32_bf16 v[42:45], v[130:133], v[170:173], v[42:45]
	v_mfma_f32_16x16x32_bf16 v[30:33], v[110:113], v[188:191], v[30:33]
	v_mfma_f32_16x16x32_bf16 v[26:29], v[130:133], v[188:191], v[26:29]
	v_mfma_f32_16x16x32_bf16 v[14:17], v[110:113], v[196:199], v[14:17]
	v_mfma_f32_16x16x32_bf16 v[10:13], v[130:133], v[196:199], v[10:13]
	v_mfma_f32_16x16x32_bf16 v[62:65], v[126:129], v[166:169], v[62:65]
	v_mfma_f32_16x16x32_bf16 v[58:61], v[142:145], v[166:169], v[58:61]
	v_mfma_f32_16x16x32_bf16 v[46:49], v[126:129], v[174:177], v[46:49]
	v_mfma_f32_16x16x32_bf16 v[42:45], v[142:145], v[174:177], v[42:45]
	v_mfma_f32_16x16x32_bf16 v[30:33], v[126:129], v[192:195], v[30:33]
	v_mfma_f32_16x16x32_bf16 v[26:29], v[142:145], v[192:195], v[26:29]
	v_mfma_f32_16x16x32_bf16 v[14:17], v[126:129], v[212:215], v[14:17]
	v_mfma_f32_16x16x32_bf16 v[10:13], v[142:145], v[212:215], v[10:13]
	v_mfma_f32_16x16x32_bf16 v[54:57], v[146:149], v[162:165], v[54:57]
	v_mfma_f32_16x16x32_bf16 v[50:53], v[154:157], v[162:165], v[50:53]
	v_mfma_f32_16x16x32_bf16 v[38:41], v[146:149], v[170:173], v[38:41]
	v_mfma_f32_16x16x32_bf16 v[34:37], v[154:157], v[170:173], v[34:37]
	v_mfma_f32_16x16x32_bf16 v[22:25], v[146:149], v[188:191], v[22:25]
	v_mfma_f32_16x16x32_bf16 v[18:21], v[154:157], v[188:191], v[18:21]
	v_mfma_f32_16x16x32_bf16 v[6:9], v[146:149], v[196:199], v[6:9]
	v_mfma_f32_16x16x32_bf16 v[2:5], v[154:157], v[196:199], v[2:5]
	v_mfma_f32_16x16x32_bf16 v[54:57], v[150:153], v[166:169], v[54:57]
	v_mfma_f32_16x16x32_bf16 v[50:53], v[158:161], v[166:169], v[50:53]
	v_mfma_f32_16x16x32_bf16 v[38:41], v[150:153], v[174:177], v[38:41]
	v_mfma_f32_16x16x32_bf16 v[34:37], v[158:161], v[174:177], v[34:37]
	v_mfma_f32_16x16x32_bf16 v[22:25], v[150:153], v[192:195], v[22:25]
	v_mfma_f32_16x16x32_bf16 v[18:21], v[158:161], v[192:195], v[18:21]
	v_mfma_f32_16x16x32_bf16 v[6:9], v[150:153], v[212:215], v[6:9]
	v_mfma_f32_16x16x32_bf16 v[2:5], v[158:161], v[212:215], v[2:5]
	s_setprio 0
	s_barrier
; #define PG8_STAGE(bufoff, gbase, voff) do { _Pragma("unroll") for (int _i = 0; _i < 2; ++_i) { unsigned keep_; \
;         asm volatile("s_mov_b32 %0, m0\n\ts_mov_b32 m0, %3\n\ts_nop 0\n\tglobal_load_lds_dwordx4 %1, %2\n\ts_mov_b32 m0, %0" \
;             : "=&s"(keep_) : "v"((voff)[_i]), "s"((const void*)(gbase)), "s"(ldsb0 + (unsigned)(bufoff) + (unsigned)(_i * 8192)) : "memory"); } } while (0)
; #define PG8_LDA(dst, b, h) do { _Pragma("unroll") for (int m = 0; m < 4; ++m) _Pragma("unroll") for (int k = 0; k < 2; ++k) dst[m][k] = *(const LAS bf16x8*)(lds + PG8_SA(b, h) + aoff + m * 2048 + k * 1024); } while (0)
; #define PG8_LDB(dst, b, h) do { _Pragma("unroll") for (int n = 0; n < 2; ++n) _Pragma("unroll") for (int k = 0; k < 2; ++k) dst[n][k] = *(const LAS bf16x8*)(lds + PG8_SB(b, h) + boff + n * 2048 + k * 1024); } while (0)
; #define PG8_MMA(ai, bj, At, Bt) do { __builtin_amdgcn_s_setprio(1); _Pragma("unroll") for (int m = 0; m < 4; ++m) _Pragma("unroll") for (int n = 0; n < 2; ++n) _Pragma("unroll") for (int k = 0; k < 2; ++k) \
;         acc[ai][bj][m][n] = __builtin_amdgcn_mfma_f32_16x16x32_bf16(Bt[n][k], At[m][k], acc[ai][bj][m][n], 0, 0, 0); __builtin_amdgcn_s_setprio(0); } while (0)
; #define PG8_WAIT_V(n) asm volatile("s_waitcnt vmcnt(" #n ")" ::: "memory")
; #define PG8_WAIT_L(n) asm volatile("s_waitcnt lgkmcnt(" #n ")" ::: "memory")
; #define PG8_BAR __builtin_amdgcn_s_barrier()
; #define PG8_SCHED __builtin_amdgcn_sched_barrier(0)
; template <class Epi, class Sched, bool ALIGN_EPI>
; __device__ __forceinline__ void gemm_phase(LAS unsigned char* lds, const Gemm g, const Sched& S, const Epi& E) {
;     ...
;             PG8_LDB(B0, 1, 0); PG8_LDB(B1, 1, 1); PG8_SCHED; PG8_LDA(At, 1, 0); PG8_STAGE(PG8_SA(0, 1), a2 + hstepA, voffA);
;             PG8_WAIT_V(8); PG8_WAIT_L(0); PG8_BAR; PG8_MMA(0, 0, At, B0); PG8_MMA(0, 1, At, B1); PG8_BAR; PG8_SCHED;
;             PG8_LDA(At, 1, 1); PG8_STAGE(PG8_SB(1, 0), b3, voffB); PG8_STAGE(PG8_SB(1, 1), b3 + hstepB, voffB); PG8_STAGE(PG8_SA(1, 0), a3, voffA);
;             PG8_WAIT_V(8); PG8_WAIT_L(0); PG8_BAR; PG8_MMA(1, 0, At, B0); PG8_MMA(1, 1, At, B1); PG8_BAR; PG8_SCHED;
;         }
	ds_read_b128 v[110:113], v209
	ds_read_b128 v[126:129], v209 offset:1024
	ds_read_b128 v[130:133], v209 offset:2048
	ds_read_b128 v[142:145], v209 offset:3072
	ds_read_b128 v[146:149], v210
	ds_read_b128 v[150:153], v210 offset:1024
	ds_read_b128 v[154:157], v210 offset:2048
	ds_read_b128 v[158:161], v210 offset:3072
	ds_read_b128 v[162:165], v208 offset:32768
	ds_read_b128 v[166:169], v208 offset:33792
	ds_read_b128 v[170:173], v208 offset:34816
	ds_read_b128 v[174:177], v208 offset:35840
	ds_read_b128 v[188:191], v208 offset:36864
	ds_read_b128 v[192:195], v208 offset:37888
	ds_read_b128 v[196:199], v208 offset:38912
	ds_read_b128 v[212:215], v208 offset:39936
	s_add_u32 s40, s40, 0x80000
	s_addc_u32 s41, s41, 0
	s_mov_b32 m0, s50
	s_nop 0
	global_load_lds_dwordx4 v179, s[40:41]
	s_nop 0
	s_mov_b32 m0, s51
	s_nop 0
	global_load_lds_dwordx4 v201, s[40:41]
	s_waitcnt vmcnt(8)
	s_waitcnt lgkmcnt(0)
	s_barrier
	s_setprio 1
	v_mfma_f32_16x16x32_bf16 v[138:141], v[110:113], v[162:165], v[138:141]
	v_mfma_f32_16x16x32_bf16 v[134:137], v[130:133], v[162:165], v[134:137]
	v_mfma_f32_16x16x32_bf16 v[114:117], v[110:113], v[170:173], v[114:117]
	v_mfma_f32_16x16x32_bf16 v[106:109], v[130:133], v[170:173], v[106:109]
	v_mfma_f32_16x16x32_bf16 v[94:97], v[110:113], v[188:191], v[94:97]
	v_mfma_f32_16x16x32_bf16 v[90:93], v[130:133], v[188:191], v[90:93]
	v_mfma_f32_16x16x32_bf16 v[78:81], v[110:113], v[196:199], v[78:81]
	v_mfma_f32_16x16x32_bf16 v[74:77], v[130:133], v[196:199], v[74:77]
	v_mfma_f32_16x16x32_bf16 v[138:141], v[126:129], v[166:169], v[138:141]
	v_mfma_f32_16x16x32_bf16 v[134:137], v[142:145], v[166:169], v[134:137]
	v_mfma_f32_16x16x32_bf16 v[114:117], v[126:129], v[174:177], v[114:117]
	v_mfma_f32_16x16x32_bf16 v[106:109], v[142:145], v[174:177], v[106:109]
	v_mfma_f32_16x16x32_bf16 v[94:97], v[126:129], v[192:195], v[94:97]
	v_mfma_f32_16x16x32_bf16 v[90:93], v[142:145], v[192:195], v[90:93]
	v_mfma_f32_16x16x32_bf16 v[78:81], v[126:129], v[212:215], v[78:81]
	v_mfma_f32_16x16x32_bf16 v[74:77], v[142:145], v[212:215], v[74:77]
	v_mfma_f32_16x16x32_bf16 v[122:125], v[146:149], v[162:165], v[122:125]
	v_mfma_f32_16x16x32_bf16 v[118:121], v[154:157], v[162:165], v[118:121]
	v_mfma_f32_16x16x32_bf16 v[102:105], v[146:149], v[170:173], v[102:105]
	v_mfma_f32_16x16x32_bf16 v[98:101], v[154:157], v[170:173], v[98:101]
	v_mfma_f32_16x16x32_bf16 v[86:89], v[146:149], v[188:191], v[86:89]
	v_mfma_f32_16x16x32_bf16 v[82:85], v[154:157], v[188:191], v[82:85]
	v_mfma_f32_16x16x32_bf16 v[70:73], v[146:149], v[196:199], v[70:73]
	v_mfma_f32_16x16x32_bf16 v[66:69], v[154:157], v[196:199], v[66:69]
	v_mfma_f32_16x16x32_bf16 v[122:125], v[150:153], v[166:169], v[122:125]
	v_mfma_f32_16x16x32_bf16 v[118:121], v[158:161], v[166:169], v[118:121]
	v_mfma_f32_16x16x32_bf16 v[102:105], v[150:153], v[174:177], v[102:105]
	v_mfma_f32_16x16x32_bf16 v[98:101], v[158:161], v[174:177], v[98:101]
	v_mfma_f32_16x16x32_bf16 v[86:89], v[150:153], v[192:195], v[86:89]
	v_mfma_f32_16x16x32_bf16 v[82:85], v[158:161], v[192:195], v[82:85]
	v_mfma_f32_16x16x32_bf16 v[70:73], v[150:153], v[212:215], v[70:73]
	v_mfma_f32_16x16x32_bf16 v[66:69], v[158:161], v[212:215], v[66:69]
	s_setprio 0
	s_barrier
	ds_read_b128 v[162:165], v208 offset:49152
	ds_read_b128 v[166:169], v208 offset:50176
	ds_read_b128 v[170:173], v208 offset:51200
	ds_read_b128 v[174:177], v208 offset:52224
	ds_read_b128 v[188:191], v208 offset:53248
	ds_read_b128 v[192:195], v208 offset:54272
	ds_read_b128 v[196:199], v208 offset:55296
	ds_read_b128 v[212:215], v208 offset:56320
	s_add_u32 s40, s38, 0x80
	s_addc_u32 s41, s39, 0
	s_mov_b32 m0, s52
	s_nop 0
	global_load_lds_dwordx4 v200, s[40:41]
	s_add_u32 s38, s38, 0x80080
	s_mov_b32 m0, s53
	s_nop 0
	global_load_lds_dwordx4 v203, s[40:41]
	s_addc_u32 s39, s39, 0
	s_mov_b32 m0, s56
	s_nop 0
	global_load_lds_dwordx4 v200, s[38:39]
	s_nop 0
	s_mov_b32 m0, s57
	s_nop 0
	global_load_lds_dwordx4 v203, s[38:39]
	s_mov_b32 m0, s54
	s_nop 0
	global_load_lds_dwordx4 v179, s[36:37]
	s_nop 0
	s_mov_b32 m0, s55
	s_nop 0
	global_load_lds_dwordx4 v201, s[36:37]
	s_waitcnt vmcnt(8)
	s_waitcnt lgkmcnt(0)
	s_barrier
	s_setprio 1
	v_mfma_f32_16x16x32_bf16 v[62:65], v[110:113], v[162:165], v[62:65]
	v_mfma_f32_16x16x32_bf16 v[58:61], v[130:133], v[162:165], v[58:61]
	v_mfma_f32_16x16x32_bf16 v[46:49], v[110:113], v[170:173], v[46:49]
	v_mfma_f32_16x16x32_bf16 v[42:45], v[130:133], v[170:173], v[42:45]
	v_mfma_f32_16x16x32_bf16 v[30:33], v[110:113], v[188:191], v[30:33]
	v_mfma_f32_16x16x32_bf16 v[26:29], v[130:133], v[188:191], v[26:29]
	v_mfma_f32_16x16x32_bf16 v[14:17], v[110:113], v[196:199], v[14:17]
	v_mfma_f32_16x16x32_bf16 v[10:13], v[130:133], v[196:199], v[10:13]
	v_mfma_f32_16x16x32_bf16 v[62:65], v[126:129], v[166:169], v[62:65]
	v_mfma_f32_16x16x32_bf16 v[58:61], v[142:145], v[166:169], v[58:61]
	v_mfma_f32_16x16x32_bf16 v[46:49], v[126:129], v[174:177], v[46:49]
	v_mfma_f32_16x16x32_bf16 v[42:45], v[142:145], v[174:177], v[42:45]
	v_mfma_f32_16x16x32_bf16 v[30:33], v[126:129], v[192:195], v[30:33]
	v_mfma_f32_16x16x32_bf16 v[26:29], v[142:145], v[192:195], v[26:29]
	v_mfma_f32_16x16x32_bf16 v[14:17], v[126:129], v[212:215], v[14:17]
	v_mfma_f32_16x16x32_bf16 v[10:13], v[142:145], v[212:215], v[10:13]
	v_mfma_f32_16x16x32_bf16 v[54:57], v[146:149], v[162:165], v[54:57]
	v_mfma_f32_16x16x32_bf16 v[50:53], v[154:157], v[162:165], v[50:53]
	v_mfma_f32_16x16x32_bf16 v[38:41], v[146:149], v[170:173], v[38:41]
	v_mfma_f32_16x16x32_bf16 v[34:37], v[154:157], v[170:173], v[34:37]
	v_mfma_f32_16x16x32_bf16 v[22:25], v[146:149], v[188:191], v[22:25]
	v_mfma_f32_16x16x32_bf16 v[18:21], v[154:157], v[188:191], v[18:21]
	v_mfma_f32_16x16x32_bf16 v[6:9], v[146:149], v[196:199], v[6:9]
	v_mfma_f32_16x16x32_bf16 v[2:5], v[154:157], v[196:199], v[2:5]
	v_mfma_f32_16x16x32_bf16 v[54:57], v[150:153], v[166:169], v[54:57]
	v_mfma_f32_16x16x32_bf16 v[50:53], v[158:161], v[166:169], v[50:53]
	v_mfma_f32_16x16x32_bf16 v[38:41], v[150:153], v[174:177], v[38:41]
	v_mfma_f32_16x16x32_bf16 v[34:37], v[158:161], v[174:177], v[34:37]
	v_mfma_f32_16x16x32_bf16 v[22:25], v[150:153], v[192:195], v[22:25]
	v_mfma_f32_16x16x32_bf16 v[18:21], v[158:161], v[192:195], v[18:21]
	v_mfma_f32_16x16x32_bf16 v[6:9], v[150:153], v[212:215], v[6:9]
	v_mfma_f32_16x16x32_bf16 v[2:5], v[158:161], v[212:215], v[2:5]
	s_setprio 0
	s_barrier
	s_add_i32 s63, s63, 2
	s_add_u32 s19, s19, 0x100
	s_addc_u32 s27, s27, 0
	s_add_u32 s61, s61, 0x100
	s_addc_u32 s62, s62, 0
	s_add_u32 s34, s34, 0x100
	s_addc_u32 s35, s35, 0
	s_cmp_gt_u32 s63, 29
	s_cbranch_scc0 .LBB0_1137
	s_and_b64 vcc, exec, s[16:17]
	s_cbranch_vccz .LBB0_1140
	s_barrier

;     __device__ bool next(int i, Unit& u) const {
;         const long L = (long)i * G + c; if (L >= nwg) return false;
;         int wgid = (int)L; { const int q = nwg / NXCD, r = nwg % NXCD, xcd = wgid % NXCD, off = wgid / NXCD; wgid = (xcd < r ? xcd * (q + 1) : r * (q + 1) + (xcd - r) * q) + off; }
;         const int nig = WGM * nN, gid = wgid / nig, fm = gid * WGM, gsz = (nM - fm) < WGM ? (nM - fm) : WGM;
;         u.pm = fm + ((wgid % nig) % gsz); u.pn = (wgid % nig) / gsz; return true;
; template <class Epi, class Sched, bool ALIGN_EPI>
; __device__ __forceinline__ void gemm_phase(LAS unsigned char* lds, const Gemm g, const Sched& S, const Epi& E) {
;     const int tid = otid(), wid = __builtin_amdgcn_readfirstlane(tid >> 6), lane = tid & 63, wr = wid >> 2, wc = wid & 3, fr = lane & 15, fq = lane >> 4;
;     const int K = g.K, nt = K / BK;
;     unsigned voffA[2], voffB[2];
; #pragma unroll
;     for (int i = 0; i < 2; ++i) { int R, C; stage_rc(tid * 16 + i * 8192, R, C); const int Rb = (R & ~31) + perm32(R & 31);
;         voffA[i] = (unsigned)(R * g.lda + C) * 2u; voffB[i] = (unsigned)(Rb * g.ldb + C) * 2u; }
;     const size_t kstep = (size_t)(BK * 2);
;     const size_t hstepA = (size_t)HALF * g.lda * 2, hstepB = (size_t)HALF * g.ldb * 2;
;     const size_t tstepA = 2 * hstepA, tstepB = 2 * hstepB;
;     const unsigned ldsw = (unsigned)wid * 1024u;
;     const int aoff = lds_byte(wr * 64 + fr, fq * 8), boff = lds_byte(wc * 32 + fr, fq * 8);
;     ...
;     const unsigned ldsb0 = (unsigned)(uintptr_t)lds + ldsw;
;     ...
;     Unit cur, nxt; int ui = 0;
;     if (!S.next(0, cur)) return;
;     f32x4 acc[2][2][4][2];
; #pragma unroll
;     for (int a = 0; a < 2; ++a)
; #pragma unroll
;         for (int b = 0; b < 2; ++b)
; #pragma unroll
;             for (int m = 0; m < 4; ++m)
; #pragma unroll
;                 for (int n = 0; n < 2; ++n) acc[a][b][m][n] = (f32x4){0.f, 0.f, 0.f, 0.f};
;     bf16x8 At[4][2], B0[2][2], B1[2][2];
;     float pre[Epi::NPRE > 0 ? Epi::NPRE : 1];
;     if constexpr (Epi::NPRE > 0) E.preload(cur, wr, fr, pre);
;     const char* cA = (const char*)g.A + (size_t)cur.pm * tstepA + (size_t)cur.pn * g.a_koff * 2; const char* cB = (const char*)g.Bt + (size_t)cur.pn * tstepB;
;     PG8_STAGE(PG8_SB(0, 0), cB, voffB); PG8_STAGE(PG8_SB(0, 1), cB + hstepB, voffB); PG8_STAGE(PG8_SA(0, 0), cA, voffA); PG8_STAGE(PG8_SA(0, 1), cA + hstepA, voffA);
.LBB0_1205:
	s_or_b64 exec, exec, s[4:5]
	s_cmpk_lt_i32 s94, 0x5ac
	s_cselect_b64 s[6:7], -1, 0
	s_mov_b64 s[4:5], s[0:1]
	s_mov_b64 s[8:9], s[0:1]
	s_mov_b64 s[12:13], s[0:1]
	s_mov_b64 s[14:15], s[0:1]
	s_waitcnt lgkmcnt(0)
	v_mov_b32_e32 v2, v0
	s_barrier
	v_writelane_b32 v242, s6, 20
	v_readfirstlane_b32 s3, v2
	s_and_b64 vcc, exec, s[6:7]
	v_writelane_b32 v242, s7, 21
	s_cbranch_vccz .LBB0_1225
	s_load_dwordx2 s[6:7], s[4:5], 0xb0
	s_load_dwordx2 s[16:17], s[8:9], 0xb0
	s_load_dwordx2 s[18:19], s[12:13], 0xb0
	s_load_dwordx2 s[10:11], s[14:15], 0xb0
	v_bfe_i32 v4, v2, 27, 1
	s_waitcnt lgkmcnt(0)
	s_add_u32 s23, s6, 0x1d800000
	s_addc_u32 s24, s7, 0
	s_add_u32 s25, s16, 0x1b00000
	s_addc_u32 s44, s17, 0
	s_add_u32 s8, s18, 0x18400
	s_addc_u32 s9, s19, 0
	s_ashr_i32 s7, s3, 6
	s_lshl_b32 s2, s7, 10
	s_add_i32 s45, s2, 0
	s_lshr_b32 s2, s95, 29
	s_add_i32 s2, s94, s2
	s_and_b32 s4, s2, -8
	s_sub_i32 s4, s94, s4
	s_ashr_i32 s6, s3, 8
	s_mul_i32 s12, s4, 0xb5
	v_lshlrev_b32_e32 v8, 4, v2
	v_lshrrev_b32_e32 v4, 22, v4
	s_lshl_b32 s16, s6, 6
	s_add_i32 s12, s12, 4
	s_ashr_i32 s2, s2, 3
	v_add_u32_e32 v4, v8, v4
	s_mul_i32 s5, s4, 0xb6
	s_cmp_lt_i32 s4, 4
	v_and_b32_e32 v4, 0xfffffc00, v4
	s_cselect_b32 s4, s5, s12
	v_sub_u32_e32 v4, v8, v4
	s_add_i32 s4, s4, s2
	v_ashrrev_i32_e32 v3, 31, v2
	v_lshrrev_b32_e32 v5, 4, v4
	s_mul_hi_i32 s2, s4, 0x2e8ba2e9
	v_lshrrev_b32_e32 v3, 26, v3
	v_bitop3_b32 v5, v5, v4, 32 bitop3:0x6c
	v_ashrrev_i32_e32 v4, 31, v4
	s_lshr_b32 s5, s2, 31
	s_ashr_i32 s2, s2, 6
	v_add_u32_e32 v3, v2, v3
	v_lshrrev_b32_e32 v4, 26, v4
	s_add_i32 s2, s2, s5
	v_ashrrev_i32_e32 v3, 6, v3
	v_add_u32_e32 v4, v5, v4
	s_lshl_b32 s12, s2, 3
	v_lshlrev_b32_e32 v6, 3, v3
	v_ashrrev_i32_e32 v9, 6, v4
	v_lshlrev_b32_e32 v3, 5, v3
	s_sub_i32 s5, 33, s12
	s_mulk_i32 s2, 0x160
	v_and_b32_e32 v11, 32, v3
	v_mul_i32_i24_e32 v3, 64, v9
	s_min_u32 s13, s5, 8
	s_sub_i32 s2, s4, s2
	v_and_b32_e32 v6, -16, v6
	v_sub_u32_e32 v12, v5, v3
	s_sext_i32_i16 s4, s2
	v_cvt_f32_ubyte0_e32 v5, s13
	v_add_u32_e32 v10, v9, v6
	v_cvt_f32_i32_e32 v4, s4
	v_rcp_iflag_f32_e32 v6, v5
	s_ashr_i32 s4, s4, 30
	s_or_b32 s14, s4, 1
	v_and_b32_e32 v3, 15, v2
	v_mul_f32_e32 v6, v4, v6
	v_trunc_f32_e32 v6, v6
	v_fma_f32 v4, -v6, v5, v4
	v_cvt_i32_f32_e32 v6, v6
	v_cmp_ge_f32_e64 s[4:5], |v4|, v5
	s_and_b64 s[4:5], s[4:5], exec
	s_cselect_b32 s4, s14, 0
	v_readfirstlane_b32 s5, v6
	s_add_i32 s14, s5, s4
	s_mul_i32 s4, s14, s13
	s_sub_i32 s2, s2, s4
	s_sext_i32_i16 s2, s2
	s_add_i32 s4, s12, s2
	s_lshl_b32 s2, s4, 8
	s_add_i32 s2, s2, s16
	v_or_b32_e32 v4, s2, v3
	v_ashrrev_i32_e32 v5, 31, v4
	v_lshl_add_u64 v[6:7], v[4:5], 2, s[8:9]
	v_add_u32_e32 v4, 0x80, v4
	v_ashrrev_i32_e32 v5, 31, v4
	v_lshl_add_u64 v[4:5], v[4:5], 2, s[8:9]
	global_load_dword v153, v[6:7], off
	global_load_dword v152, v[6:7], off offset:64
	global_load_dword v151, v[6:7], off offset:128
	global_load_dword v150, v[6:7], off offset:192
	global_load_dword v149, v[4:5], off
	global_load_dword v148, v[4:5], off offset:64
	global_load_dword v147, v[4:5], off offset:128
	global_load_dword v139, v[4:5], off offset:192
	v_mov_b32_e32 v13, 1
	v_ashrrev_i16_sdwa v4, v13, sext(v12) dst_sel:DWORD dst_unused:UNUSED_PAD src0_sel:DWORD src1_sel:BYTE_0
	v_lshlrev_b32_e32 v5, 1, v10
	v_lshrrev_b32_e32 v6, 2, v10
	v_and_b32_e32 v7, 3, v9
	s_mov_b32 s2, 0xfffe0
	v_bfe_i32 v4, v4, 0, 16
	v_and_b32_e32 v5, 24, v5
	v_and_b32_e32 v6, 4, v6
	v_and_or_b32 v7, v10, s2, v7
	v_or3_b32 v5, v7, v6, v5
	v_add_lshl_u32 v4, v11, v4, 1
	s_waitcnt vmcnt(11)
	v_lshl_add_u32 v134, v10, 12, v4
	s_waitcnt vmcnt(8)
	v_lshl_add_u32 v135, v5, 12, v4
	v_add_u32_e32 v4, 0x2000, v8
	v_ashrrev_i32_e32 v5, 31, v4
	v_lshrrev_b32_e32 v5, 22, v5
	v_add_u32_e32 v5, v4, v5
	v_ashrrev_i32_e32 v5, 10, v5
	v_mul_i32_i24_e32 v6, 0x400, v5
	v_sub_u32_e32 v4, v4, v6
	v_lshrrev_b32_e32 v6, 4, v4
	v_bitop3_b32 v4, v6, v4, 32 bitop3:0x6c
	v_ashrrev_i32_e32 v7, 31, v4
	v_lshrrev_b32_e32 v7, 26, v7
	v_lshlrev_b32_e32 v6, 3, v5
	v_add_u32_e32 v7, v4, v7
	v_and_b32_e32 v6, -16, v6
	v_ashrrev_i32_e32 v8, 6, v7
	v_and_b32_e32 v7, 0xc0, v7
	v_add_u32_e32 v6, v8, v6
	v_sub_u32_e32 v4, v4, v7
	s_ashr_i32 s5, s4, 31
	s_bfe_i64 s[18:19], s[14:15], 0x100000
	v_lshlrev_b32_e32 v5, 5, v5
	v_ashrrev_i16_sdwa v4, v13, sext(v4) dst_sel:DWORD dst_unused:UNUSED_PAD src0_sel:DWORD src1_sel:BYTE_0
	v_lshlrev_b32_e32 v7, 1, v6
	v_lshrrev_b32_e32 v9, 2, v6
	v_and_b32_e32 v8, 3, v8
	s_lshl_b64 s[12:13], s[4:5], 20
	s_lshl_b64 s[18:19], s[18:19], 20
	v_and_b32_e32 v5, 32, v5
	v_bfe_i32 v4, v4, 0, 16
	v_and_b32_e32 v7, 24, v7
	v_and_b32_e32 v9, 4, v9
	v_and_or_b32 v8, v6, s2, v8
	s_add_u32 s36, s25, s18
	v_or3_b32 v7, v8, v9, v7
	v_add_lshl_u32 v4, v5, v4, 1
	s_addc_u32 s37, s44, s19
	s_add_i32 s47, s45, 0x10000
	s_mov_b32 m0, s47
	s_nop 0
	global_load_lds_dwordx4 v135, s[36:37]
	s_add_i32 s48, s45, 0x12000
	v_lshl_add_u32 v137, v7, 12, v4
	s_mov_b32 m0, s48
	s_nop 0
	global_load_lds_dwordx4 v137, s[36:37]
	s_add_u32 s18, s36, 0x80000
	s_addc_u32 s19, s37, 0
	s_add_i32 s49, s45, 0x14000
	s_mov_b32 m0, s49
	s_nop 0
	global_load_lds_dwordx4 v135, s[18:19]
	s_add_i32 s50, s45, 0x16000
	s_mov_b32 m0, s50
	s_nop 0
	global_load_lds_dwordx4 v137, s[18:19]
	s_add_u32 s34, s23, s12
	s_addc_u32 s35, s24, s13
	s_mov_b32 m0, s45
	s_nop 0
	global_load_lds_dwordx4 v134, s[34:35]
	s_add_i32 s51, s45, 0x2000
	v_lshl_add_u32 v136, v6, 12, v4
	s_mov_b32 m0, s51
	s_nop 0
	global_load_lds_dwordx4 v136, s[34:35]
	s_add_u32 s18, s34, 0x80000
	s_addc_u32 s19, s35, 0
	s_add_i32 s52, s45, 0x4000
	s_mov_b32 m0, s52
	s_nop 0
	global_load_lds_dwordx4 v134, s[18:19]
	s_add_i32 s53, s45, 0x6000
	s_mov_b32 m0, s53
	s_nop 0
	global_load_lds_dwordx4 v136, s[18:19]
	s_cmp_eq_u32 s6, 1
	s_mov_b32 s46, 0
	s_cselect_b64 s[12:13], -1, 0
	s_cmp_lg_u32 s6, 1
	s_cbranch_scc1 .LBB0_1208
	s_barrier
; #define PG8_STAGE(bufoff, gbase, voff) do { _Pragma("unroll") for (int _i = 0; _i < 2; ++_i) { unsigned keep_; \
;         asm volatile("s_mov_b32 %0, m0\n\ts_mov_b32 m0, %3\n\ts_nop 0\n\tglobal_load_lds_dwordx4 %1, %2\n\ts_mov_b32 m0, %0" \
;             : "=&s"(keep_) : "v"((voff)[_i]), "s"((const void*)(gbase)), "s"(ldsb0 + (unsigned)(bufoff) + (unsigned)(_i * 8192)) : "memory"); } } while (0)
; #define PG8_WAIT_V(n) asm volatile("s_waitcnt vmcnt(" #n ")" ::: "memory")
; #define PG8_BAR __builtin_amdgcn_s_barrier()
; template <class Epi, class Sched, bool ALIGN_EPI>
; __device__ __forceinline__ void gemm_phase(LAS unsigned char* lds, const Gemm g, const Sched& S, const Epi& E) {
;     ...
;     if (wr == 1) PG8_BAR;
;     PG8_WAIT_V(2); PG8_BAR;
;     PG8_STAGE(PG8_SB(1, 0), cB + kstep, voffB); PG8_STAGE(PG8_SA(1, 0), cA + kstep, voffA); PG8_STAGE(PG8_SB(1, 1), cB + hstepB + kstep, voffB);
;     PG8_WAIT_V(6); PG8_BAR;
.LBB0_1208:
	v_lshrrev_b32_e32 v2, 1, v2
	v_or_b32_e32 v138, s16, v3
	v_and_b32_e32 v2, 24, v2
	s_sext_i32_i16 s2, s14
	s_add_u32 s14, s10, 0x1f900000
	v_lshlrev_b32_e32 v4, 6, v138
	v_lshlrev_b32_e32 v5, 1, v2
	s_movk_i32 s5, 0x3c0
	v_lshlrev_b32_e32 v6, 2, v138
	s_addc_u32 s15, s11, 0
	v_and_or_b32 v4, v4, s5, v5
	s_lshl_b32 s5, s6, 13
	v_and_b32_e32 v6, 32, v6
	v_bitop3_b32 v4, v4, s5, v6 bitop3:0xde
	s_lshl_b32 s5, s7, 5
	s_and_b32 s5, s5, 0x60
	v_lshl_or_b32 v5, v3, 6, v5
	v_lshlrev_b32_e32 v3, 2, v3
	s_lshl_b32 s6, s5, 7
	v_and_b32_e32 v3, 32, v3
	v_bitop3_b32 v3, v5, s6, v3 bitop3:0xde
	s_add_u32 s6, s36, 0x80
	s_waitcnt vmcnt(2)
	s_barrier
	s_addc_u32 s7, s37, 0
	s_add_i32 s54, s45, 0x18000
	s_mov_b32 m0, s54
	s_nop 0
	global_load_lds_dwordx4 v135, s[6:7]
	s_add_i32 s55, s45, 0x1a000
	s_mov_b32 m0, s55
	s_nop 0
	global_load_lds_dwordx4 v137, s[6:7]
	s_add_u32 s6, s34, 0x80
	s_addc_u32 s7, s35, 0
	s_add_i32 s56, s45, 0x8000
	s_mov_b32 m0, s56
	s_nop 0
	global_load_lds_dwordx4 v134, s[6:7]
	s_add_i32 s57, s45, 0xa000
	s_mov_b32 m0, s57
	s_nop 0
	global_load_lds_dwordx4 v136, s[6:7]
	s_add_u32 s6, s36, 0x80080
	s_addc_u32 s7, s37, 0
	s_add_i32 s58, s45, 0x1c000
	s_mov_b32 m0, s58
	s_nop 0
	global_load_lds_dwordx4 v135, s[6:7]
	s_add_i32 s59, s45, 0x1e000
	s_mov_b32 m0, s59
	s_nop 0
	global_load_lds_dwordx4 v137, s[6:7]
	s_waitcnt vmcnt(6)
	s_add_i32 s61, s45, 0xc000
	s_cmpk_lt_u32 s3, 0x100
	v_or_b32_e32 v140, s5, v2
	v_add_u32_e32 v2, 0, v3
	s_cselect_b64 s[16:17], -1, 0
	s_add_i32 s62, s45, 0xe000
	v_mov_b64_e32 v[130:131], 0x5ac
	v_mov_b64_e32 v[132:133], 0x5ab
	v_add_u32_e32 v141, 0x10000, v2
	v_add_u32_e32 v142, 0x14000, v2
	v_add_u32_e32 v143, 0, v4
	v_add_u32_e32 v144, 0x18000, v2
	v_add_u32_e32 v145, 0x1c000, v2
	v_mov_b32_e32 v146, 0x358637bd
	s_movk_i32 s63, 0x2c00
	s_barrier
	s_branch .LBB0_1211

; #define PG8_STAGE(bufoff, gbase, voff) do { _Pragma("unroll") for (int _i = 0; _i < 2; ++_i) { unsigned keep_; \
;         asm volatile("s_mov_b32 %0, m0\n\ts_mov_b32 m0, %3\n\ts_nop 0\n\tglobal_load_lds_dwordx4 %1, %2\n\ts_mov_b32 m0, %0" \
;             : "=&s"(keep_) : "v"((voff)[_i]), "s"((const void*)(gbase)), "s"(ldsb0 + (unsigned)(bufoff) + (unsigned)(_i * 8192)) : "memory"); } } while (0)
; #define PG8_LDA(dst, b, h) do { _Pragma("unroll") for (int m = 0; m < 4; ++m) _Pragma("unroll") for (int k = 0; k < 2; ++k) dst[m][k] = *(const LAS bf16x8*)(lds + PG8_SA(b, h) + aoff + m * 2048 + k * 1024); } while (0)
; #define PG8_LDB(dst, b, h) do { _Pragma("unroll") for (int n = 0; n < 2; ++n) _Pragma("unroll") for (int k = 0; k < 2; ++k) dst[n][k] = *(const LAS bf16x8*)(lds + PG8_SB(b, h) + boff + n * 2048 + k * 1024); } while (0)
; #define PG8_MMA(ai, bj, At, Bt) do { __builtin_amdgcn_s_setprio(1); _Pragma("unroll") for (int m = 0; m < 4; ++m) _Pragma("unroll") for (int n = 0; n < 2; ++n) _Pragma("unroll") for (int k = 0; k < 2; ++k) \
;         acc[ai][bj][m][n] = __builtin_amdgcn_mfma_f32_16x16x32_bf16(Bt[n][k], At[m][k], acc[ai][bj][m][n], 0, 0, 0); __builtin_amdgcn_s_setprio(0); } while (0)
; #define PG8_WAIT_V(n) asm volatile("s_waitcnt vmcnt(" #n ")" ::: "memory")
; #define PG8_BAR __builtin_amdgcn_s_barrier()
; template <class Epi, class Sched, bool ALIGN_EPI>
; __device__ __forceinline__ void gemm_phase(LAS unsigned char* lds, const Gemm g, const Sched& S, const Epi& E) {
;     ...
;         for (int t = 0; t < nt; t += 2) {
;             const bool last = (t == nt - 2);
;             const char* a1 = cA + (size_t)(t + 1) * kstep;
;             const char* a2 = last ? nA : cA + (size_t)(t + 2) * kstep; const char* b2 = last ? nB : cB + (size_t)(t + 2) * kstep;
;             const char* a3 = a2 + kstep; const char* b3 = b2 + kstep;
;             PG8_LDB(B0, 0, 0); PG8_LDB(B1, 0, 1); PG8_SCHED; PG8_LDA(At, 0, 0); PG8_STAGE(PG8_SA(1, 1), a1 + hstepA, voffA);
;             PG8_WAIT_V(8); PG8_WAIT_L(0); PG8_BAR; PG8_MMA(0, 0, At, B0); PG8_MMA(0, 1, At, B1); PG8_BAR; PG8_SCHED;
;             PG8_LDA(At, 0, 1); PG8_STAGE(PG8_SB(0, 0), b2, voffB); PG8_STAGE(PG8_SB(0, 1), b2 + hstepB, voffB); PG8_STAGE(PG8_SA(0, 0), a2, voffA);
;             PG8_WAIT_V(8); PG8_WAIT_L(0); PG8_BAR; PG8_MMA(1, 0, At, B0); PG8_MMA(1, 1, At, B1); PG8_BAR; PG8_SCHED;
.LBB0_1218:
	ds_read_b128 v[154:157], v141
	ds_read_b128 v[158:161], v141 offset:1024
	ds_read_b128 v[162:165], v141 offset:2048
	ds_read_b128 v[166:169], v141 offset:3072
	ds_read_b128 v[170:173], v142
	ds_read_b128 v[174:177], v142 offset:1024
	ds_read_b128 v[180:183], v142 offset:2048
	ds_read_b128 v[184:187], v142 offset:3072
	s_add_u32 s36, s34, 0x100
	s_addc_u32 s37, s35, 0
	s_cmp_eq_u32 s64, 28
	s_cselect_b32 s42, s5, s36
	s_cselect_b32 s43, s3, s37
	s_cselect_b32 s40, s7, s19
	s_cselect_b32 s41, s6, s27
	s_add_u32 s38, s42, 0x80
	s_addc_u32 s39, s43, 0
	ds_read_b128 v[188:191], v143
	ds_read_b128 v[192:195], v143 offset:1024
	ds_read_b128 v[196:199], v143 offset:2048
	ds_read_b128 v[204:207], v143 offset:3072
	ds_read_b128 v[208:211], v143 offset:4096
	ds_read_b128 v[212:215], v143 offset:5120
	ds_read_b128 v[216:219], v143 offset:6144
	ds_read_b128 v[220:223], v143 offset:7168
	s_add_u32 s34, s34, 0x80080
	s_addc_u32 s35, s35, 0
	s_mov_b32 m0, s61
	s_nop 0
	global_load_lds_dwordx4 v134, s[34:35]
	s_nop 0
	s_mov_b32 m0, s62
	s_nop 0
	global_load_lds_dwordx4 v136, s[34:35]
	s_waitcnt vmcnt(8)
	s_waitcnt lgkmcnt(0)
	s_barrier
	s_setprio 1
	v_mfma_f32_16x16x32_bf16 v[126:129], v[154:157], v[188:191], v[126:129]
	v_mfma_f32_16x16x32_bf16 v[122:125], v[162:165], v[188:191], v[122:125]
	v_mfma_f32_16x16x32_bf16 v[110:113], v[154:157], v[196:199], v[110:113]
	v_mfma_f32_16x16x32_bf16 v[106:109], v[162:165], v[196:199], v[106:109]
	v_mfma_f32_16x16x32_bf16 v[94:97], v[154:157], v[208:211], v[94:97]
	v_mfma_f32_16x16x32_bf16 v[90:93], v[162:165], v[208:211], v[90:93]
	v_mfma_f32_16x16x32_bf16 v[78:81], v[154:157], v[216:219], v[78:81]
	v_mfma_f32_16x16x32_bf16 v[74:77], v[162:165], v[216:219], v[74:77]
	v_mfma_f32_16x16x32_bf16 v[126:129], v[158:161], v[192:195], v[126:129]
	v_mfma_f32_16x16x32_bf16 v[122:125], v[166:169], v[192:195], v[122:125]
	v_mfma_f32_16x16x32_bf16 v[110:113], v[158:161], v[204:207], v[110:113]
	v_mfma_f32_16x16x32_bf16 v[106:109], v[166:169], v[204:207], v[106:109]
	v_mfma_f32_16x16x32_bf16 v[94:97], v[158:161], v[212:215], v[94:97]
	v_mfma_f32_16x16x32_bf16 v[90:93], v[166:169], v[212:215], v[90:93]
	v_mfma_f32_16x16x32_bf16 v[78:81], v[158:161], v[220:223], v[78:81]
	v_mfma_f32_16x16x32_bf16 v[74:77], v[166:169], v[220:223], v[74:77]
	v_mfma_f32_16x16x32_bf16 v[118:121], v[170:173], v[188:191], v[118:121]
	v_mfma_f32_16x16x32_bf16 v[114:117], v[180:183], v[188:191], v[114:117]
	v_mfma_f32_16x16x32_bf16 v[102:105], v[170:173], v[196:199], v[102:105]
	v_mfma_f32_16x16x32_bf16 v[98:101], v[180:183], v[196:199], v[98:101]
	v_mfma_f32_16x16x32_bf16 v[86:89], v[170:173], v[208:211], v[86:89]
	v_mfma_f32_16x16x32_bf16 v[82:85], v[180:183], v[208:211], v[82:85]
	v_mfma_f32_16x16x32_bf16 v[70:73], v[170:173], v[216:219], v[70:73]
	v_mfma_f32_16x16x32_bf16 v[66:69], v[180:183], v[216:219], v[66:69]
	v_mfma_f32_16x16x32_bf16 v[118:121], v[174:177], v[192:195], v[118:121]
	v_mfma_f32_16x16x32_bf16 v[114:117], v[184:187], v[192:195], v[114:117]
	v_mfma_f32_16x16x32_bf16 v[102:105], v[174:177], v[204:207], v[102:105]
	v_mfma_f32_16x16x32_bf16 v[98:101], v[184:187], v[204:207], v[98:101]
	v_mfma_f32_16x16x32_bf16 v[86:89], v[174:177], v[212:215], v[86:89]
	v_mfma_f32_16x16x32_bf16 v[82:85], v[184:187], v[212:215], v[82:85]
	v_mfma_f32_16x16x32_bf16 v[70:73], v[174:177], v[220:223], v[70:73]
	v_mfma_f32_16x16x32_bf16 v[66:69], v[184:187], v[220:223], v[66:69]
	s_setprio 0
	s_barrier
	ds_read_b128 v[188:191], v143 offset:16384
	ds_read_b128 v[192:195], v143 offset:17408
	ds_read_b128 v[196:199], v143 offset:18432
	ds_read_b128 v[204:207], v143 offset:19456
	ds_read_b128 v[208:211], v143 offset:20480
	ds_read_b128 v[212:215], v143 offset:21504
	ds_read_b128 v[216:219], v143 offset:22528
	ds_read_b128 v[220:223], v143 offset:23552
	s_mov_b32 m0, s47
	s_nop 0
	global_load_lds_dwordx4 v135, s[40:41]
	s_nop 0
	s_mov_b32 m0, s48
	s_nop 0
	global_load_lds_dwordx4 v137, s[40:41]
	s_add_u32 s34, s40, 0x80000
	s_addc_u32 s35, s41, 0
	s_mov_b32 m0, s49
	s_nop 0
	global_load_lds_dwordx4 v135, s[34:35]
	s_nop 0
	s_mov_b32 m0, s50
	s_nop 0
	global_load_lds_dwordx4 v137, s[34:35]
	s_mov_b32 m0, s45
	s_nop 0
	global_load_lds_dwordx4 v134, s[42:43]
	s_nop 0
	s_mov_b32 m0, s51
	s_nop 0
	global_load_lds_dwordx4 v136, s[42:43]
	s_waitcnt vmcnt(8)
	s_waitcnt lgkmcnt(0)
	s_barrier
	s_setprio 1
	v_mfma_f32_16x16x32_bf16 v[62:65], v[154:157], v[188:191], v[62:65]
	v_mfma_f32_16x16x32_bf16 v[58:61], v[162:165], v[188:191], v[58:61]
	v_mfma_f32_16x16x32_bf16 v[46:49], v[154:157], v[196:199], v[46:49]
	v_mfma_f32_16x16x32_bf16 v[42:45], v[162:165], v[196:199], v[42:45]
	v_mfma_f32_16x16x32_bf16 v[30:33], v[154:157], v[208:211], v[30:33]
	v_mfma_f32_16x16x32_bf16 v[26:29], v[162:165], v[208:211], v[26:29]
	v_mfma_f32_16x16x32_bf16 v[14:17], v[154:157], v[216:219], v[14:17]
	v_mfma_f32_16x16x32_bf16 v[10:13], v[162:165], v[216:219], v[10:13]
	v_mfma_f32_16x16x32_bf16 v[62:65], v[158:161], v[192:195], v[62:65]
	v_mfma_f32_16x16x32_bf16 v[58:61], v[166:169], v[192:195], v[58:61]
	v_mfma_f32_16x16x32_bf16 v[46:49], v[158:161], v[204:207], v[46:49]
	v_mfma_f32_16x16x32_bf16 v[42:45], v[166:169], v[204:207], v[42:45]
	v_mfma_f32_16x16x32_bf16 v[30:33], v[158:161], v[212:215], v[30:33]
	v_mfma_f32_16x16x32_bf16 v[26:29], v[166:169], v[212:215], v[26:29]
	v_mfma_f32_16x16x32_bf16 v[14:17], v[158:161], v[220:223], v[14:17]
	v_mfma_f32_16x16x32_bf16 v[10:13], v[166:169], v[220:223], v[10:13]
	v_mfma_f32_16x16x32_bf16 v[54:57], v[170:173], v[188:191], v[54:57]
	v_mfma_f32_16x16x32_bf16 v[50:53], v[180:183], v[188:191], v[50:53]
	v_mfma_f32_16x16x32_bf16 v[38:41], v[170:173], v[196:199], v[38:41]
	v_mfma_f32_16x16x32_bf16 v[34:37], v[180:183], v[196:199], v[34:37]
	v_mfma_f32_16x16x32_bf16 v[22:25], v[170:173], v[208:211], v[22:25]
	v_mfma_f32_16x16x32_bf16 v[18:21], v[180:183], v[208:211], v[18:21]
	v_mfma_f32_16x16x32_bf16 v[6:9], v[170:173], v[216:219], v[6:9]
	v_mfma_f32_16x16x32_bf16 v[2:5], v[180:183], v[216:219], v[2:5]
	v_mfma_f32_16x16x32_bf16 v[54:57], v[174:177], v[192:195], v[54:57]
	v_mfma_f32_16x16x32_bf16 v[50:53], v[184:187], v[192:195], v[50:53]
	v_mfma_f32_16x16x32_bf16 v[38:41], v[174:177], v[204:207], v[38:41]
	v_mfma_f32_16x16x32_bf16 v[34:37], v[184:187], v[204:207], v[34:37]
	v_mfma_f32_16x16x32_bf16 v[22:25], v[174:177], v[212:215], v[22:25]
	v_mfma_f32_16x16x32_bf16 v[18:21], v[184:187], v[212:215], v[18:21]
	v_mfma_f32_16x16x32_bf16 v[6:9], v[174:177], v[220:223], v[6:9]
	v_mfma_f32_16x16x32_bf16 v[2:5], v[184:187], v[220:223], v[2:5]
	s_setprio 0
	s_barrier
; #define PG8_STAGE(bufoff, gbase, voff) do { _Pragma("unroll") for (int _i = 0; _i < 2; ++_i) { unsigned keep_; \
;         asm volatile("s_mov_b32 %0, m0\n\ts_mov_b32 m0, %3\n\ts_nop 0\n\tglobal_load_lds_dwordx4 %1, %2\n\ts_mov_b32 m0, %0" \
;             : "=&s"(keep_) : "v"((voff)[_i]), "s"((const void*)(gbase)), "s"(ldsb0 + (unsigned)(bufoff) + (unsigned)(_i * 8192)) : "memory"); } } while (0)
; #define PG8_LDA(dst, b, h) do { _Pragma("unroll") for (int m = 0; m < 4; ++m) _Pragma("unroll") for (int k = 0; k < 2; ++k) dst[m][k] = *(const LAS bf16x8*)(lds + PG8_SA(b, h) + aoff + m * 2048 + k * 1024); } while (0)
; #define PG8_LDB(dst, b, h) do { _Pragma("unroll") for (int n = 0; n < 2; ++n) _Pragma("unroll") for (int k = 0; k < 2; ++k) dst[n][k] = *(const LAS bf16x8*)(lds + PG8_SB(b, h) + boff + n * 2048 + k * 1024); } while (0)
; #define PG8_MMA(ai, bj, At, Bt) do { __builtin_amdgcn_s_setprio(1); _Pragma("unroll") for (int m = 0; m < 4; ++m) _Pragma("unroll") for (int n = 0; n < 2; ++n) _Pragma("unroll") for (int k = 0; k < 2; ++k) \
;         acc[ai][bj][m][n] = __builtin_amdgcn_mfma_f32_16x16x32_bf16(Bt[n][k], At[m][k], acc[ai][bj][m][n], 0, 0, 0); __builtin_amdgcn_s_setprio(0); } while (0)
; #define PG8_WAIT_V(n) asm volatile("s_waitcnt vmcnt(" #n ")" ::: "memory")
; #define PG8_WAIT_L(n) asm volatile("s_waitcnt lgkmcnt(" #n ")" ::: "memory")
; #define PG8_BAR __builtin_amdgcn_s_barrier()
; #define PG8_SCHED __builtin_amdgcn_sched_barrier(0)
; template <class Epi, class Sched, bool ALIGN_EPI>
; __device__ __forceinline__ void gemm_phase(LAS unsigned char* lds, const Gemm g, const Sched& S, const Epi& E) {
;     ...
;             PG8_LDB(B0, 1, 0); PG8_LDB(B1, 1, 1); PG8_SCHED; PG8_LDA(At, 1, 0); PG8_STAGE(PG8_SA(0, 1), a2 + hstepA, voffA);
;             PG8_WAIT_V(8); PG8_WAIT_L(0); PG8_BAR; PG8_MMA(0, 0, At, B0); PG8_MMA(0, 1, At, B1); PG8_BAR; PG8_SCHED;
;             PG8_LDA(At, 1, 1); PG8_STAGE(PG8_SB(1, 0), b3, voffB); PG8_STAGE(PG8_SB(1, 1), b3 + hstepB, voffB); PG8_STAGE(PG8_SA(1, 0), a3, voffA);
;             PG8_WAIT_V(8); PG8_WAIT_L(0); PG8_BAR; PG8_MMA(1, 0, At, B0); PG8_MMA(1, 1, At, B1); PG8_BAR; PG8_SCHED;
;         }
	ds_read_b128 v[154:157], v144
	ds_read_b128 v[158:161], v144 offset:1024
	ds_read_b128 v[162:165], v144 offset:2048
	ds_read_b128 v[166:169], v144 offset:3072
	ds_read_b128 v[170:173], v145
	ds_read_b128 v[174:177], v145 offset:1024
	ds_read_b128 v[180:183], v145 offset:2048
	ds_read_b128 v[184:187], v145 offset:3072
	ds_read_b128 v[188:191], v143 offset:32768
	ds_read_b128 v[192:195], v143 offset:33792
	ds_read_b128 v[196:199], v143 offset:34816
	ds_read_b128 v[204:207], v143 offset:35840
	ds_read_b128 v[208:211], v143 offset:36864
	ds_read_b128 v[212:215], v143 offset:37888
	ds_read_b128 v[216:219], v143 offset:38912
	ds_read_b128 v[220:223], v143 offset:39936
	s_add_u32 s34, s42, 0x80000
	s_addc_u32 s35, s43, 0
	s_mov_b32 m0, s52
	s_nop 0
	global_load_lds_dwordx4 v134, s[34:35]
	s_nop 0
	s_mov_b32 m0, s53
	s_nop 0
	global_load_lds_dwordx4 v136, s[34:35]
	s_waitcnt vmcnt(8)
	s_waitcnt lgkmcnt(0)
	s_barrier
	s_setprio 1
	v_mfma_f32_16x16x32_bf16 v[126:129], v[154:157], v[188:191], v[126:129]
	v_mfma_f32_16x16x32_bf16 v[122:125], v[162:165], v[188:191], v[122:125]
	v_mfma_f32_16x16x32_bf16 v[110:113], v[154:157], v[196:199], v[110:113]
	v_mfma_f32_16x16x32_bf16 v[106:109], v[162:165], v[196:199], v[106:109]
	v_mfma_f32_16x16x32_bf16 v[94:97], v[154:157], v[208:211], v[94:97]
	v_mfma_f32_16x16x32_bf16 v[90:93], v[162:165], v[208:211], v[90:93]
	v_mfma_f32_16x16x32_bf16 v[78:81], v[154:157], v[216:219], v[78:81]
	v_mfma_f32_16x16x32_bf16 v[74:77], v[162:165], v[216:219], v[74:77]
	v_mfma_f32_16x16x32_bf16 v[126:129], v[158:161], v[192:195], v[126:129]
	v_mfma_f32_16x16x32_bf16 v[122:125], v[166:169], v[192:195], v[122:125]
	v_mfma_f32_16x16x32_bf16 v[110:113], v[158:161], v[204:207], v[110:113]
	v_mfma_f32_16x16x32_bf16 v[106:109], v[166:169], v[204:207], v[106:109]
	v_mfma_f32_16x16x32_bf16 v[94:97], v[158:161], v[212:215], v[94:97]
	v_mfma_f32_16x16x32_bf16 v[90:93], v[166:169], v[212:215], v[90:93]
	v_mfma_f32_16x16x32_bf16 v[78:81], v[158:161], v[220:223], v[78:81]
	v_mfma_f32_16x16x32_bf16 v[74:77], v[166:169], v[220:223], v[74:77]
	v_mfma_f32_16x16x32_bf16 v[118:121], v[170:173], v[188:191], v[118:121]
	v_mfma_f32_16x16x32_bf16 v[114:117], v[180:183], v[188:191], v[114:117]
	v_mfma_f32_16x16x32_bf16 v[102:105], v[170:173], v[196:199], v[102:105]
	v_mfma_f32_16x16x32_bf16 v[98:101], v[180:183], v[196:199], v[98:101]
	v_mfma_f32_16x16x32_bf16 v[86:89], v[170:173], v[208:211], v[86:89]
	v_mfma_f32_16x16x32_bf16 v[82:85], v[180:183], v[208:211], v[82:85]
	v_mfma_f32_16x16x32_bf16 v[70:73], v[170:173], v[216:219], v[70:73]
	v_mfma_f32_16x16x32_bf16 v[66:69], v[180:183], v[216:219], v[66:69]
	v_mfma_f32_16x16x32_bf16 v[118:121], v[174:177], v[192:195], v[118:121]
	v_mfma_f32_16x16x32_bf16 v[114:117], v[184:187], v[192:195], v[114:117]
	v_mfma_f32_16x16x32_bf16 v[102:105], v[174:177], v[204:207], v[102:105]
	v_mfma_f32_16x16x32_bf16 v[98:101], v[184:187], v[204:207], v[98:101]
	v_mfma_f32_16x16x32_bf16 v[86:89], v[174:177], v[212:215], v[86:89]
	v_mfma_f32_16x16x32_bf16 v[82:85], v[184:187], v[212:215], v[82:85]
	v_mfma_f32_16x16x32_bf16 v[70:73], v[174:177], v[220:223], v[70:73]
	v_mfma_f32_16x16x32_bf16 v[66:69], v[184:187], v[220:223], v[66:69]
	s_setprio 0
	s_barrier
	ds_read_b128 v[188:191], v143 offset:49152
	ds_read_b128 v[192:195], v143 offset:50176
	ds_read_b128 v[196:199], v143 offset:51200
	ds_read_b128 v[204:207], v143 offset:52224
	ds_read_b128 v[208:211], v143 offset:53248
	ds_read_b128 v[212:215], v143 offset:54272
	ds_read_b128 v[216:219], v143 offset:55296
	ds_read_b128 v[220:223], v143 offset:56320
	s_add_u32 s34, s40, 0x80
	s_addc_u32 s35, s41, 0
	s_mov_b32 m0, s54
	s_nop 0
	global_load_lds_dwordx4 v135, s[34:35]
	s_nop 0
	s_mov_b32 m0, s55
	s_nop 0
	global_load_lds_dwordx4 v137, s[34:35]
	s_add_u32 s34, s40, 0x80080
	s_addc_u32 s35, s41, 0
	s_mov_b32 m0, s58
	s_nop 0
	global_load_lds_dwordx4 v135, s[34:35]
	s_nop 0
	s_mov_b32 m0, s59
	s_nop 0
	global_load_lds_dwordx4 v137, s[34:35]
	s_mov_b32 m0, s56
	s_nop 0
	global_load_lds_dwordx4 v134, s[38:39]
	s_nop 0
	s_mov_b32 m0, s57
	s_nop 0
	global_load_lds_dwordx4 v136, s[38:39]
	s_waitcnt vmcnt(8)
	s_waitcnt lgkmcnt(0)
	s_barrier
	s_setprio 1
	v_mfma_f32_16x16x32_bf16 v[62:65], v[154:157], v[188:191], v[62:65]
	v_mfma_f32_16x16x32_bf16 v[58:61], v[162:165], v[188:191], v[58:61]
	v_mfma_f32_16x16x32_bf16 v[46:49], v[154:157], v[196:199], v[46:49]
	v_mfma_f32_16x16x32_bf16 v[42:45], v[162:165], v[196:199], v[42:45]
	v_mfma_f32_16x16x32_bf16 v[30:33], v[154:157], v[208:211], v[30:33]
	v_mfma_f32_16x16x32_bf16 v[26:29], v[162:165], v[208:211], v[26:29]
	v_mfma_f32_16x16x32_bf16 v[14:17], v[154:157], v[216:219], v[14:17]
	v_mfma_f32_16x16x32_bf16 v[10:13], v[162:165], v[216:219], v[10:13]
	v_mfma_f32_16x16x32_bf16 v[62:65], v[158:161], v[192:195], v[62:65]
	v_mfma_f32_16x16x32_bf16 v[58:61], v[166:169], v[192:195], v[58:61]
	v_mfma_f32_16x16x32_bf16 v[46:49], v[158:161], v[204:207], v[46:49]
	v_mfma_f32_16x16x32_bf16 v[42:45], v[166:169], v[204:207], v[42:45]
	v_mfma_f32_16x16x32_bf16 v[30:33], v[158:161], v[212:215], v[30:33]
	v_mfma_f32_16x16x32_bf16 v[26:29], v[166:169], v[212:215], v[26:29]
	v_mfma_f32_16x16x32_bf16 v[14:17], v[158:161], v[220:223], v[14:17]
	v_mfma_f32_16x16x32_bf16 v[10:13], v[166:169], v[220:223], v[10:13]
	v_mfma_f32_16x16x32_bf16 v[54:57], v[170:173], v[188:191], v[54:57]
	v_mfma_f32_16x16x32_bf16 v[50:53], v[180:183], v[188:191], v[50:53]
	v_mfma_f32_16x16x32_bf16 v[38:41], v[170:173], v[196:199], v[38:41]
	v_mfma_f32_16x16x32_bf16 v[34:37], v[180:183], v[196:199], v[34:37]
	v_mfma_f32_16x16x32_bf16 v[22:25], v[170:173], v[208:211], v[22:25]
	v_mfma_f32_16x16x32_bf16 v[18:21], v[180:183], v[208:211], v[18:21]
	v_mfma_f32_16x16x32_bf16 v[6:9], v[170:173], v[216:219], v[6:9]
	v_mfma_f32_16x16x32_bf16 v[2:5], v[180:183], v[216:219], v[2:5]
	v_mfma_f32_16x16x32_bf16 v[54:57], v[174:177], v[192:195], v[54:57]
	v_mfma_f32_16x16x32_bf16 v[50:53], v[184:187], v[192:195], v[50:53]
	v_mfma_f32_16x16x32_bf16 v[38:41], v[174:177], v[204:207], v[38:41]
	v_mfma_f32_16x16x32_bf16 v[34:37], v[184:187], v[204:207], v[34:37]
	v_mfma_f32_16x16x32_bf16 v[22:25], v[174:177], v[212:215], v[22:25]
	v_mfma_f32_16x16x32_bf16 v[18:21], v[184:187], v[212:215], v[18:21]
	v_mfma_f32_16x16x32_bf16 v[6:9], v[174:177], v[220:223], v[6:9]
	v_mfma_f32_16x16x32_bf16 v[2:5], v[184:187], v[220:223], v[2:5]
	s_setprio 0
	s_barrier
	s_add_i32 s64, s64, 2
	s_add_u32 s19, s19, 0x100
	s_addc_u32 s27, s27, 0
	s_cmp_gt_u32 s64, 29
	s_mov_b64 s[34:35], s[36:37]
	s_cbranch_scc0 .LBB0_1218
	s_and_b64 vcc, exec, s[16:17]
	s_cbranch_vccz .LBB0_1221
	s_barrier

;     __device__ bool next(int i, Unit& u) const {
;         const long L = (long)i * G + c; if (L >= nwg) return false;
;         int wgid = (int)L; { const int q = nwg / NXCD, r = nwg % NXCD, xcd = wgid % NXCD, off = wgid / NXCD; wgid = (xcd < r ? xcd * (q + 1) : r * (q + 1) + (xcd - r) * q) + off; }
;         const int nig = WGM * nN, gid = wgid / nig, fm = gid * WGM, gsz = (nM - fm) < WGM ? (nM - fm) : WGM;
;         u.pm = fm + ((wgid % nig) % gsz); u.pn = (wgid % nig) / gsz; return true;
; template <class Epi, class Sched, bool ALIGN_EPI>
; __device__ __forceinline__ void gemm_phase(LAS unsigned char* lds, const Gemm g, const Sched& S, const Epi& E) {
;     ...
;     for (int i = 0; i < 2; ++i) { int R, C; stage_rc(tid * 16 + i * 8192, R, C); const int Rb = (R & ~31) + perm32(R & 31);
;         voffA[i] = (unsigned)(R * g.lda + C) * 2u; voffB[i] = (unsigned)(Rb * g.ldb + C) * 2u; }
;     const size_t kstep = (size_t)(BK * 2);
;     const size_t hstepA = (size_t)HALF * g.lda * 2, hstepB = (size_t)HALF * g.ldb * 2;
;     const size_t tstepA = 2 * hstepA, tstepB = 2 * hstepB;
;     const unsigned ldsw = (unsigned)wid * 1024u;
;     const int aoff = lds_byte(wr * 64 + fr, fq * 8), boff = lds_byte(wc * 32 + fr, fq * 8);
;     ...
;     const unsigned ldsb0 = (unsigned)(uintptr_t)lds + ldsw;
;     ...
;     Unit cur, nxt; int ui = 0;
;     if (!S.next(0, cur)) return;
;     f32x4 acc[2][2][4][2];
; #pragma unroll
;     for (int a = 0; a < 2; ++a)
; #pragma unroll
;         for (int b = 0; b < 2; ++b)
; #pragma unroll
;             for (int m = 0; m < 4; ++m)
; #pragma unroll
;                 for (int n = 0; n < 2; ++n) acc[a][b][m][n] = (f32x4){0.f, 0.f, 0.f, 0.f};
;     bf16x8 At[4][2], B0[2][2], B1[2][2];
;     float pre[Epi::NPRE > 0 ? Epi::NPRE : 1];
;     if constexpr (Epi::NPRE > 0) E.preload(cur, wr, fr, pre);
;     const char* cA = (const char*)g.A + (size_t)cur.pm * tstepA + (size_t)cur.pn * g.a_koff * 2; const char* cB = (const char*)g.Bt + (size_t)cur.pn * tstepB;
;     PG8_STAGE(PG8_SB(0, 0), cB, voffB); PG8_STAGE(PG8_SB(0, 1), cB + hstepB, voffB); PG8_STAGE(PG8_SA(0, 0), cA, voffA); PG8_STAGE(PG8_SA(0, 1), cA + hstepA, voffA);
;     if (wr == 1) PG8_BAR;
;     PG8_WAIT_V(2); PG8_BAR;
;     PG8_STAGE(PG8_SB(1, 0), cB + kstep, voffB); PG8_STAGE(PG8_SA(1, 0), cA + kstep, voffA); PG8_STAGE(PG8_SB(1, 1), cB + hstepB + kstep, voffB);
;     PG8_WAIT_V(6); PG8_BAR;
.LBB0_1301:
	v_bfe_i32 v5, v2, 27, 1
	v_lshlrev_b32_e32 v3, 4, v2
	v_lshrrev_b32_e32 v5, 22, v5
	v_add_u32_e32 v5, v3, v5
	v_and_b32_e32 v5, 0xfffffc00, v5
	v_sub_u32_e32 v5, v3, v5
	v_lshrrev_b32_e32 v6, 4, v5
	v_ashrrev_i32_e32 v4, 31, v2
	v_bitop3_b32 v6, v6, v5, 32 bitop3:0x6c
	v_ashrrev_i32_e32 v5, 31, v5
	v_lshrrev_b32_e32 v4, 26, v4
	v_lshrrev_b32_e32 v5, 26, v5
	v_add_u32_e32 v4, v2, v4
	v_add_u32_e32 v5, v6, v5
	v_ashrrev_i32_e32 v4, 6, v4
	v_ashrrev_i32_e32 v5, 6, v5
	v_lshlrev_b32_e32 v7, 3, v4
	v_mul_i32_i24_e32 v8, 64, v5
	v_and_b32_e32 v7, -16, v7
	v_lshlrev_b32_e32 v4, 5, v4
	v_sub_u32_e32 v6, v6, v8
	v_mov_b32_e32 v8, 1
	v_add_u32_e32 v7, v5, v7
	v_and_b32_e32 v4, 32, v4
	v_ashrrev_i16_sdwa v6, v8, sext(v6) dst_sel:DWORD dst_unused:UNUSED_PAD src0_sel:DWORD src1_sel:BYTE_0
	v_add_u32_sdwa v4, v4, sext(v6) dst_sel:DWORD dst_unused:UNUSED_PAD src0_sel:DWORD src1_sel:WORD_0
	v_lshlrev_b32_e32 v6, 1, v7
	v_lshrrev_b32_e32 v9, 2, v7
	v_and_b32_e32 v5, 3, v5
	s_mov_b32 s4, 0x7fffe0
	v_and_b32_e32 v6, 24, v6
	v_and_b32_e32 v9, 4, v9
	v_and_or_b32 v5, v7, s4, v5
	v_or3_b32 v5, v5, v9, v6
	s_movk_i32 s5, 0x1600
	v_mul_lo_u32 v6, v7, s5
	v_mul_u32_u24_e32 v5, 0x1600, v5
	v_add_u32_e32 v3, 0x2000, v3
	v_add_lshl_u32 v179, v4, v6, 1
	v_add_lshl_u32 v200, v5, v4, 1
	v_ashrrev_i32_e32 v4, 31, v3
	v_lshrrev_b32_e32 v4, 22, v4
	v_add_u32_e32 v4, v3, v4
	v_ashrrev_i32_e32 v4, 10, v4
	v_mul_i32_i24_e32 v5, 0x400, v4
	v_sub_u32_e32 v3, v3, v5
	s_ashr_i32 s3, s3, 3
	v_lshrrev_b32_e32 v5, 4, v3
	s_waitcnt lgkmcnt(0)
	s_add_u32 s23, s14, 0x1f900000
	v_bitop3_b32 v3, v5, v3, 32 bitop3:0x6c
	s_addc_u32 s24, s15, 0
	v_ashrrev_i32_e32 v6, 31, v3
	s_add_u32 s25, s8, 0x4700000
	v_lshrrev_b32_e32 v6, 26, v6
	s_addc_u32 s36, s9, 0
	v_lshlrev_b32_e32 v5, 3, v4
	v_add_u32_e32 v6, v3, v6
	s_add_i32 s2, s2, s3
	v_and_b32_e32 v5, -16, v5
	v_ashrrev_i32_e32 v7, 6, v6
	s_ashr_i32 s3, s2, 31
	v_add_u32_e32 v5, v7, v5
	v_and_b32_e32 v7, 3, v7
	s_ashr_i32 s18, s6, 6
	s_lshr_b32 s3, s3, 26
	v_and_or_b32 v7, v5, s4, v7
	s_lshl_b32 s4, s18, 10
	s_add_i32 s3, s2, s3
	s_add_i32 s38, s4, 0
	s_ashr_i32 s4, s3, 6
	s_andn2_b32 s3, s3, 63
	v_and_b32_e32 v6, 0xc0, v6
	s_sub_i32 s2, s2, s3
	v_lshlrev_b32_e32 v4, 5, v4
	v_sub_u32_e32 v3, v3, v6
	s_bfe_i32 s3, s2, 0x80000
	v_and_b32_e32 v4, 32, v4
	v_ashrrev_i16_sdwa v3, v8, sext(v3) dst_sel:DWORD dst_unused:UNUSED_PAD src0_sel:DWORD src1_sel:BYTE_0
	s_bfe_u32 s3, s3, 0x3000c
	v_add_u32_sdwa v3, v4, sext(v3) dst_sel:DWORD dst_unused:UNUSED_PAD src0_sel:DWORD src1_sel:WORD_0
	v_lshlrev_b32_e32 v4, 1, v5
	v_lshrrev_b32_e32 v6, 2, v5
	v_mul_lo_u32 v5, v5, s5
	s_add_i32 s5, s2, s3
	s_bfe_i32 s3, s5, 0x80000
	s_and_b32 s5, s5, 0xf8
	s_sub_i32 s2, s2, s5
	s_lshl_b32 s4, s4, 3
	s_sext_i32_i16 s8, s3
	s_sext_i32_i8 s2, s2
	s_add_i32 s2, s4, s2
	s_ashr_i32 s4, s8, 3
	s_ashr_i32 s7, s6, 8
	v_and_b32_e32 v4, 24, v4
	v_and_b32_e32 v6, 4, v6
	s_lshr_b32 s3, s8, 3
	s_mul_hi_i32 s5, s4, 0x2c0000
	s_mul_i32 s4, s4, 0x2c0000
	v_or3_b32 v4, v7, v6, v4
	s_add_u32 s4, s25, s4
	v_mul_u32_u24_e32 v4, 0x1600, v4
	s_addc_u32 s5, s36, s5
	s_add_i32 s39, s38, 0x10000
	s_mov_b32 m0, s39
	s_nop 0
	global_load_lds_dwordx4 v200, s[4:5]
	s_add_i32 s40, s38, 0x12000
	v_add_lshl_u32 v203, v4, v3, 1
	s_mov_b32 m0, s40
	s_nop 0
	global_load_lds_dwordx4 v203, s[4:5]
	s_add_u32 s14, s4, 0x160000
	s_mul_i32 s16, s2, 0x2c0000
	s_addc_u32 s15, s5, 0
	s_add_i32 s41, s38, 0x14000
	s_mov_b32 m0, s41
	s_nop 0
	global_load_lds_dwordx4 v200, s[14:15]
	s_add_i32 s42, s38, 0x16000
	s_mul_hi_i32 s9, s2, 0x2c0000
	s_mov_b32 m0, s42
	s_nop 0
	global_load_lds_dwordx4 v203, s[14:15]
	s_add_u32 s28, s23, s16
	s_addc_u32 s29, s24, s9
	s_mov_b32 m0, s38
	s_nop 0
	global_load_lds_dwordx4 v179, s[28:29]
	s_add_i32 s43, s38, 0x2000
	v_add_lshl_u32 v201, v3, v5, 1
	s_mov_b32 m0, s43
	s_nop 0
	global_load_lds_dwordx4 v201, s[28:29]
	s_add_u32 s16, s28, 0x160000
	s_addc_u32 s17, s29, 0
	s_add_i32 s44, s38, 0x4000
	s_mov_b32 m0, s44
	s_nop 0
	global_load_lds_dwordx4 v179, s[16:17]
	s_add_i32 s45, s38, 0x6000
	s_mov_b32 m0, s45
	s_nop 0
	global_load_lds_dwordx4 v201, s[16:17]
	s_cmp_eq_u32 s7, 1
	s_mov_b32 s37, 0
	s_cselect_b64 s[8:9], -1, 0
	s_cmp_lg_u32 s7, 1
	s_cbranch_scc1 .LBB0_1303
	s_barrier
.LBB0_1303:
	s_add_u32 s16, s10, 0x1d800000
	v_bfe_u32 v5, v2, 4, 2
	v_and_b32_e32 v3, 15, v2
	s_addc_u32 s17, s11, 0
	s_lshl_b32 s26, s7, 6
	v_lshlrev_b32_e32 v2, 4, v5
	v_lshlrev_b32_e32 v4, 2, v3
	v_or_b32_e32 v204, s26, v3
	v_lshl_or_b32 v6, v3, 6, v2
	s_lshl_b32 s7, s7, 13
	v_and_b32_e32 v3, 32, v4
	v_bitop3_b32 v7, v6, s7, v3 bitop3:0xde
	s_lshl_b32 s7, s18, 5
	s_and_b32 s27, s7, 0x60
	s_lshl_b32 s7, s27, 7
	s_add_u32 s10, s4, 0x80
	v_bitop3_b32 v6, v6, s7, v3 bitop3:0xde
	s_waitcnt vmcnt(2)
	s_barrier
	s_addc_u32 s11, s5, 0
	s_add_i32 s46, s38, 0x18000
	s_mov_b32 m0, s46
	s_nop 0
	global_load_lds_dwordx4 v200, s[10:11]
	s_add_i32 s47, s38, 0x1a000
	s_mov_b32 m0, s47
	s_nop 0
	global_load_lds_dwordx4 v203, s[10:11]
	s_add_u32 s10, s28, 0x80
	s_addc_u32 s11, s29, 0
	s_add_i32 s48, s38, 0x8000
	s_mov_b32 m0, s48
	s_nop 0
	global_load_lds_dwordx4 v179, s[10:11]
	s_add_i32 s49, s38, 0xa000
	s_mov_b32 m0, s49
	s_nop 0
	global_load_lds_dwordx4 v201, s[10:11]
	s_add_u32 s10, s14, 0x80
	s_addc_u32 s11, s15, 0
	s_add_i32 s50, s38, 0x1c000
	s_add_i32 s51, s38, 0x1e000
	s_add_i32 s52, s38, 0xc000
	s_cmpk_lt_u32 s6, 0x100
	s_mov_b32 m0, s50
	s_nop 0
	global_load_lds_dwordx4 v200, s[10:11]
	s_cselect_b64 s[18:19], -1, 0
	s_lshl_b32 s6, s27, 1
	s_mov_b32 m0, s51
	s_nop 0
	global_load_lds_dwordx4 v203, s[10:11]
	s_add_u32 s6, s16, s6
	s_addc_u32 s7, s17, 0
	v_mov_b32_e32 v3, 0
	v_lshl_or_b32 v205, v5, 3, s27
	s_ashr_i32 s27, s26, 31
	v_lshl_add_u64 v[180:181], s[6:7], 0, v[2:3]
	s_add_i32 s53, s38, 0xe000
	s_lshl_b64 s[6:7], s[26:27], 2
	s_add_u32 s6, s12, s6
	v_cmp_eq_u32_e64 s[10:11], 0, v5
	s_addc_u32 s7, s13, s7
	v_mov_b32_e32 v5, v3
	s_waitcnt vmcnt(6)
	v_lshl_add_u64 v[2:3], s[6:7], 0, v[4:5]
	s_mov_b64 s[6:7], 0x20800
	v_lshl_add_u64 v[182:183], v[2:3], 0, s[6:7]
	v_add_u32_e32 v2, 0, v6
	s_sext_i32_i8 s3, s3
	v_mov_b64_e32 v[184:185], 0x100
	v_mov_b64_e32 v[186:187], 0xff
	v_add_u32_e32 v206, 0x10000, v2
	v_add_u32_e32 v207, 0x14000, v2
	v_add_u32_e32 v208, 0, v7
	v_add_u32_e32 v209, 0x18000, v2
	v_add_u32_e32 v210, 0x1c000, v2
	s_barrier
	s_branch .LBB0_1306

; #define PG8_STAGE(bufoff, gbase, voff) do { _Pragma("unroll") for (int _i = 0; _i < 2; ++_i) { unsigned keep_; \
;         asm volatile("s_mov_b32 %0, m0\n\ts_mov_b32 m0, %3\n\ts_nop 0\n\tglobal_load_lds_dwordx4 %1, %2\n\ts_mov_b32 m0, %0" \
;             : "=&s"(keep_) : "v"((voff)[_i]), "s"((const void*)(gbase)), "s"(ldsb0 + (unsigned)(bufoff) + (unsigned)(_i * 8192)) : "memory"); } } while (0)
; #define PG8_LDA(dst, b, h) do { _Pragma("unroll") for (int m = 0; m < 4; ++m) _Pragma("unroll") for (int k = 0; k < 2; ++k) dst[m][k] = *(const LAS bf16x8*)(lds + PG8_SA(b, h) + aoff + m * 2048 + k * 1024); } while (0)
; #define PG8_LDB(dst, b, h) do { _Pragma("unroll") for (int n = 0; n < 2; ++n) _Pragma("unroll") for (int k = 0; k < 2; ++k) dst[n][k] = *(const LAS bf16x8*)(lds + PG8_SB(b, h) + boff + n * 2048 + k * 1024); } while (0)
; #define PG8_MMA(ai, bj, At, Bt) do { __builtin_amdgcn_s_setprio(1); _Pragma("unroll") for (int m = 0; m < 4; ++m) _Pragma("unroll") for (int n = 0; n < 2; ++n) _Pragma("unroll") for (int k = 0; k < 2; ++k) \
;         acc[ai][bj][m][n] = __builtin_amdgcn_mfma_f32_16x16x32_bf16(Bt[n][k], At[m][k], acc[ai][bj][m][n], 0, 0, 0); __builtin_amdgcn_s_setprio(0); } while (0)
; #define PG8_WAIT_V(n) asm volatile("s_waitcnt vmcnt(" #n ")" ::: "memory")
; #define PG8_BAR __builtin_amdgcn_s_barrier()
; template <class Epi, class Sched, bool ALIGN_EPI>
; __device__ __forceinline__ void gemm_phase(LAS unsigned char* lds, const Gemm g, const Sched& S, const Epi& E) {
;     ...
;         for (int t = 0; t < nt; t += 2) {
;             const bool last = (t == nt - 2);
;             const char* a1 = cA + (size_t)(t + 1) * kstep;
;             const char* a2 = last ? nA : cA + (size_t)(t + 2) * kstep; const char* b2 = last ? nB : cB + (size_t)(t + 2) * kstep;
;             const char* a3 = a2 + kstep; const char* b3 = b2 + kstep;
;             PG8_LDB(B0, 0, 0); PG8_LDB(B1, 0, 1); PG8_SCHED; PG8_LDA(At, 0, 0); PG8_STAGE(PG8_SA(1, 1), a1 + hstepA, voffA);
;             PG8_WAIT_V(8); PG8_WAIT_L(0); PG8_BAR; PG8_MMA(0, 0, At, B0); PG8_MMA(0, 1, At, B1); PG8_BAR; PG8_SCHED;
;             PG8_LDA(At, 0, 1); PG8_STAGE(PG8_SB(0, 0), b2, voffB); PG8_STAGE(PG8_SB(0, 1), b2 + hstepB, voffB); PG8_STAGE(PG8_SA(0, 0), a2, voffA);
;             PG8_WAIT_V(8); PG8_WAIT_L(0); PG8_BAR; PG8_MMA(1, 0, At, B0); PG8_MMA(1, 1, At, B1); PG8_BAR; PG8_SCHED;
.LBB0_1317:
	ds_read_b128 v[110:113], v206
	ds_read_b128 v[126:129], v206 offset:1024
	ds_read_b128 v[130:133], v206 offset:2048
	ds_read_b128 v[142:145], v206 offset:3072
	ds_read_b128 v[146:149], v207
	ds_read_b128 v[150:153], v207 offset:1024
	ds_read_b128 v[154:157], v207 offset:2048
	ds_read_b128 v[158:161], v207 offset:3072
	s_cmpk_eq_i32 s58, 0x54
	s_cselect_b32 s34, s14, s6
	s_cselect_b32 s35, s15, s7
	s_cselect_b32 s30, s26, s56
	s_cselect_b32 s31, s27, s57
	s_add_u32 s28, s34, 0x80
	s_addc_u32 s29, s35, 0
	ds_read_b128 v[162:165], v208
	ds_read_b128 v[166:169], v208 offset:1024
	ds_read_b128 v[170:173], v208 offset:2048
	ds_read_b128 v[174:177], v208 offset:3072
	ds_read_b128 v[188:191], v208 offset:4096
	ds_read_b128 v[192:195], v208 offset:5120
	ds_read_b128 v[196:199], v208 offset:6144
	ds_read_b128 v[212:215], v208 offset:7168
	s_mov_b32 m0, s52
	s_nop 0
	global_load_lds_dwordx4 v179, s[4:5]
	s_nop 0
	s_mov_b32 m0, s53
	s_nop 0
	global_load_lds_dwordx4 v201, s[4:5]
	s_waitcnt vmcnt(8)
	s_waitcnt lgkmcnt(0)
	s_barrier
	s_setprio 1
	v_mfma_f32_16x16x32_bf16 v[138:141], v[110:113], v[162:165], v[138:141]
	v_mfma_f32_16x16x32_bf16 v[134:137], v[130:133], v[162:165], v[134:137]
	v_mfma_f32_16x16x32_bf16 v[114:117], v[110:113], v[170:173], v[114:117]
	v_mfma_f32_16x16x32_bf16 v[106:109], v[130:133], v[170:173], v[106:109]
	v_mfma_f32_16x16x32_bf16 v[94:97], v[110:113], v[188:191], v[94:97]
	v_mfma_f32_16x16x32_bf16 v[90:93], v[130:133], v[188:191], v[90:93]
	v_mfma_f32_16x16x32_bf16 v[78:81], v[110:113], v[196:199], v[78:81]
	v_mfma_f32_16x16x32_bf16 v[74:77], v[130:133], v[196:199], v[74:77]
	v_mfma_f32_16x16x32_bf16 v[138:141], v[126:129], v[166:169], v[138:141]
	v_mfma_f32_16x16x32_bf16 v[134:137], v[142:145], v[166:169], v[134:137]
	v_mfma_f32_16x16x32_bf16 v[114:117], v[126:129], v[174:177], v[114:117]
	v_mfma_f32_16x16x32_bf16 v[106:109], v[142:145], v[174:177], v[106:109]
	v_mfma_f32_16x16x32_bf16 v[94:97], v[126:129], v[192:195], v[94:97]
	v_mfma_f32_16x16x32_bf16 v[90:93], v[142:145], v[192:195], v[90:93]
	v_mfma_f32_16x16x32_bf16 v[78:81], v[126:129], v[212:215], v[78:81]
	v_mfma_f32_16x16x32_bf16 v[74:77], v[142:145], v[212:215], v[74:77]
	v_mfma_f32_16x16x32_bf16 v[122:125], v[146:149], v[162:165], v[122:125]
	v_mfma_f32_16x16x32_bf16 v[118:121], v[154:157], v[162:165], v[118:121]
	v_mfma_f32_16x16x32_bf16 v[102:105], v[146:149], v[170:173], v[102:105]
	v_mfma_f32_16x16x32_bf16 v[98:101], v[154:157], v[170:173], v[98:101]
	v_mfma_f32_16x16x32_bf16 v[86:89], v[146:149], v[188:191], v[86:89]
	v_mfma_f32_16x16x32_bf16 v[82:85], v[154:157], v[188:191], v[82:85]
	v_mfma_f32_16x16x32_bf16 v[70:73], v[146:149], v[196:199], v[70:73]
	v_mfma_f32_16x16x32_bf16 v[66:69], v[154:157], v[196:199], v[66:69]
	v_mfma_f32_16x16x32_bf16 v[122:125], v[150:153], v[166:169], v[122:125]
	v_mfma_f32_16x16x32_bf16 v[118:121], v[158:161], v[166:169], v[118:121]
	v_mfma_f32_16x16x32_bf16 v[102:105], v[150:153], v[174:177], v[102:105]
	v_mfma_f32_16x16x32_bf16 v[98:101], v[158:161], v[174:177], v[98:101]
	v_mfma_f32_16x16x32_bf16 v[86:89], v[150:153], v[192:195], v[86:89]
	v_mfma_f32_16x16x32_bf16 v[82:85], v[158:161], v[192:195], v[82:85]
	v_mfma_f32_16x16x32_bf16 v[70:73], v[150:153], v[212:215], v[70:73]
	v_mfma_f32_16x16x32_bf16 v[66:69], v[158:161], v[212:215], v[66:69]
	s_setprio 0
	s_barrier
	ds_read_b128 v[162:165], v208 offset:16384
	ds_read_b128 v[166:169], v208 offset:17408
	ds_read_b128 v[170:173], v208 offset:18432
	ds_read_b128 v[174:177], v208 offset:19456
	ds_read_b128 v[188:191], v208 offset:20480
	ds_read_b128 v[192:195], v208 offset:21504
	ds_read_b128 v[196:199], v208 offset:22528
	ds_read_b128 v[212:215], v208 offset:23552
	s_mov_b32 m0, s39
	s_nop 0
	global_load_lds_dwordx4 v200, s[30:31]
	s_add_u32 s62, s30, 0x160000
	s_mov_b32 m0, s40
	s_nop 0
	global_load_lds_dwordx4 v203, s[30:31]
	s_addc_u32 s63, s31, 0
	s_mov_b32 m0, s41
	s_nop 0
	global_load_lds_dwordx4 v200, s[62:63]
	s_nop 0
	s_mov_b32 m0, s42
	s_nop 0
	global_load_lds_dwordx4 v203, s[62:63]
	s_nop 0
	s_mov_b32 m0, s38
	s_nop 0
	global_load_lds_dwordx4 v179, s[34:35]
	s_nop 0
	s_mov_b32 m0, s43
	s_nop 0
	global_load_lds_dwordx4 v201, s[34:35]
	s_waitcnt vmcnt(8)
	s_waitcnt lgkmcnt(0)
	s_barrier
	s_setprio 1
	v_mfma_f32_16x16x32_bf16 v[62:65], v[110:113], v[162:165], v[62:65]
	v_mfma_f32_16x16x32_bf16 v[58:61], v[130:133], v[162:165], v[58:61]
	v_mfma_f32_16x16x32_bf16 v[46:49], v[110:113], v[170:173], v[46:49]
	v_mfma_f32_16x16x32_bf16 v[42:45], v[130:133], v[170:173], v[42:45]
	v_mfma_f32_16x16x32_bf16 v[30:33], v[110:113], v[188:191], v[30:33]
	v_mfma_f32_16x16x32_bf16 v[26:29], v[130:133], v[188:191], v[26:29]
	v_mfma_f32_16x16x32_bf16 v[14:17], v[110:113], v[196:199], v[14:17]
	v_mfma_f32_16x16x32_bf16 v[10:13], v[130:133], v[196:199], v[10:13]
	v_mfma_f32_16x16x32_bf16 v[62:65], v[126:129], v[166:169], v[62:65]
	v_mfma_f32_16x16x32_bf16 v[58:61], v[142:145], v[166:169], v[58:61]
	v_mfma_f32_16x16x32_bf16 v[46:49], v[126:129], v[174:177], v[46:49]
	v_mfma_f32_16x16x32_bf16 v[42:45], v[142:145], v[174:177], v[42:45]
	v_mfma_f32_16x16x32_bf16 v[30:33], v[126:129], v[192:195], v[30:33]
	v_mfma_f32_16x16x32_bf16 v[26:29], v[142:145], v[192:195], v[26:29]
	v_mfma_f32_16x16x32_bf16 v[14:17], v[126:129], v[212:215], v[14:17]
	v_mfma_f32_16x16x32_bf16 v[10:13], v[142:145], v[212:215], v[10:13]
	v_mfma_f32_16x16x32_bf16 v[54:57], v[146:149], v[162:165], v[54:57]
	v_mfma_f32_16x16x32_bf16 v[50:53], v[154:157], v[162:165], v[50:53]
	v_mfma_f32_16x16x32_bf16 v[38:41], v[146:149], v[170:173], v[38:41]
	v_mfma_f32_16x16x32_bf16 v[34:37], v[154:157], v[170:173], v[34:37]
	v_mfma_f32_16x16x32_bf16 v[22:25], v[146:149], v[188:191], v[22:25]
	v_mfma_f32_16x16x32_bf16 v[18:21], v[154:157], v[188:191], v[18:21]
	v_mfma_f32_16x16x32_bf16 v[6:9], v[146:149], v[196:199], v[6:9]
	v_mfma_f32_16x16x32_bf16 v[2:5], v[154:157], v[196:199], v[2:5]
	v_mfma_f32_16x16x32_bf16 v[54:57], v[150:153], v[166:169], v[54:57]
	v_mfma_f32_16x16x32_bf16 v[50:53], v[158:161], v[166:169], v[50:53]
	v_mfma_f32_16x16x32_bf16 v[38:41], v[150:153], v[174:177], v[38:41]
	v_mfma_f32_16x16x32_bf16 v[34:37], v[158:161], v[174:177], v[34:37]
	v_mfma_f32_16x16x32_bf16 v[22:25], v[150:153], v[192:195], v[22:25]
	v_mfma_f32_16x16x32_bf16 v[18:21], v[158:161], v[192:195], v[18:21]
	v_mfma_f32_16x16x32_bf16 v[6:9], v[150:153], v[212:215], v[6:9]
	v_mfma_f32_16x16x32_bf16 v[2:5], v[158:161], v[212:215], v[2:5]
	s_setprio 0
	s_barrier
; #define PG8_STAGE(bufoff, gbase, voff) do { _Pragma("unroll") for (int _i = 0; _i < 2; ++_i) { unsigned keep_; \
;         asm volatile("s_mov_b32 %0, m0\n\ts_mov_b32 m0, %3\n\ts_nop 0\n\tglobal_load_lds_dwordx4 %1, %2\n\ts_mov_b32 m0, %0" \
;             : "=&s"(keep_) : "v"((voff)[_i]), "s"((const void*)(gbase)), "s"(ldsb0 + (unsigned)(bufoff) + (unsigned)(_i * 8192)) : "memory"); } } while (0)
; #define PG8_LDA(dst, b, h) do { _Pragma("unroll") for (int m = 0; m < 4; ++m) _Pragma("unroll") for (int k = 0; k < 2; ++k) dst[m][k] = *(const LAS bf16x8*)(lds + PG8_SA(b, h) + aoff + m * 2048 + k * 1024); } while (0)
; #define PG8_LDB(dst, b, h) do { _Pragma("unroll") for (int n = 0; n < 2; ++n) _Pragma("unroll") for (int k = 0; k < 2; ++k) dst[n][k] = *(const LAS bf16x8*)(lds + PG8_SB(b, h) + boff + n * 2048 + k * 1024); } while (0)
; #define PG8_MMA(ai, bj, At, Bt) do { __builtin_amdgcn_s_setprio(1); _Pragma("unroll") for (int m = 0; m < 4; ++m) _Pragma("unroll") for (int n = 0; n < 2; ++n) _Pragma("unroll") for (int k = 0; k < 2; ++k) \
;         acc[ai][bj][m][n] = __builtin_amdgcn_mfma_f32_16x16x32_bf16(Bt[n][k], At[m][k], acc[ai][bj][m][n], 0, 0, 0); __builtin_amdgcn_s_setprio(0); } while (0)
; #define PG8_WAIT_V(n) asm volatile("s_waitcnt vmcnt(" #n ")" ::: "memory")
; #define PG8_WAIT_L(n) asm volatile("s_waitcnt lgkmcnt(" #n ")" ::: "memory")
; #define PG8_BAR __builtin_amdgcn_s_barrier()
; #define PG8_SCHED __builtin_amdgcn_sched_barrier(0)
; template <class Epi, class Sched, bool ALIGN_EPI>
; __device__ __forceinline__ void gemm_phase(LAS unsigned char* lds, const Gemm g, const Sched& S, const Epi& E) {
;     ...
;             PG8_LDB(B0, 1, 0); PG8_LDB(B1, 1, 1); PG8_SCHED; PG8_LDA(At, 1, 0); PG8_STAGE(PG8_SA(0, 1), a2 + hstepA, voffA);
;             PG8_WAIT_V(8); PG8_WAIT_L(0); PG8_BAR; PG8_MMA(0, 0, At, B0); PG8_MMA(0, 1, At, B1); PG8_BAR; PG8_SCHED;
;             PG8_LDA(At, 1, 1); PG8_STAGE(PG8_SB(1, 0), b3, voffB); PG8_STAGE(PG8_SB(1, 1), b3 + hstepB, voffB); PG8_STAGE(PG8_SA(1, 0), a3, voffA);
;             PG8_WAIT_V(8); PG8_WAIT_L(0); PG8_BAR; PG8_MMA(1, 0, At, B0); PG8_MMA(1, 1, At, B1); PG8_BAR; PG8_SCHED;
;         }
	ds_read_b128 v[110:113], v209
	ds_read_b128 v[126:129], v209 offset:1024
	ds_read_b128 v[130:133], v209 offset:2048
	ds_read_b128 v[142:145], v209 offset:3072
	ds_read_b128 v[146:149], v210
	ds_read_b128 v[150:153], v210 offset:1024
	ds_read_b128 v[154:157], v210 offset:2048
	ds_read_b128 v[158:161], v210 offset:3072
	ds_read_b128 v[162:165], v208 offset:32768
	ds_read_b128 v[166:169], v208 offset:33792
	ds_read_b128 v[170:173], v208 offset:34816
	ds_read_b128 v[174:177], v208 offset:35840
	ds_read_b128 v[188:191], v208 offset:36864
	ds_read_b128 v[192:195], v208 offset:37888
	ds_read_b128 v[196:199], v208 offset:38912
	ds_read_b128 v[212:215], v208 offset:39936
	s_add_u32 s34, s34, 0x160000
	s_addc_u32 s35, s35, 0
	s_mov_b32 m0, s44
	s_nop 0
	global_load_lds_dwordx4 v179, s[34:35]
	s_nop 0
	s_mov_b32 m0, s45
	s_nop 0
	global_load_lds_dwordx4 v201, s[34:35]
	s_waitcnt vmcnt(8)
	s_waitcnt lgkmcnt(0)
	s_barrier
	s_setprio 1
	v_mfma_f32_16x16x32_bf16 v[138:141], v[110:113], v[162:165], v[138:141]
	v_mfma_f32_16x16x32_bf16 v[134:137], v[130:133], v[162:165], v[134:137]
	v_mfma_f32_16x16x32_bf16 v[114:117], v[110:113], v[170:173], v[114:117]
	v_mfma_f32_16x16x32_bf16 v[106:109], v[130:133], v[170:173], v[106:109]
	v_mfma_f32_16x16x32_bf16 v[94:97], v[110:113], v[188:191], v[94:97]
	v_mfma_f32_16x16x32_bf16 v[90:93], v[130:133], v[188:191], v[90:93]
	v_mfma_f32_16x16x32_bf16 v[78:81], v[110:113], v[196:199], v[78:81]
	v_mfma_f32_16x16x32_bf16 v[74:77], v[130:133], v[196:199], v[74:77]
	v_mfma_f32_16x16x32_bf16 v[138:141], v[126:129], v[166:169], v[138:141]
	v_mfma_f32_16x16x32_bf16 v[134:137], v[142:145], v[166:169], v[134:137]
	v_mfma_f32_16x16x32_bf16 v[114:117], v[126:129], v[174:177], v[114:117]
	v_mfma_f32_16x16x32_bf16 v[106:109], v[142:145], v[174:177], v[106:109]
	v_mfma_f32_16x16x32_bf16 v[94:97], v[126:129], v[192:195], v[94:97]
	v_mfma_f32_16x16x32_bf16 v[90:93], v[142:145], v[192:195], v[90:93]
	v_mfma_f32_16x16x32_bf16 v[78:81], v[126:129], v[212:215], v[78:81]
	v_mfma_f32_16x16x32_bf16 v[74:77], v[142:145], v[212:215], v[74:77]
	v_mfma_f32_16x16x32_bf16 v[122:125], v[146:149], v[162:165], v[122:125]
	v_mfma_f32_16x16x32_bf16 v[118:121], v[154:157], v[162:165], v[118:121]
	v_mfma_f32_16x16x32_bf16 v[102:105], v[146:149], v[170:173], v[102:105]
	v_mfma_f32_16x16x32_bf16 v[98:101], v[154:157], v[170:173], v[98:101]
	v_mfma_f32_16x16x32_bf16 v[86:89], v[146:149], v[188:191], v[86:89]
	v_mfma_f32_16x16x32_bf16 v[82:85], v[154:157], v[188:191], v[82:85]
	v_mfma_f32_16x16x32_bf16 v[70:73], v[146:149], v[196:199], v[70:73]
	v_mfma_f32_16x16x32_bf16 v[66:69], v[154:157], v[196:199], v[66:69]
	v_mfma_f32_16x16x32_bf16 v[122:125], v[150:153], v[166:169], v[122:125]
	v_mfma_f32_16x16x32_bf16 v[118:121], v[158:161], v[166:169], v[118:121]
	v_mfma_f32_16x16x32_bf16 v[102:105], v[150:153], v[174:177], v[102:105]
	v_mfma_f32_16x16x32_bf16 v[98:101], v[158:161], v[174:177], v[98:101]
	v_mfma_f32_16x16x32_bf16 v[86:89], v[150:153], v[192:195], v[86:89]
	v_mfma_f32_16x16x32_bf16 v[82:85], v[158:161], v[192:195], v[82:85]
	v_mfma_f32_16x16x32_bf16 v[70:73], v[150:153], v[212:215], v[70:73]
	v_mfma_f32_16x16x32_bf16 v[66:69], v[158:161], v[212:215], v[66:69]
	s_setprio 0
	s_barrier
	ds_read_b128 v[162:165], v208 offset:49152
	ds_read_b128 v[166:169], v208 offset:50176
	ds_read_b128 v[170:173], v208 offset:51200
	ds_read_b128 v[174:177], v208 offset:52224
	ds_read_b128 v[188:191], v208 offset:53248
	ds_read_b128 v[192:195], v208 offset:54272
	ds_read_b128 v[196:199], v208 offset:55296
	ds_read_b128 v[212:215], v208 offset:56320
	s_add_u32 s34, s30, 0x80
	s_addc_u32 s35, s31, 0
	s_mov_b32 m0, s46
	s_nop 0
	global_load_lds_dwordx4 v200, s[34:35]
	s_add_u32 s30, s30, 0x160080
	s_mov_b32 m0, s47
	s_nop 0
	global_load_lds_dwordx4 v203, s[34:35]
	s_addc_u32 s31, s31, 0
	s_mov_b32 m0, s50
	s_nop 0
	global_load_lds_dwordx4 v200, s[30:31]
	s_nop 0
	s_mov_b32 m0, s51
	s_nop 0
	global_load_lds_dwordx4 v203, s[30:31]
	s_mov_b32 m0, s48
	s_nop 0
	global_load_lds_dwordx4 v179, s[28:29]
	s_nop 0
	s_mov_b32 m0, s49
	s_nop 0
	global_load_lds_dwordx4 v201, s[28:29]
	s_waitcnt vmcnt(8)
	s_waitcnt lgkmcnt(0)
	s_barrier
	s_setprio 1
	v_mfma_f32_16x16x32_bf16 v[62:65], v[110:113], v[162:165], v[62:65]
	v_mfma_f32_16x16x32_bf16 v[58:61], v[130:133], v[162:165], v[58:61]
	v_mfma_f32_16x16x32_bf16 v[46:49], v[110:113], v[170:173], v[46:49]
	v_mfma_f32_16x16x32_bf16 v[42:45], v[130:133], v[170:173], v[42:45]
	v_mfma_f32_16x16x32_bf16 v[30:33], v[110:113], v[188:191], v[30:33]
	v_mfma_f32_16x16x32_bf16 v[26:29], v[130:133], v[188:191], v[26:29]
	v_mfma_f32_16x16x32_bf16 v[14:17], v[110:113], v[196:199], v[14:17]
	v_mfma_f32_16x16x32_bf16 v[10:13], v[130:133], v[196:199], v[10:13]
	v_mfma_f32_16x16x32_bf16 v[62:65], v[126:129], v[166:169], v[62:65]
	v_mfma_f32_16x16x32_bf16 v[58:61], v[142:145], v[166:169], v[58:61]
	v_mfma_f32_16x16x32_bf16 v[46:49], v[126:129], v[174:177], v[46:49]
	v_mfma_f32_16x16x32_bf16 v[42:45], v[142:145], v[174:177], v[42:45]
	v_mfma_f32_16x16x32_bf16 v[30:33], v[126:129], v[192:195], v[30:33]
	v_mfma_f32_16x16x32_bf16 v[26:29], v[142:145], v[192:195], v[26:29]
	v_mfma_f32_16x16x32_bf16 v[14:17], v[126:129], v[212:215], v[14:17]
	v_mfma_f32_16x16x32_bf16 v[10:13], v[142:145], v[212:215], v[10:13]
	v_mfma_f32_16x16x32_bf16 v[54:57], v[146:149], v[162:165], v[54:57]
	v_mfma_f32_16x16x32_bf16 v[50:53], v[154:157], v[162:165], v[50:53]
	v_mfma_f32_16x16x32_bf16 v[38:41], v[146:149], v[170:173], v[38:41]
	v_mfma_f32_16x16x32_bf16 v[34:37], v[154:157], v[170:173], v[34:37]
	v_mfma_f32_16x16x32_bf16 v[22:25], v[146:149], v[188:191], v[22:25]
	v_mfma_f32_16x16x32_bf16 v[18:21], v[154:157], v[188:191], v[18:21]
	v_mfma_f32_16x16x32_bf16 v[6:9], v[146:149], v[196:199], v[6:9]
	v_mfma_f32_16x16x32_bf16 v[2:5], v[154:157], v[196:199], v[2:5]
	v_mfma_f32_16x16x32_bf16 v[54:57], v[150:153], v[166:169], v[54:57]
	v_mfma_f32_16x16x32_bf16 v[50:53], v[158:161], v[166:169], v[50:53]
	v_mfma_f32_16x16x32_bf16 v[38:41], v[150:153], v[174:177], v[38:41]
	v_mfma_f32_16x16x32_bf16 v[34:37], v[158:161], v[174:177], v[34:37]
	v_mfma_f32_16x16x32_bf16 v[22:25], v[150:153], v[192:195], v[22:25]
	v_mfma_f32_16x16x32_bf16 v[18:21], v[158:161], v[192:195], v[18:21]
	v_mfma_f32_16x16x32_bf16 v[6:9], v[150:153], v[212:215], v[6:9]
	v_mfma_f32_16x16x32_bf16 v[2:5], v[158:161], v[212:215], v[2:5]
	s_setprio 0
	s_barrier
	s_add_i32 s58, s58, 2
	s_add_u32 s6, s6, 0x100
	s_addc_u32 s7, s7, 0
	s_add_u32 s56, s56, 0x100
	s_addc_u32 s57, s57, 0
	s_add_u32 s4, s4, 0x100
	s_addc_u32 s5, s5, 0
	s_cmpk_gt_u32 s58, 0x55
	s_cbranch_scc0 .LBB0_1317
	s_and_b64 vcc, exec, s[18:19]
	s_cbranch_vccz .LBB0_1320
	s_barrier

; #define LAS __attribute__((address_space(3)))
; #define PG8_BAR __builtin_amdgcn_s_barrier()
;     __device__ bool next(int i, Unit& u) const {
;         if (G == 256) { if (i >= R) return false; const int xcd = c & 7, r = c >> 3; u.pm = (xcd >> 1) * 8 + (r & 7); u.pn = (2 * i + (xcd & 1)) * 4 + (r >> 3); return true; }
;         const int L = i * G + c; if (L >= 32 * 8 * R) return false; u.pm = L & 31; u.pn = L >> 5; return true;
;     }
; template <class Epi, class Sched, bool ALIGN_EPI>
; __device__ __forceinline__ void gemm_phase(LAS unsigned char* lds, const Gemm g, const Sched& S, const Epi& E) {
;     const int tid = otid(), wid = __builtin_amdgcn_readfirstlane(tid >> 6), lane = tid & 63, wr = wid >> 2, wc = wid & 3, fr = lane & 15, fq = lane >> 4;
;     const int K = g.K, nt = K / BK;
;     unsigned voffA[2], voffB[2];
; #pragma unroll
;     for (int i = 0; i < 2; ++i) { int R, C; stage_rc(tid * 16 + i * 8192, R, C); const int Rb = (R & ~31) + perm32(R & 31);
;         voffA[i] = (unsigned)(R * g.lda + C) * 2u; voffB[i] = (unsigned)(Rb * g.ldb + C) * 2u; }
;     const size_t kstep = (size_t)(BK * 2);
;     const size_t hstepA = (size_t)HALF * g.lda * 2, hstepB = (size_t)HALF * g.ldb * 2;
;     const size_t tstepA = 2 * hstepA, tstepB = 2 * hstepB;
;     const unsigned ldsw = (unsigned)wid * 1024u;
;     const int aoff = lds_byte(wr * 64 + fr, fq * 8), boff = lds_byte(wc * 32 + fr, fq * 8);
;     ...
;     const unsigned ldsb0 = (unsigned)(uintptr_t)lds + ldsw;
;     ...
;     Unit cur, nxt; int ui = 0;
;     if (!S.next(0, cur)) return;
;     f32x4 acc[2][2][4][2];
; #pragma unroll
;     for (int a = 0; a < 2; ++a)
; #pragma unroll
;         for (int b = 0; b < 2; ++b)
; #pragma unroll
;             for (int m = 0; m < 4; ++m)
; #pragma unroll
;                 for (int n = 0; n < 2; ++n) acc[a][b][m][n] = (f32x4){0.f, 0.f, 0.f, 0.f};
;     bf16x8 At[4][2], B0[2][2], B1[2][2];
;     float pre[Epi::NPRE > 0 ? Epi::NPRE : 1];
;     if constexpr (Epi::NPRE > 0) E.preload(cur, wr, fr, pre);
;     const char* cA = (const char*)g.A + (size_t)cur.pm * tstepA + (size_t)cur.pn * g.a_koff * 2; const char* cB = (const char*)g.Bt + (size_t)cur.pn * tstepB;
;     PG8_STAGE(PG8_SB(0, 0), cB, voffB); PG8_STAGE(PG8_SB(0, 1), cB + hstepB, voffB); PG8_STAGE(PG8_SA(0, 0), cA, voffA); PG8_STAGE(PG8_SA(0, 1), cA + hstepA, voffA);
;     if (wr == 1) PG8_BAR;
;     PG8_WAIT_V(2); PG8_BAR;
.LBB0_1395:
	s_or_b64 exec, exec, s[4:5]
	s_cmpk_lt_i32 s94, 0x300
	v_readlane_b32 s18, v242, 10
	s_cselect_b64 s[6:7], -1, 0
	v_readlane_b32 s19, v242, 11
	s_mov_b64 s[12:13], s[0:1]
	s_mov_b64 s[14:15], s[0:1]
	s_mov_b64 s[16:17], s[0:1]
	s_mov_b64 s[8:9], s[0:1]
	s_mov_b64 s[26:27], s[0:1]
	s_mov_b64 s[4:5], s[0:1]
	s_mov_b64 s[10:11], s[0:1]
	s_mov_b64 s[30:31], s[0:1]
	s_waitcnt lgkmcnt(0)
	v_mov_b32_e32 v2, v0
	s_or_b64 s[6:7], s[18:19], s[6:7]
	s_barrier
	s_and_b64 vcc, exec, s[6:7]
	v_readfirstlane_b32 s2, v2
	s_cbranch_vccz .LBB0_1544
	v_bfe_i32 v4, v2, 27, 1
	v_lshlrev_b32_e32 v6, 4, v2
	v_lshrrev_b32_e32 v4, 22, v4
	v_add_u32_e32 v4, v6, v4
	v_and_b32_e32 v4, 0xfffffc00, v4
	v_sub_u32_e32 v4, v6, v4
	s_load_dwordx2 s[6:7], s[12:13], 0xb0
	s_nop 0
	s_load_dwordx2 s[14:15], s[14:15], 0xb0
	s_nop 0
	s_load_dwordx2 s[16:17], s[16:17], 0xb0
	s_nop 0
	s_load_dwordx2 s[18:19], s[8:9], 0xb0
	s_load_dwordx2 s[12:13], s[26:27], 0xb0
	v_ashrrev_i32_e32 v3, 31, v2
	v_lshrrev_b32_e32 v5, 4, v4
	s_waitcnt lgkmcnt(0)
	s_add_u32 s48, s6, 0x1d800000
	v_lshrrev_b32_e32 v3, 26, v3
	v_bitop3_b32 v5, v5, v4, 32 bitop3:0x6c
	v_ashrrev_i32_e32 v4, 31, v4
	s_addc_u32 s49, s7, 0
	v_add_u32_e32 v3, v2, v3
	v_lshrrev_b32_e32 v4, 26, v4
	s_add_u32 s50, s14, 0x5d00000
	v_ashrrev_i32_e32 v3, 6, v3
	v_add_u32_e32 v4, v5, v4
	s_addc_u32 s51, s15, 0
	v_lshlrev_b32_e32 v7, 3, v3
	v_ashrrev_i32_e32 v8, 6, v4
	v_lshlrev_b32_e32 v3, 5, v3
	s_add_u32 s14, s16, 0x20800
	v_and_b32_e32 v9, 32, v3
	v_mul_i32_i24_e32 v3, 64, v8
	s_addc_u32 s15, s17, 0
	s_ashr_i32 s6, s2, 8
	v_sub_u32_e32 v3, v5, v3
	v_mov_b32_e32 v10, 1
	v_ashrrev_i16_sdwa v3, v10, sext(v3) dst_sel:DWORD dst_unused:UNUSED_PAD src0_sel:DWORD src1_sel:BYTE_0
	s_lshl_b32 s7, s6, 6
	s_lshl_b32 s3, s60, 8
	v_bfe_i32 v11, v3, 0, 16
	v_and_b32_e32 v3, 15, v2
	s_add_i32 s3, s3, s7
	v_or_b32_e32 v4, s3, v3
	v_ashrrev_i32_e32 v5, 31, v4
	v_lshl_add_u64 v[4:5], v[4:5], 2, s[14:15]
	s_load_dwordx2 s[26:27], s[4:5], 0xb0
	s_load_dwordx2 s[28:29], s[10:11], 0xa8
	s_nop 0
	s_load_dwordx2 s[10:11], s[30:31], 0xa8
	global_load_dword v130, v[4:5], off
	global_load_dword v159, v[4:5], off offset:64
	global_load_dword v158, v[4:5], off offset:128
	global_load_dword v156, v[4:5], off offset:192
	global_load_dword v155, v[4:5], off offset:512
	global_load_dword v154, v[4:5], off offset:576
	global_load_dword v153, v[4:5], off offset:640
	global_load_dword v152, v[4:5], off offset:704
	v_and_b32_e32 v7, -16, v7
	v_add_u32_e32 v7, v8, v7
	v_lshlrev_b32_e32 v4, 1, v7
	v_lshrrev_b32_e32 v5, 2, v7
	v_and_b32_e32 v8, 3, v8
	s_mov_b32 s3, 0xfffe0
	v_and_b32_e32 v4, 24, v4
	v_and_b32_e32 v5, 4, v5
	v_and_or_b32 v8, v7, s3, v8
	v_or3_b32 v4, v8, v5, v4
	v_add_lshl_u32 v5, v9, v11, 1
	s_waitcnt vmcnt(9)
	v_lshl_add_u32 v141, v4, 12, v5
	v_add_u32_e32 v4, 0x2000, v6
	v_lshl_add_u32 v140, v7, 12, v5
	v_ashrrev_i32_e32 v5, 31, v4
	v_lshrrev_b32_e32 v5, 22, v5
	v_add_u32_e32 v5, v4, v5
	v_ashrrev_i32_e32 v5, 10, v5
	v_mul_i32_i24_e32 v6, 0x400, v5
	v_sub_u32_e32 v4, v4, v6
	v_lshrrev_b32_e32 v6, 4, v4
	v_bitop3_b32 v4, v6, v4, 32 bitop3:0x6c
	v_ashrrev_i32_e32 v7, 31, v4
	v_lshrrev_b32_e32 v7, 26, v7
	v_lshlrev_b32_e32 v6, 3, v5
	v_add_u32_e32 v7, v4, v7
	v_and_b32_e32 v6, -16, v6
	v_ashrrev_i32_e32 v8, 6, v7
	v_and_b32_e32 v7, 0xc0, v7
	s_ashr_i32 s34, s2, 6
	v_add_u32_e32 v6, v8, v6
	v_sub_u32_e32 v4, v4, v7
	s_lshl_b32 s4, s34, 10
	s_ashr_i32 s23, s22, 31
	v_lshlrev_b32_e32 v5, 5, v5
	v_ashrrev_i16_sdwa v4, v10, sext(v4) dst_sel:DWORD dst_unused:UNUSED_PAD src0_sel:DWORD src1_sel:BYTE_0
	v_lshlrev_b32_e32 v7, 1, v6
	v_lshrrev_b32_e32 v9, 2, v6
	v_and_b32_e32 v8, 3, v8
	s_add_i32 s52, s4, 0
	s_lshl_b32 s16, s60, 20
	s_lshl_b64 s[4:5], s[22:23], 20
	v_and_b32_e32 v5, 32, v5
	v_bfe_i32 v4, v4, 0, 16
	v_and_b32_e32 v7, 24, v7
	v_and_b32_e32 v9, 4, v9
	v_and_or_b32 v8, v6, s3, v8
	s_add_u32 s8, s50, s4
	v_or3_b32 v7, v8, v9, v7
	v_add_lshl_u32 v4, v5, v4, 1
	s_addc_u32 s9, s51, s5
	s_add_i32 s53, s52, 0x10000
	s_mov_b32 m0, s53
	s_nop 0
	global_load_lds_dwordx4 v141, s[8:9]
	v_lshl_add_u32 v143, v7, 12, v4
	s_add_i32 s54, s52, 0x12000
	s_mov_b32 m0, s54
	s_nop 0
	global_load_lds_dwordx4 v143, s[8:9]
	s_add_u32 s4, s8, 0x80000
	s_addc_u32 s5, s9, 0
	s_add_i32 s55, s52, 0x14000
	s_mov_b32 m0, s55
	s_nop 0
	global_load_lds_dwordx4 v141, s[4:5]
	s_add_i32 s56, s52, 0x16000
	s_mov_b32 m0, s56
	s_nop 0
	global_load_lds_dwordx4 v143, s[4:5]
	s_add_u32 s4, s48, s16
	s_addc_u32 s5, s49, 0
	s_mov_b32 m0, s52
	s_nop 0
	global_load_lds_dwordx4 v140, s[4:5]
	s_add_i32 s57, s52, 0x2000
	v_lshl_add_u32 v142, v6, 12, v4
	s_mov_b32 m0, s57
	s_nop 0
	global_load_lds_dwordx4 v142, s[4:5]
	s_add_u32 s24, s4, 0x80000
	s_addc_u32 s25, s5, 0
	s_add_i32 s59, s52, 0x4000
	s_mov_b32 m0, s59
	s_nop 0
	global_load_lds_dwordx4 v140, s[24:25]
	s_add_i32 s61, s52, 0x6000
	s_mov_b32 m0, s61
	s_nop 0
	global_load_lds_dwordx4 v142, s[24:25]
	s_cmp_eq_u32 s6, 1
	s_mov_b32 s3, 0
	s_cselect_b64 s[16:17], -1, 0
	s_cmp_lg_u32 s6, 1
	s_cbranch_scc1 .LBB0_1398
	s_barrier
.LBB0_1398:
	s_add_u32 s18, s18, 0x10100000
	s_addc_u32 s19, s19, 0
	s_add_u32 s24, s12, 0x12200000
	s_addc_u32 s25, s13, 0
	s_waitcnt lgkmcnt(0)
	s_add_u32 s26, s26, 0x14300000
	s_addc_u32 s27, s27, 0
	s_add_u32 s28, s28, 0x814f000
	v_lshrrev_b32_e32 v2, 1, v2
	s_addc_u32 s29, s29, 0
	s_waitcnt vmcnt(8)
	v_or_b32_e32 v144, s7, v3
	v_and_b32_e32 v2, 24, v2
	s_add_u32 s30, s10, 0xc14f000
	v_lshlrev_b32_e32 v4, 6, v144
	v_lshlrev_b32_e32 v5, 1, v2
	s_movk_i32 s7, 0x3c0
	v_lshlrev_b32_e32 v6, 2, v144
	s_addc_u32 s31, s11, 0
	v_and_or_b32 v4, v4, s7, v5
	s_lshl_b32 s6, s6, 13
	v_and_b32_e32 v6, 32, v6
	v_bitop3_b32 v4, v4, s6, v6 bitop3:0xde
	s_lshl_b32 s6, s34, 5
	s_and_b32 s10, s6, 0x60
	v_lshl_or_b32 v5, v3, 6, v5
	v_lshlrev_b32_e32 v3, 2, v3
	s_lshl_b32 s6, s10, 7
	v_and_b32_e32 v3, 32, v3
	v_bitop3_b32 v3, v5, s6, v3 bitop3:0xde
	s_add_u32 s6, s8, 0x80
	s_waitcnt vmcnt(2)
	s_barrier
	s_addc_u32 s7, s9, 0
	s_add_i32 s62, s52, 0x18000
	s_mov_b32 m0, s62
	s_nop 0
	global_load_lds_dwordx4 v141, s[6:7]
	s_add_i32 s63, s52, 0x1a000
	s_mov_b32 m0, s63
	s_nop 0
	global_load_lds_dwordx4 v143, s[6:7]
	s_add_u32 s6, s4, 0x80
	s_addc_u32 s7, s5, 0
	s_add_i32 s64, s52, 0x8000
	s_mov_b32 m0, s64
	s_nop 0
	global_load_lds_dwordx4 v140, s[6:7]
	s_add_i32 s65, s52, 0xa000
	s_mov_b32 m0, s65
	s_nop 0
	global_load_lds_dwordx4 v142, s[6:7]
	s_add_u32 s6, s8, 0x80080
	s_addc_u32 s7, s9, 0
	s_add_i32 s66, s52, 0x1c000
	s_mov_b32 m0, s66
	s_nop 0
	global_load_lds_dwordx4 v141, s[6:7]
	s_add_i32 s67, s52, 0x1e000
	s_mov_b32 m0, s67
	s_nop 0
	global_load_lds_dwordx4 v143, s[6:7]
	s_waitcnt vmcnt(6)
	s_add_i32 s68, s52, 0xc000
	s_cmpk_lt_u32 s2, 0x100
	v_or_b32_e32 v145, s10, v2
	v_add_u32_e32 v2, 0, v3
	s_cselect_b64 s[34:35], -1, 0
	s_add_i32 s69, s52, 0xe000
	v_add_u32_e32 v146, 0x10000, v2
	v_add_u32_e32 v147, 0x14000, v2
	v_add_u32_e32 v148, 0, v4
	v_add_u32_e32 v149, 0x18000, v2
	v_add_u32_e32 v150, 0x1c000, v2
	v_mov_b32_e32 v151, 0x358637bd
	v_mov_b32_e32 v131, 0
	s_barrier
	s_branch .LBB0_1401

; #define PG8_STAGE(bufoff, gbase, voff) do { _Pragma("unroll") for (int _i = 0; _i < 2; ++_i) { unsigned keep_; \
;         asm volatile("s_mov_b32 %0, m0\n\ts_mov_b32 m0, %3\n\ts_nop 0\n\tglobal_load_lds_dwordx4 %1, %2\n\ts_mov_b32 m0, %0" \
;             : "=&s"(keep_) : "v"((voff)[_i]), "s"((const void*)(gbase)), "s"(ldsb0 + (unsigned)(bufoff) + (unsigned)(_i * 8192)) : "memory"); } } while (0)
; #define PG8_LDA(dst, b, h) do { _Pragma("unroll") for (int m = 0; m < 4; ++m) _Pragma("unroll") for (int k = 0; k < 2; ++k) dst[m][k] = *(const LAS bf16x8*)(lds + PG8_SA(b, h) + aoff + m * 2048 + k * 1024); } while (0)
; #define PG8_LDB(dst, b, h) do { _Pragma("unroll") for (int n = 0; n < 2; ++n) _Pragma("unroll") for (int k = 0; k < 2; ++k) dst[n][k] = *(const LAS bf16x8*)(lds + PG8_SB(b, h) + boff + n * 2048 + k * 1024); } while (0)
; #define PG8_MMA(ai, bj, At, Bt) do { __builtin_amdgcn_s_setprio(1); _Pragma("unroll") for (int m = 0; m < 4; ++m) _Pragma("unroll") for (int n = 0; n < 2; ++n) _Pragma("unroll") for (int k = 0; k < 2; ++k) \
;         acc[ai][bj][m][n] = __builtin_amdgcn_mfma_f32_16x16x32_bf16(Bt[n][k], At[m][k], acc[ai][bj][m][n], 0, 0, 0); __builtin_amdgcn_s_setprio(0); } while (0)
; #define PG8_WAIT_V(n) asm volatile("s_waitcnt vmcnt(" #n ")" ::: "memory")
; #define PG8_BAR __builtin_amdgcn_s_barrier()
; template <class Epi, class Sched, bool ALIGN_EPI>
; __device__ __forceinline__ void gemm_phase(LAS unsigned char* lds, const Gemm g, const Sched& S, const Epi& E) {
;     ...
;         for (int t = 0; t < nt; t += 2) {
;             const bool last = (t == nt - 2);
;             const char* a1 = cA + (size_t)(t + 1) * kstep;
;             const char* a2 = last ? nA : cA + (size_t)(t + 2) * kstep; const char* b2 = last ? nB : cB + (size_t)(t + 2) * kstep;
;             const char* a3 = a2 + kstep; const char* b3 = b2 + kstep;
;             PG8_LDB(B0, 0, 0); PG8_LDB(B1, 0, 1); PG8_SCHED; PG8_LDA(At, 0, 0); PG8_STAGE(PG8_SA(1, 1), a1 + hstepA, voffA);
;             PG8_WAIT_V(8); PG8_WAIT_L(0); PG8_BAR; PG8_MMA(0, 0, At, B0); PG8_MMA(0, 1, At, B1); PG8_BAR; PG8_SCHED;
;             PG8_LDA(At, 0, 1); PG8_STAGE(PG8_SB(0, 0), b2, voffB); PG8_STAGE(PG8_SB(0, 1), b2 + hstepB, voffB); PG8_STAGE(PG8_SA(0, 0), a2, voffA);
;             PG8_WAIT_V(8); PG8_WAIT_L(0); PG8_BAR; PG8_MMA(1, 0, At, B0); PG8_MMA(1, 1, At, B1); PG8_BAR; PG8_SCHED;
.LBB0_1409:
	ds_read_b128 v[132:135], v146
	ds_read_b128 v[136:139], v146 offset:1024
	ds_read_b128 v[160:163], v146 offset:2048
	ds_read_b128 v[164:167], v146 offset:3072
	ds_read_b128 v[168:171], v147
	ds_read_b128 v[172:175], v147 offset:1024
	ds_read_b128 v[180:183], v147 offset:2048
	ds_read_b128 v[184:187], v147 offset:3072
	s_add_u32 s8, s4, 0x100
	s_addc_u32 s9, s5, 0
	s_cmp_eq_u32 s39, 28
	s_cselect_b32 s46, s3, s8
	s_cselect_b32 s47, s2, s9
	s_cselect_b32 s12, s7, s23
	s_cselect_b32 s13, s6, s37
	s_add_u32 s10, s46, 0x80
	s_addc_u32 s11, s47, 0
	ds_read_b128 v[188:191], v148
	ds_read_b128 v[192:195], v148 offset:1024
	ds_read_b128 v[196:199], v148 offset:2048
	ds_read_b128 v[204:207], v148 offset:3072
	ds_read_b128 v[208:211], v148 offset:4096
	ds_read_b128 v[212:215], v148 offset:5120
	ds_read_b128 v[216:219], v148 offset:6144
	ds_read_b128 v[220:223], v148 offset:7168
	s_add_u32 s4, s4, 0x80080
	s_addc_u32 s5, s5, 0
	s_mov_b32 m0, s68
	s_nop 0
	global_load_lds_dwordx4 v140, s[4:5]
	s_nop 0
	s_mov_b32 m0, s69
	s_nop 0
	global_load_lds_dwordx4 v142, s[4:5]
	s_waitcnt vmcnt(8)
	s_waitcnt lgkmcnt(0)
	s_barrier
	s_setprio 1
	v_mfma_f32_16x16x32_bf16 v[126:129], v[132:135], v[188:191], v[126:129]
	v_mfma_f32_16x16x32_bf16 v[122:125], v[160:163], v[188:191], v[122:125]
	v_mfma_f32_16x16x32_bf16 v[110:113], v[132:135], v[196:199], v[110:113]
	v_mfma_f32_16x16x32_bf16 v[106:109], v[160:163], v[196:199], v[106:109]
	v_mfma_f32_16x16x32_bf16 v[94:97], v[132:135], v[208:211], v[94:97]
	v_mfma_f32_16x16x32_bf16 v[90:93], v[160:163], v[208:211], v[90:93]
	v_mfma_f32_16x16x32_bf16 v[78:81], v[132:135], v[216:219], v[78:81]
	v_mfma_f32_16x16x32_bf16 v[74:77], v[160:163], v[216:219], v[74:77]
	v_mfma_f32_16x16x32_bf16 v[126:129], v[136:139], v[192:195], v[126:129]
	v_mfma_f32_16x16x32_bf16 v[122:125], v[164:167], v[192:195], v[122:125]
	v_mfma_f32_16x16x32_bf16 v[110:113], v[136:139], v[204:207], v[110:113]
	v_mfma_f32_16x16x32_bf16 v[106:109], v[164:167], v[204:207], v[106:109]
	v_mfma_f32_16x16x32_bf16 v[94:97], v[136:139], v[212:215], v[94:97]
	v_mfma_f32_16x16x32_bf16 v[90:93], v[164:167], v[212:215], v[90:93]
	v_mfma_f32_16x16x32_bf16 v[78:81], v[136:139], v[220:223], v[78:81]
	v_mfma_f32_16x16x32_bf16 v[74:77], v[164:167], v[220:223], v[74:77]
	v_mfma_f32_16x16x32_bf16 v[118:121], v[168:171], v[188:191], v[118:121]
	v_mfma_f32_16x16x32_bf16 v[114:117], v[180:183], v[188:191], v[114:117]
	v_mfma_f32_16x16x32_bf16 v[102:105], v[168:171], v[196:199], v[102:105]
	v_mfma_f32_16x16x32_bf16 v[98:101], v[180:183], v[196:199], v[98:101]
	v_mfma_f32_16x16x32_bf16 v[86:89], v[168:171], v[208:211], v[86:89]
	v_mfma_f32_16x16x32_bf16 v[82:85], v[180:183], v[208:211], v[82:85]
	v_mfma_f32_16x16x32_bf16 v[70:73], v[168:171], v[216:219], v[70:73]
	v_mfma_f32_16x16x32_bf16 v[66:69], v[180:183], v[216:219], v[66:69]
	v_mfma_f32_16x16x32_bf16 v[118:121], v[172:175], v[192:195], v[118:121]
	v_mfma_f32_16x16x32_bf16 v[114:117], v[184:187], v[192:195], v[114:117]
	v_mfma_f32_16x16x32_bf16 v[102:105], v[172:175], v[204:207], v[102:105]
	v_mfma_f32_16x16x32_bf16 v[98:101], v[184:187], v[204:207], v[98:101]
	v_mfma_f32_16x16x32_bf16 v[86:89], v[172:175], v[212:215], v[86:89]
	v_mfma_f32_16x16x32_bf16 v[82:85], v[184:187], v[212:215], v[82:85]
	v_mfma_f32_16x16x32_bf16 v[70:73], v[172:175], v[220:223], v[70:73]
	v_mfma_f32_16x16x32_bf16 v[66:69], v[184:187], v[220:223], v[66:69]
	s_setprio 0
	s_barrier
	ds_read_b128 v[188:191], v148 offset:16384
	ds_read_b128 v[192:195], v148 offset:17408
	ds_read_b128 v[196:199], v148 offset:18432
	ds_read_b128 v[204:207], v148 offset:19456
	ds_read_b128 v[208:211], v148 offset:20480
	ds_read_b128 v[212:215], v148 offset:21504
	ds_read_b128 v[216:219], v148 offset:22528
	ds_read_b128 v[220:223], v148 offset:23552
	s_mov_b32 m0, s53
	s_nop 0
	global_load_lds_dwordx4 v141, s[12:13]
	s_nop 0
	s_mov_b32 m0, s54
	s_nop 0
	global_load_lds_dwordx4 v143, s[12:13]
	s_add_u32 s4, s12, 0x80000
	s_addc_u32 s5, s13, 0
	s_mov_b32 m0, s55
	s_nop 0
	global_load_lds_dwordx4 v141, s[4:5]
	s_nop 0
	s_mov_b32 m0, s56
	s_nop 0
	global_load_lds_dwordx4 v143, s[4:5]
	s_mov_b32 m0, s52
	s_nop 0
	global_load_lds_dwordx4 v140, s[46:47]
	s_nop 0
	s_mov_b32 m0, s57
	s_nop 0
	global_load_lds_dwordx4 v142, s[46:47]
	s_waitcnt vmcnt(8)
	s_waitcnt lgkmcnt(0)
	s_barrier
	s_setprio 1
	v_mfma_f32_16x16x32_bf16 v[62:65], v[132:135], v[188:191], v[62:65]
	v_mfma_f32_16x16x32_bf16 v[58:61], v[160:163], v[188:191], v[58:61]
	v_mfma_f32_16x16x32_bf16 v[46:49], v[132:135], v[196:199], v[46:49]
	v_mfma_f32_16x16x32_bf16 v[42:45], v[160:163], v[196:199], v[42:45]
	v_mfma_f32_16x16x32_bf16 v[30:33], v[132:135], v[208:211], v[30:33]
	v_mfma_f32_16x16x32_bf16 v[26:29], v[160:163], v[208:211], v[26:29]
	v_mfma_f32_16x16x32_bf16 v[14:17], v[132:135], v[216:219], v[14:17]
	v_mfma_f32_16x16x32_bf16 v[10:13], v[160:163], v[216:219], v[10:13]
	v_mfma_f32_16x16x32_bf16 v[62:65], v[136:139], v[192:195], v[62:65]
	v_mfma_f32_16x16x32_bf16 v[58:61], v[164:167], v[192:195], v[58:61]
	v_mfma_f32_16x16x32_bf16 v[46:49], v[136:139], v[204:207], v[46:49]
	v_mfma_f32_16x16x32_bf16 v[42:45], v[164:167], v[204:207], v[42:45]
	v_mfma_f32_16x16x32_bf16 v[30:33], v[136:139], v[212:215], v[30:33]
	v_mfma_f32_16x16x32_bf16 v[26:29], v[164:167], v[212:215], v[26:29]
	v_mfma_f32_16x16x32_bf16 v[14:17], v[136:139], v[220:223], v[14:17]
	v_mfma_f32_16x16x32_bf16 v[10:13], v[164:167], v[220:223], v[10:13]
	v_mfma_f32_16x16x32_bf16 v[54:57], v[168:171], v[188:191], v[54:57]
	v_mfma_f32_16x16x32_bf16 v[50:53], v[180:183], v[188:191], v[50:53]
	v_mfma_f32_16x16x32_bf16 v[38:41], v[168:171], v[196:199], v[38:41]
	v_mfma_f32_16x16x32_bf16 v[34:37], v[180:183], v[196:199], v[34:37]
	v_mfma_f32_16x16x32_bf16 v[22:25], v[168:171], v[208:211], v[22:25]
	v_mfma_f32_16x16x32_bf16 v[18:21], v[180:183], v[208:211], v[18:21]
	v_mfma_f32_16x16x32_bf16 v[6:9], v[168:171], v[216:219], v[6:9]
	v_mfma_f32_16x16x32_bf16 v[2:5], v[180:183], v[216:219], v[2:5]
	v_mfma_f32_16x16x32_bf16 v[54:57], v[172:175], v[192:195], v[54:57]
	v_mfma_f32_16x16x32_bf16 v[50:53], v[184:187], v[192:195], v[50:53]
	v_mfma_f32_16x16x32_bf16 v[38:41], v[172:175], v[204:207], v[38:41]
	v_mfma_f32_16x16x32_bf16 v[34:37], v[184:187], v[204:207], v[34:37]
	v_mfma_f32_16x16x32_bf16 v[22:25], v[172:175], v[212:215], v[22:25]
	v_mfma_f32_16x16x32_bf16 v[18:21], v[184:187], v[212:215], v[18:21]
	v_mfma_f32_16x16x32_bf16 v[6:9], v[172:175], v[220:223], v[6:9]
	v_mfma_f32_16x16x32_bf16 v[2:5], v[184:187], v[220:223], v[2:5]
	s_setprio 0
	s_barrier
; #define PG8_STAGE(bufoff, gbase, voff) do { _Pragma("unroll") for (int _i = 0; _i < 2; ++_i) { unsigned keep_; \
;         asm volatile("s_mov_b32 %0, m0\n\ts_mov_b32 m0, %3\n\ts_nop 0\n\tglobal_load_lds_dwordx4 %1, %2\n\ts_mov_b32 m0, %0" \
;             : "=&s"(keep_) : "v"((voff)[_i]), "s"((const void*)(gbase)), "s"(ldsb0 + (unsigned)(bufoff) + (unsigned)(_i * 8192)) : "memory"); } } while (0)
; #define PG8_LDA(dst, b, h) do { _Pragma("unroll") for (int m = 0; m < 4; ++m) _Pragma("unroll") for (int k = 0; k < 2; ++k) dst[m][k] = *(const LAS bf16x8*)(lds + PG8_SA(b, h) + aoff + m * 2048 + k * 1024); } while (0)
; #define PG8_LDB(dst, b, h) do { _Pragma("unroll") for (int n = 0; n < 2; ++n) _Pragma("unroll") for (int k = 0; k < 2; ++k) dst[n][k] = *(const LAS bf16x8*)(lds + PG8_SB(b, h) + boff + n * 2048 + k * 1024); } while (0)
; #define PG8_MMA(ai, bj, At, Bt) do { __builtin_amdgcn_s_setprio(1); _Pragma("unroll") for (int m = 0; m < 4; ++m) _Pragma("unroll") for (int n = 0; n < 2; ++n) _Pragma("unroll") for (int k = 0; k < 2; ++k) \
;         acc[ai][bj][m][n] = __builtin_amdgcn_mfma_f32_16x16x32_bf16(Bt[n][k], At[m][k], acc[ai][bj][m][n], 0, 0, 0); __builtin_amdgcn_s_setprio(0); } while (0)
; #define PG8_WAIT_V(n) asm volatile("s_waitcnt vmcnt(" #n ")" ::: "memory")
; #define PG8_WAIT_L(n) asm volatile("s_waitcnt lgkmcnt(" #n ")" ::: "memory")
; #define PG8_BAR __builtin_amdgcn_s_barrier()
; #define PG8_SCHED __builtin_amdgcn_sched_barrier(0)
; template <class Epi, class Sched, bool ALIGN_EPI>
; __device__ __forceinline__ void gemm_phase(LAS unsigned char* lds, const Gemm g, const Sched& S, const Epi& E) {
;     ...
;             PG8_LDB(B0, 1, 0); PG8_LDB(B1, 1, 1); PG8_SCHED; PG8_LDA(At, 1, 0); PG8_STAGE(PG8_SA(0, 1), a2 + hstepA, voffA);
;             PG8_WAIT_V(8); PG8_WAIT_L(0); PG8_BAR; PG8_MMA(0, 0, At, B0); PG8_MMA(0, 1, At, B1); PG8_BAR; PG8_SCHED;
;             PG8_LDA(At, 1, 1); PG8_STAGE(PG8_SB(1, 0), b3, voffB); PG8_STAGE(PG8_SB(1, 1), b3 + hstepB, voffB); PG8_STAGE(PG8_SA(1, 0), a3, voffA);
;             PG8_WAIT_V(8); PG8_WAIT_L(0); PG8_BAR; PG8_MMA(1, 0, At, B0); PG8_MMA(1, 1, At, B1); PG8_BAR; PG8_SCHED;
;         }
	ds_read_b128 v[132:135], v149
	ds_read_b128 v[136:139], v149 offset:1024
	ds_read_b128 v[160:163], v149 offset:2048
	ds_read_b128 v[164:167], v149 offset:3072
	ds_read_b128 v[168:171], v150
	ds_read_b128 v[172:175], v150 offset:1024
	ds_read_b128 v[180:183], v150 offset:2048
	ds_read_b128 v[184:187], v150 offset:3072
	ds_read_b128 v[188:191], v148 offset:32768
	ds_read_b128 v[192:195], v148 offset:33792
	ds_read_b128 v[196:199], v148 offset:34816
	ds_read_b128 v[204:207], v148 offset:35840
	ds_read_b128 v[208:211], v148 offset:36864
	ds_read_b128 v[212:215], v148 offset:37888
	ds_read_b128 v[216:219], v148 offset:38912
	ds_read_b128 v[220:223], v148 offset:39936
	s_add_u32 s4, s46, 0x80000
	s_addc_u32 s5, s47, 0
	s_mov_b32 m0, s59
	s_nop 0
	global_load_lds_dwordx4 v140, s[4:5]
	s_nop 0
	s_mov_b32 m0, s61
	s_nop 0
	global_load_lds_dwordx4 v142, s[4:5]
	s_waitcnt vmcnt(8)
	s_waitcnt lgkmcnt(0)
	s_barrier
	s_setprio 1
	v_mfma_f32_16x16x32_bf16 v[126:129], v[132:135], v[188:191], v[126:129]
	v_mfma_f32_16x16x32_bf16 v[122:125], v[160:163], v[188:191], v[122:125]
	v_mfma_f32_16x16x32_bf16 v[110:113], v[132:135], v[196:199], v[110:113]
	v_mfma_f32_16x16x32_bf16 v[106:109], v[160:163], v[196:199], v[106:109]
	v_mfma_f32_16x16x32_bf16 v[94:97], v[132:135], v[208:211], v[94:97]
	v_mfma_f32_16x16x32_bf16 v[90:93], v[160:163], v[208:211], v[90:93]
	v_mfma_f32_16x16x32_bf16 v[78:81], v[132:135], v[216:219], v[78:81]
	v_mfma_f32_16x16x32_bf16 v[74:77], v[160:163], v[216:219], v[74:77]
	v_mfma_f32_16x16x32_bf16 v[126:129], v[136:139], v[192:195], v[126:129]
	v_mfma_f32_16x16x32_bf16 v[122:125], v[164:167], v[192:195], v[122:125]
	v_mfma_f32_16x16x32_bf16 v[110:113], v[136:139], v[204:207], v[110:113]
	v_mfma_f32_16x16x32_bf16 v[106:109], v[164:167], v[204:207], v[106:109]
	v_mfma_f32_16x16x32_bf16 v[94:97], v[136:139], v[212:215], v[94:97]
	v_mfma_f32_16x16x32_bf16 v[90:93], v[164:167], v[212:215], v[90:93]
	v_mfma_f32_16x16x32_bf16 v[78:81], v[136:139], v[220:223], v[78:81]
	v_mfma_f32_16x16x32_bf16 v[74:77], v[164:167], v[220:223], v[74:77]
	v_mfma_f32_16x16x32_bf16 v[118:121], v[168:171], v[188:191], v[118:121]
	v_mfma_f32_16x16x32_bf16 v[114:117], v[180:183], v[188:191], v[114:117]
	v_mfma_f32_16x16x32_bf16 v[102:105], v[168:171], v[196:199], v[102:105]
	v_mfma_f32_16x16x32_bf16 v[98:101], v[180:183], v[196:199], v[98:101]
	v_mfma_f32_16x16x32_bf16 v[86:89], v[168:171], v[208:211], v[86:89]
	v_mfma_f32_16x16x32_bf16 v[82:85], v[180:183], v[208:211], v[82:85]
	v_mfma_f32_16x16x32_bf16 v[70:73], v[168:171], v[216:219], v[70:73]
	v_mfma_f32_16x16x32_bf16 v[66:69], v[180:183], v[216:219], v[66:69]
	v_mfma_f32_16x16x32_bf16 v[118:121], v[172:175], v[192:195], v[118:121]
	v_mfma_f32_16x16x32_bf16 v[114:117], v[184:187], v[192:195], v[114:117]
	v_mfma_f32_16x16x32_bf16 v[102:105], v[172:175], v[204:207], v[102:105]
	v_mfma_f32_16x16x32_bf16 v[98:101], v[184:187], v[204:207], v[98:101]
	v_mfma_f32_16x16x32_bf16 v[86:89], v[172:175], v[212:215], v[86:89]
	v_mfma_f32_16x16x32_bf16 v[82:85], v[184:187], v[212:215], v[82:85]
	v_mfma_f32_16x16x32_bf16 v[70:73], v[172:175], v[220:223], v[70:73]
	v_mfma_f32_16x16x32_bf16 v[66:69], v[184:187], v[220:223], v[66:69]
	s_setprio 0
	s_barrier
	ds_read_b128 v[188:191], v148 offset:49152
	ds_read_b128 v[192:195], v148 offset:50176
	ds_read_b128 v[196:199], v148 offset:51200
	ds_read_b128 v[204:207], v148 offset:52224
	ds_read_b128 v[208:211], v148 offset:53248
	ds_read_b128 v[212:215], v148 offset:54272
	ds_read_b128 v[216:219], v148 offset:55296
	ds_read_b128 v[220:223], v148 offset:56320
	s_add_u32 s4, s12, 0x80
	s_addc_u32 s5, s13, 0
	s_mov_b32 m0, s62
	s_nop 0
	global_load_lds_dwordx4 v141, s[4:5]
	s_nop 0
	s_mov_b32 m0, s63
	s_nop 0
	global_load_lds_dwordx4 v143, s[4:5]
	s_add_u32 s4, s12, 0x80080
	s_addc_u32 s5, s13, 0
	s_mov_b32 m0, s66
	s_nop 0
	global_load_lds_dwordx4 v141, s[4:5]
	s_nop 0
	s_mov_b32 m0, s67
	s_nop 0
	global_load_lds_dwordx4 v143, s[4:5]
	s_mov_b32 m0, s64
	s_nop 0
	global_load_lds_dwordx4 v140, s[10:11]
	s_nop 0
	s_mov_b32 m0, s65
	s_nop 0
	global_load_lds_dwordx4 v142, s[10:11]
	s_waitcnt vmcnt(8)
	s_waitcnt lgkmcnt(0)
	s_barrier
	s_setprio 1
	v_mfma_f32_16x16x32_bf16 v[62:65], v[132:135], v[188:191], v[62:65]
	v_mfma_f32_16x16x32_bf16 v[58:61], v[160:163], v[188:191], v[58:61]
	v_mfma_f32_16x16x32_bf16 v[46:49], v[132:135], v[196:199], v[46:49]
	v_mfma_f32_16x16x32_bf16 v[42:45], v[160:163], v[196:199], v[42:45]
	v_mfma_f32_16x16x32_bf16 v[30:33], v[132:135], v[208:211], v[30:33]
	v_mfma_f32_16x16x32_bf16 v[26:29], v[160:163], v[208:211], v[26:29]
	v_mfma_f32_16x16x32_bf16 v[14:17], v[132:135], v[216:219], v[14:17]
	v_mfma_f32_16x16x32_bf16 v[10:13], v[160:163], v[216:219], v[10:13]
	v_mfma_f32_16x16x32_bf16 v[62:65], v[136:139], v[192:195], v[62:65]
	v_mfma_f32_16x16x32_bf16 v[58:61], v[164:167], v[192:195], v[58:61]
	v_mfma_f32_16x16x32_bf16 v[46:49], v[136:139], v[204:207], v[46:49]
	v_mfma_f32_16x16x32_bf16 v[42:45], v[164:167], v[204:207], v[42:45]
	v_mfma_f32_16x16x32_bf16 v[30:33], v[136:139], v[212:215], v[30:33]
	v_mfma_f32_16x16x32_bf16 v[26:29], v[164:167], v[212:215], v[26:29]
	v_mfma_f32_16x16x32_bf16 v[14:17], v[136:139], v[220:223], v[14:17]
	v_mfma_f32_16x16x32_bf16 v[10:13], v[164:167], v[220:223], v[10:13]
	v_mfma_f32_16x16x32_bf16 v[54:57], v[168:171], v[188:191], v[54:57]
	v_mfma_f32_16x16x32_bf16 v[50:53], v[180:183], v[188:191], v[50:53]
	v_mfma_f32_16x16x32_bf16 v[38:41], v[168:171], v[196:199], v[38:41]
	v_mfma_f32_16x16x32_bf16 v[34:37], v[180:183], v[196:199], v[34:37]
	v_mfma_f32_16x16x32_bf16 v[22:25], v[168:171], v[208:211], v[22:25]
	v_mfma_f32_16x16x32_bf16 v[18:21], v[180:183], v[208:211], v[18:21]
	v_mfma_f32_16x16x32_bf16 v[6:9], v[168:171], v[216:219], v[6:9]
	v_mfma_f32_16x16x32_bf16 v[2:5], v[180:183], v[216:219], v[2:5]
	v_mfma_f32_16x16x32_bf16 v[54:57], v[172:175], v[192:195], v[54:57]
	v_mfma_f32_16x16x32_bf16 v[50:53], v[184:187], v[192:195], v[50:53]
	v_mfma_f32_16x16x32_bf16 v[38:41], v[172:175], v[204:207], v[38:41]
	v_mfma_f32_16x16x32_bf16 v[34:37], v[184:187], v[204:207], v[34:37]
	v_mfma_f32_16x16x32_bf16 v[22:25], v[172:175], v[212:215], v[22:25]
	v_mfma_f32_16x16x32_bf16 v[18:21], v[184:187], v[212:215], v[18:21]
	v_mfma_f32_16x16x32_bf16 v[6:9], v[172:175], v[220:223], v[6:9]
	v_mfma_f32_16x16x32_bf16 v[2:5], v[184:187], v[220:223], v[2:5]
	s_setprio 0
	s_barrier
	s_add_i32 s39, s39, 2
	s_add_u32 s23, s23, 0x100
	s_addc_u32 s37, s37, 0
	s_cmp_gt_u32 s39, 29
	s_mov_b64 s[4:5], s[8:9]
	s_cbranch_scc0 .LBB0_1409
	s_and_b64 vcc, exec, s[34:35]
	s_cbranch_vccz .LBB0_1412
	s_barrier
; __device__ __forceinline__ float rs_val(float ssqv) { return __builtin_amdgcn_rsqf(ssqv * (1.f / DM) + EPS); }
; __device__ __forceinline__ void st_bf16x8(bf16* p, f32x4 a, f32x4 b) { *(bf16x8*)p = pack8(a, b); }
;     __device__ __forceinline__ void operator()(const Acc& acc, const pg8::Unit& u, int wr, int wc, int fr, int fq, const float* rsv) const {
;         const int sec = u.pn >> 3, cin = (u.pn & 7) * 256 + wc * 32 + fq * 8;
; #pragma unroll
;         for (int ai = 0; ai < 2; ++ai)
; #pragma unroll
;             for (int m = 0; m < 4; ++m) { const int row = u.pm * 256 + ai * 128 + wr * 64 + m * 16 + fr; const float rs = rs_val(rsv[ai * 4 + m]);
; #pragma unroll
;                 for (int bj = 0; bj < 2; ++bj) { const f32x4 v0 = acc[ai][bj][m][0] * rs, v1 = acc[ai][bj][m][1] * rs; const int c = cin + bj * 128;
;                     if (sec == 0) st_bf16x8(QB + (size_t)row * DM + c, v0, v1);
;                     else if (sec == 1) { if (ai == 1) { float* p = sk + (size_t)row * DM + c; *(f32x4*)p = v0; *(f32x4*)(p + 4) = v1; } st_bf16x8(KB + (size_t)row * DM + c, v0, v1); }
;                     else { if (ai == 1) { float* p = sv + (size_t)row * DM + c; *(f32x4*)p = v0; *(f32x4*)(p + 4) = v1; }
;                         st_bf16x8(VB + (size_t)row * DM + c, v0, v1); } } }
;     }
.LBB0_1412:
	s_lshl_b32 s2, s22, 8
	s_nop 0
	v_fmamk_f32 v130, v130, 0x3a000000, v151
	s_and_b32 s2, s2, 0x700
	v_rsq_f32_e32 v136, v130
	s_cmp_gt_u32 s22, 7
	v_or_b32_e32 v157, s2, v145
	v_lshl_add_u32 v132, s60, 8, v144
	s_cselect_b64 s[4:5], -1, 0
	s_and_b32 s2, s22, -8
	s_cmp_lg_u32 s2, 8
	v_ashrrev_i32_e32 v133, 31, v132
	s_cselect_b64 s[8:9], -1, 0
	v_lshlrev_b64 v[134:135], 12, v[132:133]
	v_pk_mul_f32 v[128:129], v[136:137], v[128:129] op_sel_hi:[0,1]
	v_pk_mul_f32 v[138:139], v[136:137], v[126:127] op_sel_hi:[0,1]
	v_pk_mul_f32 v[124:125], v[136:137], v[124:125] op_sel_hi:[0,1]
	v_pk_mul_f32 v[126:127], v[136:137], v[122:123] op_sel_hi:[0,1]
	s_mov_b64 s[10:11], -1
	s_and_b64 vcc, exec, s[4:5]
	s_cbranch_vccz .LBB0_1418
	s_and_b64 vcc, exec, s[8:9]
	s_cbranch_vccz .LBB0_1415
	v_lshl_add_u64 v[122:123], s[26:27], 0, v[134:135]
	v_lshlrev_b32_e32 v130, 1, v157
	v_lshl_add_u64 v[122:123], v[122:123], 0, v[130:131]
	v_cvt_pk_bf16_f32 v160, v138, v139
	v_cvt_pk_bf16_f32 v161, v128, v129
	v_cvt_pk_bf16_f32 v162, v126, v127
	v_cvt_pk_bf16_f32 v163, v124, v125
	global_store_dwordx4 v[122:123], v[160:163], off
	s_mov_b64 s[10:11], 0

; __device__ __forceinline__ float rs_val(float ssqv) { return __builtin_amdgcn_rsqf(ssqv * (1.f / DM) + EPS); }
; __device__ __forceinline__ void st_bf16x8(bf16* p, f32x4 a, f32x4 b) { *(bf16x8*)p = pack8(a, b); }
;     __device__ __forceinline__ void operator()(const Acc& acc, const pg8::Unit& u, int wr, int wc, int fr, int fq, const float* rsv) const {
;         const int sec = u.pn >> 3, cin = (u.pn & 7) * 256 + wc * 32 + fq * 8;
; #pragma unroll
;         for (int ai = 0; ai < 2; ++ai)
; #pragma unroll
;             for (int m = 0; m < 4; ++m) { const int row = u.pm * 256 + ai * 128 + wr * 64 + m * 16 + fr; const float rs = rs_val(rsv[ai * 4 + m]);
; #pragma unroll
;                 for (int bj = 0; bj < 2; ++bj) { const f32x4 v0 = acc[ai][bj][m][0] * rs, v1 = acc[ai][bj][m][1] * rs; const int c = cin + bj * 128;
;                     if (sec == 0) st_bf16x8(QB + (size_t)row * DM + c, v0, v1);
;                     else if (sec == 1) { if (ai == 1) { float* p = sk + (size_t)row * DM + c; *(f32x4*)p = v0; *(f32x4*)(p + 4) = v1; } st_bf16x8(KB + (size_t)row * DM + c, v0, v1); }
;                     else { if (ai == 1) { float* p = sv + (size_t)row * DM + c; *(f32x4*)p = v0; *(f32x4*)(p + 4) = v1; }
;                         st_bf16x8(VB + (size_t)row * DM + c, v0, v1); } } }
;     }
.LBB0_1428:
	s_nop 0
	v_fmamk_f32 v114, v159, 0x3a000000, v151
	v_rsq_f32_e32 v116, v114
	v_or_b32_e32 v114, 16, v132
	v_ashrrev_i32_e32 v115, 31, v114
	v_lshlrev_b64 v[114:115], 12, v[114:115]
	v_pk_mul_f32 v[112:113], v[116:117], v[112:113] op_sel_hi:[0,1]
	v_pk_mul_f32 v[118:119], v[116:117], v[110:111] op_sel_hi:[0,1]
	v_pk_mul_f32 v[108:109], v[116:117], v[108:109] op_sel_hi:[0,1]
	v_pk_mul_f32 v[110:111], v[116:117], v[106:107] op_sel_hi:[0,1]
	s_and_b64 vcc, exec, s[12:13]
	s_mov_b64 s[4:5], -1
	s_cbranch_vccnz .LBB0_1434
	s_and_b64 vcc, exec, s[10:11]
	s_cbranch_vccnz .LBB0_1431
	v_lshl_add_u64 v[106:107], s[26:27], 0, v[114:115]
	v_lshl_add_u64 v[106:107], v[106:107], 0, v[130:131]
	s_mov_b64 s[4:5], 0
	v_cvt_pk_bf16_f32 v120, v118, v119
	v_cvt_pk_bf16_f32 v121, v112, v113
	v_cvt_pk_bf16_f32 v122, v110, v111
	v_cvt_pk_bf16_f32 v123, v108, v109
	global_store_dwordx4 v[106:107], v[120:123], off

; __device__ __forceinline__ float rs_val(float ssqv) { return __builtin_amdgcn_rsqf(ssqv * (1.f / DM) + EPS); }
; __device__ __forceinline__ void st_bf16x8(bf16* p, f32x4 a, f32x4 b) { *(bf16x8*)p = pack8(a, b); }
;     __device__ __forceinline__ void operator()(const Acc& acc, const pg8::Unit& u, int wr, int wc, int fr, int fq, const float* rsv) const {
;         const int sec = u.pn >> 3, cin = (u.pn & 7) * 256 + wc * 32 + fq * 8;
; #pragma unroll
;         for (int ai = 0; ai < 2; ++ai)
; #pragma unroll
;             for (int m = 0; m < 4; ++m) { const int row = u.pm * 256 + ai * 128 + wr * 64 + m * 16 + fr; const float rs = rs_val(rsv[ai * 4 + m]);
; #pragma unroll
;                 for (int bj = 0; bj < 2; ++bj) { const f32x4 v0 = acc[ai][bj][m][0] * rs, v1 = acc[ai][bj][m][1] * rs; const int c = cin + bj * 128;
;                     if (sec == 0) st_bf16x8(QB + (size_t)row * DM + c, v0, v1);
;                     else if (sec == 1) { if (ai == 1) { float* p = sk + (size_t)row * DM + c; *(f32x4*)p = v0; *(f32x4*)(p + 4) = v1; } st_bf16x8(KB + (size_t)row * DM + c, v0, v1); }
;                     else { if (ai == 1) { float* p = sv + (size_t)row * DM + c; *(f32x4*)p = v0; *(f32x4*)(p + 4) = v1; }
;                         st_bf16x8(VB + (size_t)row * DM + c, v0, v1); } } }
;     }
.LBB0_1444:
	s_nop 0
	v_fmamk_f32 v98, v158, 0x3a000000, v151
	v_rsq_f32_e32 v100, v98
	v_or_b32_e32 v98, 32, v132
	v_ashrrev_i32_e32 v99, 31, v98
	v_lshlrev_b64 v[98:99], 12, v[98:99]
	v_pk_mul_f32 v[96:97], v[100:101], v[96:97] op_sel_hi:[0,1]
	v_pk_mul_f32 v[102:103], v[100:101], v[94:95] op_sel_hi:[0,1]
	v_pk_mul_f32 v[92:93], v[100:101], v[92:93] op_sel_hi:[0,1]
	v_pk_mul_f32 v[94:95], v[100:101], v[90:91] op_sel_hi:[0,1]
	s_and_b64 vcc, exec, s[12:13]
	s_mov_b64 s[4:5], -1
	s_cbranch_vccnz .LBB0_1450
	s_and_b64 vcc, exec, s[10:11]
	s_cbranch_vccnz .LBB0_1447
	v_lshl_add_u64 v[90:91], s[26:27], 0, v[98:99]
	v_lshl_add_u64 v[90:91], v[90:91], 0, v[130:131]
	s_mov_b64 s[4:5], 0
	v_cvt_pk_bf16_f32 v104, v102, v103
	v_cvt_pk_bf16_f32 v105, v96, v97
	v_cvt_pk_bf16_f32 v106, v94, v95
	v_cvt_pk_bf16_f32 v107, v92, v93
	global_store_dwordx4 v[90:91], v[104:107], off

; __device__ __forceinline__ float rs_val(float ssqv) { return __builtin_amdgcn_rsqf(ssqv * (1.f / DM) + EPS); }
; __device__ __forceinline__ void st_bf16x8(bf16* p, f32x4 a, f32x4 b) { *(bf16x8*)p = pack8(a, b); }
;     __device__ __forceinline__ void operator()(const Acc& acc, const pg8::Unit& u, int wr, int wc, int fr, int fq, const float* rsv) const {
;         const int sec = u.pn >> 3, cin = (u.pn & 7) * 256 + wc * 32 + fq * 8;
; #pragma unroll
;         for (int ai = 0; ai < 2; ++ai)
; #pragma unroll
;             for (int m = 0; m < 4; ++m) { const int row = u.pm * 256 + ai * 128 + wr * 64 + m * 16 + fr; const float rs = rs_val(rsv[ai * 4 + m]);
; #pragma unroll
;                 for (int bj = 0; bj < 2; ++bj) { const f32x4 v0 = acc[ai][bj][m][0] * rs, v1 = acc[ai][bj][m][1] * rs; const int c = cin + bj * 128;
;                     if (sec == 0) st_bf16x8(QB + (size_t)row * DM + c, v0, v1);
;                     else if (sec == 1) { if (ai == 1) { float* p = sk + (size_t)row * DM + c; *(f32x4*)p = v0; *(f32x4*)(p + 4) = v1; } st_bf16x8(KB + (size_t)row * DM + c, v0, v1); }
;                     else { if (ai == 1) { float* p = sv + (size_t)row * DM + c; *(f32x4*)p = v0; *(f32x4*)(p + 4) = v1; }
;                         st_bf16x8(VB + (size_t)row * DM + c, v0, v1); } } }
;     }
.LBB0_1460:
	s_nop 0
	v_fmamk_f32 v82, v156, 0x3a000000, v151
	v_rsq_f32_e32 v84, v82
	v_or_b32_e32 v82, 48, v132
	v_ashrrev_i32_e32 v83, 31, v82
	v_lshlrev_b64 v[82:83], 12, v[82:83]
	v_pk_mul_f32 v[80:81], v[84:85], v[80:81] op_sel_hi:[0,1]
	v_pk_mul_f32 v[86:87], v[84:85], v[78:79] op_sel_hi:[0,1]
	v_pk_mul_f32 v[76:77], v[84:85], v[76:77] op_sel_hi:[0,1]
	v_pk_mul_f32 v[78:79], v[84:85], v[74:75] op_sel_hi:[0,1]
	s_and_b64 vcc, exec, s[12:13]
	s_mov_b64 s[4:5], -1
	s_cbranch_vccnz .LBB0_1466
	s_and_b64 vcc, exec, s[10:11]
	s_cbranch_vccnz .LBB0_1463
	v_lshl_add_u64 v[74:75], s[26:27], 0, v[82:83]
	v_lshl_add_u64 v[74:75], v[74:75], 0, v[130:131]
	s_mov_b64 s[4:5], 0
	v_cvt_pk_bf16_f32 v88, v86, v87
	v_cvt_pk_bf16_f32 v89, v80, v81
	v_cvt_pk_bf16_f32 v90, v78, v79
	v_cvt_pk_bf16_f32 v91, v76, v77
	global_store_dwordx4 v[74:75], v[88:91], off

; __device__ __forceinline__ float rs_val(float ssqv) { return __builtin_amdgcn_rsqf(ssqv * (1.f / DM) + EPS); }
; __device__ __forceinline__ void st_bf16x8(bf16* p, f32x4 a, f32x4 b) { *(bf16x8*)p = pack8(a, b); }
;     __device__ __forceinline__ void operator()(const Acc& acc, const pg8::Unit& u, int wr, int wc, int fr, int fq, const float* rsv) const {
;         const int sec = u.pn >> 3, cin = (u.pn & 7) * 256 + wc * 32 + fq * 8;
; #pragma unroll
;         for (int ai = 0; ai < 2; ++ai)
; #pragma unroll
;             for (int m = 0; m < 4; ++m) { const int row = u.pm * 256 + ai * 128 + wr * 64 + m * 16 + fr; const float rs = rs_val(rsv[ai * 4 + m]);
; #pragma unroll
;                 for (int bj = 0; bj < 2; ++bj) { const f32x4 v0 = acc[ai][bj][m][0] * rs, v1 = acc[ai][bj][m][1] * rs; const int c = cin + bj * 128;
;                     if (sec == 0) st_bf16x8(QB + (size_t)row * DM + c, v0, v1);
;                     else if (sec == 1) { if (ai == 1) { float* p = sk + (size_t)row * DM + c; *(f32x4*)p = v0; *(f32x4*)(p + 4) = v1; } st_bf16x8(KB + (size_t)row * DM + c, v0, v1); }
;                     else { if (ai == 1) { float* p = sv + (size_t)row * DM + c; *(f32x4*)p = v0; *(f32x4*)(p + 4) = v1; }
;                         st_bf16x8(VB + (size_t)row * DM + c, v0, v1); } } }
;     }
.LBB0_1476:
	s_nop 0
	v_fmamk_f32 v67, v155, 0x3a000000, v151
	v_rsq_f32_e32 v70, v67
	v_add_u32_e32 v66, 0x80, v132
	v_ashrrev_i32_e32 v67, 31, v66
	v_lshlrev_b64 v[68:69], 13, v[66:67]
	v_lshlrev_b64 v[66:67], 12, v[66:67]
	v_pk_mul_f32 v[64:65], v[70:71], v[64:65] op_sel_hi:[0,1]
	v_pk_mul_f32 v[62:63], v[70:71], v[62:63] op_sel_hi:[0,1]
	v_pk_mul_f32 v[60:61], v[70:71], v[60:61] op_sel_hi:[0,1]
	v_pk_mul_f32 v[58:59], v[70:71], v[58:59] op_sel_hi:[0,1]
	s_and_b64 vcc, exec, s[12:13]
	s_mov_b64 s[4:5], -1
	s_cbranch_vccnz .LBB0_1482
	s_and_b64 vcc, exec, s[10:11]
	s_cbranch_vccnz .LBB0_1479
	v_lshl_add_u64 v[72:73], s[30:31], 0, v[68:69]
	v_lshlrev_b32_e32 v74, 2, v157
	v_mov_b32_e32 v75, v131
	v_lshl_add_u64 v[72:73], v[72:73], 0, v[74:75]
	global_store_dwordx4 v[72:73], v[62:65], off
	global_store_dwordx4 v[72:73], v[58:61], off offset:16
	v_lshl_add_u64 v[72:73], s[26:27], 0, v[66:67]
	v_lshl_add_u64 v[76:77], v[72:73], 0, v[130:131]
	s_mov_b64 s[4:5], 0
	v_cvt_pk_bf16_f32 v72, v62, v63
	v_cvt_pk_bf16_f32 v73, v64, v65
	v_cvt_pk_bf16_f32 v74, v58, v59
	v_cvt_pk_bf16_f32 v75, v60, v61
	global_store_dwordx4 v[76:77], v[72:75], off

; __device__ __forceinline__ float rs_val(float ssqv) { return __builtin_amdgcn_rsqf(ssqv * (1.f / DM) + EPS); }
; __device__ __forceinline__ void st_bf16x8(bf16* p, f32x4 a, f32x4 b) { *(bf16x8*)p = pack8(a, b); }
;     __device__ __forceinline__ void operator()(const Acc& acc, const pg8::Unit& u, int wr, int wc, int fr, int fq, const float* rsv) const {
;         const int sec = u.pn >> 3, cin = (u.pn & 7) * 256 + wc * 32 + fq * 8;
; #pragma unroll
;         for (int ai = 0; ai < 2; ++ai)
; #pragma unroll
;             for (int m = 0; m < 4; ++m) { const int row = u.pm * 256 + ai * 128 + wr * 64 + m * 16 + fr; const float rs = rs_val(rsv[ai * 4 + m]);
; #pragma unroll
;                 for (int bj = 0; bj < 2; ++bj) { const f32x4 v0 = acc[ai][bj][m][0] * rs, v1 = acc[ai][bj][m][1] * rs; const int c = cin + bj * 128;
;                     if (sec == 0) st_bf16x8(QB + (size_t)row * DM + c, v0, v1);
;                     else if (sec == 1) { if (ai == 1) { float* p = sk + (size_t)row * DM + c; *(f32x4*)p = v0; *(f32x4*)(p + 4) = v1; } st_bf16x8(KB + (size_t)row * DM + c, v0, v1); }
;                     else { if (ai == 1) { float* p = sv + (size_t)row * DM + c; *(f32x4*)p = v0; *(f32x4*)(p + 4) = v1; }
;                         st_bf16x8(VB + (size_t)row * DM + c, v0, v1); } } }
;     }
.LBB0_1492:
	s_nop 0
	v_fmamk_f32 v51, v154, 0x3a000000, v151
	v_rsq_f32_e32 v54, v51
	v_add_u32_e32 v50, 0x90, v132
	v_ashrrev_i32_e32 v51, 31, v50
	v_lshlrev_b64 v[52:53], 13, v[50:51]
	v_lshlrev_b64 v[50:51], 12, v[50:51]
	v_pk_mul_f32 v[48:49], v[54:55], v[48:49] op_sel_hi:[0,1]
	v_pk_mul_f32 v[46:47], v[54:55], v[46:47] op_sel_hi:[0,1]
	v_pk_mul_f32 v[44:45], v[54:55], v[44:45] op_sel_hi:[0,1]
	v_pk_mul_f32 v[42:43], v[54:55], v[42:43] op_sel_hi:[0,1]
	s_and_b64 vcc, exec, s[12:13]
	s_mov_b64 s[4:5], -1
	s_cbranch_vccnz .LBB0_1498
	s_and_b64 vcc, exec, s[10:11]
	s_cbranch_vccnz .LBB0_1495
	v_lshl_add_u64 v[56:57], s[30:31], 0, v[52:53]
	v_lshlrev_b32_e32 v58, 2, v157
	v_mov_b32_e32 v59, v131
	v_lshl_add_u64 v[56:57], v[56:57], 0, v[58:59]
	global_store_dwordx4 v[56:57], v[46:49], off
	global_store_dwordx4 v[56:57], v[42:45], off offset:16
	v_lshl_add_u64 v[56:57], s[26:27], 0, v[50:51]
	v_lshl_add_u64 v[60:61], v[56:57], 0, v[130:131]
	s_mov_b64 s[4:5], 0
	v_cvt_pk_bf16_f32 v56, v46, v47
	v_cvt_pk_bf16_f32 v57, v48, v49
	v_cvt_pk_bf16_f32 v58, v42, v43
	v_cvt_pk_bf16_f32 v59, v44, v45
	global_store_dwordx4 v[60:61], v[56:59], off

; __device__ __forceinline__ float rs_val(float ssqv) { return __builtin_amdgcn_rsqf(ssqv * (1.f / DM) + EPS); }
; __device__ __forceinline__ void st_bf16x8(bf16* p, f32x4 a, f32x4 b) { *(bf16x8*)p = pack8(a, b); }
;     __device__ __forceinline__ void operator()(const Acc& acc, const pg8::Unit& u, int wr, int wc, int fr, int fq, const float* rsv) const {
;         const int sec = u.pn >> 3, cin = (u.pn & 7) * 256 + wc * 32 + fq * 8;
; #pragma unroll
;         for (int ai = 0; ai < 2; ++ai)
; #pragma unroll
;             for (int m = 0; m < 4; ++m) { const int row = u.pm * 256 + ai * 128 + wr * 64 + m * 16 + fr; const float rs = rs_val(rsv[ai * 4 + m]);
; #pragma unroll
;                 for (int bj = 0; bj < 2; ++bj) { const f32x4 v0 = acc[ai][bj][m][0] * rs, v1 = acc[ai][bj][m][1] * rs; const int c = cin + bj * 128;
;                     if (sec == 0) st_bf16x8(QB + (size_t)row * DM + c, v0, v1);
;                     else if (sec == 1) { if (ai == 1) { float* p = sk + (size_t)row * DM + c; *(f32x4*)p = v0; *(f32x4*)(p + 4) = v1; } st_bf16x8(KB + (size_t)row * DM + c, v0, v1); }
;                     else { if (ai == 1) { float* p = sv + (size_t)row * DM + c; *(f32x4*)p = v0; *(f32x4*)(p + 4) = v1; }
;                         st_bf16x8(VB + (size_t)row * DM + c, v0, v1); } } }
;     }
.LBB0_1508:
	s_nop 0
	v_fmamk_f32 v35, v153, 0x3a000000, v151
	v_rsq_f32_e32 v38, v35
	v_add_u32_e32 v34, 0xa0, v132
	v_ashrrev_i32_e32 v35, 31, v34
	v_lshlrev_b64 v[36:37], 13, v[34:35]
	v_lshlrev_b64 v[34:35], 12, v[34:35]
	v_pk_mul_f32 v[32:33], v[38:39], v[32:33] op_sel_hi:[0,1]
	v_pk_mul_f32 v[30:31], v[38:39], v[30:31] op_sel_hi:[0,1]
	v_pk_mul_f32 v[28:29], v[38:39], v[28:29] op_sel_hi:[0,1]
	v_pk_mul_f32 v[26:27], v[38:39], v[26:27] op_sel_hi:[0,1]
	s_and_b64 vcc, exec, s[12:13]
	s_mov_b64 s[4:5], -1
	s_cbranch_vccnz .LBB0_1514
	s_and_b64 vcc, exec, s[10:11]
	s_cbranch_vccnz .LBB0_1511
	v_lshl_add_u64 v[40:41], s[30:31], 0, v[36:37]
	v_lshlrev_b32_e32 v42, 2, v157
	v_mov_b32_e32 v43, v131
	v_lshl_add_u64 v[40:41], v[40:41], 0, v[42:43]
	global_store_dwordx4 v[40:41], v[30:33], off
	global_store_dwordx4 v[40:41], v[26:29], off offset:16
	v_lshl_add_u64 v[40:41], s[26:27], 0, v[34:35]
	v_lshl_add_u64 v[44:45], v[40:41], 0, v[130:131]
	s_mov_b64 s[4:5], 0
	v_cvt_pk_bf16_f32 v40, v30, v31
	v_cvt_pk_bf16_f32 v41, v32, v33
	v_cvt_pk_bf16_f32 v42, v26, v27
	v_cvt_pk_bf16_f32 v43, v28, v29
	global_store_dwordx4 v[44:45], v[40:43], off

; __device__ __forceinline__ float rs_val(float ssqv) { return __builtin_amdgcn_rsqf(ssqv * (1.f / DM) + EPS); }
; __device__ __forceinline__ void st_bf16x8(bf16* p, f32x4 a, f32x4 b) { *(bf16x8*)p = pack8(a, b); }
;     __device__ __forceinline__ void operator()(const Acc& acc, const pg8::Unit& u, int wr, int wc, int fr, int fq, const float* rsv) const {
;         const int sec = u.pn >> 3, cin = (u.pn & 7) * 256 + wc * 32 + fq * 8;
; #pragma unroll
;         for (int ai = 0; ai < 2; ++ai)
; #pragma unroll
;             for (int m = 0; m < 4; ++m) { const int row = u.pm * 256 + ai * 128 + wr * 64 + m * 16 + fr; const float rs = rs_val(rsv[ai * 4 + m]);
; #pragma unroll
;                 for (int bj = 0; bj < 2; ++bj) { const f32x4 v0 = acc[ai][bj][m][0] * rs, v1 = acc[ai][bj][m][1] * rs; const int c = cin + bj * 128;
;                     if (sec == 0) st_bf16x8(QB + (size_t)row * DM + c, v0, v1);
;                     else if (sec == 1) { if (ai == 1) { float* p = sk + (size_t)row * DM + c; *(f32x4*)p = v0; *(f32x4*)(p + 4) = v1; } st_bf16x8(KB + (size_t)row * DM + c, v0, v1); }
;                     else { if (ai == 1) { float* p = sv + (size_t)row * DM + c; *(f32x4*)p = v0; *(f32x4*)(p + 4) = v1; }
;                         st_bf16x8(VB + (size_t)row * DM + c, v0, v1); } } }
;     }
.LBB0_1524:
	s_nop 0
	v_fmamk_f32 v19, v152, 0x3a000000, v151
	v_rsq_f32_e32 v22, v19
	v_add_u32_e32 v18, 0xb0, v132
	v_ashrrev_i32_e32 v19, 31, v18
	v_lshlrev_b64 v[20:21], 13, v[18:19]
	v_lshlrev_b64 v[18:19], 12, v[18:19]
	v_pk_mul_f32 v[16:17], v[22:23], v[16:17] op_sel_hi:[0,1]
	v_pk_mul_f32 v[14:15], v[22:23], v[14:15] op_sel_hi:[0,1]
	v_pk_mul_f32 v[12:13], v[22:23], v[12:13] op_sel_hi:[0,1]
	v_pk_mul_f32 v[10:11], v[22:23], v[10:11] op_sel_hi:[0,1]
	s_and_b64 vcc, exec, s[12:13]
	s_mov_b64 s[4:5], -1
	s_cbranch_vccnz .LBB0_1530
	s_and_b64 vcc, exec, s[10:11]
	s_cbranch_vccnz .LBB0_1527
	v_lshl_add_u64 v[24:25], s[30:31], 0, v[20:21]
	v_lshlrev_b32_e32 v26, 2, v157
	v_mov_b32_e32 v27, v131
	v_lshl_add_u64 v[24:25], v[24:25], 0, v[26:27]
	global_store_dwordx4 v[24:25], v[14:17], off
	global_store_dwordx4 v[24:25], v[10:13], off offset:16
	v_lshl_add_u64 v[24:25], s[26:27], 0, v[18:19]
	v_lshl_add_u64 v[28:29], v[24:25], 0, v[130:131]
	s_mov_b64 s[4:5], 0
	v_cvt_pk_bf16_f32 v24, v14, v15
	v_cvt_pk_bf16_f32 v25, v16, v17
	v_cvt_pk_bf16_f32 v26, v10, v11
	v_cvt_pk_bf16_f32 v27, v12, v13
	global_store_dwordx4 v[28:29], v[24:27], off

; __device__ __forceinline__ int otid() { int t = threadIdx.x; asm volatile("" : "+v"(t)); return t; }
; #define PG8_WAIT_V(n) asm volatile("s_waitcnt vmcnt(" #n ")" ::: "memory")
; #define PG8_BAR __builtin_amdgcn_s_barrier()
; template <class Epi, class Sched, bool ALIGN_EPI>
; __device__ __forceinline__ void gemm_phase(LAS unsigned char* lds, const Gemm g, const Sched& S, const Epi& E) {
;     const int tid = otid(), wid = __builtin_amdgcn_readfirstlane(tid >> 6), lane = tid & 63, wr = wid >> 2, wc = wid & 3, fr = lane & 15, fq = lane >> 4;
;     const int K = g.K, nt = K / BK;
;     unsigned voffA[2], voffB[2];
; #pragma unroll
;     for (int i = 0; i < 2; ++i) { int R, C; stage_rc(tid * 16 + i * 8192, R, C); const int Rb = (R & ~31) + perm32(R & 31);
;         voffA[i] = (unsigned)(R * g.lda + C) * 2u; voffB[i] = (unsigned)(Rb * g.ldb + C) * 2u; }
;     const size_t kstep = (size_t)(BK * 2);
;     const size_t hstepA = (size_t)HALF * g.lda * 2, hstepB = (size_t)HALF * g.ldb * 2;
;     const size_t tstepA = 2 * hstepA, tstepB = 2 * hstepB;
;     const unsigned ldsw = (unsigned)wid * 1024u;
;     const int aoff = lds_byte(wr * 64 + fr, fq * 8), boff = lds_byte(wc * 32 + fr, fq * 8);
;     ...
;     const unsigned ldsb0 = (unsigned)(uintptr_t)lds + ldsw;
;     ...
;     Unit cur, nxt; int ui = 0;
;     if (!S.next(0, cur)) return;
;     f32x4 acc[2][2][4][2];
; #pragma unroll
;     for (int a = 0; a < 2; ++a)
; #pragma unroll
;         for (int b = 0; b < 2; ++b)
; #pragma unroll
;             for (int m = 0; m < 4; ++m)
; #pragma unroll
;                 for (int n = 0; n < 2; ++n) acc[a][b][m][n] = (f32x4){0.f, 0.f, 0.f, 0.f};
;     bf16x8 At[4][2], B0[2][2], B1[2][2];
;     float pre[Epi::NPRE > 0 ? Epi::NPRE : 1];
;     if constexpr (Epi::NPRE > 0) E.preload(cur, wr, fr, pre);
;     const char* cA = (const char*)g.A + (size_t)cur.pm * tstepA + (size_t)cur.pn * g.a_koff * 2; const char* cB = (const char*)g.Bt + (size_t)cur.pn * tstepB;
;     PG8_STAGE(PG8_SB(0, 0), cB, voffB); PG8_STAGE(PG8_SB(0, 1), cB + hstepB, voffB); PG8_STAGE(PG8_SA(0, 0), cA, voffA); PG8_STAGE(PG8_SA(0, 1), cA + hstepA, voffA);
;     if (wr == 1) PG8_BAR;
;     PG8_WAIT_V(2); PG8_BAR;
;     PG8_STAGE(PG8_SB(1, 0), cB + kstep, voffB); PG8_STAGE(PG8_SA(1, 0), cA + kstep, voffA); PG8_STAGE(PG8_SB(1, 1), cB + hstepB + kstep, voffB);
;     PG8_WAIT_V(6); PG8_BAR;
.LBB0_1982:
	v_bfe_i32 v5, v2, 27, 1
	v_lshlrev_b32_e32 v3, 4, v2
	v_lshrrev_b32_e32 v5, 22, v5
	v_add_u32_e32 v5, v3, v5
	v_and_b32_e32 v5, 0xfffffc00, v5
	v_sub_u32_e32 v5, v3, v5
	v_ashrrev_i32_e32 v4, 31, v2
	v_lshrrev_b32_e32 v6, 4, v5
	v_lshrrev_b32_e32 v4, 26, v4
	v_bitop3_b32 v6, v6, v5, 32 bitop3:0x6c
	v_ashrrev_i32_e32 v5, 31, v5
	v_add_u32_e32 v4, v2, v4
	v_lshrrev_b32_e32 v5, 26, v5
	v_ashrrev_i32_e32 v4, 6, v4
	v_add_u32_e32 v5, v6, v5
	s_ashr_i32 s8, s6, 3
	v_lshlrev_b32_e32 v7, 3, v4
	v_ashrrev_i32_e32 v5, 6, v5
	s_waitcnt lgkmcnt(0)
	s_add_u32 s36, s14, 0x17500000
	v_and_b32_e32 v7, -16, v7
	v_mul_i32_i24_e32 v8, 64, v5
	s_addc_u32 s37, s15, 0
	v_add_u32_e32 v7, v5, v7
	v_sub_u32_e32 v6, v6, v8
	v_mov_b32_e32 v8, 1
	s_add_u32 s38, s4, 0x7500000
	v_lshlrev_b32_e32 v4, 5, v4
	v_ashrrev_i16_sdwa v6, v8, sext(v6) dst_sel:DWORD dst_unused:UNUSED_PAD src0_sel:DWORD src1_sel:BYTE_0
	v_lshlrev_b32_e32 v9, 1, v7
	v_lshrrev_b32_e32 v10, 2, v7
	v_and_b32_e32 v5, 3, v5
	s_mov_b32 s4, 0xfffe0
	v_and_b32_e32 v4, 32, v4
	v_bfe_i32 v6, v6, 0, 16
	v_and_b32_e32 v9, 24, v9
	v_and_b32_e32 v10, 4, v10
	v_and_or_b32 v5, v7, s4, v5
	v_or3_b32 v5, v5, v10, v9
	v_add_lshl_u32 v4, v4, v6, 1
	v_add_u32_e32 v3, 0x2000, v3
	v_lshl_add_u32 v179, v7, 12, v4
	v_lshl_add_u32 v200, v5, 12, v4
	v_ashrrev_i32_e32 v4, 31, v3
	v_lshrrev_b32_e32 v4, 22, v4
	v_add_u32_e32 v4, v3, v4
	v_ashrrev_i32_e32 v4, 10, v4
	v_mul_i32_i24_e32 v5, 0x400, v4
	v_sub_u32_e32 v3, v3, v5
	v_lshrrev_b32_e32 v5, 4, v3
	v_bitop3_b32 v3, v5, v3, 32 bitop3:0x6c
	v_ashrrev_i32_e32 v6, 31, v3
	v_lshrrev_b32_e32 v6, 26, v6
	v_lshlrev_b32_e32 v5, 3, v4
	v_add_u32_e32 v6, v3, v6
	v_and_b32_e32 v5, -16, v5
	v_ashrrev_i32_e32 v7, 6, v6
	s_addc_u32 s39, s5, 0
	v_add_u32_e32 v5, v7, v5
	v_and_b32_e32 v7, 3, v7
	s_ashr_i32 s7, s3, 6
	v_and_or_b32 v7, v5, s4, v7
	s_lshl_b32 s4, s7, 10
	s_add_i32 s2, s2, s8
	s_add_i32 s41, s4, 0
	s_ashr_i32 s4, s2, 31
	s_lshr_b32 s4, s4, 26
	s_add_i32 s4, s2, s4
	s_ashr_i32 s5, s4, 6
	s_andn2_b32 s4, s4, 63
	s_sub_i32 s2, s2, s4
	s_bfe_i32 s4, s2, 0x80000
	s_bfe_u32 s4, s4, 0x3000c
	s_add_i32 s4, s2, s4
	s_bfe_i32 s8, s4, 0x80000
	s_and_b32 s4, s4, 0xf8
	s_sub_i32 s2, s2, s4
	s_lshl_b32 s5, s5, 3
	s_sext_i32_i16 s8, s8
	s_sext_i32_i8 s2, s2
	v_and_b32_e32 v6, 0xc0, v6
	s_lshr_b32 s14, s8, 3
	s_add_i32 s4, s5, s2
	v_sub_u32_e32 v3, v3, v6
	s_ashr_i32 s5, s4, 31
	s_bfe_i64 s[16:17], s[14:15], 0x100000
	s_ashr_i32 s6, s3, 8
	v_lshlrev_b32_e32 v4, 5, v4
	v_ashrrev_i16_sdwa v3, v8, sext(v3) dst_sel:DWORD dst_unused:UNUSED_PAD src0_sel:DWORD src1_sel:BYTE_0
	v_lshlrev_b32_e32 v6, 1, v5
	v_lshrrev_b32_e32 v8, 2, v5
	s_lshl_b64 s[8:9], s[4:5], 20
	s_lshl_b64 s[16:17], s[16:17], 20
	v_and_b32_e32 v4, 32, v4
	v_bfe_i32 v3, v3, 0, 16
	v_and_b32_e32 v6, 24, v6
	v_and_b32_e32 v8, 4, v8
	s_add_u32 s26, s38, s16
	v_or3_b32 v6, v7, v8, v6
	v_add_lshl_u32 v3, v4, v3, 1
	s_addc_u32 s27, s39, s17
	s_add_i32 s42, s41, 0x10000
	s_mov_b32 m0, s42
	s_nop 0
	global_load_lds_dwordx4 v200, s[26:27]
	s_add_i32 s43, s41, 0x12000
	v_lshl_add_u32 v203, v6, 12, v3
	s_mov_b32 m0, s43
	s_nop 0
	global_load_lds_dwordx4 v203, s[26:27]
	s_add_u32 s16, s26, 0x80000
	s_addc_u32 s17, s27, 0
	s_add_i32 s44, s41, 0x14000
	s_mov_b32 m0, s44
	s_nop 0
	global_load_lds_dwordx4 v200, s[16:17]
	s_add_i32 s45, s41, 0x16000
	s_mov_b32 m0, s45
	s_nop 0
	global_load_lds_dwordx4 v203, s[16:17]
	s_add_u32 s28, s36, s8
	s_addc_u32 s29, s37, s9
	s_mov_b32 m0, s41
	s_nop 0
	global_load_lds_dwordx4 v179, s[28:29]
	s_add_i32 s46, s41, 0x2000
	v_lshl_add_u32 v201, v5, 12, v3
	s_mov_b32 m0, s46
	s_nop 0
	global_load_lds_dwordx4 v201, s[28:29]
	s_add_u32 s18, s28, 0x80000
	s_addc_u32 s19, s29, 0
	s_add_i32 s47, s41, 0x4000
	s_mov_b32 m0, s47
	s_nop 0
	global_load_lds_dwordx4 v179, s[18:19]
	s_add_i32 s48, s41, 0x6000
	s_mov_b32 m0, s48
	s_nop 0
	global_load_lds_dwordx4 v201, s[18:19]
	s_cmp_eq_u32 s6, 1
	s_mov_b32 s40, 0
	s_cselect_b64 s[8:9], -1, 0
	s_cmp_lg_u32 s6, 1
	s_cbranch_scc1 .LBB0_1984
	s_barrier
.LBB0_1984:
	s_sext_i32_i8 s2, s14
	s_add_u32 s14, s10, 0x1d800000
	v_bfe_u32 v5, v2, 4, 2
	v_and_b32_e32 v3, 15, v2
	s_addc_u32 s15, s11, 0
	s_lshl_b32 s18, s6, 6
	v_lshlrev_b32_e32 v2, 4, v5
	v_lshlrev_b32_e32 v4, 2, v3
	v_or_b32_e32 v204, s18, v3
	v_lshl_or_b32 v6, v3, 6, v2
	s_lshl_b32 s5, s6, 13
	v_and_b32_e32 v3, 32, v4
	v_bitop3_b32 v7, v6, s5, v3 bitop3:0xde
	s_lshl_b32 s5, s7, 5
	s_and_b32 s5, s5, 0x60
	s_lshl_b32 s6, s5, 7
	v_bitop3_b32 v6, v6, s6, v3 bitop3:0xde
	s_add_u32 s6, s26, 0x80
	s_waitcnt vmcnt(2)
	s_barrier
	s_addc_u32 s7, s27, 0
	s_add_i32 s49, s41, 0x18000
	s_mov_b32 m0, s49
	s_nop 0
	global_load_lds_dwordx4 v200, s[6:7]
	s_add_i32 s50, s41, 0x1a000
	s_mov_b32 m0, s50
	s_nop 0
	global_load_lds_dwordx4 v203, s[6:7]
	s_add_u32 s6, s28, 0x80
	s_addc_u32 s7, s29, 0
	s_add_i32 s51, s41, 0x8000
	s_mov_b32 m0, s51
	s_nop 0
	global_load_lds_dwordx4 v179, s[6:7]
	s_add_i32 s52, s41, 0xa000
	s_mov_b32 m0, s52
	s_nop 0
	global_load_lds_dwordx4 v201, s[6:7]
	s_add_u32 s6, s16, 0x80
	s_addc_u32 s7, s17, 0
	s_add_i32 s53, s41, 0x1c000
	s_add_i32 s54, s41, 0x1e000
	s_add_i32 s55, s41, 0xc000
	s_cmpk_lt_u32 s3, 0x100
	s_mov_b32 m0, s53
	s_nop 0
	global_load_lds_dwordx4 v200, s[6:7]
	s_cselect_b64 s[16:17], -1, 0
	s_lshl_b32 s3, s5, 1
	s_mov_b32 m0, s54
	s_nop 0
	global_load_lds_dwordx4 v203, s[6:7]
	s_add_u32 s6, s14, s3
	s_addc_u32 s7, s15, 0
	v_mov_b32_e32 v3, 0
	s_ashr_i32 s19, s18, 31
	v_lshl_add_u64 v[180:181], s[6:7], 0, v[2:3]
	s_add_i32 s56, s41, 0xe000
	s_lshl_b64 s[6:7], s[18:19], 2
	s_add_u32 s6, s12, s6
	v_lshl_or_b32 v205, v5, 3, s5
	v_cmp_eq_u32_e64 s[10:11], 0, v5
	s_addc_u32 s7, s13, s7
	v_mov_b32_e32 v5, v3
	s_waitcnt vmcnt(6)
	v_lshl_add_u64 v[2:3], s[6:7], 0, v[4:5]
	s_mov_b64 s[6:7], 0x28c00
	v_lshl_add_u64 v[182:183], v[2:3], 0, s[6:7]
	v_add_u32_e32 v2, 0, v6
	v_mov_b64_e32 v[184:185], 0x100
	v_mov_b64_e32 v[186:187], 0xff
	v_add_u32_e32 v206, 0x10000, v2
	v_add_u32_e32 v207, 0x14000, v2
	v_add_u32_e32 v208, 0, v7
	v_add_u32_e32 v209, 0x18000, v2
	v_add_u32_e32 v210, 0x1c000, v2
	s_barrier
	s_branch .LBB0_1987

; #define PG8_STAGE(bufoff, gbase, voff) do { _Pragma("unroll") for (int _i = 0; _i < 2; ++_i) { unsigned keep_; \
;         asm volatile("s_mov_b32 %0, m0\n\ts_mov_b32 m0, %3\n\ts_nop 0\n\tglobal_load_lds_dwordx4 %1, %2\n\ts_mov_b32 m0, %0" \
;             : "=&s"(keep_) : "v"((voff)[_i]), "s"((const void*)(gbase)), "s"(ldsb0 + (unsigned)(bufoff) + (unsigned)(_i * 8192)) : "memory"); } } while (0)
; #define PG8_LDA(dst, b, h) do { _Pragma("unroll") for (int m = 0; m < 4; ++m) _Pragma("unroll") for (int k = 0; k < 2; ++k) dst[m][k] = *(const LAS bf16x8*)(lds + PG8_SA(b, h) + aoff + m * 2048 + k * 1024); } while (0)
; #define PG8_LDB(dst, b, h) do { _Pragma("unroll") for (int n = 0; n < 2; ++n) _Pragma("unroll") for (int k = 0; k < 2; ++k) dst[n][k] = *(const LAS bf16x8*)(lds + PG8_SB(b, h) + boff + n * 2048 + k * 1024); } while (0)
; #define PG8_MMA(ai, bj, At, Bt) do { __builtin_amdgcn_s_setprio(1); _Pragma("unroll") for (int m = 0; m < 4; ++m) _Pragma("unroll") for (int n = 0; n < 2; ++n) _Pragma("unroll") for (int k = 0; k < 2; ++k) \
;         acc[ai][bj][m][n] = __builtin_amdgcn_mfma_f32_16x16x32_bf16(Bt[n][k], At[m][k], acc[ai][bj][m][n], 0, 0, 0); __builtin_amdgcn_s_setprio(0); } while (0)
; #define PG8_WAIT_V(n) asm volatile("s_waitcnt vmcnt(" #n ")" ::: "memory")
; #define PG8_BAR __builtin_amdgcn_s_barrier()
; template <class Epi, class Sched, bool ALIGN_EPI>
; __device__ __forceinline__ void gemm_phase(LAS unsigned char* lds, const Gemm g, const Sched& S, const Epi& E) {
;     ...
;         for (int t = 0; t < nt; t += 2) {
;             const bool last = (t == nt - 2);
;             const char* a1 = cA + (size_t)(t + 1) * kstep;
;             const char* a2 = last ? nA : cA + (size_t)(t + 2) * kstep; const char* b2 = last ? nB : cB + (size_t)(t + 2) * kstep;
;             const char* a3 = a2 + kstep; const char* b3 = b2 + kstep;
;             PG8_LDB(B0, 0, 0); PG8_LDB(B1, 0, 1); PG8_SCHED; PG8_LDA(At, 0, 0); PG8_STAGE(PG8_SA(1, 1), a1 + hstepA, voffA);
;             PG8_WAIT_V(8); PG8_WAIT_L(0); PG8_BAR; PG8_MMA(0, 0, At, B0); PG8_MMA(0, 1, At, B1); PG8_BAR; PG8_SCHED;
;             PG8_LDA(At, 0, 1); PG8_STAGE(PG8_SB(0, 0), b2, voffB); PG8_STAGE(PG8_SB(0, 1), b2 + hstepB, voffB); PG8_STAGE(PG8_SA(0, 0), a2, voffA);
;             PG8_WAIT_V(8); PG8_WAIT_L(0); PG8_BAR; PG8_MMA(1, 0, At, B0); PG8_MMA(1, 1, At, B1); PG8_BAR; PG8_SCHED;
.LBB0_1994:
	ds_read_b128 v[110:113], v206
	ds_read_b128 v[126:129], v206 offset:1024
	ds_read_b128 v[130:133], v206 offset:2048
	ds_read_b128 v[142:145], v206 offset:3072
	ds_read_b128 v[146:149], v207
	ds_read_b128 v[150:153], v207 offset:1024
	ds_read_b128 v[154:157], v207 offset:2048
	ds_read_b128 v[158:161], v207 offset:3072
	s_cmp_eq_u32 s59, 28
	s_cselect_b32 s34, s5, s19
	s_cselect_b32 s35, s3, s21
	s_cselect_b32 s30, s7, s57
	s_cselect_b32 s31, s6, s58
	s_add_u32 s28, s34, 0x80
	s_addc_u32 s29, s35, 0
	ds_read_b128 v[162:165], v208
	ds_read_b128 v[166:169], v208 offset:1024
	ds_read_b128 v[170:173], v208 offset:2048
	ds_read_b128 v[174:177], v208 offset:3072
	ds_read_b128 v[188:191], v208 offset:4096
	ds_read_b128 v[192:195], v208 offset:5120
	ds_read_b128 v[196:199], v208 offset:6144
	ds_read_b128 v[212:215], v208 offset:7168
	s_mov_b32 m0, s55
	s_nop 0
	global_load_lds_dwordx4 v179, s[26:27]
	s_nop 0
	s_mov_b32 m0, s56
	s_nop 0
	global_load_lds_dwordx4 v201, s[26:27]
	s_waitcnt vmcnt(8)
	s_waitcnt lgkmcnt(0)
	s_barrier
	s_setprio 1
	v_mfma_f32_16x16x32_bf16 v[138:141], v[110:113], v[162:165], v[138:141]
	v_mfma_f32_16x16x32_bf16 v[134:137], v[130:133], v[162:165], v[134:137]
	v_mfma_f32_16x16x32_bf16 v[114:117], v[110:113], v[170:173], v[114:117]
	v_mfma_f32_16x16x32_bf16 v[106:109], v[130:133], v[170:173], v[106:109]
	v_mfma_f32_16x16x32_bf16 v[94:97], v[110:113], v[188:191], v[94:97]
	v_mfma_f32_16x16x32_bf16 v[90:93], v[130:133], v[188:191], v[90:93]
	v_mfma_f32_16x16x32_bf16 v[78:81], v[110:113], v[196:199], v[78:81]
	v_mfma_f32_16x16x32_bf16 v[74:77], v[130:133], v[196:199], v[74:77]
	v_mfma_f32_16x16x32_bf16 v[138:141], v[126:129], v[166:169], v[138:141]
	v_mfma_f32_16x16x32_bf16 v[134:137], v[142:145], v[166:169], v[134:137]
	v_mfma_f32_16x16x32_bf16 v[114:117], v[126:129], v[174:177], v[114:117]
	v_mfma_f32_16x16x32_bf16 v[106:109], v[142:145], v[174:177], v[106:109]
	v_mfma_f32_16x16x32_bf16 v[94:97], v[126:129], v[192:195], v[94:97]
	v_mfma_f32_16x16x32_bf16 v[90:93], v[142:145], v[192:195], v[90:93]
	v_mfma_f32_16x16x32_bf16 v[78:81], v[126:129], v[212:215], v[78:81]
	v_mfma_f32_16x16x32_bf16 v[74:77], v[142:145], v[212:215], v[74:77]
	v_mfma_f32_16x16x32_bf16 v[122:125], v[146:149], v[162:165], v[122:125]
	v_mfma_f32_16x16x32_bf16 v[118:121], v[154:157], v[162:165], v[118:121]
	v_mfma_f32_16x16x32_bf16 v[102:105], v[146:149], v[170:173], v[102:105]
	v_mfma_f32_16x16x32_bf16 v[98:101], v[154:157], v[170:173], v[98:101]
	v_mfma_f32_16x16x32_bf16 v[86:89], v[146:149], v[188:191], v[86:89]
	v_mfma_f32_16x16x32_bf16 v[82:85], v[154:157], v[188:191], v[82:85]
	v_mfma_f32_16x16x32_bf16 v[70:73], v[146:149], v[196:199], v[70:73]
	v_mfma_f32_16x16x32_bf16 v[66:69], v[154:157], v[196:199], v[66:69]
	v_mfma_f32_16x16x32_bf16 v[122:125], v[150:153], v[166:169], v[122:125]
	v_mfma_f32_16x16x32_bf16 v[118:121], v[158:161], v[166:169], v[118:121]
	v_mfma_f32_16x16x32_bf16 v[102:105], v[150:153], v[174:177], v[102:105]
	v_mfma_f32_16x16x32_bf16 v[98:101], v[158:161], v[174:177], v[98:101]
	v_mfma_f32_16x16x32_bf16 v[86:89], v[150:153], v[192:195], v[86:89]
	v_mfma_f32_16x16x32_bf16 v[82:85], v[158:161], v[192:195], v[82:85]
	v_mfma_f32_16x16x32_bf16 v[70:73], v[150:153], v[212:215], v[70:73]
	v_mfma_f32_16x16x32_bf16 v[66:69], v[158:161], v[212:215], v[66:69]
	s_setprio 0
	s_barrier
	ds_read_b128 v[162:165], v208 offset:16384
	ds_read_b128 v[166:169], v208 offset:17408
	ds_read_b128 v[170:173], v208 offset:18432
	ds_read_b128 v[174:177], v208 offset:19456
	ds_read_b128 v[188:191], v208 offset:20480
	ds_read_b128 v[192:195], v208 offset:21504
	ds_read_b128 v[196:199], v208 offset:22528
	ds_read_b128 v[212:215], v208 offset:23552
	s_mov_b32 m0, s42
	s_nop 0
	global_load_lds_dwordx4 v200, s[30:31]
	s_nop 0
	s_mov_b32 m0, s43
	s_nop 0
	global_load_lds_dwordx4 v203, s[30:31]
	s_add_u32 s60, s30, 0x80000
	s_addc_u32 s61, s31, 0
	s_mov_b32 m0, s44
	s_nop 0
	global_load_lds_dwordx4 v200, s[60:61]
	s_nop 0
	s_mov_b32 m0, s45
	s_nop 0
	global_load_lds_dwordx4 v203, s[60:61]
	s_mov_b32 m0, s41
	s_nop 0
	global_load_lds_dwordx4 v179, s[34:35]
	s_nop 0
	s_mov_b32 m0, s46
	s_nop 0
	global_load_lds_dwordx4 v201, s[34:35]
	s_waitcnt vmcnt(8)
	s_waitcnt lgkmcnt(0)
	s_barrier
	s_setprio 1
	v_mfma_f32_16x16x32_bf16 v[62:65], v[110:113], v[162:165], v[62:65]
	v_mfma_f32_16x16x32_bf16 v[58:61], v[130:133], v[162:165], v[58:61]
	v_mfma_f32_16x16x32_bf16 v[46:49], v[110:113], v[170:173], v[46:49]
	v_mfma_f32_16x16x32_bf16 v[42:45], v[130:133], v[170:173], v[42:45]
	v_mfma_f32_16x16x32_bf16 v[30:33], v[110:113], v[188:191], v[30:33]
	v_mfma_f32_16x16x32_bf16 v[26:29], v[130:133], v[188:191], v[26:29]
	v_mfma_f32_16x16x32_bf16 v[14:17], v[110:113], v[196:199], v[14:17]
	v_mfma_f32_16x16x32_bf16 v[10:13], v[130:133], v[196:199], v[10:13]
	v_mfma_f32_16x16x32_bf16 v[62:65], v[126:129], v[166:169], v[62:65]
	v_mfma_f32_16x16x32_bf16 v[58:61], v[142:145], v[166:169], v[58:61]
	v_mfma_f32_16x16x32_bf16 v[46:49], v[126:129], v[174:177], v[46:49]
	v_mfma_f32_16x16x32_bf16 v[42:45], v[142:145], v[174:177], v[42:45]
	v_mfma_f32_16x16x32_bf16 v[30:33], v[126:129], v[192:195], v[30:33]
	v_mfma_f32_16x16x32_bf16 v[26:29], v[142:145], v[192:195], v[26:29]
	v_mfma_f32_16x16x32_bf16 v[14:17], v[126:129], v[212:215], v[14:17]
	v_mfma_f32_16x16x32_bf16 v[10:13], v[142:145], v[212:215], v[10:13]
	v_mfma_f32_16x16x32_bf16 v[54:57], v[146:149], v[162:165], v[54:57]
	v_mfma_f32_16x16x32_bf16 v[50:53], v[154:157], v[162:165], v[50:53]
	v_mfma_f32_16x16x32_bf16 v[38:41], v[146:149], v[170:173], v[38:41]
	v_mfma_f32_16x16x32_bf16 v[34:37], v[154:157], v[170:173], v[34:37]
	v_mfma_f32_16x16x32_bf16 v[22:25], v[146:149], v[188:191], v[22:25]
	v_mfma_f32_16x16x32_bf16 v[18:21], v[154:157], v[188:191], v[18:21]
	v_mfma_f32_16x16x32_bf16 v[6:9], v[146:149], v[196:199], v[6:9]
	v_mfma_f32_16x16x32_bf16 v[2:5], v[154:157], v[196:199], v[2:5]
	v_mfma_f32_16x16x32_bf16 v[54:57], v[150:153], v[166:169], v[54:57]
	v_mfma_f32_16x16x32_bf16 v[50:53], v[158:161], v[166:169], v[50:53]
	v_mfma_f32_16x16x32_bf16 v[38:41], v[150:153], v[174:177], v[38:41]
	v_mfma_f32_16x16x32_bf16 v[34:37], v[158:161], v[174:177], v[34:37]
	v_mfma_f32_16x16x32_bf16 v[22:25], v[150:153], v[192:195], v[22:25]
	v_mfma_f32_16x16x32_bf16 v[18:21], v[158:161], v[192:195], v[18:21]
	v_mfma_f32_16x16x32_bf16 v[6:9], v[150:153], v[212:215], v[6:9]
	v_mfma_f32_16x16x32_bf16 v[2:5], v[158:161], v[212:215], v[2:5]
	s_setprio 0
	s_barrier
; #define PG8_STAGE(bufoff, gbase, voff) do { _Pragma("unroll") for (int _i = 0; _i < 2; ++_i) { unsigned keep_; \
;         asm volatile("s_mov_b32 %0, m0\n\ts_mov_b32 m0, %3\n\ts_nop 0\n\tglobal_load_lds_dwordx4 %1, %2\n\ts_mov_b32 m0, %0" \
;             : "=&s"(keep_) : "v"((voff)[_i]), "s"((const void*)(gbase)), "s"(ldsb0 + (unsigned)(bufoff) + (unsigned)(_i * 8192)) : "memory"); } } while (0)
; #define PG8_LDA(dst, b, h) do { _Pragma("unroll") for (int m = 0; m < 4; ++m) _Pragma("unroll") for (int k = 0; k < 2; ++k) dst[m][k] = *(const LAS bf16x8*)(lds + PG8_SA(b, h) + aoff + m * 2048 + k * 1024); } while (0)
; #define PG8_LDB(dst, b, h) do { _Pragma("unroll") for (int n = 0; n < 2; ++n) _Pragma("unroll") for (int k = 0; k < 2; ++k) dst[n][k] = *(const LAS bf16x8*)(lds + PG8_SB(b, h) + boff + n * 2048 + k * 1024); } while (0)
; #define PG8_MMA(ai, bj, At, Bt) do { __builtin_amdgcn_s_setprio(1); _Pragma("unroll") for (int m = 0; m < 4; ++m) _Pragma("unroll") for (int n = 0; n < 2; ++n) _Pragma("unroll") for (int k = 0; k < 2; ++k) \
;         acc[ai][bj][m][n] = __builtin_amdgcn_mfma_f32_16x16x32_bf16(Bt[n][k], At[m][k], acc[ai][bj][m][n], 0, 0, 0); __builtin_amdgcn_s_setprio(0); } while (0)
; #define PG8_WAIT_V(n) asm volatile("s_waitcnt vmcnt(" #n ")" ::: "memory")
; #define PG8_WAIT_L(n) asm volatile("s_waitcnt lgkmcnt(" #n ")" ::: "memory")
; #define PG8_BAR __builtin_amdgcn_s_barrier()
; #define PG8_SCHED __builtin_amdgcn_sched_barrier(0)
; template <class Epi, class Sched, bool ALIGN_EPI>
; __device__ __forceinline__ void gemm_phase(LAS unsigned char* lds, const Gemm g, const Sched& S, const Epi& E) {
;     ...
;             PG8_LDB(B0, 1, 0); PG8_LDB(B1, 1, 1); PG8_SCHED; PG8_LDA(At, 1, 0); PG8_STAGE(PG8_SA(0, 1), a2 + hstepA, voffA);
;             PG8_WAIT_V(8); PG8_WAIT_L(0); PG8_BAR; PG8_MMA(0, 0, At, B0); PG8_MMA(0, 1, At, B1); PG8_BAR; PG8_SCHED;
;             PG8_LDA(At, 1, 1); PG8_STAGE(PG8_SB(1, 0), b3, voffB); PG8_STAGE(PG8_SB(1, 1), b3 + hstepB, voffB); PG8_STAGE(PG8_SA(1, 0), a3, voffA);
;             PG8_WAIT_V(8); PG8_WAIT_L(0); PG8_BAR; PG8_MMA(1, 0, At, B0); PG8_MMA(1, 1, At, B1); PG8_BAR; PG8_SCHED;
;         }
	ds_read_b128 v[110:113], v209
	ds_read_b128 v[126:129], v209 offset:1024
	ds_read_b128 v[130:133], v209 offset:2048
	ds_read_b128 v[142:145], v209 offset:3072
	ds_read_b128 v[146:149], v210
	ds_read_b128 v[150:153], v210 offset:1024
	ds_read_b128 v[154:157], v210 offset:2048
	ds_read_b128 v[158:161], v210 offset:3072
	ds_read_b128 v[162:165], v208 offset:32768
	ds_read_b128 v[166:169], v208 offset:33792
	ds_read_b128 v[170:173], v208 offset:34816
	ds_read_b128 v[174:177], v208 offset:35840
	ds_read_b128 v[188:191], v208 offset:36864
	ds_read_b128 v[192:195], v208 offset:37888
	ds_read_b128 v[196:199], v208 offset:38912
	ds_read_b128 v[212:215], v208 offset:39936
	s_add_u32 s34, s34, 0x80000
	s_addc_u32 s35, s35, 0
	s_mov_b32 m0, s47
	s_nop 0
	global_load_lds_dwordx4 v179, s[34:35]
	s_nop 0
	s_mov_b32 m0, s48
	s_nop 0
	global_load_lds_dwordx4 v201, s[34:35]
	s_waitcnt vmcnt(8)
	s_waitcnt lgkmcnt(0)
	s_barrier
	s_setprio 1
	v_mfma_f32_16x16x32_bf16 v[138:141], v[110:113], v[162:165], v[138:141]
	v_mfma_f32_16x16x32_bf16 v[134:137], v[130:133], v[162:165], v[134:137]
	v_mfma_f32_16x16x32_bf16 v[114:117], v[110:113], v[170:173], v[114:117]
	v_mfma_f32_16x16x32_bf16 v[106:109], v[130:133], v[170:173], v[106:109]
	v_mfma_f32_16x16x32_bf16 v[94:97], v[110:113], v[188:191], v[94:97]
	v_mfma_f32_16x16x32_bf16 v[90:93], v[130:133], v[188:191], v[90:93]
	v_mfma_f32_16x16x32_bf16 v[78:81], v[110:113], v[196:199], v[78:81]
	v_mfma_f32_16x16x32_bf16 v[74:77], v[130:133], v[196:199], v[74:77]
	v_mfma_f32_16x16x32_bf16 v[138:141], v[126:129], v[166:169], v[138:141]
	v_mfma_f32_16x16x32_bf16 v[134:137], v[142:145], v[166:169], v[134:137]
	v_mfma_f32_16x16x32_bf16 v[114:117], v[126:129], v[174:177], v[114:117]
	v_mfma_f32_16x16x32_bf16 v[106:109], v[142:145], v[174:177], v[106:109]
	v_mfma_f32_16x16x32_bf16 v[94:97], v[126:129], v[192:195], v[94:97]
	v_mfma_f32_16x16x32_bf16 v[90:93], v[142:145], v[192:195], v[90:93]
	v_mfma_f32_16x16x32_bf16 v[78:81], v[126:129], v[212:215], v[78:81]
	v_mfma_f32_16x16x32_bf16 v[74:77], v[142:145], v[212:215], v[74:77]
	v_mfma_f32_16x16x32_bf16 v[122:125], v[146:149], v[162:165], v[122:125]
	v_mfma_f32_16x16x32_bf16 v[118:121], v[154:157], v[162:165], v[118:121]
	v_mfma_f32_16x16x32_bf16 v[102:105], v[146:149], v[170:173], v[102:105]
	v_mfma_f32_16x16x32_bf16 v[98:101], v[154:157], v[170:173], v[98:101]
	v_mfma_f32_16x16x32_bf16 v[86:89], v[146:149], v[188:191], v[86:89]
	v_mfma_f32_16x16x32_bf16 v[82:85], v[154:157], v[188:191], v[82:85]
	v_mfma_f32_16x16x32_bf16 v[70:73], v[146:149], v[196:199], v[70:73]
	v_mfma_f32_16x16x32_bf16 v[66:69], v[154:157], v[196:199], v[66:69]
	v_mfma_f32_16x16x32_bf16 v[122:125], v[150:153], v[166:169], v[122:125]
	v_mfma_f32_16x16x32_bf16 v[118:121], v[158:161], v[166:169], v[118:121]
	v_mfma_f32_16x16x32_bf16 v[102:105], v[150:153], v[174:177], v[102:105]
	v_mfma_f32_16x16x32_bf16 v[98:101], v[158:161], v[174:177], v[98:101]
	v_mfma_f32_16x16x32_bf16 v[86:89], v[150:153], v[192:195], v[86:89]
	v_mfma_f32_16x16x32_bf16 v[82:85], v[158:161], v[192:195], v[82:85]
	v_mfma_f32_16x16x32_bf16 v[70:73], v[150:153], v[212:215], v[70:73]
	v_mfma_f32_16x16x32_bf16 v[66:69], v[158:161], v[212:215], v[66:69]
	s_setprio 0
	s_barrier
	ds_read_b128 v[162:165], v208 offset:49152
	ds_read_b128 v[166:169], v208 offset:50176
	ds_read_b128 v[170:173], v208 offset:51200
	ds_read_b128 v[174:177], v208 offset:52224
	ds_read_b128 v[188:191], v208 offset:53248
	ds_read_b128 v[192:195], v208 offset:54272
	ds_read_b128 v[196:199], v208 offset:55296
	ds_read_b128 v[212:215], v208 offset:56320
	s_add_u32 s34, s30, 0x80
	s_addc_u32 s35, s31, 0
	s_mov_b32 m0, s49
	s_nop 0
	global_load_lds_dwordx4 v200, s[34:35]
	s_add_u32 s30, s30, 0x80080
	s_mov_b32 m0, s50
	s_nop 0
	global_load_lds_dwordx4 v203, s[34:35]
	s_addc_u32 s31, s31, 0
	s_mov_b32 m0, s53
	s_nop 0
	global_load_lds_dwordx4 v200, s[30:31]
	s_nop 0
	s_mov_b32 m0, s54
	s_nop 0
	global_load_lds_dwordx4 v203, s[30:31]
	s_mov_b32 m0, s51
	s_nop 0
	global_load_lds_dwordx4 v179, s[28:29]
	s_nop 0
	s_mov_b32 m0, s52
	s_nop 0
	global_load_lds_dwordx4 v201, s[28:29]
	s_waitcnt vmcnt(8)
	s_waitcnt lgkmcnt(0)
	s_barrier
	s_setprio 1
	v_mfma_f32_16x16x32_bf16 v[62:65], v[110:113], v[162:165], v[62:65]
	v_mfma_f32_16x16x32_bf16 v[58:61], v[130:133], v[162:165], v[58:61]
	v_mfma_f32_16x16x32_bf16 v[46:49], v[110:113], v[170:173], v[46:49]
	v_mfma_f32_16x16x32_bf16 v[42:45], v[130:133], v[170:173], v[42:45]
	v_mfma_f32_16x16x32_bf16 v[30:33], v[110:113], v[188:191], v[30:33]
	v_mfma_f32_16x16x32_bf16 v[26:29], v[130:133], v[188:191], v[26:29]
	v_mfma_f32_16x16x32_bf16 v[14:17], v[110:113], v[196:199], v[14:17]
	v_mfma_f32_16x16x32_bf16 v[10:13], v[130:133], v[196:199], v[10:13]
	v_mfma_f32_16x16x32_bf16 v[62:65], v[126:129], v[166:169], v[62:65]
	v_mfma_f32_16x16x32_bf16 v[58:61], v[142:145], v[166:169], v[58:61]
	v_mfma_f32_16x16x32_bf16 v[46:49], v[126:129], v[174:177], v[46:49]
	v_mfma_f32_16x16x32_bf16 v[42:45], v[142:145], v[174:177], v[42:45]
	v_mfma_f32_16x16x32_bf16 v[30:33], v[126:129], v[192:195], v[30:33]
	v_mfma_f32_16x16x32_bf16 v[26:29], v[142:145], v[192:195], v[26:29]
	v_mfma_f32_16x16x32_bf16 v[14:17], v[126:129], v[212:215], v[14:17]
	v_mfma_f32_16x16x32_bf16 v[10:13], v[142:145], v[212:215], v[10:13]
	v_mfma_f32_16x16x32_bf16 v[54:57], v[146:149], v[162:165], v[54:57]
	v_mfma_f32_16x16x32_bf16 v[50:53], v[154:157], v[162:165], v[50:53]
	v_mfma_f32_16x16x32_bf16 v[38:41], v[146:149], v[170:173], v[38:41]
	v_mfma_f32_16x16x32_bf16 v[34:37], v[154:157], v[170:173], v[34:37]
	v_mfma_f32_16x16x32_bf16 v[22:25], v[146:149], v[188:191], v[22:25]
	v_mfma_f32_16x16x32_bf16 v[18:21], v[154:157], v[188:191], v[18:21]
	v_mfma_f32_16x16x32_bf16 v[6:9], v[146:149], v[196:199], v[6:9]
	v_mfma_f32_16x16x32_bf16 v[2:5], v[154:157], v[196:199], v[2:5]
	v_mfma_f32_16x16x32_bf16 v[54:57], v[150:153], v[166:169], v[54:57]
	v_mfma_f32_16x16x32_bf16 v[50:53], v[158:161], v[166:169], v[50:53]
	v_mfma_f32_16x16x32_bf16 v[38:41], v[150:153], v[174:177], v[38:41]
	v_mfma_f32_16x16x32_bf16 v[34:37], v[158:161], v[174:177], v[34:37]
	v_mfma_f32_16x16x32_bf16 v[22:25], v[150:153], v[192:195], v[22:25]
	v_mfma_f32_16x16x32_bf16 v[18:21], v[158:161], v[192:195], v[18:21]
	v_mfma_f32_16x16x32_bf16 v[6:9], v[150:153], v[212:215], v[6:9]
	v_mfma_f32_16x16x32_bf16 v[2:5], v[158:161], v[212:215], v[2:5]
	s_setprio 0
	s_barrier
	s_add_i32 s59, s59, 2
	s_add_u32 s19, s19, 0x100
	s_addc_u32 s21, s21, 0
	s_add_u32 s57, s57, 0x100
	s_addc_u32 s58, s58, 0
	s_add_u32 s26, s26, 0x100
	s_addc_u32 s27, s27, 0
	s_cmp_gt_u32 s59, 29
	s_cbranch_scc0 .LBB0_1994
	s_and_b64 vcc, exec, s[16:17]
	s_cbranch_vccz .LBB0_1997
	s_barrier

; __device__ __forceinline__ int otid() { int t = threadIdx.x; asm volatile("" : "+v"(t)); return t; }
;     __device__ bool next(int i, Unit& u) const {
;         const long L = (long)i * G + c; if (L >= nwg) return false;
;         int wgid = (int)L; { const int q = nwg / NXCD, r = nwg % NXCD, xcd = wgid % NXCD, off = wgid / NXCD; wgid = (xcd < r ? xcd * (q + 1) : r * (q + 1) + (xcd - r) * q) + off; }
;         const int nig = WGM * nN, gid = wgid / nig, fm = gid * WGM, gsz = (nM - fm) < WGM ? (nM - fm) : WGM;
;         u.pm = fm + ((wgid % nig) % gsz); u.pn = (wgid % nig) / gsz; return true;
;     }
; template <class Epi, class Sched, bool ALIGN_EPI>
; __device__ __forceinline__ void gemm_phase(LAS unsigned char* lds, const Gemm g, const Sched& S, const Epi& E) {
;     const int tid = otid(), wid = __builtin_amdgcn_readfirstlane(tid >> 6), lane = tid & 63, wr = wid >> 2, wc = wid & 3, fr = lane & 15, fq = lane >> 4;
;     const int K = g.K, nt = K / BK;
;     unsigned voffA[2], voffB[2];
; #pragma unroll
;     for (int i = 0; i < 2; ++i) { int R, C; stage_rc(tid * 16 + i * 8192, R, C); const int Rb = (R & ~31) + perm32(R & 31);
;         voffA[i] = (unsigned)(R * g.lda + C) * 2u; voffB[i] = (unsigned)(Rb * g.ldb + C) * 2u; }
;     const size_t kstep = (size_t)(BK * 2);
;     const size_t hstepA = (size_t)HALF * g.lda * 2, hstepB = (size_t)HALF * g.ldb * 2;
;     const size_t tstepA = 2 * hstepA, tstepB = 2 * hstepB;
;     const unsigned ldsw = (unsigned)wid * 1024u;
;     const int aoff = lds_byte(wr * 64 + fr, fq * 8), boff = lds_byte(wc * 32 + fr, fq * 8);
;     ...
;     const unsigned ldsb0 = (unsigned)(uintptr_t)lds + ldsw;
;     ...
;     Unit cur, nxt; int ui = 0;
;     if (!S.next(0, cur)) return;
;     f32x4 acc[2][2][4][2];
; #pragma unroll
;     for (int a = 0; a < 2; ++a)
; #pragma unroll
;         for (int b = 0; b < 2; ++b)
; #pragma unroll
;             for (int m = 0; m < 4; ++m)
; #pragma unroll
;                 for (int n = 0; n < 2; ++n) acc[a][b][m][n] = (f32x4){0.f, 0.f, 0.f, 0.f};
;     bf16x8 At[4][2], B0[2][2], B1[2][2];
;     float pre[Epi::NPRE > 0 ? Epi::NPRE : 1];
;     if constexpr (Epi::NPRE > 0) E.preload(cur, wr, fr, pre);
;     const char* cA = (const char*)g.A + (size_t)cur.pm * tstepA + (size_t)cur.pn * g.a_koff * 2; const char* cB = (const char*)g.Bt + (size_t)cur.pn * tstepB;
.LBB0_2062:
	s_or_b64 exec, exec, s[4:5]
	v_readlane_b32 s6, v242, 20
	s_mov_b64 s[4:5], s[0:1]
	s_mov_b64 s[8:9], s[0:1]
	s_mov_b64 s[12:13], s[0:1]
	s_mov_b64 s[14:15], s[0:1]
	s_waitcnt lgkmcnt(0)
	v_mov_b32_e32 v2, v0
	v_readlane_b32 s7, v242, 21
	s_barrier
	s_and_b64 vcc, exec, s[6:7]
	v_readfirstlane_b32 s3, v2
	s_cbranch_vccz .LBB0_2082
	s_load_dwordx2 s[6:7], s[4:5], 0xb0
	s_load_dwordx2 s[16:17], s[8:9], 0xb0
	s_load_dwordx2 s[18:19], s[12:13], 0xb0
	s_load_dwordx2 s[10:11], s[14:15], 0xb0
	v_bfe_i32 v4, v2, 27, 1
	s_waitcnt lgkmcnt(0)
	s_add_u32 s38, s6, 0x1d800000
	s_addc_u32 s39, s7, 0
	s_add_u32 s40, s16, 0x7d00000
	s_addc_u32 s41, s17, 0
	s_add_u32 s8, s18, 0x28c00
	s_addc_u32 s9, s19, 0
	s_ashr_i32 s7, s3, 6
	s_lshl_b32 s2, s7, 10
	s_add_i32 s42, s2, 0
	s_lshr_b32 s2, s93, 29
	s_add_i32 s2, s92, s2
	s_ashr_i32 s4, s2, 3
	s_and_b32 s2, s2, -8
	s_sub_i32 s2, s92, s2
	s_ashr_i32 s6, s3, 8
	s_mul_i32 s12, s2, 0xb5
	v_lshlrev_b32_e32 v8, 4, v2
	v_lshrrev_b32_e32 v4, 22, v4
	s_lshl_b32 s16, s6, 6
	s_add_i32 s12, s12, 4
	v_add_u32_e32 v4, v8, v4
	s_mul_i32 s5, s2, 0xb6
	s_cmp_lt_i32 s2, 4
	v_and_b32_e32 v4, 0xfffffc00, v4
	s_cselect_b32 s2, s5, s12
	v_sub_u32_e32 v4, v8, v4
	s_add_i32 s2, s2, s4
	v_ashrrev_i32_e32 v3, 31, v2
	v_lshrrev_b32_e32 v5, 4, v4
	s_mul_hi_i32 s4, s2, 0x2e8ba2e9
	v_lshrrev_b32_e32 v3, 26, v3
	v_bitop3_b32 v5, v5, v4, 32 bitop3:0x6c
	v_ashrrev_i32_e32 v4, 31, v4
	s_lshr_b32 s5, s4, 31
	s_ashr_i32 s4, s4, 6
	v_add_u32_e32 v3, v2, v3
	v_lshrrev_b32_e32 v4, 26, v4
	s_add_i32 s4, s4, s5
	v_ashrrev_i32_e32 v3, 6, v3
	v_add_u32_e32 v4, v5, v4
	s_lshl_b32 s12, s4, 3
	v_lshlrev_b32_e32 v6, 3, v3
	v_ashrrev_i32_e32 v9, 6, v4
	v_lshlrev_b32_e32 v3, 5, v3
	s_sub_i32 s5, 33, s12
	v_and_b32_e32 v11, 32, v3
	v_mul_i32_i24_e32 v3, 64, v9
	s_min_u32 s13, s5, 8
	s_mulk_i32 s4, 0x160
	v_and_b32_e32 v6, -16, v6
	v_sub_u32_e32 v12, v5, v3
	s_sub_i32 s2, s2, s4
	v_cvt_f32_ubyte0_e32 v5, s13
	v_add_u32_e32 v10, v9, v6
	v_cvt_f32_i32_e32 v4, s2
	v_rcp_iflag_f32_e32 v6, v5
	s_ashr_i32 s4, s2, 30
	s_or_b32 s14, s4, 1
	v_and_b32_e32 v3, 15, v2
	v_mul_f32_e32 v6, v4, v6
	v_trunc_f32_e32 v6, v6
	v_fma_f32 v4, -v6, v5, v4
	v_cvt_i32_f32_e32 v6, v6
	v_cmp_ge_f32_e64 s[4:5], |v4|, v5
	s_and_b64 s[4:5], s[4:5], exec
	s_cselect_b32 s4, s14, 0
	v_readfirstlane_b32 s5, v6
	s_add_i32 s14, s5, s4
	s_mul_i32 s4, s14, s13
	s_sub_i32 s2, s2, s4
	s_sext_i32_i16 s2, s2
	s_add_i32 s4, s12, s2
	s_lshl_b32 s2, s4, 8
	s_add_i32 s2, s2, s16
	v_or_b32_e32 v4, s2, v3
	v_ashrrev_i32_e32 v5, 31, v4
	v_lshl_add_u64 v[6:7], v[4:5], 2, s[8:9]
	v_add_u32_e32 v4, 0x80, v4
	v_ashrrev_i32_e32 v5, 31, v4
	v_lshl_add_u64 v[4:5], v[4:5], 2, s[8:9]
	global_load_dword v153, v[6:7], off
	global_load_dword v152, v[6:7], off offset:64
	global_load_dword v151, v[6:7], off offset:128
	global_load_dword v150, v[6:7], off offset:192
	global_load_dword v149, v[4:5], off
	global_load_dword v148, v[4:5], off offset:64
	global_load_dword v147, v[4:5], off offset:128
	global_load_dword v139, v[4:5], off offset:192
	v_mov_b32_e32 v13, 1
	v_ashrrev_i16_sdwa v4, v13, sext(v12) dst_sel:DWORD dst_unused:UNUSED_PAD src0_sel:DWORD src1_sel:BYTE_0
	v_lshlrev_b32_e32 v5, 1, v10
	v_lshrrev_b32_e32 v6, 2, v10
	v_and_b32_e32 v7, 3, v9
	s_mov_b32 s2, 0xfffe0
	v_bfe_i32 v4, v4, 0, 16
	v_and_b32_e32 v5, 24, v5
	v_and_b32_e32 v6, 4, v6
	v_and_or_b32 v7, v10, s2, v7
	v_or3_b32 v5, v7, v6, v5
	v_add_lshl_u32 v4, v11, v4, 1
	s_waitcnt vmcnt(10)
	v_lshl_add_u32 v134, v10, 12, v4
	s_waitcnt vmcnt(8)
	v_lshl_add_u32 v135, v5, 12, v4
	v_add_u32_e32 v4, 0x2000, v8
	v_ashrrev_i32_e32 v5, 31, v4
	v_lshrrev_b32_e32 v5, 22, v5
	v_add_u32_e32 v5, v4, v5
	v_ashrrev_i32_e32 v5, 10, v5
	v_mul_i32_i24_e32 v6, 0x400, v5
	v_sub_u32_e32 v4, v4, v6
	v_lshrrev_b32_e32 v6, 4, v4
	v_bitop3_b32 v4, v6, v4, 32 bitop3:0x6c
	v_ashrrev_i32_e32 v7, 31, v4
	v_lshrrev_b32_e32 v7, 26, v7
	v_lshlrev_b32_e32 v6, 3, v5
	v_add_u32_e32 v7, v4, v7
	v_and_b32_e32 v6, -16, v6
	v_ashrrev_i32_e32 v8, 6, v7
	v_and_b32_e32 v7, 0xc0, v7
	v_add_u32_e32 v6, v8, v6
	v_sub_u32_e32 v4, v4, v7
	s_ashr_i32 s5, s4, 31
	s_bfe_i64 s[18:19], s[14:15], 0x100000
	v_lshlrev_b32_e32 v5, 5, v5
	v_ashrrev_i16_sdwa v4, v13, sext(v4) dst_sel:DWORD dst_unused:UNUSED_PAD src0_sel:DWORD src1_sel:BYTE_0
	v_lshlrev_b32_e32 v7, 1, v6
	v_lshrrev_b32_e32 v9, 2, v6
	v_and_b32_e32 v8, 3, v8
	s_lshl_b64 s[12:13], s[4:5], 20
	s_lshl_b64 s[18:19], s[18:19], 20
	v_and_b32_e32 v5, 32, v5
	v_bfe_i32 v4, v4, 0, 16
	v_and_b32_e32 v7, 24, v7
	v_and_b32_e32 v9, 4, v9
	v_and_or_b32 v8, v6, s2, v8
	s_add_u32 s28, s40, s18
	v_or3_b32 v7, v8, v9, v7
	v_add_lshl_u32 v4, v5, v4, 1
	s_addc_u32 s29, s41, s19
	s_add_i32 s44, s42, 0x10000
	s_mov_b32 m0, s44
	s_nop 0
	global_load_lds_dwordx4 v135, s[28:29]
	s_add_i32 s45, s42, 0x12000
	v_lshl_add_u32 v137, v7, 12, v4
	s_mov_b32 m0, s45
	s_nop 0
	global_load_lds_dwordx4 v137, s[28:29]
	s_add_u32 s18, s28, 0x80000
	s_addc_u32 s19, s29, 0
	s_add_i32 s46, s42, 0x14000
	s_mov_b32 m0, s46
	s_nop 0
	global_load_lds_dwordx4 v135, s[18:19]
	s_add_i32 s47, s42, 0x16000
	s_mov_b32 m0, s47
	s_nop 0
	global_load_lds_dwordx4 v137, s[18:19]
	s_add_u32 s26, s38, s12
	s_addc_u32 s27, s39, s13
	s_mov_b32 m0, s42
	s_nop 0
	global_load_lds_dwordx4 v134, s[26:27]
	s_add_i32 s48, s42, 0x2000
	v_lshl_add_u32 v136, v6, 12, v4
	s_mov_b32 m0, s48
	s_nop 0
	global_load_lds_dwordx4 v136, s[26:27]
	s_add_u32 s18, s26, 0x80000
	s_addc_u32 s19, s27, 0
	s_add_i32 s49, s42, 0x4000
	s_mov_b32 m0, s49
	s_nop 0
	global_load_lds_dwordx4 v134, s[18:19]
	s_add_i32 s50, s42, 0x6000
	s_mov_b32 m0, s50
	s_nop 0
	global_load_lds_dwordx4 v136, s[18:19]
	s_cmp_eq_u32 s6, 1
	s_mov_b32 s43, 0
	s_cselect_b64 s[12:13], -1, 0
	s_cmp_lg_u32 s6, 1
	s_cbranch_scc1 .LBB0_2065
	s_barrier
; #define PG8_STAGE(bufoff, gbase, voff) do { _Pragma("unroll") for (int _i = 0; _i < 2; ++_i) { unsigned keep_; \
;         asm volatile("s_mov_b32 %0, m0\n\ts_mov_b32 m0, %3\n\ts_nop 0\n\tglobal_load_lds_dwordx4 %1, %2\n\ts_mov_b32 m0, %0" \
;             : "=&s"(keep_) : "v"((voff)[_i]), "s"((const void*)(gbase)), "s"(ldsb0 + (unsigned)(bufoff) + (unsigned)(_i * 8192)) : "memory"); } } while (0)
; #define PG8_WAIT_V(n) asm volatile("s_waitcnt vmcnt(" #n ")" ::: "memory")
; #define PG8_BAR __builtin_amdgcn_s_barrier()
; template <class Epi, class Sched, bool ALIGN_EPI>
; __device__ __forceinline__ void gemm_phase(LAS unsigned char* lds, const Gemm g, const Sched& S, const Epi& E) {
;     ...
;     const int aoff = lds_byte(wr * 64 + fr, fq * 8), boff = lds_byte(wc * 32 + fr, fq * 8);
;     ...
;     const unsigned ldsb0 = (unsigned)(uintptr_t)lds + ldsw;
;     ...
;     Unit cur, nxt; int ui = 0;
;     if (!S.next(0, cur)) return;
;     f32x4 acc[2][2][4][2];
; #pragma unroll
;     for (int a = 0; a < 2; ++a)
; #pragma unroll
;         for (int b = 0; b < 2; ++b)
; #pragma unroll
;             for (int m = 0; m < 4; ++m)
; #pragma unroll
;                 for (int n = 0; n < 2; ++n) acc[a][b][m][n] = (f32x4){0.f, 0.f, 0.f, 0.f};
;     bf16x8 At[4][2], B0[2][2], B1[2][2];
;     float pre[Epi::NPRE > 0 ? Epi::NPRE : 1];
;     if constexpr (Epi::NPRE > 0) E.preload(cur, wr, fr, pre);
;     const char* cA = (const char*)g.A + (size_t)cur.pm * tstepA + (size_t)cur.pn * g.a_koff * 2; const char* cB = (const char*)g.Bt + (size_t)cur.pn * tstepB;
;     PG8_STAGE(PG8_SB(0, 0), cB, voffB); PG8_STAGE(PG8_SB(0, 1), cB + hstepB, voffB); PG8_STAGE(PG8_SA(0, 0), cA, voffA); PG8_STAGE(PG8_SA(0, 1), cA + hstepA, voffA);
;     if (wr == 1) PG8_BAR;
;     PG8_WAIT_V(2); PG8_BAR;
;     PG8_STAGE(PG8_SB(1, 0), cB + kstep, voffB); PG8_STAGE(PG8_SA(1, 0), cA + kstep, voffA); PG8_STAGE(PG8_SB(1, 1), cB + hstepB + kstep, voffB);
;     PG8_WAIT_V(6); PG8_BAR;
.LBB0_2065:
	v_lshrrev_b32_e32 v2, 1, v2
	v_or_b32_e32 v138, s16, v3
	v_and_b32_e32 v2, 24, v2
	s_sext_i32_i16 s2, s14
	s_add_u32 s14, s10, 0x1f900000
	v_lshlrev_b32_e32 v4, 6, v138
	v_lshlrev_b32_e32 v5, 1, v2
	s_movk_i32 s5, 0x3c0
	v_lshlrev_b32_e32 v6, 2, v138
	s_addc_u32 s15, s11, 0
	v_and_or_b32 v4, v4, s5, v5
	s_lshl_b32 s5, s6, 13
	v_and_b32_e32 v6, 32, v6
	v_bitop3_b32 v4, v4, s5, v6 bitop3:0xde
	s_lshl_b32 s5, s7, 5
	s_and_b32 s5, s5, 0x60
	v_lshl_or_b32 v5, v3, 6, v5
	v_lshlrev_b32_e32 v3, 2, v3
	s_lshl_b32 s6, s5, 7
	v_and_b32_e32 v3, 32, v3
	v_bitop3_b32 v3, v5, s6, v3 bitop3:0xde
	s_add_u32 s6, s28, 0x80
	s_waitcnt vmcnt(2)
	s_barrier
	s_addc_u32 s7, s29, 0
	s_add_i32 s51, s42, 0x18000
	s_mov_b32 m0, s51
	s_nop 0
	global_load_lds_dwordx4 v135, s[6:7]
	s_add_i32 s52, s42, 0x1a000
	s_mov_b32 m0, s52
	s_nop 0
	global_load_lds_dwordx4 v137, s[6:7]
	s_add_u32 s6, s26, 0x80
	s_addc_u32 s7, s27, 0
	s_add_i32 s53, s42, 0x8000
	s_mov_b32 m0, s53
	s_nop 0
	global_load_lds_dwordx4 v134, s[6:7]
	s_add_i32 s54, s42, 0xa000
	s_mov_b32 m0, s54
	s_nop 0
	global_load_lds_dwordx4 v136, s[6:7]
	s_add_u32 s6, s28, 0x80080
	s_addc_u32 s7, s29, 0
	s_add_i32 s55, s42, 0x1c000
	s_mov_b32 m0, s55
	s_nop 0
	global_load_lds_dwordx4 v135, s[6:7]
	s_add_i32 s56, s42, 0x1e000
	s_mov_b32 m0, s56
	s_nop 0
	global_load_lds_dwordx4 v137, s[6:7]
	s_waitcnt vmcnt(6)
	s_add_i32 s57, s42, 0xc000
	s_cmpk_lt_u32 s3, 0x100
	v_or_b32_e32 v140, s5, v2
	v_add_u32_e32 v2, 0, v3
	s_cselect_b64 s[16:17], -1, 0
	s_add_i32 s58, s42, 0xe000
	v_mov_b64_e32 v[130:131], 0x5ac
	v_mov_b64_e32 v[132:133], 0x5ab
	v_add_u32_e32 v141, 0x10000, v2
	v_add_u32_e32 v142, 0x14000, v2
	v_add_u32_e32 v143, 0, v4
	v_add_u32_e32 v144, 0x18000, v2
	v_add_u32_e32 v145, 0x1c000, v2
	v_mov_b32_e32 v146, 0x358637bd
	s_movk_i32 s59, 0x2c00
	s_barrier
	s_branch .LBB0_2068

; #define PG8_STAGE(bufoff, gbase, voff) do { _Pragma("unroll") for (int _i = 0; _i < 2; ++_i) { unsigned keep_; \
;         asm volatile("s_mov_b32 %0, m0\n\ts_mov_b32 m0, %3\n\ts_nop 0\n\tglobal_load_lds_dwordx4 %1, %2\n\ts_mov_b32 m0, %0" \
;             : "=&s"(keep_) : "v"((voff)[_i]), "s"((const void*)(gbase)), "s"(ldsb0 + (unsigned)(bufoff) + (unsigned)(_i * 8192)) : "memory"); } } while (0)
; #define PG8_LDA(dst, b, h) do { _Pragma("unroll") for (int m = 0; m < 4; ++m) _Pragma("unroll") for (int k = 0; k < 2; ++k) dst[m][k] = *(const LAS bf16x8*)(lds + PG8_SA(b, h) + aoff + m * 2048 + k * 1024); } while (0)
; #define PG8_LDB(dst, b, h) do { _Pragma("unroll") for (int n = 0; n < 2; ++n) _Pragma("unroll") for (int k = 0; k < 2; ++k) dst[n][k] = *(const LAS bf16x8*)(lds + PG8_SB(b, h) + boff + n * 2048 + k * 1024); } while (0)
; #define PG8_MMA(ai, bj, At, Bt) do { __builtin_amdgcn_s_setprio(1); _Pragma("unroll") for (int m = 0; m < 4; ++m) _Pragma("unroll") for (int n = 0; n < 2; ++n) _Pragma("unroll") for (int k = 0; k < 2; ++k) \
;         acc[ai][bj][m][n] = __builtin_amdgcn_mfma_f32_16x16x32_bf16(Bt[n][k], At[m][k], acc[ai][bj][m][n], 0, 0, 0); __builtin_amdgcn_s_setprio(0); } while (0)
; #define PG8_WAIT_V(n) asm volatile("s_waitcnt vmcnt(" #n ")" ::: "memory")
; #define PG8_BAR __builtin_amdgcn_s_barrier()
; template <class Epi, class Sched, bool ALIGN_EPI>
; __device__ __forceinline__ void gemm_phase(LAS unsigned char* lds, const Gemm g, const Sched& S, const Epi& E) {
;     ...
;         for (int t = 0; t < nt; t += 2) {
;             const bool last = (t == nt - 2);
;             const char* a1 = cA + (size_t)(t + 1) * kstep;
;             const char* a2 = last ? nA : cA + (size_t)(t + 2) * kstep; const char* b2 = last ? nB : cB + (size_t)(t + 2) * kstep;
;             const char* a3 = a2 + kstep; const char* b3 = b2 + kstep;
;             PG8_LDB(B0, 0, 0); PG8_LDB(B1, 0, 1); PG8_SCHED; PG8_LDA(At, 0, 0); PG8_STAGE(PG8_SA(1, 1), a1 + hstepA, voffA);
;             PG8_WAIT_V(8); PG8_WAIT_L(0); PG8_BAR; PG8_MMA(0, 0, At, B0); PG8_MMA(0, 1, At, B1); PG8_BAR; PG8_SCHED;
;             PG8_LDA(At, 0, 1); PG8_STAGE(PG8_SB(0, 0), b2, voffB); PG8_STAGE(PG8_SB(0, 1), b2 + hstepB, voffB); PG8_STAGE(PG8_SA(0, 0), a2, voffA);
;             PG8_WAIT_V(8); PG8_WAIT_L(0); PG8_BAR; PG8_MMA(1, 0, At, B0); PG8_MMA(1, 1, At, B1); PG8_BAR; PG8_SCHED;
.LBB0_2075:
	ds_read_b128 v[154:157], v141
	ds_read_b128 v[158:161], v141 offset:1024
	ds_read_b128 v[162:165], v141 offset:2048
	ds_read_b128 v[166:169], v141 offset:3072
	ds_read_b128 v[170:173], v142
	ds_read_b128 v[174:177], v142 offset:1024
	ds_read_b128 v[180:183], v142 offset:2048
	ds_read_b128 v[184:187], v142 offset:3072
	s_add_u32 s28, s26, 0x100
	s_addc_u32 s29, s27, 0
	s_cmp_eq_u32 s60, 28
	s_cselect_b32 s36, s5, s28
	s_cselect_b32 s37, s3, s29
	s_cselect_b32 s34, s7, s19
	s_cselect_b32 s35, s6, s21
	s_add_u32 s30, s36, 0x80
	s_addc_u32 s31, s37, 0
	ds_read_b128 v[188:191], v143
	ds_read_b128 v[192:195], v143 offset:1024
	ds_read_b128 v[196:199], v143 offset:2048
	ds_read_b128 v[204:207], v143 offset:3072
	ds_read_b128 v[208:211], v143 offset:4096
	ds_read_b128 v[212:215], v143 offset:5120
	ds_read_b128 v[216:219], v143 offset:6144
	ds_read_b128 v[220:223], v143 offset:7168
	s_add_u32 s26, s26, 0x80080
	s_addc_u32 s27, s27, 0
	s_mov_b32 m0, s57
	s_nop 0
	global_load_lds_dwordx4 v134, s[26:27]
	s_nop 0
	s_mov_b32 m0, s58
	s_nop 0
	global_load_lds_dwordx4 v136, s[26:27]
	s_waitcnt vmcnt(8)
	s_waitcnt lgkmcnt(0)
	s_barrier
	s_setprio 1
	v_mfma_f32_16x16x32_bf16 v[126:129], v[154:157], v[188:191], v[126:129]
	v_mfma_f32_16x16x32_bf16 v[122:125], v[162:165], v[188:191], v[122:125]
	v_mfma_f32_16x16x32_bf16 v[110:113], v[154:157], v[196:199], v[110:113]
	v_mfma_f32_16x16x32_bf16 v[106:109], v[162:165], v[196:199], v[106:109]
	v_mfma_f32_16x16x32_bf16 v[94:97], v[154:157], v[208:211], v[94:97]
	v_mfma_f32_16x16x32_bf16 v[90:93], v[162:165], v[208:211], v[90:93]
	v_mfma_f32_16x16x32_bf16 v[78:81], v[154:157], v[216:219], v[78:81]
	v_mfma_f32_16x16x32_bf16 v[74:77], v[162:165], v[216:219], v[74:77]
	v_mfma_f32_16x16x32_bf16 v[126:129], v[158:161], v[192:195], v[126:129]
	v_mfma_f32_16x16x32_bf16 v[122:125], v[166:169], v[192:195], v[122:125]
	v_mfma_f32_16x16x32_bf16 v[110:113], v[158:161], v[204:207], v[110:113]
	v_mfma_f32_16x16x32_bf16 v[106:109], v[166:169], v[204:207], v[106:109]
	v_mfma_f32_16x16x32_bf16 v[94:97], v[158:161], v[212:215], v[94:97]
	v_mfma_f32_16x16x32_bf16 v[90:93], v[166:169], v[212:215], v[90:93]
	v_mfma_f32_16x16x32_bf16 v[78:81], v[158:161], v[220:223], v[78:81]
	v_mfma_f32_16x16x32_bf16 v[74:77], v[166:169], v[220:223], v[74:77]
	v_mfma_f32_16x16x32_bf16 v[118:121], v[170:173], v[188:191], v[118:121]
	v_mfma_f32_16x16x32_bf16 v[114:117], v[180:183], v[188:191], v[114:117]
	v_mfma_f32_16x16x32_bf16 v[102:105], v[170:173], v[196:199], v[102:105]
	v_mfma_f32_16x16x32_bf16 v[98:101], v[180:183], v[196:199], v[98:101]
	v_mfma_f32_16x16x32_bf16 v[86:89], v[170:173], v[208:211], v[86:89]
	v_mfma_f32_16x16x32_bf16 v[82:85], v[180:183], v[208:211], v[82:85]
	v_mfma_f32_16x16x32_bf16 v[70:73], v[170:173], v[216:219], v[70:73]
	v_mfma_f32_16x16x32_bf16 v[66:69], v[180:183], v[216:219], v[66:69]
	v_mfma_f32_16x16x32_bf16 v[118:121], v[174:177], v[192:195], v[118:121]
	v_mfma_f32_16x16x32_bf16 v[114:117], v[184:187], v[192:195], v[114:117]
	v_mfma_f32_16x16x32_bf16 v[102:105], v[174:177], v[204:207], v[102:105]
	v_mfma_f32_16x16x32_bf16 v[98:101], v[184:187], v[204:207], v[98:101]
	v_mfma_f32_16x16x32_bf16 v[86:89], v[174:177], v[212:215], v[86:89]
	v_mfma_f32_16x16x32_bf16 v[82:85], v[184:187], v[212:215], v[82:85]
	v_mfma_f32_16x16x32_bf16 v[70:73], v[174:177], v[220:223], v[70:73]
	v_mfma_f32_16x16x32_bf16 v[66:69], v[184:187], v[220:223], v[66:69]
	s_setprio 0
	s_barrier
	ds_read_b128 v[188:191], v143 offset:16384
	ds_read_b128 v[192:195], v143 offset:17408
	ds_read_b128 v[196:199], v143 offset:18432
	ds_read_b128 v[204:207], v143 offset:19456
	ds_read_b128 v[208:211], v143 offset:20480
	ds_read_b128 v[212:215], v143 offset:21504
	ds_read_b128 v[216:219], v143 offset:22528
	ds_read_b128 v[220:223], v143 offset:23552
	s_mov_b32 m0, s44
	s_nop 0
	global_load_lds_dwordx4 v135, s[34:35]
	s_nop 0
	s_mov_b32 m0, s45
	s_nop 0
	global_load_lds_dwordx4 v137, s[34:35]
	s_add_u32 s26, s34, 0x80000
	s_addc_u32 s27, s35, 0
	s_mov_b32 m0, s46
	s_nop 0
	global_load_lds_dwordx4 v135, s[26:27]
	s_nop 0
	s_mov_b32 m0, s47
	s_nop 0
	global_load_lds_dwordx4 v137, s[26:27]
	s_mov_b32 m0, s42
	s_nop 0
	global_load_lds_dwordx4 v134, s[36:37]
	s_nop 0
	s_mov_b32 m0, s48
	s_nop 0
	global_load_lds_dwordx4 v136, s[36:37]
	s_waitcnt vmcnt(8)
	s_waitcnt lgkmcnt(0)
	s_barrier
	s_setprio 1
	v_mfma_f32_16x16x32_bf16 v[62:65], v[154:157], v[188:191], v[62:65]
	v_mfma_f32_16x16x32_bf16 v[58:61], v[162:165], v[188:191], v[58:61]
	v_mfma_f32_16x16x32_bf16 v[46:49], v[154:157], v[196:199], v[46:49]
	v_mfma_f32_16x16x32_bf16 v[42:45], v[162:165], v[196:199], v[42:45]
	v_mfma_f32_16x16x32_bf16 v[30:33], v[154:157], v[208:211], v[30:33]
	v_mfma_f32_16x16x32_bf16 v[26:29], v[162:165], v[208:211], v[26:29]
	v_mfma_f32_16x16x32_bf16 v[14:17], v[154:157], v[216:219], v[14:17]
	v_mfma_f32_16x16x32_bf16 v[10:13], v[162:165], v[216:219], v[10:13]
	v_mfma_f32_16x16x32_bf16 v[62:65], v[158:161], v[192:195], v[62:65]
	v_mfma_f32_16x16x32_bf16 v[58:61], v[166:169], v[192:195], v[58:61]
	v_mfma_f32_16x16x32_bf16 v[46:49], v[158:161], v[204:207], v[46:49]
	v_mfma_f32_16x16x32_bf16 v[42:45], v[166:169], v[204:207], v[42:45]
	v_mfma_f32_16x16x32_bf16 v[30:33], v[158:161], v[212:215], v[30:33]
	v_mfma_f32_16x16x32_bf16 v[26:29], v[166:169], v[212:215], v[26:29]
	v_mfma_f32_16x16x32_bf16 v[14:17], v[158:161], v[220:223], v[14:17]
	v_mfma_f32_16x16x32_bf16 v[10:13], v[166:169], v[220:223], v[10:13]
	v_mfma_f32_16x16x32_bf16 v[54:57], v[170:173], v[188:191], v[54:57]
	v_mfma_f32_16x16x32_bf16 v[50:53], v[180:183], v[188:191], v[50:53]
	v_mfma_f32_16x16x32_bf16 v[38:41], v[170:173], v[196:199], v[38:41]
	v_mfma_f32_16x16x32_bf16 v[34:37], v[180:183], v[196:199], v[34:37]
	v_mfma_f32_16x16x32_bf16 v[22:25], v[170:173], v[208:211], v[22:25]
	v_mfma_f32_16x16x32_bf16 v[18:21], v[180:183], v[208:211], v[18:21]
	v_mfma_f32_16x16x32_bf16 v[6:9], v[170:173], v[216:219], v[6:9]
	v_mfma_f32_16x16x32_bf16 v[2:5], v[180:183], v[216:219], v[2:5]
	v_mfma_f32_16x16x32_bf16 v[54:57], v[174:177], v[192:195], v[54:57]
	v_mfma_f32_16x16x32_bf16 v[50:53], v[184:187], v[192:195], v[50:53]
	v_mfma_f32_16x16x32_bf16 v[38:41], v[174:177], v[204:207], v[38:41]
	v_mfma_f32_16x16x32_bf16 v[34:37], v[184:187], v[204:207], v[34:37]
	v_mfma_f32_16x16x32_bf16 v[22:25], v[174:177], v[212:215], v[22:25]
	v_mfma_f32_16x16x32_bf16 v[18:21], v[184:187], v[212:215], v[18:21]
	v_mfma_f32_16x16x32_bf16 v[6:9], v[174:177], v[220:223], v[6:9]
	v_mfma_f32_16x16x32_bf16 v[2:5], v[184:187], v[220:223], v[2:5]
	s_setprio 0
	s_barrier
; #define PG8_STAGE(bufoff, gbase, voff) do { _Pragma("unroll") for (int _i = 0; _i < 2; ++_i) { unsigned keep_; \
;         asm volatile("s_mov_b32 %0, m0\n\ts_mov_b32 m0, %3\n\ts_nop 0\n\tglobal_load_lds_dwordx4 %1, %2\n\ts_mov_b32 m0, %0" \
;             : "=&s"(keep_) : "v"((voff)[_i]), "s"((const void*)(gbase)), "s"(ldsb0 + (unsigned)(bufoff) + (unsigned)(_i * 8192)) : "memory"); } } while (0)
; #define PG8_LDA(dst, b, h) do { _Pragma("unroll") for (int m = 0; m < 4; ++m) _Pragma("unroll") for (int k = 0; k < 2; ++k) dst[m][k] = *(const LAS bf16x8*)(lds + PG8_SA(b, h) + aoff + m * 2048 + k * 1024); } while (0)
; #define PG8_LDB(dst, b, h) do { _Pragma("unroll") for (int n = 0; n < 2; ++n) _Pragma("unroll") for (int k = 0; k < 2; ++k) dst[n][k] = *(const LAS bf16x8*)(lds + PG8_SB(b, h) + boff + n * 2048 + k * 1024); } while (0)
; #define PG8_MMA(ai, bj, At, Bt) do { __builtin_amdgcn_s_setprio(1); _Pragma("unroll") for (int m = 0; m < 4; ++m) _Pragma("unroll") for (int n = 0; n < 2; ++n) _Pragma("unroll") for (int k = 0; k < 2; ++k) \
;         acc[ai][bj][m][n] = __builtin_amdgcn_mfma_f32_16x16x32_bf16(Bt[n][k], At[m][k], acc[ai][bj][m][n], 0, 0, 0); __builtin_amdgcn_s_setprio(0); } while (0)
; #define PG8_WAIT_V(n) asm volatile("s_waitcnt vmcnt(" #n ")" ::: "memory")
; #define PG8_WAIT_L(n) asm volatile("s_waitcnt lgkmcnt(" #n ")" ::: "memory")
; #define PG8_BAR __builtin_amdgcn_s_barrier()
; #define PG8_SCHED __builtin_amdgcn_sched_barrier(0)
; template <class Epi, class Sched, bool ALIGN_EPI>
; __device__ __forceinline__ void gemm_phase(LAS unsigned char* lds, const Gemm g, const Sched& S, const Epi& E) {
;     ...
;             PG8_LDB(B0, 1, 0); PG8_LDB(B1, 1, 1); PG8_SCHED; PG8_LDA(At, 1, 0); PG8_STAGE(PG8_SA(0, 1), a2 + hstepA, voffA);
;             PG8_WAIT_V(8); PG8_WAIT_L(0); PG8_BAR; PG8_MMA(0, 0, At, B0); PG8_MMA(0, 1, At, B1); PG8_BAR; PG8_SCHED;
;             PG8_LDA(At, 1, 1); PG8_STAGE(PG8_SB(1, 0), b3, voffB); PG8_STAGE(PG8_SB(1, 1), b3 + hstepB, voffB); PG8_STAGE(PG8_SA(1, 0), a3, voffA);
;             PG8_WAIT_V(8); PG8_WAIT_L(0); PG8_BAR; PG8_MMA(1, 0, At, B0); PG8_MMA(1, 1, At, B1); PG8_BAR; PG8_SCHED;
;         }
	ds_read_b128 v[154:157], v144
	ds_read_b128 v[158:161], v144 offset:1024
	ds_read_b128 v[162:165], v144 offset:2048
	ds_read_b128 v[166:169], v144 offset:3072
	ds_read_b128 v[170:173], v145
	ds_read_b128 v[174:177], v145 offset:1024
	ds_read_b128 v[180:183], v145 offset:2048
	ds_read_b128 v[184:187], v145 offset:3072
	ds_read_b128 v[188:191], v143 offset:32768
	ds_read_b128 v[192:195], v143 offset:33792
	ds_read_b128 v[196:199], v143 offset:34816
	ds_read_b128 v[204:207], v143 offset:35840
	ds_read_b128 v[208:211], v143 offset:36864
	ds_read_b128 v[212:215], v143 offset:37888
	ds_read_b128 v[216:219], v143 offset:38912
	ds_read_b128 v[220:223], v143 offset:39936
	s_add_u32 s26, s36, 0x80000
	s_addc_u32 s27, s37, 0
	s_mov_b32 m0, s49
	s_nop 0
	global_load_lds_dwordx4 v134, s[26:27]
	s_nop 0
	s_mov_b32 m0, s50
	s_nop 0
	global_load_lds_dwordx4 v136, s[26:27]
	s_waitcnt vmcnt(8)
	s_waitcnt lgkmcnt(0)
	s_barrier
	s_setprio 1
	v_mfma_f32_16x16x32_bf16 v[126:129], v[154:157], v[188:191], v[126:129]
	v_mfma_f32_16x16x32_bf16 v[122:125], v[162:165], v[188:191], v[122:125]
	v_mfma_f32_16x16x32_bf16 v[110:113], v[154:157], v[196:199], v[110:113]
	v_mfma_f32_16x16x32_bf16 v[106:109], v[162:165], v[196:199], v[106:109]
	v_mfma_f32_16x16x32_bf16 v[94:97], v[154:157], v[208:211], v[94:97]
	v_mfma_f32_16x16x32_bf16 v[90:93], v[162:165], v[208:211], v[90:93]
	v_mfma_f32_16x16x32_bf16 v[78:81], v[154:157], v[216:219], v[78:81]
	v_mfma_f32_16x16x32_bf16 v[74:77], v[162:165], v[216:219], v[74:77]
	v_mfma_f32_16x16x32_bf16 v[126:129], v[158:161], v[192:195], v[126:129]
	v_mfma_f32_16x16x32_bf16 v[122:125], v[166:169], v[192:195], v[122:125]
	v_mfma_f32_16x16x32_bf16 v[110:113], v[158:161], v[204:207], v[110:113]
	v_mfma_f32_16x16x32_bf16 v[106:109], v[166:169], v[204:207], v[106:109]
	v_mfma_f32_16x16x32_bf16 v[94:97], v[158:161], v[212:215], v[94:97]
	v_mfma_f32_16x16x32_bf16 v[90:93], v[166:169], v[212:215], v[90:93]
	v_mfma_f32_16x16x32_bf16 v[78:81], v[158:161], v[220:223], v[78:81]
	v_mfma_f32_16x16x32_bf16 v[74:77], v[166:169], v[220:223], v[74:77]
	v_mfma_f32_16x16x32_bf16 v[118:121], v[170:173], v[188:191], v[118:121]
	v_mfma_f32_16x16x32_bf16 v[114:117], v[180:183], v[188:191], v[114:117]
	v_mfma_f32_16x16x32_bf16 v[102:105], v[170:173], v[196:199], v[102:105]
	v_mfma_f32_16x16x32_bf16 v[98:101], v[180:183], v[196:199], v[98:101]
	v_mfma_f32_16x16x32_bf16 v[86:89], v[170:173], v[208:211], v[86:89]
	v_mfma_f32_16x16x32_bf16 v[82:85], v[180:183], v[208:211], v[82:85]
	v_mfma_f32_16x16x32_bf16 v[70:73], v[170:173], v[216:219], v[70:73]
	v_mfma_f32_16x16x32_bf16 v[66:69], v[180:183], v[216:219], v[66:69]
	v_mfma_f32_16x16x32_bf16 v[118:121], v[174:177], v[192:195], v[118:121]
	v_mfma_f32_16x16x32_bf16 v[114:117], v[184:187], v[192:195], v[114:117]
	v_mfma_f32_16x16x32_bf16 v[102:105], v[174:177], v[204:207], v[102:105]
	v_mfma_f32_16x16x32_bf16 v[98:101], v[184:187], v[204:207], v[98:101]
	v_mfma_f32_16x16x32_bf16 v[86:89], v[174:177], v[212:215], v[86:89]
	v_mfma_f32_16x16x32_bf16 v[82:85], v[184:187], v[212:215], v[82:85]
	v_mfma_f32_16x16x32_bf16 v[70:73], v[174:177], v[220:223], v[70:73]
	v_mfma_f32_16x16x32_bf16 v[66:69], v[184:187], v[220:223], v[66:69]
	s_setprio 0
	s_barrier
	ds_read_b128 v[188:191], v143 offset:49152
	ds_read_b128 v[192:195], v143 offset:50176
	ds_read_b128 v[196:199], v143 offset:51200
	ds_read_b128 v[204:207], v143 offset:52224
	ds_read_b128 v[208:211], v143 offset:53248
	ds_read_b128 v[212:215], v143 offset:54272
	ds_read_b128 v[216:219], v143 offset:55296
	ds_read_b128 v[220:223], v143 offset:56320
	s_add_u32 s26, s34, 0x80
	s_addc_u32 s27, s35, 0
	s_mov_b32 m0, s51
	s_nop 0
	global_load_lds_dwordx4 v135, s[26:27]
	s_nop 0
	s_mov_b32 m0, s52
	s_nop 0
	global_load_lds_dwordx4 v137, s[26:27]
	s_add_u32 s26, s34, 0x80080
	s_addc_u32 s27, s35, 0
	s_mov_b32 m0, s55
	s_nop 0
	global_load_lds_dwordx4 v135, s[26:27]
	s_nop 0
	s_mov_b32 m0, s56
	s_nop 0
	global_load_lds_dwordx4 v137, s[26:27]
	s_mov_b32 m0, s53
	s_nop 0
	global_load_lds_dwordx4 v134, s[30:31]
	s_nop 0
	s_mov_b32 m0, s54
	s_nop 0
	global_load_lds_dwordx4 v136, s[30:31]
	s_waitcnt vmcnt(8)
	s_waitcnt lgkmcnt(0)
	s_barrier
	s_setprio 1
	v_mfma_f32_16x16x32_bf16 v[62:65], v[154:157], v[188:191], v[62:65]
	v_mfma_f32_16x16x32_bf16 v[58:61], v[162:165], v[188:191], v[58:61]
	v_mfma_f32_16x16x32_bf16 v[46:49], v[154:157], v[196:199], v[46:49]
	v_mfma_f32_16x16x32_bf16 v[42:45], v[162:165], v[196:199], v[42:45]
	v_mfma_f32_16x16x32_bf16 v[30:33], v[154:157], v[208:211], v[30:33]
	v_mfma_f32_16x16x32_bf16 v[26:29], v[162:165], v[208:211], v[26:29]
	v_mfma_f32_16x16x32_bf16 v[14:17], v[154:157], v[216:219], v[14:17]
	v_mfma_f32_16x16x32_bf16 v[10:13], v[162:165], v[216:219], v[10:13]
	v_mfma_f32_16x16x32_bf16 v[62:65], v[158:161], v[192:195], v[62:65]
	v_mfma_f32_16x16x32_bf16 v[58:61], v[166:169], v[192:195], v[58:61]
	v_mfma_f32_16x16x32_bf16 v[46:49], v[158:161], v[204:207], v[46:49]
	v_mfma_f32_16x16x32_bf16 v[42:45], v[166:169], v[204:207], v[42:45]
	v_mfma_f32_16x16x32_bf16 v[30:33], v[158:161], v[212:215], v[30:33]
	v_mfma_f32_16x16x32_bf16 v[26:29], v[166:169], v[212:215], v[26:29]
	v_mfma_f32_16x16x32_bf16 v[14:17], v[158:161], v[220:223], v[14:17]
	v_mfma_f32_16x16x32_bf16 v[10:13], v[166:169], v[220:223], v[10:13]
	v_mfma_f32_16x16x32_bf16 v[54:57], v[170:173], v[188:191], v[54:57]
	v_mfma_f32_16x16x32_bf16 v[50:53], v[180:183], v[188:191], v[50:53]
	v_mfma_f32_16x16x32_bf16 v[38:41], v[170:173], v[196:199], v[38:41]
	v_mfma_f32_16x16x32_bf16 v[34:37], v[180:183], v[196:199], v[34:37]
	v_mfma_f32_16x16x32_bf16 v[22:25], v[170:173], v[208:211], v[22:25]
	v_mfma_f32_16x16x32_bf16 v[18:21], v[180:183], v[208:211], v[18:21]
	v_mfma_f32_16x16x32_bf16 v[6:9], v[170:173], v[216:219], v[6:9]
	v_mfma_f32_16x16x32_bf16 v[2:5], v[180:183], v[216:219], v[2:5]
	v_mfma_f32_16x16x32_bf16 v[54:57], v[174:177], v[192:195], v[54:57]
	v_mfma_f32_16x16x32_bf16 v[50:53], v[184:187], v[192:195], v[50:53]
	v_mfma_f32_16x16x32_bf16 v[38:41], v[174:177], v[204:207], v[38:41]
	v_mfma_f32_16x16x32_bf16 v[34:37], v[184:187], v[204:207], v[34:37]
	v_mfma_f32_16x16x32_bf16 v[22:25], v[174:177], v[212:215], v[22:25]
	v_mfma_f32_16x16x32_bf16 v[18:21], v[184:187], v[212:215], v[18:21]
	v_mfma_f32_16x16x32_bf16 v[6:9], v[174:177], v[220:223], v[6:9]
	v_mfma_f32_16x16x32_bf16 v[2:5], v[184:187], v[220:223], v[2:5]
	s_setprio 0
	s_barrier
	s_add_i32 s60, s60, 2
	s_add_u32 s19, s19, 0x100
	s_addc_u32 s21, s21, 0
	s_cmp_gt_u32 s60, 29
	s_mov_b64 s[26:27], s[28:29]
	s_cbranch_scc0 .LBB0_2075
	s_and_b64 vcc, exec, s[16:17]
	s_cbranch_vccz .LBB0_2078
	s_barrier

; __device__ __forceinline__ int otid() { int t = threadIdx.x; asm volatile("" : "+v"(t)); return t; }
;     __device__ bool next(int i, Unit& u) const {
;         const long L = (long)i * G + c; if (L >= nwg) return false;
;         int wgid = (int)L; { const int q = nwg / NXCD, r = nwg % NXCD, xcd = wgid % NXCD, off = wgid / NXCD; wgid = (xcd < r ? xcd * (q + 1) : r * (q + 1) + (xcd - r) * q) + off; }
;         const int nig = WGM * nN, gid = wgid / nig, fm = gid * WGM, gsz = (nM - fm) < WGM ? (nM - fm) : WGM;
;         u.pm = fm + ((wgid % nig) % gsz); u.pn = (wgid % nig) / gsz; return true;
;     }
; template <class Epi, class Sched, bool ALIGN_EPI>
; __device__ __forceinline__ void gemm_phase(LAS unsigned char* lds, const Gemm g, const Sched& S, const Epi& E) {
;     const int tid = otid(), wid = __builtin_amdgcn_readfirstlane(tid >> 6), lane = tid & 63, wr = wid >> 2, wc = wid & 3, fr = lane & 15, fq = lane >> 4;
;     const int K = g.K, nt = K / BK;
;     unsigned voffA[2], voffB[2];
; #pragma unroll
;     for (int i = 0; i < 2; ++i) { int R, C; stage_rc(tid * 16 + i * 8192, R, C); const int Rb = (R & ~31) + perm32(R & 31);
;         voffA[i] = (unsigned)(R * g.lda + C) * 2u; voffB[i] = (unsigned)(Rb * g.ldb + C) * 2u; }
;     const size_t kstep = (size_t)(BK * 2);
;     const size_t hstepA = (size_t)HALF * g.lda * 2, hstepB = (size_t)HALF * g.ldb * 2;
;     const size_t tstepA = 2 * hstepA, tstepB = 2 * hstepB;
;     const unsigned ldsw = (unsigned)wid * 1024u;
;     const int aoff = lds_byte(wr * 64 + fr, fq * 8), boff = lds_byte(wc * 32 + fr, fq * 8);
;     ...
;     const unsigned ldsb0 = (unsigned)(uintptr_t)lds + ldsw;
;     ...
;     Unit cur, nxt; int ui = 0;
;     if (!S.next(0, cur)) return;
;     f32x4 acc[2][2][4][2];
; #pragma unroll
;     for (int a = 0; a < 2; ++a)
; #pragma unroll
;         for (int b = 0; b < 2; ++b)
; #pragma unroll
;             for (int m = 0; m < 4; ++m)
; #pragma unroll
;                 for (int n = 0; n < 2; ++n) acc[a][b][m][n] = (f32x4){0.f, 0.f, 0.f, 0.f};
;     bf16x8 At[4][2], B0[2][2], B1[2][2];
;     float pre[Epi::NPRE > 0 ? Epi::NPRE : 1];
;     if constexpr (Epi::NPRE > 0) E.preload(cur, wr, fr, pre);
;     const char* cA = (const char*)g.A + (size_t)cur.pm * tstepA + (size_t)cur.pn * g.a_koff * 2; const char* cB = (const char*)g.Bt + (size_t)cur.pn * tstepB;
.LBB0_2157:
	v_bfe_i32 v4, v2, 27, 1
	v_lshlrev_b32_e32 v1, 4, v2
	v_lshrrev_b32_e32 v4, 22, v4
	v_add_u32_e32 v4, v1, v4
	v_and_b32_e32 v4, 0xfffffc00, v4
	v_sub_u32_e32 v4, v1, v4
	v_lshrrev_b32_e32 v5, 4, v4
	v_ashrrev_i32_e32 v3, 31, v2
	v_bitop3_b32 v5, v5, v4, 32 bitop3:0x6c
	v_ashrrev_i32_e32 v4, 31, v4
	v_lshrrev_b32_e32 v3, 26, v3
	v_lshrrev_b32_e32 v4, 26, v4
	v_add_u32_e32 v3, v2, v3
	v_add_u32_e32 v4, v5, v4
	v_ashrrev_i32_e32 v3, 6, v3
	v_ashrrev_i32_e32 v4, 6, v4
	v_lshlrev_b32_e32 v6, 3, v3
	v_mul_i32_i24_e32 v7, 64, v4
	v_and_b32_e32 v6, -16, v6
	v_lshlrev_b32_e32 v3, 5, v3
	v_sub_u32_e32 v5, v5, v7
	v_mov_b32_e32 v7, 1
	v_add_u32_e32 v6, v4, v6
	v_and_b32_e32 v3, 32, v3
	v_ashrrev_i16_sdwa v5, v7, sext(v5) dst_sel:DWORD dst_unused:UNUSED_PAD src0_sel:DWORD src1_sel:BYTE_0
	s_load_dwordx2 s[4:5], s[6:7], 0xb0
	s_load_dwordx2 s[18:19], s[16:17], 0xb0
	s_load_dwordx2 s[14:15], s[10:11], 0xa8
	s_load_dwordx2 s[8:9], s[12:13], 0xa0
	s_ashr_i32 s10, s2, 3
	v_add_u32_sdwa v3, v3, sext(v5) dst_sel:DWORD dst_unused:UNUSED_PAD src0_sel:DWORD src1_sel:WORD_0
	v_lshlrev_b32_e32 v5, 1, v6
	v_lshrrev_b32_e32 v8, 2, v6
	v_and_b32_e32 v4, 3, v4
	s_mov_b32 s2, 0x7fffe0
	v_and_b32_e32 v5, 24, v5
	v_and_b32_e32 v8, 4, v8
	v_and_or_b32 v4, v6, s2, v4
	v_or3_b32 v4, v4, v8, v5
	s_movk_i32 s7, 0x1600
	v_mul_lo_u32 v5, v6, s7
	v_mul_u32_u24_e32 v4, 0x1600, v4
	v_add_u32_e32 v1, 0x2000, v1
	s_waitcnt lgkmcnt(0)
	s_add_u32 s37, s22, 0x1f900000
	s_waitcnt vmcnt(3)
	v_add_lshl_u32 v131, v3, v5, 1
	s_waitcnt vmcnt(2)
	v_add_lshl_u32 v136, v4, v3, 1
	v_ashrrev_i32_e32 v3, 31, v1
	s_addc_u32 s38, s23, 0
	v_lshrrev_b32_e32 v3, 22, v3
	s_add_u32 s39, s20, 0xa900000
	v_add_u32_e32 v3, v1, v3
	s_addc_u32 s40, s21, 0
	v_ashrrev_i32_e32 v3, 10, v3
	s_add_i32 s3, s3, s10
	v_mul_i32_i24_e32 v4, 0x400, v3
	s_ashr_i32 s10, s3, 31
	v_sub_u32_e32 v1, v1, v4
	s_lshr_b32 s10, s10, 26
	v_lshrrev_b32_e32 v4, 4, v1
	s_add_i32 s10, s3, s10
	v_bitop3_b32 v1, v4, v1, 32 bitop3:0x6c
	s_ashr_i32 s11, s10, 6
	s_andn2_b32 s10, s10, 63
	v_ashrrev_i32_e32 v5, 31, v1
	s_sub_i32 s3, s3, s10
	v_lshrrev_b32_e32 v5, 26, v5
	s_bfe_i32 s10, s3, 0x80000
	v_add_u32_e32 v5, v1, v5
	s_bfe_u32 s10, s10, 0x3000c
	v_lshlrev_b32_e32 v4, 3, v3
	v_ashrrev_i32_e32 v6, 6, v5
	v_and_b32_e32 v5, 0xc0, v5
	s_add_i32 s12, s3, s10
	v_and_b32_e32 v4, -16, v4
	v_lshlrev_b32_e32 v3, 5, v3
	v_sub_u32_e32 v1, v1, v5
	s_bfe_i32 s10, s12, 0x80000
	s_and_b32 s12, s12, 0xf8
	v_add_u32_e32 v4, v6, v4
	v_and_b32_e32 v3, 32, v3
	v_ashrrev_i16_sdwa v1, v7, sext(v1) dst_sel:DWORD dst_unused:UNUSED_PAD src0_sel:DWORD src1_sel:BYTE_0
	v_and_b32_e32 v6, 3, v6
	s_sub_i32 s3, s3, s12
	v_add_u32_sdwa v1, v3, sext(v1) dst_sel:DWORD dst_unused:UNUSED_PAD src0_sel:DWORD src1_sel:WORD_0
	v_lshlrev_b32_e32 v3, 1, v4
	v_lshrrev_b32_e32 v5, 2, v4
	v_and_or_b32 v6, v4, s2, v6
	v_mul_lo_u32 v4, v4, s7
	s_ashr_i32 s7, s36, 6
	s_lshl_b32 s11, s11, 3
	s_sext_i32_i16 s13, s10
	s_sext_i32_i8 s3, s3
	s_lshl_b32 s2, s7, 10
	s_add_i32 s17, s11, s3
	s_ashr_i32 s3, s13, 3
	s_ashr_i32 s6, s36, 8
	v_and_b32_e32 v3, 24, v3
	v_and_b32_e32 v5, 4, v5
	s_add_i32 s2, s2, 0
	s_lshr_b32 s10, s13, 3
	s_mul_hi_i32 s12, s3, 0x2c0000
	s_mul_i32 s3, s3, 0x2c0000
	v_or3_b32 v3, v6, v5, v3
	s_add_u32 s20, s39, s3
	v_mul_u32_u24_e32 v3, 0x1600, v3
	s_addc_u32 s21, s40, s12
	s_add_i32 s3, s2, 0x10000
	s_mov_b32 m0, s3
	s_nop 0
	global_load_lds_dwordx4 v136, s[20:21]
	s_waitcnt vmcnt(1)
	v_add_lshl_u32 v138, v3, v1, 1
	s_add_i32 s41, s2, 0x12000
	s_mov_b32 m0, s41
	s_nop 0
	global_load_lds_dwordx4 v138, s[20:21]
	s_add_u32 s12, s20, 0x160000
	s_addc_u32 s13, s21, 0
	s_add_i32 s42, s2, 0x14000
	s_mov_b32 m0, s42
	s_nop 0
	global_load_lds_dwordx4 v136, s[12:13]
	s_mul_i32 s16, s17, 0x2c0000
	s_add_i32 s43, s2, 0x16000
	s_mov_b32 m0, s43
	s_nop 0
	global_load_lds_dwordx4 v138, s[12:13]
	s_mul_hi_i32 s11, s17, 0x2c0000
	s_add_u32 s22, s37, s16
	s_addc_u32 s23, s38, s11
	s_mov_b32 m0, s2
	s_nop 0
	global_load_lds_dwordx4 v131, s[22:23]
	s_add_i32 s44, s2, 0x2000
	v_add_lshl_u32 v137, v1, v4, 1
	s_mov_b32 m0, s44
	s_nop 0
	global_load_lds_dwordx4 v137, s[22:23]
	s_add_u32 s12, s22, 0x160000
	s_addc_u32 s13, s23, 0
	s_add_i32 s46, s2, 0x4000
	s_mov_b32 m0, s46
	s_nop 0
	global_load_lds_dwordx4 v131, s[12:13]
	s_add_i32 s47, s2, 0x6000
	s_mov_b32 m0, s47
	s_nop 0
	global_load_lds_dwordx4 v137, s[12:13]
	s_cmp_lg_u32 s6, 1
	s_cbranch_scc1 .LBB0_2159
	s_barrier
; #define PG8_STAGE(bufoff, gbase, voff) do { _Pragma("unroll") for (int _i = 0; _i < 2; ++_i) { unsigned keep_; \
;         asm volatile("s_mov_b32 %0, m0\n\ts_mov_b32 m0, %3\n\ts_nop 0\n\tglobal_load_lds_dwordx4 %1, %2\n\ts_mov_b32 m0, %0" \
;             : "=&s"(keep_) : "v"((voff)[_i]), "s"((const void*)(gbase)), "s"(ldsb0 + (unsigned)(bufoff) + (unsigned)(_i * 8192)) : "memory"); } } while (0)
; #define PG8_WAIT_V(n) asm volatile("s_waitcnt vmcnt(" #n ")" ::: "memory")
; #define PG8_BAR __builtin_amdgcn_s_barrier()
; template <class Epi, class Sched, bool ALIGN_EPI>
; __device__ __forceinline__ void gemm_phase(LAS unsigned char* lds, const Gemm g, const Sched& S, const Epi& E) {
;     ...
;     f32x4 acc[2][2][4][2];
; #pragma unroll
;     for (int a = 0; a < 2; ++a)
; #pragma unroll
;         for (int b = 0; b < 2; ++b)
; #pragma unroll
;             for (int m = 0; m < 4; ++m)
; #pragma unroll
;                 for (int n = 0; n < 2; ++n) acc[a][b][m][n] = (f32x4){0.f, 0.f, 0.f, 0.f};
;     bf16x8 At[4][2], B0[2][2], B1[2][2];
;     float pre[Epi::NPRE > 0 ? Epi::NPRE : 1];
;     if constexpr (Epi::NPRE > 0) E.preload(cur, wr, fr, pre);
;     const char* cA = (const char*)g.A + (size_t)cur.pm * tstepA + (size_t)cur.pn * g.a_koff * 2; const char* cB = (const char*)g.Bt + (size_t)cur.pn * tstepB;
;     PG8_STAGE(PG8_SB(0, 0), cB, voffB); PG8_STAGE(PG8_SB(0, 1), cB + hstepB, voffB); PG8_STAGE(PG8_SA(0, 0), cA, voffA); PG8_STAGE(PG8_SA(0, 1), cA + hstepA, voffA);
;     if (wr == 1) PG8_BAR;
;     PG8_WAIT_V(2); PG8_BAR;
;     PG8_STAGE(PG8_SB(1, 0), cB + kstep, voffB); PG8_STAGE(PG8_SA(1, 0), cA + kstep, voffA); PG8_STAGE(PG8_SB(1, 1), cB + hstepB + kstep, voffB);
;     PG8_WAIT_V(6); PG8_BAR;
;     for (;;) {
.LBB0_2159:
	v_bfe_u32 v203, v2, 4, 2
	v_and_b32_e32 v1, 15, v2
	v_lshlrev_b32_e32 v130, 4, v203
	v_lshlrev_b32_e32 v2, 2, v2
	s_lshl_b32 s16, s6, 6
	v_lshl_or_b32 v3, v1, 6, v130
	s_lshl_b32 s6, s6, 13
	v_and_b32_e32 v2, 32, v2
	v_bitop3_b32 v6, v3, s6, v2 bitop3:0xde
	s_lshl_b32 s6, s7, 5
	s_and_b32 s33, s6, 0x60
	s_lshl_b32 s6, s33, 7
	v_bitop3_b32 v7, v3, s6, v2 bitop3:0xde
	s_add_u32 s6, s20, 0x80
	s_sext_i32_i8 s45, s10
	s_waitcnt vmcnt(2)
	s_barrier
	s_addc_u32 s7, s21, 0
	s_add_i32 s48, s2, 0x18000
	s_mov_b32 m0, s48
	s_nop 0
	global_load_lds_dwordx4 v136, s[6:7]
	s_add_i32 s49, s2, 0x1a000
	s_mov_b32 m0, s49
	s_nop 0
	global_load_lds_dwordx4 v138, s[6:7]
	s_add_u32 s6, s22, 0x80
	s_addc_u32 s7, s23, 0
	s_add_i32 s50, s2, 0x8000
	s_mov_b32 m0, s50
	s_nop 0
	global_load_lds_dwordx4 v131, s[6:7]
	s_add_i32 s51, s2, 0xa000
	s_mov_b32 m0, s51
	s_nop 0
	global_load_lds_dwordx4 v137, s[6:7]
	s_add_u32 s6, s20, 0x160080
	s_addc_u32 s7, s21, 0
	s_add_i32 s52, s2, 0x1c000
	s_mov_b32 m0, s52
	s_nop 0
	global_load_lds_dwordx4 v136, s[6:7]
	s_add_i32 s53, s2, 0x1e000
	s_mov_b32 m0, s53
	s_nop 0
	global_load_lds_dwordx4 v138, s[6:7]
	v_mov_b32_e32 v2, 0
	s_waitcnt vmcnt(6)
	v_mov_b32_e32 v4, v2
	v_mov_b32_e32 v5, v2
	v_mov_b32_e32 v3, v2
	s_waitcnt vmcnt(0)
	v_add_u32_e32 v139, 0, v7
	v_add_u32_e32 v140, 0, v6
	v_mov_b64_e32 v[8:9], v[4:5]
	v_mov_b64_e32 v[20:21], v[4:5]
	v_mov_b64_e32 v[24:25], v[4:5]
	v_mov_b64_e32 v[36:37], v[4:5]
	v_mov_b64_e32 v[40:41], v[4:5]
	v_mov_b64_e32 v[52:53], v[4:5]
	v_mov_b64_e32 v[56:57], v[4:5]
	v_mov_b64_e32 v[12:13], v[4:5]
	v_mov_b64_e32 v[16:17], v[4:5]
	v_mov_b64_e32 v[28:29], v[4:5]
	v_mov_b64_e32 v[32:33], v[4:5]
	v_mov_b64_e32 v[44:45], v[4:5]
	v_mov_b64_e32 v[48:49], v[4:5]
	v_mov_b64_e32 v[60:61], v[4:5]
	v_mov_b64_e32 v[64:65], v[4:5]
	v_mov_b64_e32 v[68:69], v[4:5]
	v_mov_b64_e32 v[72:73], v[4:5]
	v_mov_b64_e32 v[84:85], v[4:5]
	v_mov_b64_e32 v[88:89], v[4:5]
	v_mov_b64_e32 v[100:101], v[4:5]
	v_mov_b64_e32 v[104:105], v[4:5]
	v_mov_b64_e32 v[116:117], v[4:5]
	v_mov_b64_e32 v[120:121], v[4:5]
	v_mov_b64_e32 v[76:77], v[4:5]
	v_mov_b64_e32 v[80:81], v[4:5]
	v_mov_b64_e32 v[92:93], v[4:5]
	v_mov_b64_e32 v[96:97], v[4:5]
	v_mov_b64_e32 v[108:109], v[4:5]
	v_mov_b64_e32 v[112:113], v[4:5]
	v_mov_b64_e32 v[124:125], v[4:5]
	v_mov_b64_e32 v[128:129], v[4:5]
	s_add_i32 s54, s2, 0xc000
	s_add_i32 s55, s2, 0xe000
	s_mov_b32 s56, 0
	v_mov_b64_e32 v[132:133], 0x100
	v_mov_b64_e32 v[134:135], 0xff
	v_mov_b64_e32 v[6:7], v[2:3]
	v_mov_b64_e32 v[18:19], v[2:3]
	v_mov_b64_e32 v[22:23], v[2:3]
	v_mov_b64_e32 v[34:35], v[2:3]
	v_mov_b64_e32 v[38:39], v[2:3]
	v_mov_b64_e32 v[50:51], v[2:3]
	v_mov_b64_e32 v[54:55], v[2:3]
	v_mov_b64_e32 v[10:11], v[2:3]
	v_mov_b64_e32 v[14:15], v[2:3]
	v_mov_b64_e32 v[26:27], v[2:3]
	v_mov_b64_e32 v[30:31], v[2:3]
	v_mov_b64_e32 v[42:43], v[2:3]
	v_mov_b64_e32 v[46:47], v[2:3]
	v_mov_b64_e32 v[58:59], v[2:3]
	v_mov_b64_e32 v[62:63], v[2:3]
	v_mov_b64_e32 v[66:67], v[2:3]
	v_mov_b64_e32 v[70:71], v[2:3]
	v_mov_b64_e32 v[82:83], v[2:3]
	v_mov_b64_e32 v[86:87], v[2:3]
	v_mov_b64_e32 v[98:99], v[2:3]
	v_mov_b64_e32 v[102:103], v[2:3]
	v_mov_b64_e32 v[114:115], v[2:3]
	v_mov_b64_e32 v[118:119], v[2:3]
	v_mov_b64_e32 v[74:75], v[2:3]
	v_mov_b64_e32 v[78:79], v[2:3]
	v_mov_b64_e32 v[90:91], v[2:3]
	v_mov_b64_e32 v[94:95], v[2:3]
	v_mov_b64_e32 v[106:107], v[2:3]
	v_mov_b64_e32 v[110:111], v[2:3]
	v_mov_b64_e32 v[122:123], v[2:3]
	v_mov_b64_e32 v[126:127], v[2:3]
	s_barrier
	s_branch .LBB0_2161

; #define PG8_STAGE(bufoff, gbase, voff) do { _Pragma("unroll") for (int _i = 0; _i < 2; ++_i) { unsigned keep_; \
;         asm volatile("s_mov_b32 %0, m0\n\ts_mov_b32 m0, %3\n\ts_nop 0\n\tglobal_load_lds_dwordx4 %1, %2\n\ts_mov_b32 m0, %0" \
;             : "=&s"(keep_) : "v"((voff)[_i]), "s"((const void*)(gbase)), "s"(ldsb0 + (unsigned)(bufoff) + (unsigned)(_i * 8192)) : "memory"); } } while (0)
; #define PG8_LDA(dst, b, h) do { _Pragma("unroll") for (int m = 0; m < 4; ++m) _Pragma("unroll") for (int k = 0; k < 2; ++k) dst[m][k] = *(const LAS bf16x8*)(lds + PG8_SA(b, h) + aoff + m * 2048 + k * 1024); } while (0)
; #define PG8_LDB(dst, b, h) do { _Pragma("unroll") for (int n = 0; n < 2; ++n) _Pragma("unroll") for (int k = 0; k < 2; ++k) dst[n][k] = *(const LAS bf16x8*)(lds + PG8_SB(b, h) + boff + n * 2048 + k * 1024); } while (0)
; #define PG8_MMA(ai, bj, At, Bt) do { __builtin_amdgcn_s_setprio(1); _Pragma("unroll") for (int m = 0; m < 4; ++m) _Pragma("unroll") for (int n = 0; n < 2; ++n) _Pragma("unroll") for (int k = 0; k < 2; ++k) \
;         acc[ai][bj][m][n] = __builtin_amdgcn_mfma_f32_16x16x32_bf16(Bt[n][k], At[m][k], acc[ai][bj][m][n], 0, 0, 0); __builtin_amdgcn_s_setprio(0); } while (0)
; #define PG8_WAIT_V(n) asm volatile("s_waitcnt vmcnt(" #n ")" ::: "memory")
; #define PG8_BAR __builtin_amdgcn_s_barrier()
; template <class Epi, class Sched, bool ALIGN_EPI>
; __device__ __forceinline__ void gemm_phase(LAS unsigned char* lds, const Gemm g, const Sched& S, const Epi& E) {
;     ...
;         for (int t = 0; t < nt; t += 2) {
;             const bool last = (t == nt - 2);
;             const char* a1 = cA + (size_t)(t + 1) * kstep;
;             const char* a2 = last ? nA : cA + (size_t)(t + 2) * kstep; const char* b2 = last ? nB : cB + (size_t)(t + 2) * kstep;
;             const char* a3 = a2 + kstep; const char* b3 = b2 + kstep;
;             PG8_LDB(B0, 0, 0); PG8_LDB(B1, 0, 1); PG8_SCHED; PG8_LDA(At, 0, 0); PG8_STAGE(PG8_SA(1, 1), a1 + hstepA, voffA);
;             PG8_WAIT_V(8); PG8_WAIT_L(0); PG8_BAR; PG8_MMA(0, 0, At, B0); PG8_MMA(0, 1, At, B1); PG8_BAR; PG8_SCHED;
;             PG8_LDA(At, 0, 1); PG8_STAGE(PG8_SB(0, 0), b2, voffB); PG8_STAGE(PG8_SB(0, 1), b2 + hstepB, voffB); PG8_STAGE(PG8_SA(0, 0), a2, voffA);
;             PG8_WAIT_V(8); PG8_WAIT_L(0); PG8_BAR; PG8_MMA(1, 0, At, B0); PG8_MMA(1, 1, At, B1); PG8_BAR; PG8_SCHED;
.LBB0_2172:
	s_add_u32 s61, s22, s26
	s_addc_u32 s63, s23, s27
	s_add_u32 s28, s61, 0x100
	v_add_u32_e32 v141, 0x10000, v139
	s_addc_u32 s29, s63, 0
	ds_read_b128 v[142:145], v141
	ds_read_b128 v[146:149], v141 offset:1024
	ds_read_b128 v[150:153], v141 offset:2048
	ds_read_b128 v[154:157], v141 offset:3072
	v_add_u32_e32 v141, 0x14000, v139
	s_add_u32 s30, s20, s26
	ds_read_b128 v[158:161], v141
	ds_read_b128 v[162:165], v141 offset:1024
	ds_read_b128 v[166:169], v141 offset:2048
	ds_read_b128 v[170:173], v141 offset:3072
	s_addc_u32 s31, s21, s27
	s_add_u32 s30, s30, 0x100
	s_addc_u32 s31, s31, 0
	s_cmpk_eq_i32 s60, 0x54
	s_cselect_b32 s34, s12, s28
	s_cselect_b32 s35, s13, s29
	s_cselect_b32 s30, s24, s30
	s_cselect_b32 s31, s25, s31
	s_add_u32 s28, s34, 0x80
	s_addc_u32 s29, s35, 0
	ds_read_b128 v[174:177], v140
	ds_read_b128 v[178:181], v140 offset:1024
	ds_read_b128 v[182:185], v140 offset:2048
	ds_read_b128 v[186:189], v140 offset:3072
	ds_read_b128 v[190:193], v140 offset:4096
	ds_read_b128 v[194:197], v140 offset:5120
	ds_read_b128 v[198:201], v140 offset:6144
	ds_read_b128 v[204:207], v140 offset:7168
	s_add_u32 s62, s61, 0x160080
	s_addc_u32 s63, s63, 0
	s_mov_b32 m0, s54
	s_nop 0
	global_load_lds_dwordx4 v131, s[62:63]
	s_nop 0
	s_mov_b32 m0, s55
	s_nop 0
	global_load_lds_dwordx4 v137, s[62:63]
	s_waitcnt vmcnt(8)
	s_waitcnt lgkmcnt(0)
	s_barrier
	s_setprio 1
	v_mfma_f32_16x16x32_bf16 v[126:129], v[142:145], v[174:177], v[126:129]
	v_mfma_f32_16x16x32_bf16 v[122:125], v[150:153], v[174:177], v[122:125]
	v_mfma_f32_16x16x32_bf16 v[110:113], v[142:145], v[182:185], v[110:113]
	v_mfma_f32_16x16x32_bf16 v[106:109], v[150:153], v[182:185], v[106:109]
	v_mfma_f32_16x16x32_bf16 v[94:97], v[142:145], v[190:193], v[94:97]
	v_mfma_f32_16x16x32_bf16 v[90:93], v[150:153], v[190:193], v[90:93]
	v_mfma_f32_16x16x32_bf16 v[78:81], v[142:145], v[198:201], v[78:81]
	v_mfma_f32_16x16x32_bf16 v[74:77], v[150:153], v[198:201], v[74:77]
	v_mfma_f32_16x16x32_bf16 v[126:129], v[146:149], v[178:181], v[126:129]
	v_mfma_f32_16x16x32_bf16 v[122:125], v[154:157], v[178:181], v[122:125]
	v_mfma_f32_16x16x32_bf16 v[110:113], v[146:149], v[186:189], v[110:113]
	v_mfma_f32_16x16x32_bf16 v[106:109], v[154:157], v[186:189], v[106:109]
	v_mfma_f32_16x16x32_bf16 v[94:97], v[146:149], v[194:197], v[94:97]
	v_mfma_f32_16x16x32_bf16 v[90:93], v[154:157], v[194:197], v[90:93]
	v_mfma_f32_16x16x32_bf16 v[78:81], v[146:149], v[204:207], v[78:81]
	v_mfma_f32_16x16x32_bf16 v[74:77], v[154:157], v[204:207], v[74:77]
	v_mfma_f32_16x16x32_bf16 v[118:121], v[158:161], v[174:177], v[118:121]
	v_mfma_f32_16x16x32_bf16 v[114:117], v[166:169], v[174:177], v[114:117]
	v_mfma_f32_16x16x32_bf16 v[102:105], v[158:161], v[182:185], v[102:105]
	v_mfma_f32_16x16x32_bf16 v[98:101], v[166:169], v[182:185], v[98:101]
	v_mfma_f32_16x16x32_bf16 v[86:89], v[158:161], v[190:193], v[86:89]
	v_mfma_f32_16x16x32_bf16 v[82:85], v[166:169], v[190:193], v[82:85]
	v_mfma_f32_16x16x32_bf16 v[70:73], v[158:161], v[198:201], v[70:73]
	v_mfma_f32_16x16x32_bf16 v[66:69], v[166:169], v[198:201], v[66:69]
	v_mfma_f32_16x16x32_bf16 v[118:121], v[162:165], v[178:181], v[118:121]
	v_mfma_f32_16x16x32_bf16 v[114:117], v[170:173], v[178:181], v[114:117]
	v_mfma_f32_16x16x32_bf16 v[102:105], v[162:165], v[186:189], v[102:105]
	v_mfma_f32_16x16x32_bf16 v[98:101], v[170:173], v[186:189], v[98:101]
	v_mfma_f32_16x16x32_bf16 v[86:89], v[162:165], v[194:197], v[86:89]
	v_mfma_f32_16x16x32_bf16 v[82:85], v[170:173], v[194:197], v[82:85]
	v_mfma_f32_16x16x32_bf16 v[70:73], v[162:165], v[204:207], v[70:73]
	v_mfma_f32_16x16x32_bf16 v[66:69], v[170:173], v[204:207], v[66:69]
	s_setprio 0
	s_barrier
	ds_read_b128 v[174:177], v140 offset:16384
	ds_read_b128 v[178:181], v140 offset:17408
	ds_read_b128 v[182:185], v140 offset:18432
	ds_read_b128 v[186:189], v140 offset:19456
	ds_read_b128 v[190:193], v140 offset:20480
	ds_read_b128 v[194:197], v140 offset:21504
	ds_read_b128 v[198:201], v140 offset:22528
	ds_read_b128 v[204:207], v140 offset:23552
	s_mov_b32 m0, s3
	s_nop 0
	global_load_lds_dwordx4 v136, s[30:31]
	s_add_u32 s62, s30, 0x160000
	s_mov_b32 m0, s41
	s_nop 0
	global_load_lds_dwordx4 v138, s[30:31]
	s_addc_u32 s63, s31, 0
	s_mov_b32 m0, s42
	s_nop 0
	global_load_lds_dwordx4 v136, s[62:63]
	s_nop 0
	s_mov_b32 m0, s43
	s_nop 0
	global_load_lds_dwordx4 v138, s[62:63]
	s_nop 0
	s_mov_b32 m0, s2
	s_nop 0
	global_load_lds_dwordx4 v131, s[34:35]
	s_nop 0
	s_mov_b32 m0, s44
	s_nop 0
	global_load_lds_dwordx4 v137, s[34:35]
	s_waitcnt vmcnt(8)
	s_waitcnt lgkmcnt(0)
	s_barrier
; #define PG8_STAGE(bufoff, gbase, voff) do { _Pragma("unroll") for (int _i = 0; _i < 2; ++_i) { unsigned keep_; \
;         asm volatile("s_mov_b32 %0, m0\n\ts_mov_b32 m0, %3\n\ts_nop 0\n\tglobal_load_lds_dwordx4 %1, %2\n\ts_mov_b32 m0, %0" \
;             : "=&s"(keep_) : "v"((voff)[_i]), "s"((const void*)(gbase)), "s"(ldsb0 + (unsigned)(bufoff) + (unsigned)(_i * 8192)) : "memory"); } } while (0)
; #define PG8_LDA(dst, b, h) do { _Pragma("unroll") for (int m = 0; m < 4; ++m) _Pragma("unroll") for (int k = 0; k < 2; ++k) dst[m][k] = *(const LAS bf16x8*)(lds + PG8_SA(b, h) + aoff + m * 2048 + k * 1024); } while (0)
; #define PG8_LDB(dst, b, h) do { _Pragma("unroll") for (int n = 0; n < 2; ++n) _Pragma("unroll") for (int k = 0; k < 2; ++k) dst[n][k] = *(const LAS bf16x8*)(lds + PG8_SB(b, h) + boff + n * 2048 + k * 1024); } while (0)
; #define PG8_MMA(ai, bj, At, Bt) do { __builtin_amdgcn_s_setprio(1); _Pragma("unroll") for (int m = 0; m < 4; ++m) _Pragma("unroll") for (int n = 0; n < 2; ++n) _Pragma("unroll") for (int k = 0; k < 2; ++k) \
;         acc[ai][bj][m][n] = __builtin_amdgcn_mfma_f32_16x16x32_bf16(Bt[n][k], At[m][k], acc[ai][bj][m][n], 0, 0, 0); __builtin_amdgcn_s_setprio(0); } while (0)
; #define PG8_WAIT_V(n) asm volatile("s_waitcnt vmcnt(" #n ")" ::: "memory")
; #define PG8_WAIT_L(n) asm volatile("s_waitcnt lgkmcnt(" #n ")" ::: "memory")
; #define PG8_BAR __builtin_amdgcn_s_barrier()
; #define PG8_SCHED __builtin_amdgcn_sched_barrier(0)
; template <class Epi, class Sched, bool ALIGN_EPI>
; __device__ __forceinline__ void gemm_phase(LAS unsigned char* lds, const Gemm g, const Sched& S, const Epi& E) {
;     ...
;             PG8_WAIT_V(8); PG8_WAIT_L(0); PG8_BAR; PG8_MMA(1, 0, At, B0); PG8_MMA(1, 1, At, B1); PG8_BAR; PG8_SCHED;
;             PG8_LDB(B0, 1, 0); PG8_LDB(B1, 1, 1); PG8_SCHED; PG8_LDA(At, 1, 0); PG8_STAGE(PG8_SA(0, 1), a2 + hstepA, voffA);
;             PG8_WAIT_V(8); PG8_WAIT_L(0); PG8_BAR; PG8_MMA(0, 0, At, B0); PG8_MMA(0, 1, At, B1); PG8_BAR; PG8_SCHED;
;             PG8_LDA(At, 1, 1); PG8_STAGE(PG8_SB(1, 0), b3, voffB); PG8_STAGE(PG8_SB(1, 1), b3 + hstepB, voffB); PG8_STAGE(PG8_SA(1, 0), a3, voffA);
	s_setprio 1
	v_mfma_f32_16x16x32_bf16 v[62:65], v[142:145], v[174:177], v[62:65]
	v_mfma_f32_16x16x32_bf16 v[58:61], v[150:153], v[174:177], v[58:61]
	v_mfma_f32_16x16x32_bf16 v[46:49], v[142:145], v[182:185], v[46:49]
	v_mfma_f32_16x16x32_bf16 v[42:45], v[150:153], v[182:185], v[42:45]
	v_mfma_f32_16x16x32_bf16 v[30:33], v[142:145], v[190:193], v[30:33]
	v_mfma_f32_16x16x32_bf16 v[26:29], v[150:153], v[190:193], v[26:29]
	v_mfma_f32_16x16x32_bf16 v[14:17], v[142:145], v[198:201], v[14:17]
	v_mfma_f32_16x16x32_bf16 v[10:13], v[150:153], v[198:201], v[10:13]
	v_mfma_f32_16x16x32_bf16 v[62:65], v[146:149], v[178:181], v[62:65]
	v_mfma_f32_16x16x32_bf16 v[58:61], v[154:157], v[178:181], v[58:61]
	v_mfma_f32_16x16x32_bf16 v[46:49], v[146:149], v[186:189], v[46:49]
	v_mfma_f32_16x16x32_bf16 v[42:45], v[154:157], v[186:189], v[42:45]
	v_mfma_f32_16x16x32_bf16 v[30:33], v[146:149], v[194:197], v[30:33]
	v_mfma_f32_16x16x32_bf16 v[26:29], v[154:157], v[194:197], v[26:29]
	v_mfma_f32_16x16x32_bf16 v[14:17], v[146:149], v[204:207], v[14:17]
	v_mfma_f32_16x16x32_bf16 v[10:13], v[154:157], v[204:207], v[10:13]
	v_mfma_f32_16x16x32_bf16 v[54:57], v[158:161], v[174:177], v[54:57]
	v_mfma_f32_16x16x32_bf16 v[50:53], v[166:169], v[174:177], v[50:53]
	v_mfma_f32_16x16x32_bf16 v[38:41], v[158:161], v[182:185], v[38:41]
	v_mfma_f32_16x16x32_bf16 v[34:37], v[166:169], v[182:185], v[34:37]
	v_mfma_f32_16x16x32_bf16 v[22:25], v[158:161], v[190:193], v[22:25]
	v_mfma_f32_16x16x32_bf16 v[18:21], v[166:169], v[190:193], v[18:21]
	v_mfma_f32_16x16x32_bf16 v[6:9], v[158:161], v[198:201], v[6:9]
	v_mfma_f32_16x16x32_bf16 v[2:5], v[166:169], v[198:201], v[2:5]
	v_mfma_f32_16x16x32_bf16 v[54:57], v[162:165], v[178:181], v[54:57]
	v_mfma_f32_16x16x32_bf16 v[50:53], v[170:173], v[178:181], v[50:53]
	v_mfma_f32_16x16x32_bf16 v[38:41], v[162:165], v[186:189], v[38:41]
	v_mfma_f32_16x16x32_bf16 v[34:37], v[170:173], v[186:189], v[34:37]
	v_mfma_f32_16x16x32_bf16 v[22:25], v[162:165], v[194:197], v[22:25]
	v_mfma_f32_16x16x32_bf16 v[18:21], v[170:173], v[194:197], v[18:21]
	v_mfma_f32_16x16x32_bf16 v[6:9], v[162:165], v[204:207], v[6:9]
	v_mfma_f32_16x16x32_bf16 v[2:5], v[170:173], v[204:207], v[2:5]
	s_setprio 0
	s_barrier
	v_add_u32_e32 v141, 0x18000, v139
	ds_read_b128 v[142:145], v141
	ds_read_b128 v[146:149], v141 offset:1024
	ds_read_b128 v[150:153], v141 offset:2048
	ds_read_b128 v[154:157], v141 offset:3072
	v_add_u32_e32 v141, 0x1c000, v139
	ds_read_b128 v[158:161], v141
	ds_read_b128 v[162:165], v141 offset:1024
	ds_read_b128 v[166:169], v141 offset:2048
	ds_read_b128 v[170:173], v141 offset:3072
	ds_read_b128 v[174:177], v140 offset:32768
	ds_read_b128 v[178:181], v140 offset:33792
	ds_read_b128 v[182:185], v140 offset:34816
	ds_read_b128 v[186:189], v140 offset:35840
	ds_read_b128 v[190:193], v140 offset:36864
	ds_read_b128 v[194:197], v140 offset:37888
	ds_read_b128 v[198:201], v140 offset:38912
	ds_read_b128 v[204:207], v140 offset:39936
	s_add_u32 s34, s34, 0x160000
	s_addc_u32 s35, s35, 0
	s_mov_b32 m0, s46
	s_nop 0
	global_load_lds_dwordx4 v131, s[34:35]
	s_nop 0
	s_mov_b32 m0, s47
	s_nop 0
	global_load_lds_dwordx4 v137, s[34:35]
	s_waitcnt vmcnt(8)
	s_waitcnt lgkmcnt(0)
	s_barrier
	s_setprio 1
	v_mfma_f32_16x16x32_bf16 v[126:129], v[142:145], v[174:177], v[126:129]
	v_mfma_f32_16x16x32_bf16 v[122:125], v[150:153], v[174:177], v[122:125]
	v_mfma_f32_16x16x32_bf16 v[110:113], v[142:145], v[182:185], v[110:113]
	v_mfma_f32_16x16x32_bf16 v[106:109], v[150:153], v[182:185], v[106:109]
	v_mfma_f32_16x16x32_bf16 v[94:97], v[142:145], v[190:193], v[94:97]
	v_mfma_f32_16x16x32_bf16 v[90:93], v[150:153], v[190:193], v[90:93]
	v_mfma_f32_16x16x32_bf16 v[78:81], v[142:145], v[198:201], v[78:81]
	v_mfma_f32_16x16x32_bf16 v[74:77], v[150:153], v[198:201], v[74:77]
	v_mfma_f32_16x16x32_bf16 v[126:129], v[146:149], v[178:181], v[126:129]
	v_mfma_f32_16x16x32_bf16 v[122:125], v[154:157], v[178:181], v[122:125]
	v_mfma_f32_16x16x32_bf16 v[110:113], v[146:149], v[186:189], v[110:113]
	v_mfma_f32_16x16x32_bf16 v[106:109], v[154:157], v[186:189], v[106:109]
	v_mfma_f32_16x16x32_bf16 v[94:97], v[146:149], v[194:197], v[94:97]
	v_mfma_f32_16x16x32_bf16 v[90:93], v[154:157], v[194:197], v[90:93]
	v_mfma_f32_16x16x32_bf16 v[78:81], v[146:149], v[204:207], v[78:81]
	v_mfma_f32_16x16x32_bf16 v[74:77], v[154:157], v[204:207], v[74:77]
	v_mfma_f32_16x16x32_bf16 v[118:121], v[158:161], v[174:177], v[118:121]
	v_mfma_f32_16x16x32_bf16 v[114:117], v[166:169], v[174:177], v[114:117]
	v_mfma_f32_16x16x32_bf16 v[102:105], v[158:161], v[182:185], v[102:105]
	v_mfma_f32_16x16x32_bf16 v[98:101], v[166:169], v[182:185], v[98:101]
	v_mfma_f32_16x16x32_bf16 v[86:89], v[158:161], v[190:193], v[86:89]
	v_mfma_f32_16x16x32_bf16 v[82:85], v[166:169], v[190:193], v[82:85]
	v_mfma_f32_16x16x32_bf16 v[70:73], v[158:161], v[198:201], v[70:73]
	v_mfma_f32_16x16x32_bf16 v[66:69], v[166:169], v[198:201], v[66:69]
	v_mfma_f32_16x16x32_bf16 v[118:121], v[162:165], v[178:181], v[118:121]
	v_mfma_f32_16x16x32_bf16 v[114:117], v[170:173], v[178:181], v[114:117]
	v_mfma_f32_16x16x32_bf16 v[102:105], v[162:165], v[186:189], v[102:105]
	v_mfma_f32_16x16x32_bf16 v[98:101], v[170:173], v[186:189], v[98:101]
	v_mfma_f32_16x16x32_bf16 v[86:89], v[162:165], v[194:197], v[86:89]
	v_mfma_f32_16x16x32_bf16 v[82:85], v[170:173], v[194:197], v[82:85]
	v_mfma_f32_16x16x32_bf16 v[70:73], v[162:165], v[204:207], v[70:73]
	v_mfma_f32_16x16x32_bf16 v[66:69], v[170:173], v[204:207], v[66:69]
	s_setprio 0
	s_barrier
; #define PG8_STAGE(bufoff, gbase, voff) do { _Pragma("unroll") for (int _i = 0; _i < 2; ++_i) { unsigned keep_; \
;         asm volatile("s_mov_b32 %0, m0\n\ts_mov_b32 m0, %3\n\ts_nop 0\n\tglobal_load_lds_dwordx4 %1, %2\n\ts_mov_b32 m0, %0" \
;             : "=&s"(keep_) : "v"((voff)[_i]), "s"((const void*)(gbase)), "s"(ldsb0 + (unsigned)(bufoff) + (unsigned)(_i * 8192)) : "memory"); } } while (0)
; #define PG8_LDA(dst, b, h) do { _Pragma("unroll") for (int m = 0; m < 4; ++m) _Pragma("unroll") for (int k = 0; k < 2; ++k) dst[m][k] = *(const LAS bf16x8*)(lds + PG8_SA(b, h) + aoff + m * 2048 + k * 1024); } while (0)
; #define PG8_MMA(ai, bj, At, Bt) do { __builtin_amdgcn_s_setprio(1); _Pragma("unroll") for (int m = 0; m < 4; ++m) _Pragma("unroll") for (int n = 0; n < 2; ++n) _Pragma("unroll") for (int k = 0; k < 2; ++k) \
;         acc[ai][bj][m][n] = __builtin_amdgcn_mfma_f32_16x16x32_bf16(Bt[n][k], At[m][k], acc[ai][bj][m][n], 0, 0, 0); __builtin_amdgcn_s_setprio(0); } while (0)
; #define PG8_WAIT_V(n) asm volatile("s_waitcnt vmcnt(" #n ")" ::: "memory")
; #define PG8_WAIT_L(n) asm volatile("s_waitcnt lgkmcnt(" #n ")" ::: "memory")
; #define PG8_BAR __builtin_amdgcn_s_barrier()
; template <class Epi, class Sched, bool ALIGN_EPI>
; __device__ __forceinline__ void gemm_phase(LAS unsigned char* lds, const Gemm g, const Sched& S, const Epi& E) {
;     ...
;             PG8_LDA(At, 1, 1); PG8_STAGE(PG8_SB(1, 0), b3, voffB); PG8_STAGE(PG8_SB(1, 1), b3 + hstepB, voffB); PG8_STAGE(PG8_SA(1, 0), a3, voffA);
;             PG8_WAIT_V(8); PG8_WAIT_L(0); PG8_BAR; PG8_MMA(1, 0, At, B0); PG8_MMA(1, 1, At, B1); PG8_BAR; PG8_SCHED;
;         }
;         if constexpr (ALIGN_EPI) { if (wr == 0) PG8_BAR; }
;         if constexpr (Epi::NPRE > 0) E(acc, cur, wr, wc, fr, fq, pre); else
;         if constexpr (!Epi::AFTER_DRAIN) E(acc, cur, wr, wc, fr, fq);
;         if (!has_next) break;
; #pragma unroll
;         for (int a = 0; a < 2; ++a)
; #pragma unroll
;             for (int b = 0; b < 2; ++b)
; #pragma unroll
;                 for (int m = 0; m < 4; ++m)
; #pragma unroll
;                     for (int n = 0; n < 2; ++n) acc[a][b][m][n] = (f32x4){0.f, 0.f, 0.f, 0.f};
;         cur = nxt; cA = nA; cB = nB; ++ui;
;         if constexpr (Epi::NPRE > 0) E.preload(cur, wr, fr, pre);
;         if constexpr (ALIGN_EPI) { if (wr == 1) PG8_BAR; }
	ds_read_b128 v[174:177], v140 offset:49152
	ds_read_b128 v[178:181], v140 offset:50176
	ds_read_b128 v[182:185], v140 offset:51200
	ds_read_b128 v[186:189], v140 offset:52224
	ds_read_b128 v[190:193], v140 offset:53248
	ds_read_b128 v[194:197], v140 offset:54272
	ds_read_b128 v[198:201], v140 offset:55296
	ds_read_b128 v[204:207], v140 offset:56320
	s_add_u32 s34, s30, 0x80
	s_addc_u32 s35, s31, 0
	s_mov_b32 m0, s48
	s_nop 0
	global_load_lds_dwordx4 v136, s[34:35]
	s_add_u32 s30, s30, 0x160080
	s_mov_b32 m0, s49
	s_nop 0
	global_load_lds_dwordx4 v138, s[34:35]
	s_addc_u32 s31, s31, 0
	s_mov_b32 m0, s52
	s_nop 0
	global_load_lds_dwordx4 v136, s[30:31]
	s_nop 0
	s_mov_b32 m0, s53
	s_nop 0
	global_load_lds_dwordx4 v138, s[30:31]
	s_mov_b32 m0, s50
	s_nop 0
	global_load_lds_dwordx4 v131, s[28:29]
	s_nop 0
	s_mov_b32 m0, s51
	s_nop 0
	global_load_lds_dwordx4 v137, s[28:29]
	s_waitcnt vmcnt(8)
	s_waitcnt lgkmcnt(0)
	s_barrier
	s_setprio 1
	v_mfma_f32_16x16x32_bf16 v[62:65], v[142:145], v[174:177], v[62:65]
	v_mfma_f32_16x16x32_bf16 v[58:61], v[150:153], v[174:177], v[58:61]
	v_mfma_f32_16x16x32_bf16 v[46:49], v[142:145], v[182:185], v[46:49]
	v_mfma_f32_16x16x32_bf16 v[42:45], v[150:153], v[182:185], v[42:45]
	v_mfma_f32_16x16x32_bf16 v[30:33], v[142:145], v[190:193], v[30:33]
	v_mfma_f32_16x16x32_bf16 v[26:29], v[150:153], v[190:193], v[26:29]
	v_mfma_f32_16x16x32_bf16 v[14:17], v[142:145], v[198:201], v[14:17]
	v_mfma_f32_16x16x32_bf16 v[10:13], v[150:153], v[198:201], v[10:13]
	v_mfma_f32_16x16x32_bf16 v[62:65], v[146:149], v[178:181], v[62:65]
	v_mfma_f32_16x16x32_bf16 v[58:61], v[154:157], v[178:181], v[58:61]
	v_mfma_f32_16x16x32_bf16 v[46:49], v[146:149], v[186:189], v[46:49]
	v_mfma_f32_16x16x32_bf16 v[42:45], v[154:157], v[186:189], v[42:45]
	v_mfma_f32_16x16x32_bf16 v[30:33], v[146:149], v[194:197], v[30:33]
	v_mfma_f32_16x16x32_bf16 v[26:29], v[154:157], v[194:197], v[26:29]
	v_mfma_f32_16x16x32_bf16 v[14:17], v[146:149], v[204:207], v[14:17]
	v_mfma_f32_16x16x32_bf16 v[10:13], v[154:157], v[204:207], v[10:13]
	v_mfma_f32_16x16x32_bf16 v[54:57], v[158:161], v[174:177], v[54:57]
	v_mfma_f32_16x16x32_bf16 v[50:53], v[166:169], v[174:177], v[50:53]
	v_mfma_f32_16x16x32_bf16 v[38:41], v[158:161], v[182:185], v[38:41]
	v_mfma_f32_16x16x32_bf16 v[34:37], v[166:169], v[182:185], v[34:37]
	v_mfma_f32_16x16x32_bf16 v[22:25], v[158:161], v[190:193], v[22:25]
	v_mfma_f32_16x16x32_bf16 v[18:21], v[166:169], v[190:193], v[18:21]
	v_mfma_f32_16x16x32_bf16 v[6:9], v[158:161], v[198:201], v[6:9]
	v_mfma_f32_16x16x32_bf16 v[2:5], v[166:169], v[198:201], v[2:5]
	v_mfma_f32_16x16x32_bf16 v[54:57], v[162:165], v[178:181], v[54:57]
	v_mfma_f32_16x16x32_bf16 v[50:53], v[170:173], v[178:181], v[50:53]
	v_mfma_f32_16x16x32_bf16 v[38:41], v[162:165], v[186:189], v[38:41]
	v_mfma_f32_16x16x32_bf16 v[34:37], v[170:173], v[186:189], v[34:37]
	v_mfma_f32_16x16x32_bf16 v[22:25], v[162:165], v[194:197], v[22:25]
	v_mfma_f32_16x16x32_bf16 v[18:21], v[170:173], v[194:197], v[18:21]
	v_mfma_f32_16x16x32_bf16 v[6:9], v[162:165], v[204:207], v[6:9]
	v_mfma_f32_16x16x32_bf16 v[2:5], v[170:173], v[204:207], v[2:5]
	s_setprio 0
	s_barrier
	s_add_i32 s60, s60, 2
	s_add_u32 s26, s26, 0x100
	s_addc_u32 s27, s27, 0
	s_cmpk_gt_u32 s60, 0x55
	s_cbranch_scc0 .LBB0_2172
	s_and_b64 vcc, exec, s[10:11]
	s_cbranch_vccnz .LBB0_2160
	v_mov_b32_e32 v2, 0
	s_mov_b32 s45, s57
	s_mov_b32 s17, s58
	s_mov_b64 s[20:21], s[24:25]
	s_mov_b64 s[22:23], s[12:13]
	s_mov_b32 s56, s59
	v_mov_b32_e32 v3, v2
	v_mov_b32_e32 v4, v2
	v_mov_b32_e32 v5, v2
	v_mov_b32_e32 v6, v2
	v_mov_b32_e32 v7, v2
	v_mov_b32_e32 v8, v2
	v_mov_b32_e32 v9, v2
	v_mov_b32_e32 v18, v2
	v_mov_b32_e32 v19, v2
	v_mov_b32_e32 v20, v2
	v_mov_b32_e32 v21, v2
	v_mov_b32_e32 v22, v2
	v_mov_b32_e32 v23, v2
	v_mov_b32_e32 v24, v2
	v_mov_b32_e32 v25, v2
	v_mov_b32_e32 v34, v2
	v_mov_b32_e32 v35, v2
	v_mov_b32_e32 v36, v2
	v_mov_b32_e32 v37, v2
	v_mov_b32_e32 v38, v2
	v_mov_b32_e32 v39, v2
	v_mov_b32_e32 v40, v2
	v_mov_b32_e32 v41, v2
	v_mov_b32_e32 v50, v2
	v_mov_b32_e32 v51, v2
	v_mov_b32_e32 v52, v2
	v_mov_b32_e32 v53, v2
	v_mov_b32_e32 v54, v2
	v_mov_b32_e32 v55, v2
	v_mov_b32_e32 v56, v2
	v_mov_b32_e32 v57, v2
	v_mov_b32_e32 v10, v2
	v_mov_b32_e32 v11, v2
	v_mov_b32_e32 v12, v2
	v_mov_b32_e32 v13, v2
	v_mov_b32_e32 v14, v2
	v_mov_b32_e32 v15, v2
	v_mov_b32_e32 v16, v2
	v_mov_b32_e32 v17, v2
	v_mov_b32_e32 v26, v2
	v_mov_b32_e32 v27, v2
	v_mov_b32_e32 v28, v2
	v_mov_b32_e32 v29, v2
	v_mov_b32_e32 v30, v2
	v_mov_b32_e32 v31, v2
	v_mov_b32_e32 v32, v2
	v_mov_b32_e32 v33, v2
	v_mov_b32_e32 v42, v2
	v_mov_b32_e32 v43, v2
	v_mov_b32_e32 v44, v2
	v_mov_b32_e32 v45, v2
	v_mov_b32_e32 v46, v2
	v_mov_b32_e32 v47, v2
	v_mov_b32_e32 v48, v2
	v_mov_b32_e32 v49, v2
	v_mov_b32_e32 v58, v2
	v_mov_b32_e32 v59, v2
	v_mov_b32_e32 v60, v2
	v_mov_b32_e32 v61, v2
	v_mov_b32_e32 v62, v2
	v_mov_b32_e32 v63, v2
	v_mov_b32_e32 v64, v2
	v_mov_b32_e32 v65, v2
	v_mov_b32_e32 v66, v2
	v_mov_b32_e32 v67, v2
	v_mov_b32_e32 v68, v2
	v_mov_b32_e32 v69, v2
	v_mov_b32_e32 v70, v2
	v_mov_b32_e32 v71, v2
	v_mov_b32_e32 v72, v2
	v_mov_b32_e32 v73, v2
	v_mov_b32_e32 v82, v2
	v_mov_b32_e32 v83, v2
	v_mov_b32_e32 v84, v2
	v_mov_b32_e32 v85, v2
	v_mov_b32_e32 v86, v2
	v_mov_b32_e32 v87, v2
	v_mov_b32_e32 v88, v2
	v_mov_b32_e32 v89, v2
	v_mov_b32_e32 v98, v2
	v_mov_b32_e32 v99, v2
	v_mov_b32_e32 v100, v2
	v_mov_b32_e32 v101, v2
	v_mov_b32_e32 v102, v2
	v_mov_b32_e32 v103, v2
	v_mov_b32_e32 v104, v2
	v_mov_b32_e32 v105, v2
	v_mov_b32_e32 v114, v2
	v_mov_b32_e32 v115, v2
	v_mov_b32_e32 v116, v2
	v_mov_b32_e32 v117, v2
	v_mov_b32_e32 v118, v2
	v_mov_b32_e32 v119, v2
	v_mov_b32_e32 v120, v2
	v_mov_b32_e32 v121, v2
	v_mov_b32_e32 v74, v2
	v_mov_b32_e32 v75, v2
	v_mov_b32_e32 v76, v2
	v_mov_b32_e32 v77, v2
	v_mov_b32_e32 v78, v2
	v_mov_b32_e32 v79, v2
	v_mov_b32_e32 v80, v2
	v_mov_b32_e32 v81, v2
	v_mov_b32_e32 v90, v2
	v_mov_b32_e32 v91, v2
	v_mov_b32_e32 v92, v2
	v_mov_b32_e32 v93, v2
	v_mov_b32_e32 v94, v2
	v_mov_b32_e32 v95, v2
	v_mov_b32_e32 v96, v2
	v_mov_b32_e32 v97, v2
	v_mov_b32_e32 v106, v2
	v_mov_b32_e32 v107, v2
	v_mov_b32_e32 v108, v2
	v_mov_b32_e32 v109, v2
	v_mov_b32_e32 v110, v2
	v_mov_b32_e32 v111, v2
	v_mov_b32_e32 v112, v2
	v_mov_b32_e32 v113, v2
	v_mov_b32_e32 v122, v2
	v_mov_b32_e32 v123, v2
	v_mov_b32_e32 v124, v2
	v_mov_b32_e32 v125, v2
	v_mov_b32_e32 v126, v2
	v_mov_b32_e32 v127, v2
	v_mov_b32_e32 v128, v2
	v_mov_b32_e32 v129, v2
	s_branch .LBB0_2160
